# main-loop LDS-DMA loads: VALU 64-bit address adds replaced by saddr+voffset with offset:128 and M0-128
# speedup vs baseline: 1.0058x; 1.0058x over previous
; #define G_STAGE(bufoff, gbase, voff) do { _Pragma("unroll") for (int _i = 0; _i < 2; ++_i) { unsigned _vo = (voff)[_i]; asm volatile("" : "+v"(_vo));   \
;     __builtin_amdgcn_global_load_lds((const unsigned*)((const char*)(gbase) + _vo), (LAS unsigned*)(lds + (bufoff) + ldsw + _i * 8192), 16, 0, 0); } } while (0)
; #define G_LDA(dst, b, h) do { _Pragma("unroll") for (int m = 0; m < 4; ++m) _Pragma("unroll") for (int k = 0; k < 2; ++k) dst[m][k] = *(const LAS bf16x8*)(lds + G_SA(b, h) + aoff + m * 2048 + k * 1024); } while (0)
; #define G_LDB(dst, b, h) do { _Pragma("unroll") for (int n = 0; n < 2; ++n) _Pragma("unroll") for (int k = 0; k < 2; ++k) dst[n][k] = *(const LAS bf16x8*)(lds + G_SB(b, h) + boff + n * 2048 + k * 1024); } while (0)
; #define G_MMA(ai, bj, At, Bt) do { __builtin_amdgcn_s_setprio(1); _Pragma("unroll") for (int m = 0; m < 4; ++m) _Pragma("unroll") for (int n = 0; n < 2; ++n) _Pragma("unroll") for (int k = 0; k < 2; ++k) \
;     acc[ai][bj][m][n] = __builtin_amdgcn_mfma_f32_16x16x32_bf16(Bt[n][k], At[m][k], acc[ai][bj][m][n], 0, 0, 0); __builtin_amdgcn_s_setprio(0); } while (0)
; #define G_WAIT_V(n) asm volatile("s_waitcnt vmcnt(" #n ")" ::: "memory")
; #define G_WAIT_L(n) asm volatile("s_waitcnt lgkmcnt(" #n ")" ::: "memory")
; #define G_BAR __builtin_amdgcn_s_barrier()
; template <class Epi>
; __device__ __forceinline__ void gemm_phase(LAS unsigned char* lds, const int K, const unsigned lda_b, const unsigned ldb_b, const Map& M, const Epi& E) {
;     ...
;     for (int t = 0; t < nt; t += 2) {
;       const bool last = (t == nt - 2);
;       const char* a1h1 = cur.a0 + a_h + (size_t)(t + 1) * kstep;
;       const char* a2h0 = last ? nxt.a0 : cur.a0 + (size_t)(t + 2) * kstep; const char* a2h1 = a2h0 + a_h;
;       const char* b2h0 = last ? nxt.b0 : cur.b0 + (size_t)(t + 2) * kstep; const char* b2h1 = last ? nxt.b1 : cur.b1 + (size_t)(t + 2) * kstep;
;       G_LDB(B0, 0, 0); G_SCHED; G_LDA(At, 0, 0); G_STAGE(G_SA(1, 1), a1h1, voffA);
;       G_WAIT_L(8); G_BAR; G_WAIT_L(0); G_MMA(0, 0, At, B0); G_BAR; G_SCHED;
;       G_LDB(B1, 0, 1); G_STAGE(G_SB(0, 0), b2h0, voffB);
;       G_BAR; G_WAIT_L(0); G_MMA(0, 1, At, B1); G_BAR;
;       G_LDA(At, 0, 1); G_STAGE(G_SA(0, 0), a2h0, voffA);
;       G_BAR; G_WAIT_L(0); G_MMA(1, 0, At, B0); G_BAR; G_SCHED;
;       G_STAGE(G_SB(0, 1), b2h1, voffB);
;       G_WAIT_V(6); G_BAR; G_MMA(1, 1, At, B1); G_BAR;
.LBB0_235:
	s_add_u32 s22, s2, 0xfff80080
	s_addc_u32 s34, s3, -1
	s_add_u32 s35, s29, 0xfffe0000
	s_addc_u32 s38, s30, -1
	s_add_i32 s81, 0, 0x10000
	v_add_u32_e32 v80, s81, v160
	ds_read_b128 v[138:141], v80
	ds_read_b128 v[142:145], v80 offset:1024
	ds_read_b128 v[146:149], v80 offset:2048
	ds_read_b128 v[150:153], v80 offset:3072
	s_cmp_eq_u32 s31, 28
	s_cselect_b32 s43, s7, s34
	s_cselect_b32 s42, s6, s22
	s_cselect_b32 s45, s9, s38
	s_cselect_b32 s44, s8, s35
	v_mov_b32_e32 v80, v154
	s_cselect_b32 s39, s28, s30
	s_cselect_b32 s38, s0, s29
	s_add_u32 s68, s42, 0x80000
	ds_read_b128 v[166:169], v165
	ds_read_b128 v[170:173], v165 offset:1024
	ds_read_b128 v[174:177], v165 offset:2048
	ds_read_b128 v[184:187], v165 offset:3072
	ds_read_b128 v[190:193], v165 offset:4096
	ds_read_b128 v[194:197], v165 offset:5120
	ds_read_b128 v[198:201], v165 offset:6144
	ds_read_b128 v[202:205], v165 offset:7168
	s_addc_u32 s69, s43, 0
	s_add_i32 m0, s19, 0xc000
	s_nop 0
	global_load_lds_dwordx4 v80, s[2:3]
	v_mov_b32_e32 v80, v156
	s_add_i32 m0, s19, 0xe000
	s_nop 0
	global_load_lds_dwordx4 v80, s[2:3]
	s_waitcnt lgkmcnt(8)
	s_barrier
	s_waitcnt lgkmcnt(0)
	s_setprio 1
	s_waitcnt lgkmcnt(0)
	v_mfma_f32_16x16x32_bf16 v[126:129], v[138:141], v[166:169], v[126:129]
	v_mfma_f32_16x16x32_bf16 v[122:125], v[146:149], v[166:169], v[122:125]
	v_mfma_f32_16x16x32_bf16 v[110:113], v[138:141], v[174:177], v[110:113]
	v_mfma_f32_16x16x32_bf16 v[106:109], v[146:149], v[174:177], v[106:109]
	v_mfma_f32_16x16x32_bf16 v[94:97], v[138:141], v[190:193], v[94:97]
	v_mfma_f32_16x16x32_bf16 v[90:93], v[146:149], v[190:193], v[90:93]
	v_mfma_f32_16x16x32_bf16 v[76:79], v[138:141], v[198:201], v[76:79]
	v_mfma_f32_16x16x32_bf16 v[72:75], v[146:149], v[198:201], v[72:75]
	v_mfma_f32_16x16x32_bf16 v[126:129], v[142:145], v[170:173], v[126:129]
	v_mfma_f32_16x16x32_bf16 v[122:125], v[150:153], v[170:173], v[122:125]
	v_mfma_f32_16x16x32_bf16 v[110:113], v[142:145], v[184:187], v[110:113]
	v_mfma_f32_16x16x32_bf16 v[106:109], v[150:153], v[184:187], v[106:109]
	v_mfma_f32_16x16x32_bf16 v[94:97], v[142:145], v[194:197], v[94:97]
	v_mfma_f32_16x16x32_bf16 v[90:93], v[150:153], v[194:197], v[90:93]
	v_mfma_f32_16x16x32_bf16 v[76:79], v[142:145], v[202:205], v[76:79]
	v_mfma_f32_16x16x32_bf16 v[72:75], v[150:153], v[202:205], v[72:75]
	s_setprio 0
	s_barrier
	s_add_i32 s22, 0, 0x14000
	v_add_u32_e32 v80, s22, v160
	ds_read_b128 v[206:209], v80
	ds_read_b128 v[210:213], v80 offset:1024
	ds_read_b128 v[214:217], v80 offset:2048
	ds_read_b128 v[218:221], v80 offset:3072
	v_mov_b32_e32 v80, v155
	s_add_i32 s34, s81, s18
	s_mov_b32 m0, s34
	s_nop 0
	global_load_lds_dwordx4 v80, s[44:45]
	v_mov_b32_e32 v80, v157
	s_add_i32 m0, s34, 0x2000
	s_nop 0
	global_load_lds_dwordx4 v80, s[44:45]
	s_barrier
	s_waitcnt lgkmcnt(0)
	s_setprio 1
	s_waitcnt lgkmcnt(0)
	v_mfma_f32_16x16x32_bf16 v[118:121], v[206:209], v[166:169], v[118:121]
	v_mfma_f32_16x16x32_bf16 v[114:117], v[214:217], v[166:169], v[114:117]
	v_mfma_f32_16x16x32_bf16 v[102:105], v[206:209], v[174:177], v[102:105]
	v_mfma_f32_16x16x32_bf16 v[98:101], v[214:217], v[174:177], v[98:101]
	v_mfma_f32_16x16x32_bf16 v[86:89], v[206:209], v[190:193], v[86:89]
	v_mfma_f32_16x16x32_bf16 v[82:85], v[214:217], v[190:193], v[82:85]
	v_mfma_f32_16x16x32_bf16 v[68:71], v[206:209], v[198:201], v[68:71]
	v_mfma_f32_16x16x32_bf16 v[64:67], v[214:217], v[198:201], v[64:67]
	v_mfma_f32_16x16x32_bf16 v[118:121], v[210:213], v[170:173], v[118:121]
	v_mfma_f32_16x16x32_bf16 v[114:117], v[218:221], v[170:173], v[114:117]
	v_mfma_f32_16x16x32_bf16 v[102:105], v[210:213], v[184:187], v[102:105]
	v_mfma_f32_16x16x32_bf16 v[98:101], v[218:221], v[184:187], v[98:101]
	v_mfma_f32_16x16x32_bf16 v[86:89], v[210:213], v[194:197], v[86:89]
	v_mfma_f32_16x16x32_bf16 v[82:85], v[218:221], v[194:197], v[82:85]
	v_mfma_f32_16x16x32_bf16 v[68:71], v[210:213], v[202:205], v[68:71]
	v_mfma_f32_16x16x32_bf16 v[64:67], v[218:221], v[202:205], v[64:67]
	s_setprio 0
	v_mov_b32_e32 v80, v154
	s_mov_b32 m0, s19
	s_barrier
	ds_read_b128 v[166:169], v165 offset:16384
	ds_read_b128 v[170:173], v165 offset:17408
	ds_read_b128 v[174:177], v165 offset:18432
	ds_read_b128 v[184:187], v165 offset:19456
	ds_read_b128 v[190:193], v165 offset:20480
	ds_read_b128 v[194:197], v165 offset:21504
	ds_read_b128 v[198:201], v165 offset:22528
	ds_read_b128 v[202:205], v165 offset:23552
	s_nop 0
	global_load_lds_dwordx4 v80, s[42:43]
	v_mov_b32_e32 v80, v156
	s_mov_b32 m0, s46
	s_nop 0
	global_load_lds_dwordx4 v80, s[42:43]
	s_barrier
	s_waitcnt lgkmcnt(0)
	s_setprio 1
	s_waitcnt lgkmcnt(0)
	v_mfma_f32_16x16x32_bf16 v[60:63], v[138:141], v[166:169], v[60:63]
	v_mfma_f32_16x16x32_bf16 v[56:59], v[146:149], v[166:169], v[56:59]
	v_mfma_f32_16x16x32_bf16 v[44:47], v[138:141], v[174:177], v[44:47]
	v_mfma_f32_16x16x32_bf16 v[40:43], v[146:149], v[174:177], v[40:43]
	v_mfma_f32_16x16x32_bf16 v[28:31], v[138:141], v[190:193], v[28:31]
	v_mfma_f32_16x16x32_bf16 v[24:27], v[146:149], v[190:193], v[24:27]
	v_mfma_f32_16x16x32_bf16 v[12:15], v[138:141], v[198:201], v[12:15]
	v_mfma_f32_16x16x32_bf16 v[8:11], v[146:149], v[198:201], v[8:11]
	v_mfma_f32_16x16x32_bf16 v[60:63], v[142:145], v[170:173], v[60:63]
	v_mfma_f32_16x16x32_bf16 v[56:59], v[150:153], v[170:173], v[56:59]
	v_mfma_f32_16x16x32_bf16 v[44:47], v[142:145], v[184:187], v[44:47]
	v_mfma_f32_16x16x32_bf16 v[40:43], v[150:153], v[184:187], v[40:43]
	v_mfma_f32_16x16x32_bf16 v[28:31], v[142:145], v[194:197], v[28:31]
	v_mfma_f32_16x16x32_bf16 v[24:27], v[150:153], v[194:197], v[24:27]
	v_mfma_f32_16x16x32_bf16 v[12:15], v[142:145], v[202:205], v[12:15]
	v_mfma_f32_16x16x32_bf16 v[8:11], v[150:153], v[202:205], v[8:11]
	s_setprio 0
	s_barrier
; #define G_STAGE(bufoff, gbase, voff) do { _Pragma("unroll") for (int _i = 0; _i < 2; ++_i) { unsigned _vo = (voff)[_i]; asm volatile("" : "+v"(_vo));   \
;     __builtin_amdgcn_global_load_lds((const unsigned*)((const char*)(gbase) + _vo), (LAS unsigned*)(lds + (bufoff) + ldsw + _i * 8192), 16, 0, 0); } } while (0)
; #define G_LDA(dst, b, h) do { _Pragma("unroll") for (int m = 0; m < 4; ++m) _Pragma("unroll") for (int k = 0; k < 2; ++k) dst[m][k] = *(const LAS bf16x8*)(lds + G_SA(b, h) + aoff + m * 2048 + k * 1024); } while (0)
; #define G_LDB(dst, b, h) do { _Pragma("unroll") for (int n = 0; n < 2; ++n) _Pragma("unroll") for (int k = 0; k < 2; ++k) dst[n][k] = *(const LAS bf16x8*)(lds + G_SB(b, h) + boff + n * 2048 + k * 1024); } while (0)
; #define G_MMA(ai, bj, At, Bt) do { __builtin_amdgcn_s_setprio(1); _Pragma("unroll") for (int m = 0; m < 4; ++m) _Pragma("unroll") for (int n = 0; n < 2; ++n) _Pragma("unroll") for (int k = 0; k < 2; ++k) \
;     acc[ai][bj][m][n] = __builtin_amdgcn_mfma_f32_16x16x32_bf16(Bt[n][k], At[m][k], acc[ai][bj][m][n], 0, 0, 0); __builtin_amdgcn_s_setprio(0); } while (0)
; #define G_WAIT_V(n) asm volatile("s_waitcnt vmcnt(" #n ")" ::: "memory")
; #define G_WAIT_L(n) asm volatile("s_waitcnt lgkmcnt(" #n ")" ::: "memory")
; #define G_BAR __builtin_amdgcn_s_barrier()
; #define G_SCHED __builtin_amdgcn_sched_barrier(0)
; template <class Epi>
; __device__ __forceinline__ void gemm_phase(LAS unsigned char* lds, const int K, const unsigned lda_b, const unsigned ldb_b, const Map& M, const Epi& E) {
;     ...
;       G_WAIT_V(6); G_BAR; G_MMA(1, 1, At, B1); G_BAR;
;       G_LDB(B0, 1, 0); G_SCHED; G_LDA(At, 1, 0); G_STAGE(G_SA(0, 1), a2h1, voffA);
;       G_WAIT_L(8); G_BAR; G_WAIT_L(0); G_MMA(0, 0, At, B0); G_BAR; G_SCHED;
;       G_LDB(B1, 1, 1); G_STAGE(G_SB(1, 0), b2h0 + kstep, voffB);
;       G_BAR; G_WAIT_L(0); G_MMA(0, 1, At, B1); G_BAR;
;       G_LDA(At, 1, 1); G_STAGE(G_SA(1, 0), a2h0 + kstep, voffA);
;       G_BAR; G_WAIT_L(0); G_MMA(1, 0, At, B0); G_BAR; G_SCHED;
	v_mov_b32_e32 v80, v155
	s_add_i32 s22, s22, s18
	s_mov_b32 m0, s22
	s_nop 0
	global_load_lds_dwordx4 v80, s[38:39]
	v_mov_b32_e32 v80, v157
	s_add_i32 m0, s22, 0x2000
	s_nop 0
	global_load_lds_dwordx4 v80, s[38:39]
	s_waitcnt vmcnt(6)
	s_barrier
	s_setprio 1
	v_mfma_f32_16x16x32_bf16 v[52:55], v[206:209], v[166:169], v[52:55]
	v_mfma_f32_16x16x32_bf16 v[48:51], v[214:217], v[166:169], v[48:51]
	v_mfma_f32_16x16x32_bf16 v[36:39], v[206:209], v[174:177], v[36:39]
	v_mfma_f32_16x16x32_bf16 v[32:35], v[214:217], v[174:177], v[32:35]
	v_mfma_f32_16x16x32_bf16 v[20:23], v[206:209], v[190:193], v[20:23]
	v_mfma_f32_16x16x32_bf16 v[16:19], v[214:217], v[190:193], v[16:19]
	v_mfma_f32_16x16x32_bf16 v[4:7], v[206:209], v[198:201], v[4:7]
	v_mfma_f32_16x16x32_bf16 v[0:3], v[214:217], v[198:201], v[0:3]
	v_mfma_f32_16x16x32_bf16 v[52:55], v[210:213], v[170:173], v[52:55]
	v_mfma_f32_16x16x32_bf16 v[48:51], v[218:221], v[170:173], v[48:51]
	v_mfma_f32_16x16x32_bf16 v[36:39], v[210:213], v[184:187], v[36:39]
	v_mfma_f32_16x16x32_bf16 v[32:35], v[218:221], v[184:187], v[32:35]
	v_mfma_f32_16x16x32_bf16 v[20:23], v[210:213], v[194:197], v[20:23]
	v_mfma_f32_16x16x32_bf16 v[16:19], v[218:221], v[194:197], v[16:19]
	v_mfma_f32_16x16x32_bf16 v[4:7], v[210:213], v[202:205], v[4:7]
	v_mfma_f32_16x16x32_bf16 v[0:3], v[218:221], v[202:205], v[0:3]
	s_setprio 0
	s_add_i32 s22, 0, 0x18000
	v_add_u32_e32 v80, s22, v160
	s_barrier
	ds_read_b128 v[138:141], v80
	ds_read_b128 v[142:145], v80 offset:1024
	ds_read_b128 v[146:149], v80 offset:2048
	ds_read_b128 v[150:153], v80 offset:3072
	v_mov_b32_e32 v80, v154
	s_mov_b32 m0, s47
	ds_read_b128 v[166:169], v165 offset:32768
	ds_read_b128 v[170:173], v165 offset:33792
	ds_read_b128 v[174:177], v165 offset:34816
	ds_read_b128 v[184:187], v165 offset:35840
	ds_read_b128 v[190:193], v165 offset:36864
	ds_read_b128 v[194:197], v165 offset:37888
	ds_read_b128 v[198:201], v165 offset:38912
	ds_read_b128 v[202:205], v165 offset:39936
	s_nop 0
	global_load_lds_dwordx4 v80, s[68:69]
	v_mov_b32_e32 v80, v156
	s_mov_b32 m0, s48
	s_nop 0
	global_load_lds_dwordx4 v80, s[68:69]
	s_waitcnt lgkmcnt(8)
	s_barrier
	s_waitcnt lgkmcnt(0)
	s_setprio 1
	s_waitcnt lgkmcnt(0)
	v_mfma_f32_16x16x32_bf16 v[126:129], v[138:141], v[166:169], v[126:129]
	v_mfma_f32_16x16x32_bf16 v[122:125], v[146:149], v[166:169], v[122:125]
	v_mfma_f32_16x16x32_bf16 v[110:113], v[138:141], v[174:177], v[110:113]
	v_mfma_f32_16x16x32_bf16 v[106:109], v[146:149], v[174:177], v[106:109]
	v_mfma_f32_16x16x32_bf16 v[94:97], v[138:141], v[190:193], v[94:97]
	v_mfma_f32_16x16x32_bf16 v[90:93], v[146:149], v[190:193], v[90:93]
	v_mfma_f32_16x16x32_bf16 v[76:79], v[138:141], v[198:201], v[76:79]
	v_mfma_f32_16x16x32_bf16 v[72:75], v[146:149], v[198:201], v[72:75]
	v_mfma_f32_16x16x32_bf16 v[126:129], v[142:145], v[170:173], v[126:129]
	v_mfma_f32_16x16x32_bf16 v[122:125], v[150:153], v[170:173], v[122:125]
	v_mfma_f32_16x16x32_bf16 v[110:113], v[142:145], v[184:187], v[110:113]
	v_mfma_f32_16x16x32_bf16 v[106:109], v[150:153], v[184:187], v[106:109]
	v_mfma_f32_16x16x32_bf16 v[94:97], v[142:145], v[194:197], v[94:97]
	v_mfma_f32_16x16x32_bf16 v[90:93], v[150:153], v[194:197], v[90:93]
	v_mfma_f32_16x16x32_bf16 v[76:79], v[142:145], v[202:205], v[76:79]
	v_mfma_f32_16x16x32_bf16 v[72:75], v[150:153], v[202:205], v[72:75]
	s_setprio 0
	s_barrier
	s_add_i32 s34, 0, 0x1c000
	v_add_u32_e32 v80, s34, v160
	ds_read_b128 v[206:209], v80
	ds_read_b128 v[210:213], v80 offset:1024
	ds_read_b128 v[214:217], v80 offset:2048
	ds_read_b128 v[218:221], v80 offset:3072
	v_mov_b32_e32 v80, v155
	s_add_i32 s22, s22, s18
	s_add_i32 m0, s22, 0xffffff80
	v_mov_b32_e32 v80, v157
	global_load_lds_dwordx4 v155, s[44:45] offset:128
	s_add_i32 m0, s22, 0x1f80
	s_nop 0
	global_load_lds_dwordx4 v157, s[44:45] offset:128
	s_barrier
	s_waitcnt lgkmcnt(0)
	s_setprio 1
	s_waitcnt lgkmcnt(0)
	v_mfma_f32_16x16x32_bf16 v[118:121], v[206:209], v[166:169], v[118:121]
	v_mfma_f32_16x16x32_bf16 v[114:117], v[214:217], v[166:169], v[114:117]
	v_mfma_f32_16x16x32_bf16 v[102:105], v[206:209], v[174:177], v[102:105]
	v_mfma_f32_16x16x32_bf16 v[98:101], v[214:217], v[174:177], v[98:101]
	v_mfma_f32_16x16x32_bf16 v[86:89], v[206:209], v[190:193], v[86:89]
	v_mfma_f32_16x16x32_bf16 v[82:85], v[214:217], v[190:193], v[82:85]
	v_mfma_f32_16x16x32_bf16 v[68:71], v[206:209], v[198:201], v[68:71]
	v_mfma_f32_16x16x32_bf16 v[64:67], v[214:217], v[198:201], v[64:67]
	v_mfma_f32_16x16x32_bf16 v[118:121], v[210:213], v[170:173], v[118:121]
	v_mfma_f32_16x16x32_bf16 v[114:117], v[218:221], v[170:173], v[114:117]
	v_mfma_f32_16x16x32_bf16 v[102:105], v[210:213], v[184:187], v[102:105]
	v_mfma_f32_16x16x32_bf16 v[98:101], v[218:221], v[184:187], v[98:101]
	v_mfma_f32_16x16x32_bf16 v[86:89], v[210:213], v[194:197], v[86:89]
	v_mfma_f32_16x16x32_bf16 v[82:85], v[218:221], v[194:197], v[82:85]
	v_mfma_f32_16x16x32_bf16 v[68:71], v[210:213], v[202:205], v[68:71]
	v_mfma_f32_16x16x32_bf16 v[64:67], v[218:221], v[202:205], v[64:67]
	s_setprio 0
	v_mov_b32_e32 v80, v154
	s_barrier
	ds_read_b128 v[166:169], v165 offset:49152
	ds_read_b128 v[170:173], v165 offset:50176
	ds_read_b128 v[174:177], v165 offset:51200
	ds_read_b128 v[184:187], v165 offset:52224
	ds_read_b128 v[190:193], v165 offset:53248
	ds_read_b128 v[194:197], v165 offset:54272
	ds_read_b128 v[198:201], v165 offset:55296
	ds_read_b128 v[202:205], v165 offset:56320
	s_add_i32 m0, s49, 0xffffff80
	v_mov_b32_e32 v80, v156
	global_load_lds_dwordx4 v154, s[42:43] offset:128
	s_add_i32 m0, s61, 0xffffff80
	s_nop 0
	global_load_lds_dwordx4 v156, s[42:43] offset:128
	s_barrier
; __device__ __forceinline__ float rinv_of(unsigned long long ss) { return rsqrtf((float)ss * (1.f / 16777216.f) * (1.f / DM) + 1e-6f); }
; #define G_STAGE(bufoff, gbase, voff) do { _Pragma("unroll") for (int _i = 0; _i < 2; ++_i) { unsigned _vo = (voff)[_i]; asm volatile("" : "+v"(_vo));   \
;     __builtin_amdgcn_global_load_lds((const unsigned*)((const char*)(gbase) + _vo), (LAS unsigned*)(lds + (bufoff) + ldsw + _i * 8192), 16, 0, 0); } } while (0)
; #define G_LDA(dst, b, h) do { _Pragma("unroll") for (int m = 0; m < 4; ++m) _Pragma("unroll") for (int k = 0; k < 2; ++k) dst[m][k] = *(const LAS bf16x8*)(lds + G_SA(b, h) + aoff + m * 2048 + k * 1024); } while (0)
; #define G_LDB(dst, b, h) do { _Pragma("unroll") for (int n = 0; n < 2; ++n) _Pragma("unroll") for (int k = 0; k < 2; ++k) dst[n][k] = *(const LAS bf16x8*)(lds + G_SB(b, h) + boff + n * 2048 + k * 1024); } while (0)
; #define G_WAIT_V(n) asm volatile("s_waitcnt vmcnt(" #n ")" ::: "memory")
; #define G_WAIT_L(n) asm volatile("s_waitcnt lgkmcnt(" #n ")" ::: "memory")
; #define G_BAR __builtin_amdgcn_s_barrier()
;   __device__ __forceinline__ void operator()(const f32x4 (&acc)[2][2][4][2], const Unit& u, const EpiCtx& x_, int wr, int wc, int fr, int fq) const {
;     ...
;     if (SCALE == 2) {
; #pragma unroll
;       for (int bj = 0; bj < 2; ++bj) {
;         const unsigned long long* sp = x_.ss + u.c0 + (PERM ? wc * 64 + bj * 32 + 8 * fq : bj * 128 + wc * 32 + 4 * fq);
; #pragma unroll
;         for (int i = 0; i < 4; ++i) { cs[bj][0][i] = rinv_of(sp[i]); cs[bj][1][i] = rinv_of(sp[(PERM ? 4 : 16) + i]); }
;       }
; template <class Epi>
; __device__ __forceinline__ void gemm_phase(LAS unsigned char* lds, const int K, const unsigned lda_b, const unsigned ldb_b, const Map& M, const Epi& E) {
;     ...
;       G_WAIT_V(6); G_BAR; G_MMA(1, 1, At, B1); G_BAR;
;       G_LDB(B0, 1, 0); G_SCHED; G_LDA(At, 1, 0); G_STAGE(G_SA(0, 1), a2h1, voffA);
;       G_WAIT_L(8); G_BAR; G_WAIT_L(0); G_MMA(0, 0, At, B0); G_BAR; G_SCHED;
;       G_LDB(B1, 1, 1); G_STAGE(G_SB(1, 0), b2h0 + kstep, voffB);
;       G_BAR; G_WAIT_L(0); G_MMA(0, 1, At, B1); G_BAR;
;       G_LDA(At, 1, 1); G_STAGE(G_SA(1, 0), a2h0 + kstep, voffA);
;       G_BAR; G_WAIT_L(0); G_MMA(1, 0, At, B0); G_BAR; G_SCHED;
;       G_STAGE(G_SB(1, 1), b2h1 + kstep, voffB);
;       G_WAIT_V(6); G_BAR; G_MMA(1, 1, At, B1); G_BAR;
;     }
	s_waitcnt lgkmcnt(0)
	s_setprio 1
	s_waitcnt lgkmcnt(0)
	v_mfma_f32_16x16x32_bf16 v[60:63], v[138:141], v[166:169], v[60:63]
	v_mfma_f32_16x16x32_bf16 v[56:59], v[146:149], v[166:169], v[56:59]
	v_mfma_f32_16x16x32_bf16 v[44:47], v[138:141], v[174:177], v[44:47]
	v_mfma_f32_16x16x32_bf16 v[40:43], v[146:149], v[174:177], v[40:43]
	v_mfma_f32_16x16x32_bf16 v[28:31], v[138:141], v[190:193], v[28:31]
	v_mfma_f32_16x16x32_bf16 v[24:27], v[146:149], v[190:193], v[24:27]
	v_mfma_f32_16x16x32_bf16 v[12:15], v[138:141], v[198:201], v[12:15]
	v_mfma_f32_16x16x32_bf16 v[8:11], v[146:149], v[198:201], v[8:11]
	v_mfma_f32_16x16x32_bf16 v[60:63], v[142:145], v[170:173], v[60:63]
	v_mfma_f32_16x16x32_bf16 v[56:59], v[150:153], v[170:173], v[56:59]
	v_mfma_f32_16x16x32_bf16 v[44:47], v[142:145], v[184:187], v[44:47]
	v_mfma_f32_16x16x32_bf16 v[40:43], v[150:153], v[184:187], v[40:43]
	v_mfma_f32_16x16x32_bf16 v[28:31], v[142:145], v[194:197], v[28:31]
	v_mfma_f32_16x16x32_bf16 v[24:27], v[150:153], v[194:197], v[24:27]
	v_mfma_f32_16x16x32_bf16 v[12:15], v[142:145], v[202:205], v[12:15]
	v_mfma_f32_16x16x32_bf16 v[8:11], v[150:153], v[202:205], v[8:11]
	s_setprio 0
	s_barrier
	v_mov_b32_e32 v80, v155
	s_add_i32 s22, s34, s18
	s_add_i32 m0, s22, 0xffffff80
	v_mov_b32_e32 v80, v157
	global_load_lds_dwordx4 v155, s[38:39] offset:128
	s_add_i32 m0, s22, 0x1f80
	s_nop 0
	global_load_lds_dwordx4 v157, s[38:39] offset:128
	s_waitcnt vmcnt(6)
	s_barrier
	s_setprio 1
	v_mfma_f32_16x16x32_bf16 v[52:55], v[206:209], v[166:169], v[52:55]
	v_mfma_f32_16x16x32_bf16 v[48:51], v[214:217], v[166:169], v[48:51]
	v_mfma_f32_16x16x32_bf16 v[36:39], v[206:209], v[174:177], v[36:39]
	v_mfma_f32_16x16x32_bf16 v[32:35], v[214:217], v[174:177], v[32:35]
	v_mfma_f32_16x16x32_bf16 v[20:23], v[206:209], v[190:193], v[20:23]
	v_mfma_f32_16x16x32_bf16 v[16:19], v[214:217], v[190:193], v[16:19]
	v_mfma_f32_16x16x32_bf16 v[4:7], v[206:209], v[198:201], v[4:7]
	v_mfma_f32_16x16x32_bf16 v[0:3], v[214:217], v[198:201], v[0:3]
	v_mfma_f32_16x16x32_bf16 v[52:55], v[210:213], v[170:173], v[52:55]
	v_mfma_f32_16x16x32_bf16 v[48:51], v[218:221], v[170:173], v[48:51]
	v_mfma_f32_16x16x32_bf16 v[36:39], v[210:213], v[184:187], v[36:39]
	v_mfma_f32_16x16x32_bf16 v[32:35], v[218:221], v[184:187], v[32:35]
	v_mfma_f32_16x16x32_bf16 v[20:23], v[210:213], v[194:197], v[20:23]
	v_mfma_f32_16x16x32_bf16 v[16:19], v[218:221], v[194:197], v[16:19]
	v_mfma_f32_16x16x32_bf16 v[4:7], v[210:213], v[202:205], v[4:7]
	v_mfma_f32_16x16x32_bf16 v[0:3], v[218:221], v[202:205], v[0:3]
	s_setprio 0
	s_add_i32 s31, s31, 2
	s_add_u32 s29, s29, 0x100
	s_addc_u32 s30, s30, 0
	s_add_u32 s2, s2, 0x100
	s_addc_u32 s3, s3, 0
	s_cmp_gt_u32 s31, 29
	s_barrier
	s_cbranch_scc0 .LBB0_235
	s_ashr_i32 s95, s94, 31
	v_readfirstlane_b32 s0, v130
	v_readfirstlane_b32 s42, v131
	v_lshl_add_u64 v[130:131], s[94:95], 3, v[134:135]
	s_nop 1
	global_load_dwordx4 v[170:173], v[130:131], off
	global_load_dwordx4 v[174:177], v[130:131], off offset:48
	global_load_dwordx4 v[184:187], v[130:131], off offset:272
	global_load_dwordx4 v[190:193], v[130:131], off offset:32
	global_load_dwordx4 v[194:197], v[130:131], off offset:16
	global_load_dwordx4 v[198:201], v[130:131], off offset:256
	global_load_dwordx4 v[202:205], v[130:131], off offset:288
	global_load_dwordx4 v[206:209], v[130:131], off offset:304
	s_nop 0
	s_nop 0
	v_mov_b64_e32 v[146:147], s[62:63]
	v_mov_b32_e32 v137, v81
	s_add_i32 s28, s67, s94
	s_ashr_i32 s29, s28, 31
	s_lshl_b64 s[38:39], s[28:29], 1
	s_nop 0
	s_waitcnt lgkmcnt(0)
	s_waitcnt vmcnt(7)
	v_ffbh_u32_e32 v80, v173
	v_min_u32_e32 v80, 32, v80
	v_lshlrev_b64 v[132:133], v80, v[172:173]
	s_nop 0
	v_min_u32_e32 v132, 1, v132
	v_or_b32_e32 v132, v133, v132
	v_cvt_f32_u32_e32 v132, v132
	v_sub_u32_e32 v80, 32, v80
	v_ldexp_f32 v133, v132, v80
	v_ffbh_u32_e32 v80, v171
	v_min_u32_e32 v80, 32, v80
	v_lshlrev_b64 v[138:139], v80, v[170:171]
	v_min_u32_e32 v132, 1, v138
	v_or_b32_e32 v132, v139, v132
	v_cvt_f32_u32_e32 v132, v132
	v_sub_u32_e32 v80, 32, v80
	v_ldexp_f32 v132, v132, v80
	v_pk_mul_f32 v[132:133], v[132:133], s[60:61] op_sel_hi:[1,0]
	s_nop 0
	v_pk_fma_f32 v[132:133], v[132:133], s[26:27], v[146:147] op_sel_hi:[1,0,0]
	s_nop 0
	v_mul_f32_e32 v80, 0x4b800000, v132
	v_cmp_gt_f32_e64 s[2:3], s50, v132
	v_cmp_gt_f32_e32 vcc, s50, v133
	s_nop 0
	v_cndmask_b32_e64 v80, v132, v80, s[2:3]
	v_rsq_f32_e32 v132, v80
	v_mul_f32_e32 v80, 0x4b800000, v133
	v_cndmask_b32_e32 v80, v133, v80, vcc
	v_rsq_f32_e32 v133, v80
	s_waitcnt lgkmcnt(0)
	s_waitcnt vmcnt(4)
	v_ffbh_u32_e32 v80, v193
	v_pk_mul_f32 v[138:139], v[132:133], s[64:65] op_sel_hi:[1,0]
	v_min_u32_e32 v80, 32, v80
	v_cndmask_b32_e32 v139, v133, v139, vcc
	v_cndmask_b32_e64 v138, v132, v138, s[2:3]
	v_lshlrev_b64 v[132:133], v80, v[192:193]
	s_nop 0
	v_min_u32_e32 v132, 1, v132
	v_or_b32_e32 v132, v133, v132
	v_cvt_f32_u32_e32 v132, v132
	v_sub_u32_e32 v80, 32, v80
	v_pk_mul_f32 v[126:127], v[126:127], v[138:139]
	v_pk_mul_f32 v[110:111], v[110:111], v[138:139]
	v_ldexp_f32 v133, v132, v80
	v_ffbh_u32_e32 v80, v191
	v_min_u32_e32 v80, 32, v80
	v_lshlrev_b64 v[140:141], v80, v[190:191]
	v_min_u32_e32 v132, 1, v140
	v_or_b32_e32 v132, v141, v132
	v_cvt_f32_u32_e32 v132, v132
	v_sub_u32_e32 v80, 32, v80
	v_pk_mul_f32 v[94:95], v[94:95], v[138:139]
	v_pk_mul_f32 v[76:77], v[76:77], v[138:139]
	v_ldexp_f32 v132, v132, v80
	v_pk_mul_f32 v[132:133], v[132:133], s[60:61] op_sel_hi:[1,0]
	v_pk_mul_f32 v[60:61], v[60:61], v[138:139]
	v_pk_fma_f32 v[132:133], v[132:133], s[26:27], v[146:147] op_sel_hi:[1,0,0]
	v_pk_mul_f32 v[44:45], v[44:45], v[138:139]
	v_mul_f32_e32 v80, 0x4b800000, v132
	v_cmp_gt_f32_e64 s[2:3], s50, v132
	v_cmp_gt_f32_e32 vcc, s50, v133
	v_pk_mul_f32 v[28:29], v[28:29], v[138:139]
	v_cndmask_b32_e64 v80, v132, v80, s[2:3]
	v_rsq_f32_e32 v132, v80
	v_mul_f32_e32 v80, 0x4b800000, v133
	v_cndmask_b32_e32 v80, v133, v80, vcc
	v_rsq_f32_e32 v133, v80
	v_pk_mul_f32 v[12:13], v[12:13], v[138:139]
	v_pk_mul_f32 v[140:141], v[132:133], s[64:65] op_sel_hi:[1,0]
	s_nop 0
	v_cndmask_b32_e32 v141, v133, v141, vcc
	v_cndmask_b32_e64 v140, v132, v140, s[2:3]
	s_waitcnt lgkmcnt(0)
; __device__ __forceinline__ unsigned cvt_pk_bf16(float lo, float hi) { unsigned r; asm("v_cvt_pk_bf16_f32 %0, %1, %2" : "=v"(r) : "v"(lo), "v"(hi)); return r; }
; __device__ __forceinline__ float rinv_of(unsigned long long ss) { return rsqrtf((float)ss * (1.f / 16777216.f) * (1.f / DM) + 1e-6f); }
;   __device__ __forceinline__ void operator()(const f32x4 (&acc)[2][2][4][2], const Unit& u, const EpiCtx& x_, int wr, int wc, int fr, int fq) const {
;     ...
;     if (SCALE == 2) {
; #pragma unroll
;       for (int bj = 0; bj < 2; ++bj) {
;         const unsigned long long* sp = x_.ss + u.c0 + (PERM ? wc * 64 + bj * 32 + 8 * fq : bj * 128 + wc * 32 + 4 * fq);
; #pragma unroll
;         for (int i = 0; i < 4; ++i) { cs[bj][0][i] = rinv_of(sp[i]); cs[bj][1][i] = rinv_of(sp[(PERM ? 4 : 16) + i]); }
;       }
;     }
; #pragma unroll
;     for (int ai = 0; ai < 2; ++ai)
; #pragma unroll
;       for (int m = 0; m < 4; ++m) {
;         const int row = (u.r0 + (ai ? x_.rdelta : 0)) + wr * 64 + m * 16 + fr;
;         bf16_t* rowp = (bf16_t*)u.C + (size_t)row * x_.ldc;
;         const float rs = (SCALE == 1) ? rinv_of(x_.ss[row]) : 1.f;
; #pragma unroll
;         for (int bj = 0; bj < 2; ++bj) {
;           const int cb = PERM ? (u.c0 + wc * 64 + bj * 32) : (u.c0 + bj * 128) + wc * 32;
;           f32x4 v0 = acc[ai][bj][m][0], v1 = acc[ai][bj][m][1];
;           if (SCALE == 1) { v0 *= rs; v1 *= rs; }
;           if (SCALE == 2) { v0 *= cs[bj][0]; v1 *= cs[bj][1]; }
;           if (PERM) {
;             uint4 o; o.x = cvt_pk_bf16(v0[0], v0[1]); o.y = cvt_pk_bf16(v0[2], v0[3]); o.z = cvt_pk_bf16(v1[0], v1[1]); o.w = cvt_pk_bf16(v1[2], v1[3]);
;             *(uint4*)(rowp + cb + 8 * fq) = o;
	s_waitcnt vmcnt(3)
	v_ffbh_u32_e32 v80, v197
	v_min_u32_e32 v80, 32, v80
	v_lshlrev_b64 v[132:133], v80, v[196:197]
	v_min_u32_e32 v132, 1, v132
	v_or_b32_e32 v132, v133, v132
	v_cvt_f32_u32_e32 v132, v132
	v_sub_u32_e32 v80, 32, v80
	v_ldexp_f32 v133, v132, v80
	v_ffbh_u32_e32 v80, v195
	v_min_u32_e32 v80, 32, v80
	v_lshlrev_b64 v[142:143], v80, v[194:195]
	v_min_u32_e32 v132, 1, v142
	v_or_b32_e32 v132, v143, v132
	v_cvt_f32_u32_e32 v132, v132
	v_sub_u32_e32 v80, 32, v80
	v_ldexp_f32 v132, v132, v80
	v_pk_mul_f32 v[132:133], v[132:133], s[60:61] op_sel_hi:[1,0]
	s_nop 0
	v_pk_fma_f32 v[132:133], v[132:133], s[26:27], v[146:147] op_sel_hi:[1,0,0]
	s_nop 0
	v_mul_f32_e32 v80, 0x4b800000, v132
	v_cmp_gt_f32_e64 s[2:3], s50, v132
	v_cmp_gt_f32_e32 vcc, s50, v133
	s_nop 0
	v_cndmask_b32_e64 v80, v132, v80, s[2:3]
	v_rsq_f32_e32 v132, v80
	v_mul_f32_e32 v80, 0x4b800000, v133
	v_cndmask_b32_e32 v80, v133, v80, vcc
	v_rsq_f32_e32 v133, v80
	v_ffbh_u32_e32 v80, v177
	v_min_u32_e32 v80, 32, v80
	v_pk_mul_f32 v[142:143], v[132:133], s[64:65] op_sel_hi:[1,0]
	s_nop 0
	v_cndmask_b32_e32 v143, v133, v143, vcc
	v_cndmask_b32_e64 v142, v132, v142, s[2:3]
	v_lshlrev_b64 v[132:133], v80, v[176:177]
	v_min_u32_e32 v132, 1, v132
	v_or_b32_e32 v132, v133, v132
	v_cvt_f32_u32_e32 v132, v132
	v_sub_u32_e32 v80, 32, v80
	v_pk_mul_f32 v[128:129], v[128:129], v[142:143]
	v_pk_mul_f32 v[112:113], v[112:113], v[142:143]
	v_ldexp_f32 v133, v132, v80
	v_ffbh_u32_e32 v80, v175
	v_min_u32_e32 v80, 32, v80
	v_lshlrev_b64 v[144:145], v80, v[174:175]
	s_nop 0
	v_min_u32_e32 v132, 1, v144
	v_or_b32_e32 v132, v145, v132
	v_cvt_f32_u32_e32 v132, v132
	v_sub_u32_e32 v80, 32, v80
	v_pk_mul_f32 v[96:97], v[96:97], v[142:143]
	v_pk_mul_f32 v[78:79], v[78:79], v[142:143]
	v_ldexp_f32 v132, v132, v80
	v_pk_mul_f32 v[132:133], v[132:133], s[60:61] op_sel_hi:[1,0]
	v_pk_mul_f32 v[62:63], v[62:63], v[142:143]
	v_pk_fma_f32 v[132:133], v[132:133], s[26:27], v[146:147] op_sel_hi:[1,0,0]
	v_pk_mul_f32 v[46:47], v[46:47], v[142:143]
	v_mul_f32_e32 v80, 0x4b800000, v132
	v_cmp_gt_f32_e64 s[2:3], s50, v132
	v_cmp_gt_f32_e32 vcc, s50, v133
	v_pk_mul_f32 v[30:31], v[30:31], v[142:143]
	v_cndmask_b32_e64 v80, v132, v80, s[2:3]
	v_rsq_f32_e32 v132, v80
	v_mul_f32_e32 v80, 0x4b800000, v133
	v_cndmask_b32_e32 v80, v133, v80, vcc
	v_rsq_f32_e32 v133, v80
	v_pk_mul_f32 v[14:15], v[14:15], v[142:143]
	v_pk_mul_f32 v[144:145], v[132:133], s[64:65] op_sel_hi:[1,0]
	s_nop 0
	v_cndmask_b32_e32 v145, v133, v145, vcc
	v_cndmask_b32_e64 v144, v132, v144, s[2:3]
	s_waitcnt lgkmcnt(0)
	s_waitcnt vmcnt(2)
	v_ffbh_u32_e32 v80, v201
	v_min_u32_e32 v80, 32, v80
	v_lshlrev_b64 v[132:133], v80, v[200:201]
	s_nop 0
	v_min_u32_e32 v132, 1, v132
	v_or_b32_e32 v132, v133, v132
	v_cvt_f32_u32_e32 v132, v132
	v_sub_u32_e32 v80, 32, v80
	v_ldexp_f32 v133, v132, v80
	v_ffbh_u32_e32 v80, v199
	v_min_u32_e32 v80, 32, v80
	v_lshlrev_b64 v[148:149], v80, v[198:199]
	v_min_u32_e32 v132, 1, v148
	v_or_b32_e32 v132, v149, v132
	v_cvt_f32_u32_e32 v132, v132
	v_sub_u32_e32 v80, 32, v80
	v_ldexp_f32 v132, v132, v80
	v_pk_mul_f32 v[132:133], v[132:133], s[60:61] op_sel_hi:[1,0]
	s_nop 0
	v_pk_fma_f32 v[132:133], v[132:133], s[26:27], v[146:147] op_sel_hi:[1,0,0]
	s_nop 0
	v_mul_f32_e32 v80, 0x4b800000, v132
	v_cmp_gt_f32_e64 s[2:3], s50, v132
	v_cmp_gt_f32_e32 vcc, s50, v133
	s_nop 0
	v_cndmask_b32_e64 v80, v132, v80, s[2:3]
	v_rsq_f32_e32 v132, v80
	v_mul_f32_e32 v80, 0x4b800000, v133
	v_cndmask_b32_e32 v80, v133, v80, vcc
	v_rsq_f32_e32 v133, v80
	s_waitcnt lgkmcnt(0)
	s_waitcnt vmcnt(1)
	v_ffbh_u32_e32 v80, v205
	v_pk_mul_f32 v[148:149], v[132:133], s[64:65] op_sel_hi:[1,0]
	v_min_u32_e32 v80, 32, v80
	v_cndmask_b32_e32 v149, v133, v149, vcc
	v_cndmask_b32_e64 v148, v132, v148, s[2:3]
	v_lshlrev_b64 v[132:133], v80, v[204:205]
	v_min_u32_e32 v132, 1, v132
	v_or_b32_e32 v132, v133, v132
	v_cvt_f32_u32_e32 v132, v132
	v_sub_u32_e32 v80, 32, v80
	v_pk_mul_f32 v[118:119], v[118:119], v[148:149]
	v_pk_mul_f32 v[102:103], v[102:103], v[148:149]
	v_ldexp_f32 v133, v132, v80
	v_ffbh_u32_e32 v80, v203
	v_min_u32_e32 v80, 32, v80
	v_lshlrev_b64 v[150:151], v80, v[202:203]
	v_min_u32_e32 v132, 1, v150
	v_or_b32_e32 v132, v151, v132
	v_cvt_f32_u32_e32 v132, v132
	v_sub_u32_e32 v80, 32, v80
	v_pk_mul_f32 v[86:87], v[86:87], v[148:149]
	v_pk_mul_f32 v[68:69], v[68:69], v[148:149]
	v_ldexp_f32 v132, v132, v80
	v_pk_mul_f32 v[132:133], v[132:133], s[60:61] op_sel_hi:[1,0]
	v_pk_mul_f32 v[52:53], v[52:53], v[148:149]
	v_pk_fma_f32 v[132:133], v[132:133], s[26:27], v[146:147] op_sel_hi:[1,0,0]
	v_pk_mul_f32 v[36:37], v[36:37], v[148:149]
	v_mul_f32_e32 v80, 0x4b800000, v132
	v_cmp_gt_f32_e64 s[2:3], s50, v132
	v_cmp_gt_f32_e32 vcc, s50, v133
	v_pk_mul_f32 v[20:21], v[20:21], v[148:149]
	v_cndmask_b32_e64 v80, v132, v80, s[2:3]
	v_rsq_f32_e32 v132, v80
	v_mul_f32_e32 v80, 0x4b800000, v133
	v_cndmask_b32_e32 v80, v133, v80, vcc
	v_rsq_f32_e32 v133, v80
	v_ffbh_u32_e32 v80, v187
	v_min_u32_e32 v80, 32, v80
	v_pk_mul_f32 v[4:5], v[4:5], v[148:149]
	v_pk_mul_f32 v[150:151], v[132:133], s[64:65] op_sel_hi:[1,0]
	s_nop 0
	v_cndmask_b32_e32 v151, v133, v151, vcc
	v_cndmask_b32_e64 v150, v132, v150, s[2:3]
	v_lshlrev_b64 v[132:133], v80, v[186:187]
	v_min_u32_e32 v132, 1, v132
	v_or_b32_e32 v132, v133, v132
	v_cvt_f32_u32_e32 v132, v132
	v_sub_u32_e32 v80, 32, v80
	v_ldexp_f32 v133, v132, v80
	v_ffbh_u32_e32 v80, v185
	v_min_u32_e32 v80, 32, v80
	v_lshlrev_b64 v[152:153], v80, v[184:185]
	v_min_u32_e32 v132, 1, v152
	v_or_b32_e32 v132, v153, v132
	v_cvt_f32_u32_e32 v132, v132
	v_sub_u32_e32 v80, 32, v80
	v_pk_mul_f32 v[166:167], v[124:125], v[144:145]
	v_pk_mul_f32 v[124:125], v[122:123], v[140:141]
	v_ldexp_f32 v132, v132, v80
	v_pk_mul_f32 v[132:133], v[132:133], s[60:61] op_sel_hi:[1,0]
	v_cvt_pk_bf16_f32 v122, v126, v127
	v_cvt_pk_bf16_f32 v123, v128, v129
	v_cvt_pk_bf16_f32 v124, v124, v125
	v_cvt_pk_bf16_f32 v125, v166, v167
	s_nop 0
	v_pk_fma_f32 v[132:133], v[132:133], s[26:27], v[146:147] op_sel_hi:[1,0,0]
	s_nop 0
	v_mul_f32_e32 v80, 0x4b800000, v132
	v_cmp_gt_f32_e64 s[2:3], s50, v132
	v_cmp_gt_f32_e32 vcc, s50, v133
	s_nop 0
	v_cndmask_b32_e64 v80, v132, v80, s[2:3]
	v_rsq_f32_e32 v132, v80
	v_mul_f32_e32 v80, 0x4b800000, v133
	v_cndmask_b32_e32 v80, v133, v80, vcc
	v_rsq_f32_e32 v133, v80
	s_nop 0
	v_pk_mul_f32 v[152:153], v[132:133], s[64:65] op_sel_hi:[1,0]
	s_nop 0
	v_cndmask_b32_e32 v153, v133, v153, vcc
	v_cndmask_b32_e64 v152, v132, v152, s[2:3]
	s_nop 0
	v_pk_mul_f32 v[120:121], v[120:121], v[152:153]
	v_pk_mul_f32 v[104:105], v[104:105], v[152:153]
	v_pk_mul_f32 v[88:89], v[88:89], v[152:153]
	v_pk_mul_f32 v[70:71], v[70:71], v[152:153]
	v_pk_mul_f32 v[54:55], v[54:55], v[152:153]
	v_pk_mul_f32 v[38:39], v[38:39], v[152:153]
	v_pk_mul_f32 v[22:23], v[22:23], v[152:153]
	v_pk_mul_f32 v[6:7], v[6:7], v[152:153]
	s_waitcnt lgkmcnt(0)
; __device__ __forceinline__ unsigned cvt_pk_bf16(float lo, float hi) { unsigned r; asm("v_cvt_pk_bf16_f32 %0, %1, %2" : "=v"(r) : "v"(lo), "v"(hi)); return r; }
; __device__ __forceinline__ float rinv_of(unsigned long long ss) { return rsqrtf((float)ss * (1.f / 16777216.f) * (1.f / DM) + 1e-6f); }
;   __device__ __forceinline__ void operator()(const f32x4 (&acc)[2][2][4][2], const Unit& u, const EpiCtx& x_, int wr, int wc, int fr, int fq) const {
;     ...
;         for (int i = 0; i < 4; ++i) { cs[bj][0][i] = rinv_of(sp[i]); cs[bj][1][i] = rinv_of(sp[(PERM ? 4 : 16) + i]); }
;       }
;     }
; #pragma unroll
;     for (int ai = 0; ai < 2; ++ai)
; #pragma unroll
;       for (int m = 0; m < 4; ++m) {
;         const int row = (u.r0 + (ai ? x_.rdelta : 0)) + wr * 64 + m * 16 + fr;
;         bf16_t* rowp = (bf16_t*)u.C + (size_t)row * x_.ldc;
;         const float rs = (SCALE == 1) ? rinv_of(x_.ss[row]) : 1.f;
; #pragma unroll
;         for (int bj = 0; bj < 2; ++bj) {
;           const int cb = PERM ? (u.c0 + wc * 64 + bj * 32) : (u.c0 + bj * 128) + wc * 32;
;           f32x4 v0 = acc[ai][bj][m][0], v1 = acc[ai][bj][m][1];
;           if (SCALE == 1) { v0 *= rs; v1 *= rs; }
;           if (SCALE == 2) { v0 *= cs[bj][0]; v1 *= cs[bj][1]; }
;           if (PERM) {
;             uint4 o; o.x = cvt_pk_bf16(v0[0], v0[1]); o.y = cvt_pk_bf16(v0[2], v0[3]); o.z = cvt_pk_bf16(v1[0], v1[1]); o.w = cvt_pk_bf16(v1[2], v1[3]);
;             *(uint4*)(rowp + cb + 8 * fq) = o;
;           } else {
;             uint2 o0, o1; o0.x = cvt_pk_bf16(v0[0], v0[1]); o0.y = cvt_pk_bf16(v0[2], v0[3]); o1.x = cvt_pk_bf16(v1[0], v1[1]); o1.y = cvt_pk_bf16(v1[2], v1[3]);
;             *(uint2*)(rowp + cb + 4 * fq) = o0; *(uint2*)(rowp + cb + 16 + 4 * fq) = o1;
	s_waitcnt vmcnt(0)
	v_ffbh_u32_e32 v80, v209
	v_min_u32_e32 v80, 32, v80
	v_lshlrev_b64 v[132:133], v80, v[208:209]
	v_min_u32_e32 v132, 1, v132
	v_or_b32_e32 v132, v133, v132
	v_cvt_f32_u32_e32 v132, v132
	v_sub_u32_e32 v80, 32, v80
	v_ldexp_f32 v133, v132, v80
	v_ffbh_u32_e32 v80, v207
	v_min_u32_e32 v80, 32, v80
	v_lshlrev_b64 v[130:131], v80, v[206:207]
	v_min_u32_e32 v130, 1, v130
	v_or_b32_e32 v130, v131, v130
	v_cvt_f32_u32_e32 v130, v130
	v_sub_u32_e32 v80, 32, v80
	v_ldexp_f32 v132, v130, v80
	v_pk_mul_f32 v[130:131], v[132:133], s[60:61] op_sel_hi:[1,0]
	s_nop 0
	v_pk_fma_f32 v[130:131], v[130:131], s[26:27], v[146:147] op_sel_hi:[1,0,0]
	s_nop 0
	v_mul_f32_e32 v80, 0x4b800000, v130
	v_cmp_gt_f32_e64 s[2:3], s50, v130
	v_cmp_gt_f32_e32 vcc, s50, v131
	s_nop 0
	v_cndmask_b32_e64 v80, v130, v80, s[2:3]
	v_rsq_f32_e32 v130, v80
	v_mul_f32_e32 v80, 0x4b800000, v131
	v_cndmask_b32_e32 v80, v131, v80, vcc
	v_rsq_f32_e32 v131, v80
	s_nop 0
	v_pk_mul_f32 v[132:133], v[130:131], s[64:65] op_sel_hi:[1,0]
	s_nop 0
	v_cndmask_b32_e64 v130, v130, v132, s[2:3]
	v_add_u32_e32 v132, s79, v159
	v_cndmask_b32_e32 v131, v131, v133, vcc
	v_ashrrev_i32_e32 v133, 31, v132
	v_lshlrev_b64 v[146:147], 15, v[132:133]
	s_add_i32 s2, s94, s66
	v_lshl_add_u64 v[146:147], s[4:5], 0, v[146:147]
	s_ashr_i32 s3, s2, 31
	v_lshl_add_u64 v[146:147], v[146:147], 0, v[136:137]
	s_lshl_b64 s[2:3], s[2:3], 1
	v_lshl_add_u64 v[126:127], v[146:147], 0, s[2:3]
	global_store_dwordx4 v[126:127], v[122:125], off
	s_cmp_eq_u32 s76, s75
	s_mov_b32 s94, s42
	v_pk_mul_f32 v[122:123], v[116:117], v[130:131]
	v_pk_mul_f32 v[116:117], v[114:115], v[150:151]
	v_cvt_pk_bf16_f32 v114, v118, v119
	v_lshl_add_u64 v[118:119], v[146:147], 0, s[38:39]
	v_cvt_pk_bf16_f32 v115, v120, v121
	v_cvt_pk_bf16_f32 v116, v116, v117
	v_cvt_pk_bf16_f32 v117, v122, v123
	global_store_dwordx4 v[118:119], v[114:117], off
	v_pk_mul_f32 v[118:119], v[108:109], v[144:145]
	v_pk_mul_f32 v[108:109], v[106:107], v[140:141]
	v_add_u32_e32 v114, s79, v161
	v_ashrrev_i32_e32 v115, 31, v114
	v_lshlrev_b64 v[116:117], 15, v[114:115]
	v_lshl_add_u64 v[116:117], s[4:5], 0, v[116:117]
	v_lshl_add_u64 v[116:117], v[116:117], 0, v[136:137]
	v_cvt_pk_bf16_f32 v106, v110, v111
	v_cvt_pk_bf16_f32 v107, v112, v113
	v_lshl_add_u64 v[110:111], v[116:117], 0, s[2:3]
	v_cvt_pk_bf16_f32 v108, v108, v109
	v_cvt_pk_bf16_f32 v109, v118, v119
	global_store_dwordx4 v[110:111], v[106:109], off
	s_nop 1
	v_pk_mul_f32 v[106:107], v[100:101], v[130:131]
	v_pk_mul_f32 v[100:101], v[98:99], v[150:151]
	v_cvt_pk_bf16_f32 v98, v102, v103
	v_lshl_add_u64 v[102:103], v[116:117], 0, s[38:39]
	v_cvt_pk_bf16_f32 v99, v104, v105
	v_cvt_pk_bf16_f32 v100, v100, v101
	v_cvt_pk_bf16_f32 v101, v106, v107
	global_store_dwordx4 v[102:103], v[98:101], off
	v_pk_mul_f32 v[102:103], v[92:93], v[144:145]
	v_pk_mul_f32 v[92:93], v[90:91], v[140:141]
	v_add_u32_e32 v98, s79, v163
	v_ashrrev_i32_e32 v99, 31, v98
	v_lshlrev_b64 v[100:101], 15, v[98:99]
	v_lshl_add_u64 v[100:101], s[4:5], 0, v[100:101]
	v_lshl_add_u64 v[100:101], v[100:101], 0, v[136:137]
	v_cvt_pk_bf16_f32 v90, v94, v95
	v_cvt_pk_bf16_f32 v91, v96, v97
	v_lshl_add_u64 v[94:95], v[100:101], 0, s[2:3]
	v_cvt_pk_bf16_f32 v92, v92, v93
	v_cvt_pk_bf16_f32 v93, v102, v103
	global_store_dwordx4 v[94:95], v[90:93], off
	s_nop 1
	v_pk_mul_f32 v[90:91], v[84:85], v[130:131]
	v_pk_mul_f32 v[84:85], v[82:83], v[150:151]
	v_cvt_pk_bf16_f32 v82, v86, v87
	v_lshl_add_u64 v[86:87], v[100:101], 0, s[38:39]
	v_cvt_pk_bf16_f32 v83, v88, v89
	v_cvt_pk_bf16_f32 v84, v84, v85
	v_cvt_pk_bf16_f32 v85, v90, v91
	global_store_dwordx4 v[86:87], v[82:85], off
	v_pk_mul_f32 v[86:87], v[74:75], v[144:145]
	v_pk_mul_f32 v[74:75], v[72:73], v[140:141]
	v_add_u32_e32 v82, s79, v164
	v_ashrrev_i32_e32 v83, 31, v82
	v_lshlrev_b64 v[84:85], 15, v[82:83]
	v_lshl_add_u64 v[84:85], s[4:5], 0, v[84:85]
	v_lshl_add_u64 v[84:85], v[84:85], 0, v[136:137]
	v_cvt_pk_bf16_f32 v72, v76, v77
	v_cvt_pk_bf16_f32 v73, v78, v79
; __device__ __forceinline__ unsigned cvt_pk_bf16(float lo, float hi) { unsigned r; asm("v_cvt_pk_bf16_f32 %0, %1, %2" : "=v"(r) : "v"(lo), "v"(hi)); return r; }
; __device__ __forceinline__ float rinv_of(unsigned long long ss) { return rsqrtf((float)ss * (1.f / 16777216.f) * (1.f / DM) + 1e-6f); }
; #define G_WAIT_V(n) asm volatile("s_waitcnt vmcnt(" #n ")" ::: "memory")
; #define G_BAR __builtin_amdgcn_s_barrier()
;   __device__ __forceinline__ void operator()(const f32x4 (&acc)[2][2][4][2], const Unit& u, const EpiCtx& x_, int wr, int wc, int fr, int fq) const {
;     ...
;         const int row = (u.r0 + (ai ? x_.rdelta : 0)) + wr * 64 + m * 16 + fr;
;         bf16_t* rowp = (bf16_t*)u.C + (size_t)row * x_.ldc;
;         const float rs = (SCALE == 1) ? rinv_of(x_.ss[row]) : 1.f;
; #pragma unroll
;         for (int bj = 0; bj < 2; ++bj) {
;           const int cb = PERM ? (u.c0 + wc * 64 + bj * 32) : (u.c0 + bj * 128) + wc * 32;
;           f32x4 v0 = acc[ai][bj][m][0], v1 = acc[ai][bj][m][1];
;           if (SCALE == 1) { v0 *= rs; v1 *= rs; }
;           if (SCALE == 2) { v0 *= cs[bj][0]; v1 *= cs[bj][1]; }
;           if (PERM) {
;             uint4 o; o.x = cvt_pk_bf16(v0[0], v0[1]); o.y = cvt_pk_bf16(v0[2], v0[3]); o.z = cvt_pk_bf16(v1[0], v1[1]); o.w = cvt_pk_bf16(v1[2], v1[3]);
;             *(uint4*)(rowp + cb + 8 * fq) = o;
;           } else {
;             uint2 o0, o1; o0.x = cvt_pk_bf16(v0[0], v0[1]); o0.y = cvt_pk_bf16(v0[2], v0[3]); o1.x = cvt_pk_bf16(v1[0], v1[1]); o1.y = cvt_pk_bf16(v1[2], v1[3]);
;             *(uint2*)(rowp + cb + 4 * fq) = o0; *(uint2*)(rowp + cb + 16 + 4 * fq) = o1;
; template <class Epi>
; __device__ __forceinline__ void gemm_phase(LAS unsigned char* lds, const int K, const unsigned lda_b, const unsigned ldb_b, const Map& M, const Epi& E) {
;     ...
;     E(acc, cur, X, wr, wc, fr, fq);
;     if (!has_next) break;
; #pragma unroll
;     for (int a = 0; a < 2; ++a)
; #pragma unroll
;       for (int b = 0; b < 2; ++b)
; #pragma unroll
;         for (int m = 0; m < 4; ++m)
; #pragma unroll
;           for (int n = 0; n < 2; ++n) acc[a][b][m][n] = (f32x4){0.f, 0.f, 0.f, 0.f};
;     cur = nxt; ++ui;
;   }
;   G_WAIT_V(0);
;   if (wr == 0) G_BAR;
;   G_BAR;
	v_lshl_add_u64 v[76:77], v[84:85], 0, s[2:3]
	v_cvt_pk_bf16_f32 v74, v74, v75
	v_cvt_pk_bf16_f32 v75, v86, v87
	global_store_dwordx4 v[76:77], v[72:75], off
	s_mov_b32 s79, s0
	s_nop 0
	v_pk_mul_f32 v[72:73], v[66:67], v[130:131]
	v_pk_mul_f32 v[66:67], v[64:65], v[150:151]
	v_cvt_pk_bf16_f32 v64, v68, v69
	v_lshl_add_u64 v[68:69], v[84:85], 0, s[38:39]
	v_cvt_pk_bf16_f32 v65, v70, v71
	v_cvt_pk_bf16_f32 v66, v66, v67
	v_cvt_pk_bf16_f32 v67, v72, v73
	global_store_dwordx4 v[68:69], v[64:67], off
	s_nop 1
	v_add_u32_e32 v64, 0x80, v132
	v_ashrrev_i32_e32 v65, 31, v64
	v_lshlrev_b64 v[64:65], 15, v[64:65]
	v_lshl_add_u64 v[64:65], s[4:5], 0, v[64:65]
	v_lshl_add_u64 v[64:65], v[64:65], 0, v[136:137]
	v_pk_mul_f32 v[66:67], v[58:59], v[144:145]
	v_pk_mul_f32 v[58:59], v[56:57], v[140:141]
	v_cvt_pk_bf16_f32 v56, v60, v61
	v_cvt_pk_bf16_f32 v57, v62, v63
	v_lshl_add_u64 v[60:61], v[64:65], 0, s[2:3]
	v_cvt_pk_bf16_f32 v58, v58, v59
	v_cvt_pk_bf16_f32 v59, v66, v67
	global_store_dwordx4 v[60:61], v[56:59], off
	s_nop 1
	v_pk_mul_f32 v[56:57], v[50:51], v[130:131]
	v_pk_mul_f32 v[50:51], v[48:49], v[150:151]
	v_cvt_pk_bf16_f32 v48, v52, v53
	v_lshl_add_u64 v[52:53], v[64:65], 0, s[38:39]
	v_cvt_pk_bf16_f32 v49, v54, v55
	v_cvt_pk_bf16_f32 v50, v50, v51
	v_cvt_pk_bf16_f32 v51, v56, v57
	global_store_dwordx4 v[52:53], v[48:51], off
	s_nop 1
	v_add_u32_e32 v48, 0x80, v114
	v_ashrrev_i32_e32 v49, 31, v48
	v_lshlrev_b64 v[48:49], 15, v[48:49]
	v_lshl_add_u64 v[48:49], s[4:5], 0, v[48:49]
	v_lshl_add_u64 v[48:49], v[48:49], 0, v[136:137]
	v_pk_mul_f32 v[50:51], v[42:43], v[144:145]
	v_pk_mul_f32 v[42:43], v[40:41], v[140:141]
	v_cvt_pk_bf16_f32 v40, v44, v45
	v_cvt_pk_bf16_f32 v41, v46, v47
	v_lshl_add_u64 v[44:45], v[48:49], 0, s[2:3]
	v_cvt_pk_bf16_f32 v42, v42, v43
	v_cvt_pk_bf16_f32 v43, v50, v51
	global_store_dwordx4 v[44:45], v[40:43], off
	s_nop 1
	v_pk_mul_f32 v[40:41], v[34:35], v[130:131]
	v_pk_mul_f32 v[34:35], v[32:33], v[150:151]
	v_cvt_pk_bf16_f32 v32, v36, v37
	v_lshl_add_u64 v[36:37], v[48:49], 0, s[38:39]
	v_cvt_pk_bf16_f32 v33, v38, v39
	v_cvt_pk_bf16_f32 v34, v34, v35
	v_cvt_pk_bf16_f32 v35, v40, v41
	global_store_dwordx4 v[36:37], v[32:35], off
	s_nop 1
	v_add_u32_e32 v32, 0x80, v98
	v_ashrrev_i32_e32 v33, 31, v32
	v_lshlrev_b64 v[32:33], 15, v[32:33]
	v_lshl_add_u64 v[32:33], s[4:5], 0, v[32:33]
	v_lshl_add_u64 v[32:33], v[32:33], 0, v[136:137]
	v_pk_mul_f32 v[34:35], v[26:27], v[144:145]
	v_pk_mul_f32 v[26:27], v[24:25], v[140:141]
	v_cvt_pk_bf16_f32 v24, v28, v29
	v_cvt_pk_bf16_f32 v25, v30, v31
	v_lshl_add_u64 v[28:29], v[32:33], 0, s[2:3]
	v_cvt_pk_bf16_f32 v26, v26, v27
	v_cvt_pk_bf16_f32 v27, v34, v35
	global_store_dwordx4 v[28:29], v[24:27], off
	s_nop 1
	v_pk_mul_f32 v[24:25], v[18:19], v[130:131]
	v_pk_mul_f32 v[18:19], v[16:17], v[150:151]
	v_cvt_pk_bf16_f32 v16, v20, v21
	v_lshl_add_u64 v[20:21], v[32:33], 0, s[38:39]
	v_cvt_pk_bf16_f32 v17, v22, v23
	v_cvt_pk_bf16_f32 v18, v18, v19
	v_cvt_pk_bf16_f32 v19, v24, v25
	global_store_dwordx4 v[20:21], v[16:19], off
	s_nop 1
	v_add_u32_e32 v16, 0x80, v82
	v_ashrrev_i32_e32 v17, 31, v16
	v_lshlrev_b64 v[16:17], 15, v[16:17]
	v_lshl_add_u64 v[16:17], s[4:5], 0, v[16:17]
	v_lshl_add_u64 v[16:17], v[16:17], 0, v[136:137]
	v_pk_mul_f32 v[18:19], v[10:11], v[144:145]
	v_pk_mul_f32 v[10:11], v[8:9], v[140:141]
	v_cvt_pk_bf16_f32 v8, v12, v13
	v_cvt_pk_bf16_f32 v9, v14, v15
	v_lshl_add_u64 v[12:13], v[16:17], 0, s[2:3]
	v_cvt_pk_bf16_f32 v10, v10, v11
	v_cvt_pk_bf16_f32 v11, v18, v19
	global_store_dwordx4 v[12:13], v[8:11], off
	s_mov_b64 s[2:3], s[6:7]
	s_mov_b64 s[4:5], s[40:41]
	v_pk_mul_f32 v[8:9], v[2:3], v[130:131]
	v_pk_mul_f32 v[2:3], v[0:1], v[150:151]
	v_cvt_pk_bf16_f32 v0, v4, v5
	v_lshl_add_u64 v[4:5], v[16:17], 0, s[38:39]
	s_mov_b64 s[38:39], s[8:9]
	v_cvt_pk_bf16_f32 v1, v6, v7
	v_cvt_pk_bf16_f32 v2, v2, v3
	v_cvt_pk_bf16_f32 v3, v8, v9
	global_store_dwordx4 v[4:5], v[0:3], off
	s_cbranch_scc0 .LBB0_234
	s_waitcnt vmcnt(0)
	s_cmpk_gt_u32 s13, 0xff
	s_cbranch_scc1 .LBB0_239
	s_barrier

; #define G_STAGE(bufoff, gbase, voff) do { _Pragma("unroll") for (int _i = 0; _i < 2; ++_i) { unsigned _vo = (voff)[_i]; asm volatile("" : "+v"(_vo));   \
;     __builtin_amdgcn_global_load_lds((const unsigned*)((const char*)(gbase) + _vo), (LAS unsigned*)(lds + (bufoff) + ldsw + _i * 8192), 16, 0, 0); } } while (0)
; #define G_LDA(dst, b, h) do { _Pragma("unroll") for (int m = 0; m < 4; ++m) _Pragma("unroll") for (int k = 0; k < 2; ++k) dst[m][k] = *(const LAS bf16x8*)(lds + G_SA(b, h) + aoff + m * 2048 + k * 1024); } while (0)
; #define G_LDB(dst, b, h) do { _Pragma("unroll") for (int n = 0; n < 2; ++n) _Pragma("unroll") for (int k = 0; k < 2; ++k) dst[n][k] = *(const LAS bf16x8*)(lds + G_SB(b, h) + boff + n * 2048 + k * 1024); } while (0)
; #define G_MMA(ai, bj, At, Bt) do { __builtin_amdgcn_s_setprio(1); _Pragma("unroll") for (int m = 0; m < 4; ++m) _Pragma("unroll") for (int n = 0; n < 2; ++n) _Pragma("unroll") for (int k = 0; k < 2; ++k) \
;     acc[ai][bj][m][n] = __builtin_amdgcn_mfma_f32_16x16x32_bf16(Bt[n][k], At[m][k], acc[ai][bj][m][n], 0, 0, 0); __builtin_amdgcn_s_setprio(0); } while (0)
; #define G_WAIT_V(n) asm volatile("s_waitcnt vmcnt(" #n ")" ::: "memory")
; #define G_WAIT_L(n) asm volatile("s_waitcnt lgkmcnt(" #n ")" ::: "memory")
; #define G_BAR __builtin_amdgcn_s_barrier()
; template <class Epi>
; __device__ __forceinline__ void gemm_phase(LAS unsigned char* lds, const int K, const unsigned lda_b, const unsigned ldb_b, const Map& M, const Epi& E) {
;     ...
;     for (int t = 0; t < nt; t += 2) {
;       const bool last = (t == nt - 2);
;       const char* a1h1 = cur.a0 + a_h + (size_t)(t + 1) * kstep;
;       const char* a2h0 = last ? nxt.a0 : cur.a0 + (size_t)(t + 2) * kstep; const char* a2h1 = a2h0 + a_h;
;       const char* b2h0 = last ? nxt.b0 : cur.b0 + (size_t)(t + 2) * kstep; const char* b2h1 = last ? nxt.b1 : cur.b1 + (size_t)(t + 2) * kstep;
;       G_LDB(B0, 0, 0); G_SCHED; G_LDA(At, 0, 0); G_STAGE(G_SA(1, 1), a1h1, voffA);
;       G_WAIT_L(8); G_BAR; G_WAIT_L(0); G_MMA(0, 0, At, B0); G_BAR; G_SCHED;
;       G_LDB(B1, 0, 1); G_STAGE(G_SB(0, 0), b2h0, voffB);
;       G_BAR; G_WAIT_L(0); G_MMA(0, 1, At, B1); G_BAR;
;       G_LDA(At, 0, 1); G_STAGE(G_SA(0, 0), a2h0, voffA);
;       G_BAR; G_WAIT_L(0); G_MMA(1, 0, At, B0); G_BAR; G_SCHED;
;       G_STAGE(G_SB(0, 1), b2h1, voffB);
;       G_WAIT_V(6); G_BAR; G_MMA(1, 1, At, B1); G_BAR;
.LBB0_257:
	s_add_u32 s22, s38, 0xfff80080
	s_addc_u32 s35, s39, -1
	s_add_u32 s42, s30, 0xfffe0000
	s_addc_u32 s43, s31, -1
	s_add_i32 s81, 0, 0x10000
	v_add_u32_e32 v0, s81, v149
	ds_read_b128 v[136:139], v0
	ds_read_b128 v[140:143], v0 offset:1024
	ds_read_b128 v[154:157], v0 offset:2048
	ds_read_b128 v[164:167], v0 offset:3072
	s_cmp_eq_u32 s34, 28
	s_cselect_b32 s45, s9, s35
	s_cselect_b32 s44, s8, s22
	s_cselect_b32 s69, s41, s43
	s_cselect_b32 s68, s40, s42
	v_mov_b32_e32 v0, v144
	s_cselect_b32 s43, s29, s31
	s_cselect_b32 s42, s28, s30
	s_add_u32 s94, s44, 0x80000
	ds_read_b128 v[168:171], v153
	ds_read_b128 v[172:175], v153 offset:1024
	ds_read_b128 v[176:179], v153 offset:2048
	ds_read_b128 v[184:187], v153 offset:3072
	ds_read_b128 v[190:193], v153 offset:4096
	ds_read_b128 v[194:197], v153 offset:5120
	ds_read_b128 v[198:201], v153 offset:6144
	ds_read_b128 v[202:205], v153 offset:7168
	s_addc_u32 s95, s45, 0
	s_add_i32 m0, s18, 0xc000
	s_nop 0
	global_load_lds_dwordx4 v0, s[38:39]
	v_mov_b32_e32 v0, v146
	s_add_i32 m0, s18, 0xe000
	s_nop 0
	global_load_lds_dwordx4 v0, s[38:39]
	s_waitcnt lgkmcnt(8)
	s_barrier
	s_waitcnt lgkmcnt(0)
	s_setprio 1
	s_waitcnt lgkmcnt(0)
	v_mfma_f32_16x16x32_bf16 v[130:133], v[136:139], v[168:171], v[130:133]
	v_mfma_f32_16x16x32_bf16 v[126:129], v[154:157], v[168:171], v[126:129]
	v_mfma_f32_16x16x32_bf16 v[114:117], v[136:139], v[176:179], v[114:117]
	v_mfma_f32_16x16x32_bf16 v[110:113], v[154:157], v[176:179], v[110:113]
	v_mfma_f32_16x16x32_bf16 v[98:101], v[136:139], v[190:193], v[98:101]
	v_mfma_f32_16x16x32_bf16 v[94:97], v[154:157], v[190:193], v[94:97]
	v_mfma_f32_16x16x32_bf16 v[82:85], v[136:139], v[198:201], v[82:85]
	v_mfma_f32_16x16x32_bf16 v[76:79], v[154:157], v[198:201], v[76:79]
	v_mfma_f32_16x16x32_bf16 v[130:133], v[140:143], v[172:175], v[130:133]
	v_mfma_f32_16x16x32_bf16 v[126:129], v[164:167], v[172:175], v[126:129]
	v_mfma_f32_16x16x32_bf16 v[114:117], v[140:143], v[184:187], v[114:117]
	v_mfma_f32_16x16x32_bf16 v[110:113], v[164:167], v[184:187], v[110:113]
	v_mfma_f32_16x16x32_bf16 v[98:101], v[140:143], v[194:197], v[98:101]
	v_mfma_f32_16x16x32_bf16 v[94:97], v[164:167], v[194:197], v[94:97]
	v_mfma_f32_16x16x32_bf16 v[82:85], v[140:143], v[202:205], v[82:85]
	v_mfma_f32_16x16x32_bf16 v[76:79], v[164:167], v[202:205], v[76:79]
	s_setprio 0
	s_barrier
	s_add_i32 s22, 0, 0x14000
	v_add_u32_e32 v0, s22, v149
	ds_read_b128 v[206:209], v0
	ds_read_b128 v[210:213], v0 offset:1024
	ds_read_b128 v[214:217], v0 offset:2048
	ds_read_b128 v[218:221], v0 offset:3072
	v_mov_b32_e32 v0, v145
	s_add_i32 s35, s81, s13
	s_mov_b32 m0, s35
	s_nop 0
	global_load_lds_dwordx4 v0, s[68:69]
	v_mov_b32_e32 v0, v147
	s_add_i32 m0, s35, 0x2000
	s_nop 0
	global_load_lds_dwordx4 v0, s[68:69]
	s_barrier
	s_waitcnt lgkmcnt(0)
	s_setprio 1
	s_waitcnt lgkmcnt(0)
	v_mfma_f32_16x16x32_bf16 v[122:125], v[206:209], v[168:171], v[122:125]
	v_mfma_f32_16x16x32_bf16 v[118:121], v[214:217], v[168:171], v[118:121]
	v_mfma_f32_16x16x32_bf16 v[106:109], v[206:209], v[176:179], v[106:109]
	v_mfma_f32_16x16x32_bf16 v[102:105], v[214:217], v[176:179], v[102:105]
	v_mfma_f32_16x16x32_bf16 v[90:93], v[206:209], v[190:193], v[90:93]
	v_mfma_f32_16x16x32_bf16 v[86:89], v[214:217], v[190:193], v[86:89]
	v_mfma_f32_16x16x32_bf16 v[72:75], v[206:209], v[198:201], v[72:75]
	v_mfma_f32_16x16x32_bf16 v[68:71], v[214:217], v[198:201], v[68:71]
	v_mfma_f32_16x16x32_bf16 v[122:125], v[210:213], v[172:175], v[122:125]
	v_mfma_f32_16x16x32_bf16 v[118:121], v[218:221], v[172:175], v[118:121]
	v_mfma_f32_16x16x32_bf16 v[106:109], v[210:213], v[184:187], v[106:109]
	v_mfma_f32_16x16x32_bf16 v[102:105], v[218:221], v[184:187], v[102:105]
	v_mfma_f32_16x16x32_bf16 v[90:93], v[210:213], v[194:197], v[90:93]
	v_mfma_f32_16x16x32_bf16 v[86:89], v[218:221], v[194:197], v[86:89]
	v_mfma_f32_16x16x32_bf16 v[72:75], v[210:213], v[202:205], v[72:75]
	v_mfma_f32_16x16x32_bf16 v[68:71], v[218:221], v[202:205], v[68:71]
	s_setprio 0
	v_mov_b32_e32 v0, v144
	s_mov_b32 m0, s18
	s_barrier
	ds_read_b128 v[168:171], v153 offset:16384
	ds_read_b128 v[172:175], v153 offset:17408
	ds_read_b128 v[176:179], v153 offset:18432
	ds_read_b128 v[184:187], v153 offset:19456
	ds_read_b128 v[190:193], v153 offset:20480
	ds_read_b128 v[194:197], v153 offset:21504
	ds_read_b128 v[198:201], v153 offset:22528
	ds_read_b128 v[202:205], v153 offset:23552
	s_nop 0
	global_load_lds_dwordx4 v0, s[44:45]
	v_mov_b32_e32 v0, v146
	s_mov_b32 m0, s19
	s_nop 0
	global_load_lds_dwordx4 v0, s[44:45]
	s_barrier
	s_waitcnt lgkmcnt(0)
	s_setprio 1
	s_waitcnt lgkmcnt(0)
	v_mfma_f32_16x16x32_bf16 v[64:67], v[136:139], v[168:171], v[64:67]
	v_mfma_f32_16x16x32_bf16 v[60:63], v[154:157], v[168:171], v[60:63]
	v_mfma_f32_16x16x32_bf16 v[48:51], v[136:139], v[176:179], v[48:51]
	v_mfma_f32_16x16x32_bf16 v[44:47], v[154:157], v[176:179], v[44:47]
	v_mfma_f32_16x16x32_bf16 v[32:35], v[136:139], v[190:193], v[32:35]
	v_mfma_f32_16x16x32_bf16 v[28:31], v[154:157], v[190:193], v[28:31]
	v_mfma_f32_16x16x32_bf16 v[16:19], v[136:139], v[198:201], v[16:19]
	v_mfma_f32_16x16x32_bf16 v[12:15], v[154:157], v[198:201], v[12:15]
	v_mfma_f32_16x16x32_bf16 v[64:67], v[140:143], v[172:175], v[64:67]
	v_mfma_f32_16x16x32_bf16 v[60:63], v[164:167], v[172:175], v[60:63]
	v_mfma_f32_16x16x32_bf16 v[48:51], v[140:143], v[184:187], v[48:51]
	v_mfma_f32_16x16x32_bf16 v[44:47], v[164:167], v[184:187], v[44:47]
	v_mfma_f32_16x16x32_bf16 v[32:35], v[140:143], v[194:197], v[32:35]
	v_mfma_f32_16x16x32_bf16 v[28:31], v[164:167], v[194:197], v[28:31]
	v_mfma_f32_16x16x32_bf16 v[16:19], v[140:143], v[202:205], v[16:19]
	v_mfma_f32_16x16x32_bf16 v[12:15], v[164:167], v[202:205], v[12:15]
	s_setprio 0
	s_barrier
; #define G_STAGE(bufoff, gbase, voff) do { _Pragma("unroll") for (int _i = 0; _i < 2; ++_i) { unsigned _vo = (voff)[_i]; asm volatile("" : "+v"(_vo));   \
;     __builtin_amdgcn_global_load_lds((const unsigned*)((const char*)(gbase) + _vo), (LAS unsigned*)(lds + (bufoff) + ldsw + _i * 8192), 16, 0, 0); } } while (0)
; #define G_LDA(dst, b, h) do { _Pragma("unroll") for (int m = 0; m < 4; ++m) _Pragma("unroll") for (int k = 0; k < 2; ++k) dst[m][k] = *(const LAS bf16x8*)(lds + G_SA(b, h) + aoff + m * 2048 + k * 1024); } while (0)
; #define G_LDB(dst, b, h) do { _Pragma("unroll") for (int n = 0; n < 2; ++n) _Pragma("unroll") for (int k = 0; k < 2; ++k) dst[n][k] = *(const LAS bf16x8*)(lds + G_SB(b, h) + boff + n * 2048 + k * 1024); } while (0)
; #define G_MMA(ai, bj, At, Bt) do { __builtin_amdgcn_s_setprio(1); _Pragma("unroll") for (int m = 0; m < 4; ++m) _Pragma("unroll") for (int n = 0; n < 2; ++n) _Pragma("unroll") for (int k = 0; k < 2; ++k) \
;     acc[ai][bj][m][n] = __builtin_amdgcn_mfma_f32_16x16x32_bf16(Bt[n][k], At[m][k], acc[ai][bj][m][n], 0, 0, 0); __builtin_amdgcn_s_setprio(0); } while (0)
; #define G_WAIT_V(n) asm volatile("s_waitcnt vmcnt(" #n ")" ::: "memory")
; #define G_WAIT_L(n) asm volatile("s_waitcnt lgkmcnt(" #n ")" ::: "memory")
; #define G_BAR __builtin_amdgcn_s_barrier()
; #define G_SCHED __builtin_amdgcn_sched_barrier(0)
; template <class Epi>
; __device__ __forceinline__ void gemm_phase(LAS unsigned char* lds, const int K, const unsigned lda_b, const unsigned ldb_b, const Map& M, const Epi& E) {
;     ...
;       G_WAIT_V(6); G_BAR; G_MMA(1, 1, At, B1); G_BAR;
;       G_LDB(B0, 1, 0); G_SCHED; G_LDA(At, 1, 0); G_STAGE(G_SA(0, 1), a2h1, voffA);
;       G_WAIT_L(8); G_BAR; G_WAIT_L(0); G_MMA(0, 0, At, B0); G_BAR; G_SCHED;
;       G_LDB(B1, 1, 1); G_STAGE(G_SB(1, 0), b2h0 + kstep, voffB);
;       G_BAR; G_WAIT_L(0); G_MMA(0, 1, At, B1); G_BAR;
;       G_LDA(At, 1, 1); G_STAGE(G_SA(1, 0), a2h0 + kstep, voffA);
;       G_BAR; G_WAIT_L(0); G_MMA(1, 0, At, B0); G_BAR; G_SCHED;
	v_mov_b32_e32 v0, v145
	s_add_i32 s22, s22, s13
	s_mov_b32 m0, s22
	s_nop 0
	global_load_lds_dwordx4 v0, s[42:43]
	v_mov_b32_e32 v0, v147
	s_add_i32 m0, s22, 0x2000
	s_nop 0
	global_load_lds_dwordx4 v0, s[42:43]
	s_waitcnt vmcnt(6)
	s_barrier
	s_setprio 1
	v_mfma_f32_16x16x32_bf16 v[56:59], v[206:209], v[168:171], v[56:59]
	v_mfma_f32_16x16x32_bf16 v[52:55], v[214:217], v[168:171], v[52:55]
	v_mfma_f32_16x16x32_bf16 v[40:43], v[206:209], v[176:179], v[40:43]
	v_mfma_f32_16x16x32_bf16 v[36:39], v[214:217], v[176:179], v[36:39]
	v_mfma_f32_16x16x32_bf16 v[24:27], v[206:209], v[190:193], v[24:27]
	v_mfma_f32_16x16x32_bf16 v[20:23], v[214:217], v[190:193], v[20:23]
	v_mfma_f32_16x16x32_bf16 v[8:11], v[206:209], v[198:201], v[8:11]
	v_mfma_f32_16x16x32_bf16 v[4:7], v[214:217], v[198:201], v[4:7]
	v_mfma_f32_16x16x32_bf16 v[56:59], v[210:213], v[172:175], v[56:59]
	v_mfma_f32_16x16x32_bf16 v[52:55], v[218:221], v[172:175], v[52:55]
	v_mfma_f32_16x16x32_bf16 v[40:43], v[210:213], v[184:187], v[40:43]
	v_mfma_f32_16x16x32_bf16 v[36:39], v[218:221], v[184:187], v[36:39]
	v_mfma_f32_16x16x32_bf16 v[24:27], v[210:213], v[194:197], v[24:27]
	v_mfma_f32_16x16x32_bf16 v[20:23], v[218:221], v[194:197], v[20:23]
	v_mfma_f32_16x16x32_bf16 v[8:11], v[210:213], v[202:205], v[8:11]
	v_mfma_f32_16x16x32_bf16 v[4:7], v[218:221], v[202:205], v[4:7]
	s_setprio 0
	s_add_i32 s22, 0, 0x18000
	v_add_u32_e32 v0, s22, v149
	s_barrier
	ds_read_b128 v[136:139], v0
	ds_read_b128 v[140:143], v0 offset:1024
	ds_read_b128 v[154:157], v0 offset:2048
	ds_read_b128 v[164:167], v0 offset:3072
	v_mov_b32_e32 v0, v144
	s_mov_b32 m0, s46
	ds_read_b128 v[168:171], v153 offset:32768
	ds_read_b128 v[172:175], v153 offset:33792
	ds_read_b128 v[176:179], v153 offset:34816
	ds_read_b128 v[184:187], v153 offset:35840
	ds_read_b128 v[190:193], v153 offset:36864
	ds_read_b128 v[194:197], v153 offset:37888
	ds_read_b128 v[198:201], v153 offset:38912
	ds_read_b128 v[202:205], v153 offset:39936
	s_nop 0
	global_load_lds_dwordx4 v0, s[94:95]
	v_mov_b32_e32 v0, v146
	s_mov_b32 m0, s47
	s_nop 0
	global_load_lds_dwordx4 v0, s[94:95]
	s_waitcnt lgkmcnt(8)
	s_barrier
	s_waitcnt lgkmcnt(0)
	s_setprio 1
	s_waitcnt lgkmcnt(0)
	v_mfma_f32_16x16x32_bf16 v[130:133], v[136:139], v[168:171], v[130:133]
	v_mfma_f32_16x16x32_bf16 v[126:129], v[154:157], v[168:171], v[126:129]
	v_mfma_f32_16x16x32_bf16 v[114:117], v[136:139], v[176:179], v[114:117]
	v_mfma_f32_16x16x32_bf16 v[110:113], v[154:157], v[176:179], v[110:113]
	v_mfma_f32_16x16x32_bf16 v[98:101], v[136:139], v[190:193], v[98:101]
	v_mfma_f32_16x16x32_bf16 v[94:97], v[154:157], v[190:193], v[94:97]
	v_mfma_f32_16x16x32_bf16 v[82:85], v[136:139], v[198:201], v[82:85]
	v_mfma_f32_16x16x32_bf16 v[76:79], v[154:157], v[198:201], v[76:79]
	v_mfma_f32_16x16x32_bf16 v[130:133], v[140:143], v[172:175], v[130:133]
	v_mfma_f32_16x16x32_bf16 v[126:129], v[164:167], v[172:175], v[126:129]
	v_mfma_f32_16x16x32_bf16 v[114:117], v[140:143], v[184:187], v[114:117]
	v_mfma_f32_16x16x32_bf16 v[110:113], v[164:167], v[184:187], v[110:113]
	v_mfma_f32_16x16x32_bf16 v[98:101], v[140:143], v[194:197], v[98:101]
	v_mfma_f32_16x16x32_bf16 v[94:97], v[164:167], v[194:197], v[94:97]
	v_mfma_f32_16x16x32_bf16 v[82:85], v[140:143], v[202:205], v[82:85]
	v_mfma_f32_16x16x32_bf16 v[76:79], v[164:167], v[202:205], v[76:79]
	s_setprio 0
	s_barrier
	s_add_i32 s35, 0, 0x1c000
	v_add_u32_e32 v0, s35, v149
	v_mov_b32_e32 v80, v145
	ds_read_b128 v[206:209], v0
	ds_read_b128 v[210:213], v0 offset:1024
	ds_read_b128 v[214:217], v0 offset:2048
	ds_read_b128 v[218:221], v0 offset:3072
	s_add_i32 s22, s22, s13
	s_add_i32 m0, s22, 0xffffff80
	v_mov_b32_e32 v80, v147
	global_load_lds_dwordx4 v145, s[68:69] offset:128
	s_add_i32 m0, s22, 0x1f80
	s_nop 0
	global_load_lds_dwordx4 v147, s[68:69] offset:128
	s_barrier
	s_waitcnt lgkmcnt(0)
	s_setprio 1
	s_waitcnt lgkmcnt(0)
	v_mfma_f32_16x16x32_bf16 v[122:125], v[206:209], v[168:171], v[122:125]
	v_mfma_f32_16x16x32_bf16 v[118:121], v[214:217], v[168:171], v[118:121]
	v_mfma_f32_16x16x32_bf16 v[106:109], v[206:209], v[176:179], v[106:109]
	v_mfma_f32_16x16x32_bf16 v[102:105], v[214:217], v[176:179], v[102:105]
	v_mfma_f32_16x16x32_bf16 v[90:93], v[206:209], v[190:193], v[90:93]
	v_mfma_f32_16x16x32_bf16 v[86:89], v[214:217], v[190:193], v[86:89]
	v_mfma_f32_16x16x32_bf16 v[72:75], v[206:209], v[198:201], v[72:75]
	v_mfma_f32_16x16x32_bf16 v[68:71], v[214:217], v[198:201], v[68:71]
	v_mfma_f32_16x16x32_bf16 v[122:125], v[210:213], v[172:175], v[122:125]
	v_mfma_f32_16x16x32_bf16 v[118:121], v[218:221], v[172:175], v[118:121]
	v_mfma_f32_16x16x32_bf16 v[106:109], v[210:213], v[184:187], v[106:109]
	v_mfma_f32_16x16x32_bf16 v[102:105], v[218:221], v[184:187], v[102:105]
	v_mfma_f32_16x16x32_bf16 v[90:93], v[210:213], v[194:197], v[90:93]
	v_mfma_f32_16x16x32_bf16 v[86:89], v[218:221], v[194:197], v[86:89]
	v_mfma_f32_16x16x32_bf16 v[72:75], v[210:213], v[202:205], v[72:75]
	v_mfma_f32_16x16x32_bf16 v[68:71], v[218:221], v[202:205], v[68:71]
	s_setprio 0
	v_mov_b32_e32 v80, v144
	s_barrier
	ds_read_b128 v[168:171], v153 offset:49152
	ds_read_b128 v[172:175], v153 offset:50176
	ds_read_b128 v[176:179], v153 offset:51200
	ds_read_b128 v[184:187], v153 offset:52224
	ds_read_b128 v[190:193], v153 offset:53248
	ds_read_b128 v[194:197], v153 offset:54272
	ds_read_b128 v[198:201], v153 offset:55296
	ds_read_b128 v[202:205], v153 offset:56320
	s_add_i32 m0, s48, 0xffffff80
	v_mov_b32_e32 v80, v146
	global_load_lds_dwordx4 v144, s[44:45] offset:128
	s_add_i32 m0, s49, 0xffffff80
	s_nop 0
	global_load_lds_dwordx4 v146, s[44:45] offset:128
	s_barrier
; __device__ __forceinline__ unsigned cvt_pk_bf16(float lo, float hi) { unsigned r; asm("v_cvt_pk_bf16_f32 %0, %1, %2" : "=v"(r) : "v"(lo), "v"(hi)); return r; }
; __device__ __forceinline__ float rinv_of(unsigned long long ss) { return rsqrtf((float)ss * (1.f / 16777216.f) * (1.f / DM) + 1e-6f); }
; #define G_STAGE(bufoff, gbase, voff) do { _Pragma("unroll") for (int _i = 0; _i < 2; ++_i) { unsigned _vo = (voff)[_i]; asm volatile("" : "+v"(_vo));   \
;     __builtin_amdgcn_global_load_lds((const unsigned*)((const char*)(gbase) + _vo), (LAS unsigned*)(lds + (bufoff) + ldsw + _i * 8192), 16, 0, 0); } } while (0)
; #define G_WAIT_V(n) asm volatile("s_waitcnt vmcnt(" #n ")" ::: "memory")
;   __device__ __forceinline__ void operator()(const f32x4 (&acc)[2][2][4][2], const Unit& u, const EpiCtx& x_, int wr, int wc, int fr, int fq) const {
;     ...
;         const int row = (u.r0 + (ai ? x_.rdelta : 0)) + wr * 64 + m * 16 + fr;
;         bf16_t* rowp = (bf16_t*)u.C + (size_t)row * x_.ldc;
;         const float rs = (SCALE == 1) ? rinv_of(x_.ss[row]) : 1.f;
; #pragma unroll
;         for (int bj = 0; bj < 2; ++bj) {
;           const int cb = PERM ? (u.c0 + wc * 64 + bj * 32) : (u.c0 + bj * 128) + wc * 32;
;           f32x4 v0 = acc[ai][bj][m][0], v1 = acc[ai][bj][m][1];
;           if (SCALE == 1) { v0 *= rs; v1 *= rs; }
;           if (SCALE == 2) { v0 *= cs[bj][0]; v1 *= cs[bj][1]; }
;           if (PERM) {
;             uint4 o; o.x = cvt_pk_bf16(v0[0], v0[1]); o.y = cvt_pk_bf16(v0[2], v0[3]); o.z = cvt_pk_bf16(v1[0], v1[1]); o.w = cvt_pk_bf16(v1[2], v1[3]);
;             *(uint4*)(rowp + cb + 8 * fq) = o;
; template <class Epi>
; __device__ __forceinline__ void gemm_phase(LAS unsigned char* lds, const int K, const unsigned lda_b, const unsigned ldb_b, const Map& M, const Epi& E) {
;     ...
;       G_WAIT_V(6); G_BAR; G_MMA(1, 1, At, B1); G_BAR;
;       G_LDB(B0, 1, 0); G_SCHED; G_LDA(At, 1, 0); G_STAGE(G_SA(0, 1), a2h1, voffA);
;       G_WAIT_L(8); G_BAR; G_WAIT_L(0); G_MMA(0, 0, At, B0); G_BAR; G_SCHED;
;       G_LDB(B1, 1, 1); G_STAGE(G_SB(1, 0), b2h0 + kstep, voffB);
;       G_BAR; G_WAIT_L(0); G_MMA(0, 1, At, B1); G_BAR;
;       G_LDA(At, 1, 1); G_STAGE(G_SA(1, 0), a2h0 + kstep, voffA);
;       G_BAR; G_WAIT_L(0); G_MMA(1, 0, At, B0); G_BAR; G_SCHED;
;       G_STAGE(G_SB(1, 1), b2h1 + kstep, voffB);
;       G_WAIT_V(6); G_BAR; G_MMA(1, 1, At, B1); G_BAR;
;     }
	s_waitcnt lgkmcnt(0)
	s_setprio 1
	s_waitcnt lgkmcnt(0)
	v_mfma_f32_16x16x32_bf16 v[64:67], v[136:139], v[168:171], v[64:67]
	v_mfma_f32_16x16x32_bf16 v[60:63], v[154:157], v[168:171], v[60:63]
	v_mfma_f32_16x16x32_bf16 v[48:51], v[136:139], v[176:179], v[48:51]
	v_mfma_f32_16x16x32_bf16 v[44:47], v[154:157], v[176:179], v[44:47]
	v_mfma_f32_16x16x32_bf16 v[32:35], v[136:139], v[190:193], v[32:35]
	v_mfma_f32_16x16x32_bf16 v[28:31], v[154:157], v[190:193], v[28:31]
	v_mfma_f32_16x16x32_bf16 v[16:19], v[136:139], v[198:201], v[16:19]
	v_mfma_f32_16x16x32_bf16 v[12:15], v[154:157], v[198:201], v[12:15]
	v_mfma_f32_16x16x32_bf16 v[64:67], v[140:143], v[172:175], v[64:67]
	v_mfma_f32_16x16x32_bf16 v[60:63], v[164:167], v[172:175], v[60:63]
	v_mfma_f32_16x16x32_bf16 v[48:51], v[140:143], v[184:187], v[48:51]
	v_mfma_f32_16x16x32_bf16 v[44:47], v[164:167], v[184:187], v[44:47]
	v_mfma_f32_16x16x32_bf16 v[32:35], v[140:143], v[194:197], v[32:35]
	v_mfma_f32_16x16x32_bf16 v[28:31], v[164:167], v[194:197], v[28:31]
	v_mfma_f32_16x16x32_bf16 v[16:19], v[140:143], v[202:205], v[16:19]
	v_mfma_f32_16x16x32_bf16 v[12:15], v[164:167], v[202:205], v[12:15]
	s_setprio 0
	s_barrier
	v_mov_b32_e32 v80, v145
	s_add_i32 s22, s35, s13
	s_add_i32 m0, s22, 0xffffff80
	v_mov_b32_e32 v80, v147
	global_load_lds_dwordx4 v145, s[42:43] offset:128
	s_add_i32 m0, s22, 0x1f80
	s_nop 0
	global_load_lds_dwordx4 v147, s[42:43] offset:128
	s_waitcnt vmcnt(6)
	s_barrier
	s_setprio 1
	v_mfma_f32_16x16x32_bf16 v[56:59], v[206:209], v[168:171], v[56:59]
	v_mfma_f32_16x16x32_bf16 v[52:55], v[214:217], v[168:171], v[52:55]
	v_mfma_f32_16x16x32_bf16 v[40:43], v[206:209], v[176:179], v[40:43]
	v_mfma_f32_16x16x32_bf16 v[36:39], v[214:217], v[176:179], v[36:39]
	v_mfma_f32_16x16x32_bf16 v[24:27], v[206:209], v[190:193], v[24:27]
	v_mfma_f32_16x16x32_bf16 v[20:23], v[214:217], v[190:193], v[20:23]
	v_mfma_f32_16x16x32_bf16 v[8:11], v[206:209], v[198:201], v[8:11]
	v_mfma_f32_16x16x32_bf16 v[4:7], v[214:217], v[198:201], v[4:7]
	v_mfma_f32_16x16x32_bf16 v[56:59], v[210:213], v[172:175], v[56:59]
	v_mfma_f32_16x16x32_bf16 v[52:55], v[218:221], v[172:175], v[52:55]
	v_mfma_f32_16x16x32_bf16 v[40:43], v[210:213], v[184:187], v[40:43]
	v_mfma_f32_16x16x32_bf16 v[36:39], v[218:221], v[184:187], v[36:39]
	v_mfma_f32_16x16x32_bf16 v[24:27], v[210:213], v[194:197], v[24:27]
	v_mfma_f32_16x16x32_bf16 v[20:23], v[218:221], v[194:197], v[20:23]
	v_mfma_f32_16x16x32_bf16 v[8:11], v[210:213], v[202:205], v[8:11]
	v_mfma_f32_16x16x32_bf16 v[4:7], v[218:221], v[202:205], v[4:7]
	s_setprio 0
	s_add_i32 s34, s34, 2
	s_add_u32 s30, s30, 0x100
	s_addc_u32 s31, s31, 0
	s_add_u32 s38, s38, 0x100
	s_addc_u32 s39, s39, 0
	s_cmp_gt_u32 s34, 29
	s_barrier
	s_cbranch_scc0 .LBB0_257
	s_nop 1
	v_add_u32_e32 v184, s76, v148
	v_ashrrev_i32_e32 v185, 31, v184
	v_lshl_add_u64 v[186:187], v[184:185], 3, s[4:5]
	global_load_dwordx2 v[164:165], v[186:187], off
	v_add_u32_e32 v190, s76, v150
	v_ashrrev_i32_e32 v191, 31, v190
	v_lshl_add_u64 v[192:193], v[190:191], 3, s[4:5]
	global_load_dwordx2 v[166:167], v[192:193], off
	v_add_u32_e32 v194, s76, v151
	v_ashrrev_i32_e32 v195, 31, v194
	v_lshl_add_u64 v[196:197], v[194:195], 3, s[4:5]
	global_load_dwordx2 v[168:169], v[196:197], off
	v_add_u32_e32 v198, s76, v152
	v_ashrrev_i32_e32 v199, 31, v198
	v_lshl_add_u64 v[200:201], v[198:199], 3, s[4:5]
	global_load_dwordx2 v[170:171], v[200:201], off
	global_load_dwordx2 v[172:173], v[186:187], off offset:1024
	global_load_dwordx2 v[174:175], v[192:193], off offset:1024
	global_load_dwordx2 v[176:177], v[196:197], off offset:1024
	global_load_dwordx2 v[178:179], v[200:201], off offset:1024
	v_add_u32_e32 v138, s76, v148
	v_ashrrev_i32_e32 v139, 31, v138
	v_lshl_add_u64 v[140:141], v[138:139], 3, s[4:5]
	s_nop 0
	v_lshlrev_b64 v[154:155], 13, v[138:139]
	s_add_i32 s28, s79, s61
	v_mov_b32_e32 v135, v81
	s_add_i32 s30, s66, s79
	s_ashr_i32 s29, s28, 31
	v_add_u32_e32 v136, s76, v150
	s_ashr_i32 s31, s30, 31
	s_lshl_b64 s[38:39], s[28:29], 1
	v_ashrrev_i32_e32 v137, 31, v136
	s_lshl_b64 s[42:43], s[30:31], 1
	v_lshl_add_u64 v[142:143], v[136:137], 3, s[4:5]
	v_readfirstlane_b32 s79, v3
	s_mov_b64 s[44:45], s[8:9]
	s_mov_b64 s[68:69], s[40:41]
	s_cmp_eq_u32 s75, s67
	s_waitcnt lgkmcnt(0)
	s_waitcnt vmcnt(7)
	v_ffbh_u32_e32 v80, v165
	v_min_u32_e32 v80, 32, v80
	v_lshlrev_b64 v[0:1], v80, v[164:165]
	v_min_u32_e32 v0, 1, v0
	v_or_b32_e32 v0, v1, v0
	v_cvt_f32_u32_e32 v139, v0
	v_sub_u32_e32 v80, 32, v80
	v_lshl_add_u64 v[0:1], s[2:3], 0, v[154:155]
	v_lshl_add_u64 v[0:1], v[0:1], 0, v[134:135]
	v_ldexp_f32 v80, v139, v80
	v_mul_f32_e32 v80, 0x33800000, v80
	v_fmamk_f32 v80, v80, 0x3a000000, v234
	v_mul_f32_e32 v139, 0x4b800000, v80
	v_cmp_gt_f32_e32 vcc, s50, v80
	v_lshl_add_u64 v[154:155], v[0:1], 0, s[38:39]
	v_lshl_add_u64 v[0:1], v[0:1], 0, s[42:43]
	v_cndmask_b32_e32 v80, v80, v139, vcc
	v_rsq_f32_e32 v80, v80
	s_nop 0
	v_mul_f32_e32 v139, 0x45800000, v80
	v_cndmask_b32_e32 v80, v80, v139, vcc
	v_pk_mul_f32 v[132:133], v[132:133], v[80:81] op_sel_hi:[1,0]
	v_pk_mul_f32 v[130:131], v[130:131], v[80:81] op_sel_hi:[1,0]
	v_pk_mul_f32 v[128:129], v[128:129], v[80:81] op_sel_hi:[1,0]
	v_pk_mul_f32 v[126:127], v[126:127], v[80:81] op_sel_hi:[1,0]
	v_pk_mul_f32 v[124:125], v[124:125], v[80:81] op_sel_hi:[1,0]
	v_pk_mul_f32 v[122:123], v[122:123], v[80:81] op_sel_hi:[1,0]
	v_pk_mul_f32 v[156:157], v[120:121], v[80:81] op_sel_hi:[1,0]
	v_pk_mul_f32 v[160:161], v[118:119], v[80:81] op_sel_hi:[1,0]
	v_cvt_pk_bf16_f32 v118, v130, v131
	v_cvt_pk_bf16_f32 v119, v132, v133
	v_cvt_pk_bf16_f32 v120, v126, v127
	v_cvt_pk_bf16_f32 v121, v128, v129
	v_cvt_pk_bf16_f32 v122, v122, v123
	v_cvt_pk_bf16_f32 v123, v124, v125
	s_nop 0
	v_cvt_pk_bf16_f32 v124, v160, v161
	v_cvt_pk_bf16_f32 v125, v156, v157
	global_store_dwordx4 v[154:155], v[118:121], off
	global_store_dwordx4 v[0:1], v[122:125], off
	s_nop 0
	v_add_u32_e32 v118, s76, v151
	v_lshlrev_b64 v[122:123], 13, v[136:137]
	v_ashrrev_i32_e32 v119, 31, v118
	v_lshl_add_u64 v[120:121], v[118:119], 3, s[4:5]
	s_waitcnt lgkmcnt(0)
; __device__ __forceinline__ unsigned cvt_pk_bf16(float lo, float hi) { unsigned r; asm("v_cvt_pk_bf16_f32 %0, %1, %2" : "=v"(r) : "v"(lo), "v"(hi)); return r; }
; __device__ __forceinline__ float rinv_of(unsigned long long ss) { return rsqrtf((float)ss * (1.f / 16777216.f) * (1.f / DM) + 1e-6f); }
;   __device__ __forceinline__ void operator()(const f32x4 (&acc)[2][2][4][2], const Unit& u, const EpiCtx& x_, int wr, int wc, int fr, int fq) const {
;     ...
;         const int row = (u.r0 + (ai ? x_.rdelta : 0)) + wr * 64 + m * 16 + fr;
;         bf16_t* rowp = (bf16_t*)u.C + (size_t)row * x_.ldc;
;         const float rs = (SCALE == 1) ? rinv_of(x_.ss[row]) : 1.f;
; #pragma unroll
;         for (int bj = 0; bj < 2; ++bj) {
;           const int cb = PERM ? (u.c0 + wc * 64 + bj * 32) : (u.c0 + bj * 128) + wc * 32;
;           f32x4 v0 = acc[ai][bj][m][0], v1 = acc[ai][bj][m][1];
;           if (SCALE == 1) { v0 *= rs; v1 *= rs; }
;           if (SCALE == 2) { v0 *= cs[bj][0]; v1 *= cs[bj][1]; }
;           if (PERM) {
;             uint4 o; o.x = cvt_pk_bf16(v0[0], v0[1]); o.y = cvt_pk_bf16(v0[2], v0[3]); o.z = cvt_pk_bf16(v1[0], v1[1]); o.w = cvt_pk_bf16(v1[2], v1[3]);
;             *(uint4*)(rowp + cb + 8 * fq) = o;
;           } else {
;             uint2 o0, o1; o0.x = cvt_pk_bf16(v0[0], v0[1]); o0.y = cvt_pk_bf16(v0[2], v0[3]); o1.x = cvt_pk_bf16(v1[0], v1[1]); o1.y = cvt_pk_bf16(v1[2], v1[3]);
;             *(uint2*)(rowp + cb + 4 * fq) = o0; *(uint2*)(rowp + cb + 16 + 4 * fq) = o1;
	s_waitcnt vmcnt(8)
	v_ffbh_u32_e32 v80, v167
	v_min_u32_e32 v80, 32, v80
	v_lshlrev_b64 v[0:1], v80, v[166:167]
	v_min_u32_e32 v0, 1, v0
	v_or_b32_e32 v0, v1, v0
	v_cvt_f32_u32_e32 v124, v0
	v_sub_u32_e32 v80, 32, v80
	v_lshl_add_u64 v[0:1], s[2:3], 0, v[122:123]
	v_lshl_add_u64 v[0:1], v[0:1], 0, v[134:135]
	v_ldexp_f32 v80, v124, v80
	v_mul_f32_e32 v80, 0x33800000, v80
	v_fmamk_f32 v80, v80, 0x3a000000, v234
	v_mul_f32_e32 v122, 0x4b800000, v80
	v_cmp_gt_f32_e32 vcc, s50, v80
	s_nop 1
	v_cndmask_b32_e32 v80, v80, v122, vcc
	v_rsq_f32_e32 v80, v80
	v_lshl_add_u64 v[122:123], v[0:1], 0, s[38:39]
	v_lshl_add_u64 v[0:1], v[0:1], 0, s[42:43]
	v_mul_f32_e32 v124, 0x45800000, v80
	v_cndmask_b32_e32 v80, v80, v124, vcc
	v_pk_mul_f32 v[116:117], v[116:117], v[80:81] op_sel_hi:[1,0]
	v_pk_mul_f32 v[114:115], v[114:115], v[80:81] op_sel_hi:[1,0]
	v_pk_mul_f32 v[112:113], v[112:113], v[80:81] op_sel_hi:[1,0]
	v_pk_mul_f32 v[110:111], v[110:111], v[80:81] op_sel_hi:[1,0]
	v_pk_mul_f32 v[108:109], v[108:109], v[80:81] op_sel_hi:[1,0]
	v_pk_mul_f32 v[106:107], v[106:107], v[80:81] op_sel_hi:[1,0]
	v_pk_mul_f32 v[124:125], v[104:105], v[80:81] op_sel_hi:[1,0]
	v_pk_mul_f32 v[126:127], v[102:103], v[80:81] op_sel_hi:[1,0]
	v_cvt_pk_bf16_f32 v102, v114, v115
	v_cvt_pk_bf16_f32 v103, v116, v117
	v_cvt_pk_bf16_f32 v104, v110, v111
	v_cvt_pk_bf16_f32 v105, v112, v113
	v_cvt_pk_bf16_f32 v106, v106, v107
	v_cvt_pk_bf16_f32 v107, v108, v109
	s_nop 0
	v_cvt_pk_bf16_f32 v108, v126, v127
	v_cvt_pk_bf16_f32 v109, v124, v125
	global_store_dwordx4 v[122:123], v[102:105], off
	global_store_dwordx4 v[0:1], v[106:109], off
	s_nop 0
	v_lshlrev_b64 v[104:105], 13, v[118:119]
	v_lshl_add_u64 v[104:105], s[2:3], 0, v[104:105]
	v_add_u32_e32 v0, s76, v152
	v_lshl_add_u64 v[104:105], v[104:105], 0, v[134:135]
	v_ashrrev_i32_e32 v1, 31, v0
	v_readfirstlane_b32 s76, v2
	s_waitcnt lgkmcnt(0)
	s_waitcnt vmcnt(9)
	v_ffbh_u32_e32 v80, v169
	v_min_u32_e32 v80, 32, v80
	v_lshlrev_b64 v[102:103], v80, v[168:169]
	v_min_u32_e32 v102, 1, v102
	v_or_b32_e32 v102, v103, v102
	v_cvt_f32_u32_e32 v106, v102
	v_sub_u32_e32 v80, 32, v80
	v_lshl_add_u64 v[102:103], v[0:1], 3, s[4:5]
	v_ldexp_f32 v80, v106, v80
	v_mul_f32_e32 v80, 0x33800000, v80
	v_fmamk_f32 v80, v80, 0x3a000000, v234
	v_mul_f32_e32 v106, 0x4b800000, v80
	v_cmp_gt_f32_e32 vcc, s50, v80
	s_nop 1
	v_cndmask_b32_e32 v80, v80, v106, vcc
	v_rsq_f32_e32 v80, v80
	v_lshl_add_u64 v[106:107], v[104:105], 0, s[38:39]
	v_lshl_add_u64 v[104:105], v[104:105], 0, s[42:43]
	v_mul_f32_e32 v108, 0x45800000, v80
	v_cndmask_b32_e32 v80, v80, v108, vcc
	v_pk_mul_f32 v[100:101], v[100:101], v[80:81] op_sel_hi:[1,0]
	v_pk_mul_f32 v[98:99], v[98:99], v[80:81] op_sel_hi:[1,0]
	v_pk_mul_f32 v[96:97], v[96:97], v[80:81] op_sel_hi:[1,0]
	v_pk_mul_f32 v[94:95], v[94:95], v[80:81] op_sel_hi:[1,0]
	v_pk_mul_f32 v[92:93], v[92:93], v[80:81] op_sel_hi:[1,0]
	v_pk_mul_f32 v[90:91], v[90:91], v[80:81] op_sel_hi:[1,0]
	v_pk_mul_f32 v[108:109], v[88:89], v[80:81] op_sel_hi:[1,0]
	v_pk_mul_f32 v[110:111], v[86:87], v[80:81] op_sel_hi:[1,0]
	v_cvt_pk_bf16_f32 v86, v98, v99
	v_cvt_pk_bf16_f32 v87, v100, v101
	v_cvt_pk_bf16_f32 v88, v94, v95
	v_cvt_pk_bf16_f32 v89, v96, v97
	v_cvt_pk_bf16_f32 v90, v90, v91
	v_cvt_pk_bf16_f32 v91, v92, v93
	s_nop 0
	v_cvt_pk_bf16_f32 v92, v110, v111
	v_cvt_pk_bf16_f32 v93, v108, v109
	global_store_dwordx4 v[106:107], v[86:89], off
	global_store_dwordx4 v[104:105], v[90:93], off
	s_nop 0
	s_waitcnt lgkmcnt(0)
	s_waitcnt vmcnt(10)
	v_ffbh_u32_e32 v80, v171
	v_min_u32_e32 v80, 32, v80
	v_lshlrev_b64 v[86:87], v80, v[170:171]
	v_min_u32_e32 v86, 1, v86
	v_or_b32_e32 v86, v87, v86
	v_cvt_f32_u32_e32 v88, v86
	v_lshlrev_b64 v[86:87], 13, v[0:1]
	v_sub_u32_e32 v1, 32, v80
	v_lshl_add_u64 v[86:87], s[2:3], 0, v[86:87]
	v_ldexp_f32 v1, v88, v1
	v_mul_f32_e32 v1, 0x33800000, v1
	v_fmamk_f32 v1, v1, 0x3a000000, v234
	v_mul_f32_e32 v80, 0x4b800000, v1
	v_cmp_gt_f32_e32 vcc, s50, v1
	v_lshl_add_u64 v[86:87], v[86:87], 0, v[134:135]
	v_lshl_add_u64 v[88:89], v[86:87], 0, s[38:39]
	v_cndmask_b32_e32 v1, v1, v80, vcc
	v_rsq_f32_e32 v1, v1
	v_lshl_add_u64 v[86:87], v[86:87], 0, s[42:43]
	v_add_u32_e32 v0, 0x80, v0
	v_mul_f32_e32 v80, 0x45800000, v1
	v_cndmask_b32_e32 v80, v1, v80, vcc
	v_pk_mul_f32 v[84:85], v[84:85], v[80:81] op_sel_hi:[1,0]
	v_pk_mul_f32 v[82:83], v[82:83], v[80:81] op_sel_hi:[1,0]
	v_pk_mul_f32 v[78:79], v[78:79], v[80:81] op_sel_hi:[1,0]
	v_pk_mul_f32 v[76:77], v[76:77], v[80:81] op_sel_hi:[1,0]
	v_pk_mul_f32 v[74:75], v[74:75], v[80:81] op_sel_hi:[1,0]
	v_pk_mul_f32 v[72:73], v[72:73], v[80:81] op_sel_hi:[1,0]
	v_pk_mul_f32 v[90:91], v[70:71], v[80:81] op_sel_hi:[1,0]
	v_pk_mul_f32 v[92:93], v[68:69], v[80:81] op_sel_hi:[1,0]
	v_cvt_pk_bf16_f32 v68, v82, v83
	v_cvt_pk_bf16_f32 v69, v84, v85
	v_cvt_pk_bf16_f32 v70, v76, v77
	v_cvt_pk_bf16_f32 v71, v78, v79
	v_cvt_pk_bf16_f32 v72, v72, v73
	v_cvt_pk_bf16_f32 v73, v74, v75
	s_nop 0
	v_cvt_pk_bf16_f32 v74, v92, v93
	v_cvt_pk_bf16_f32 v75, v90, v91
	global_store_dwordx4 v[88:89], v[68:71], off
	global_store_dwordx4 v[86:87], v[72:75], off
	s_nop 0
	v_add_u32_e32 v70, 0x80, v138
	v_ashrrev_i32_e32 v71, 31, v70
	s_waitcnt lgkmcnt(0)
	s_waitcnt vmcnt(11)
; __device__ __forceinline__ unsigned cvt_pk_bf16(float lo, float hi) { unsigned r; asm("v_cvt_pk_bf16_f32 %0, %1, %2" : "=v"(r) : "v"(lo), "v"(hi)); return r; }
; __device__ __forceinline__ float rinv_of(unsigned long long ss) { return rsqrtf((float)ss * (1.f / 16777216.f) * (1.f / DM) + 1e-6f); }
; #define G_WAIT_V(n) asm volatile("s_waitcnt vmcnt(" #n ")" ::: "memory")
; #define G_BAR __builtin_amdgcn_s_barrier()
;   __device__ __forceinline__ void operator()(const f32x4 (&acc)[2][2][4][2], const Unit& u, const EpiCtx& x_, int wr, int wc, int fr, int fq) const {
;     ...
;         const int row = (u.r0 + (ai ? x_.rdelta : 0)) + wr * 64 + m * 16 + fr;
;         bf16_t* rowp = (bf16_t*)u.C + (size_t)row * x_.ldc;
;         const float rs = (SCALE == 1) ? rinv_of(x_.ss[row]) : 1.f;
; #pragma unroll
;         for (int bj = 0; bj < 2; ++bj) {
;           const int cb = PERM ? (u.c0 + wc * 64 + bj * 32) : (u.c0 + bj * 128) + wc * 32;
;           f32x4 v0 = acc[ai][bj][m][0], v1 = acc[ai][bj][m][1];
;           if (SCALE == 1) { v0 *= rs; v1 *= rs; }
;           if (SCALE == 2) { v0 *= cs[bj][0]; v1 *= cs[bj][1]; }
;           if (PERM) {
;             uint4 o; o.x = cvt_pk_bf16(v0[0], v0[1]); o.y = cvt_pk_bf16(v0[2], v0[3]); o.z = cvt_pk_bf16(v1[0], v1[1]); o.w = cvt_pk_bf16(v1[2], v1[3]);
;             *(uint4*)(rowp + cb + 8 * fq) = o;
;           } else {
;             uint2 o0, o1; o0.x = cvt_pk_bf16(v0[0], v0[1]); o0.y = cvt_pk_bf16(v0[2], v0[3]); o1.x = cvt_pk_bf16(v1[0], v1[1]); o1.y = cvt_pk_bf16(v1[2], v1[3]);
;             *(uint2*)(rowp + cb + 4 * fq) = o0; *(uint2*)(rowp + cb + 16 + 4 * fq) = o1;
; template <class Epi>
; __device__ __forceinline__ void gemm_phase(LAS unsigned char* lds, const int K, const unsigned lda_b, const unsigned ldb_b, const Map& M, const Epi& E) {
;     ...
;     E(acc, cur, X, wr, wc, fr, fq);
;     if (!has_next) break;
; #pragma unroll
;     for (int a = 0; a < 2; ++a)
; #pragma unroll
;       for (int b = 0; b < 2; ++b)
; #pragma unroll
;         for (int m = 0; m < 4; ++m)
; #pragma unroll
;           for (int n = 0; n < 2; ++n) acc[a][b][m][n] = (f32x4){0.f, 0.f, 0.f, 0.f};
;     cur = nxt; ++ui;
;   }
;   G_WAIT_V(0);
;   if (wr == 0) G_BAR;
;   G_BAR;
	v_ffbh_u32_e32 v1, v173
	v_min_u32_e32 v1, 32, v1
	v_lshlrev_b64 v[68:69], v1, v[172:173]
	v_min_u32_e32 v68, 1, v68
	v_or_b32_e32 v68, v69, v68
	v_cvt_f32_u32_e32 v72, v68
	v_sub_u32_e32 v1, 32, v1
	v_lshlrev_b64 v[68:69], 13, v[70:71]
	v_lshl_add_u64 v[68:69], s[2:3], 0, v[68:69]
	v_ldexp_f32 v1, v72, v1
	v_mul_f32_e32 v1, 0x33800000, v1
	v_fmamk_f32 v1, v1, 0x3a000000, v234
	v_mul_f32_e32 v70, 0x4b800000, v1
	v_cmp_gt_f32_e32 vcc, s50, v1
	v_lshl_add_u64 v[68:69], v[68:69], 0, v[134:135]
	s_nop 0
	v_cndmask_b32_e32 v1, v1, v70, vcc
	v_rsq_f32_e32 v1, v1
	v_lshl_add_u64 v[70:71], v[68:69], 0, s[38:39]
	v_lshl_add_u64 v[68:69], v[68:69], 0, s[42:43]
	v_mul_f32_e32 v72, 0x45800000, v1
	v_cndmask_b32_e32 v72, v1, v72, vcc
	v_pk_mul_f32 v[66:67], v[66:67], v[72:73] op_sel_hi:[1,0]
	v_pk_mul_f32 v[64:65], v[64:65], v[72:73] op_sel_hi:[1,0]
	v_pk_mul_f32 v[62:63], v[62:63], v[72:73] op_sel_hi:[1,0]
	v_pk_mul_f32 v[60:61], v[60:61], v[72:73] op_sel_hi:[1,0]
	v_pk_mul_f32 v[58:59], v[58:59], v[72:73] op_sel_hi:[1,0]
	v_pk_mul_f32 v[56:57], v[56:57], v[72:73] op_sel_hi:[1,0]
	v_pk_mul_f32 v[74:75], v[54:55], v[72:73] op_sel_hi:[1,0]
	v_pk_mul_f32 v[72:73], v[52:53], v[72:73] op_sel_hi:[1,0]
	v_cvt_pk_bf16_f32 v52, v64, v65
	v_cvt_pk_bf16_f32 v53, v66, v67
	v_cvt_pk_bf16_f32 v54, v60, v61
	v_cvt_pk_bf16_f32 v55, v62, v63
	v_cvt_pk_bf16_f32 v56, v56, v57
	v_cvt_pk_bf16_f32 v57, v58, v59
	s_nop 0
	v_cvt_pk_bf16_f32 v58, v72, v73
	v_cvt_pk_bf16_f32 v59, v74, v75
	global_store_dwordx4 v[70:71], v[52:55], off
	global_store_dwordx4 v[68:69], v[56:59], off
	s_nop 0
	v_add_u32_e32 v54, 0x80, v136
	v_ashrrev_i32_e32 v55, 31, v54
	s_waitcnt lgkmcnt(0)
	s_waitcnt vmcnt(12)
	v_ffbh_u32_e32 v1, v175
	v_min_u32_e32 v1, 32, v1
	v_lshlrev_b64 v[52:53], v1, v[174:175]
	v_min_u32_e32 v52, 1, v52
	v_or_b32_e32 v52, v53, v52
	v_cvt_f32_u32_e32 v56, v52
	v_sub_u32_e32 v1, 32, v1
	v_lshlrev_b64 v[52:53], 13, v[54:55]
	v_lshl_add_u64 v[52:53], s[2:3], 0, v[52:53]
	v_ldexp_f32 v1, v56, v1
	v_mul_f32_e32 v1, 0x33800000, v1
	v_fmamk_f32 v1, v1, 0x3a000000, v234
	v_mul_f32_e32 v54, 0x4b800000, v1
	v_cmp_gt_f32_e32 vcc, s50, v1
	v_lshl_add_u64 v[52:53], v[52:53], 0, v[134:135]
	s_nop 0
	v_cndmask_b32_e32 v1, v1, v54, vcc
	v_rsq_f32_e32 v1, v1
	v_lshl_add_u64 v[54:55], v[52:53], 0, s[38:39]
	v_lshl_add_u64 v[52:53], v[52:53], 0, s[42:43]
	v_mul_f32_e32 v56, 0x45800000, v1
	v_cndmask_b32_e32 v56, v1, v56, vcc
	v_pk_mul_f32 v[50:51], v[50:51], v[56:57] op_sel_hi:[1,0]
	v_pk_mul_f32 v[48:49], v[48:49], v[56:57] op_sel_hi:[1,0]
	v_pk_mul_f32 v[46:47], v[46:47], v[56:57] op_sel_hi:[1,0]
	v_pk_mul_f32 v[44:45], v[44:45], v[56:57] op_sel_hi:[1,0]
	v_pk_mul_f32 v[42:43], v[42:43], v[56:57] op_sel_hi:[1,0]
	v_pk_mul_f32 v[40:41], v[40:41], v[56:57] op_sel_hi:[1,0]
	v_pk_mul_f32 v[58:59], v[38:39], v[56:57] op_sel_hi:[1,0]
	v_pk_mul_f32 v[56:57], v[36:37], v[56:57] op_sel_hi:[1,0]
	v_cvt_pk_bf16_f32 v36, v48, v49
	v_cvt_pk_bf16_f32 v37, v50, v51
	v_cvt_pk_bf16_f32 v38, v44, v45
	v_cvt_pk_bf16_f32 v39, v46, v47
	v_cvt_pk_bf16_f32 v40, v40, v41
	v_cvt_pk_bf16_f32 v41, v42, v43
	s_nop 0
	v_cvt_pk_bf16_f32 v42, v56, v57
	v_cvt_pk_bf16_f32 v43, v58, v59
	global_store_dwordx4 v[54:55], v[36:39], off
	global_store_dwordx4 v[52:53], v[40:43], off
	s_nop 0
	v_add_u32_e32 v38, 0x80, v118
	v_ashrrev_i32_e32 v39, 31, v38
	s_waitcnt lgkmcnt(0)
	s_waitcnt vmcnt(13)
	v_ffbh_u32_e32 v1, v177
	v_min_u32_e32 v1, 32, v1
	v_lshlrev_b64 v[36:37], v1, v[176:177]
	v_min_u32_e32 v36, 1, v36
	v_or_b32_e32 v36, v37, v36
	v_cvt_f32_u32_e32 v40, v36
	v_sub_u32_e32 v1, 32, v1
	v_lshlrev_b64 v[36:37], 13, v[38:39]
	v_lshl_add_u64 v[36:37], s[2:3], 0, v[36:37]
	v_ldexp_f32 v1, v40, v1
	v_mul_f32_e32 v1, 0x33800000, v1
	v_fmamk_f32 v1, v1, 0x3a000000, v234
	v_mul_f32_e32 v38, 0x4b800000, v1
	v_cmp_gt_f32_e32 vcc, s50, v1
	v_lshl_add_u64 v[36:37], v[36:37], 0, v[134:135]
	s_nop 0
	v_cndmask_b32_e32 v1, v1, v38, vcc
	v_rsq_f32_e32 v1, v1
	v_lshl_add_u64 v[38:39], v[36:37], 0, s[38:39]
	v_lshl_add_u64 v[36:37], v[36:37], 0, s[42:43]
	v_mul_f32_e32 v40, 0x45800000, v1
	v_cndmask_b32_e32 v40, v1, v40, vcc
	v_pk_mul_f32 v[34:35], v[34:35], v[40:41] op_sel_hi:[1,0]
	v_pk_mul_f32 v[32:33], v[32:33], v[40:41] op_sel_hi:[1,0]
	v_pk_mul_f32 v[30:31], v[30:31], v[40:41] op_sel_hi:[1,0]
	v_pk_mul_f32 v[28:29], v[28:29], v[40:41] op_sel_hi:[1,0]
	v_pk_mul_f32 v[26:27], v[26:27], v[40:41] op_sel_hi:[1,0]
	v_pk_mul_f32 v[24:25], v[24:25], v[40:41] op_sel_hi:[1,0]
	v_pk_mul_f32 v[42:43], v[22:23], v[40:41] op_sel_hi:[1,0]
	v_pk_mul_f32 v[40:41], v[20:21], v[40:41] op_sel_hi:[1,0]
	v_cvt_pk_bf16_f32 v20, v32, v33
	v_cvt_pk_bf16_f32 v21, v34, v35
	v_cvt_pk_bf16_f32 v22, v28, v29
	v_cvt_pk_bf16_f32 v23, v30, v31
	v_cvt_pk_bf16_f32 v24, v24, v25
	v_cvt_pk_bf16_f32 v25, v26, v27
	s_nop 0
	v_cvt_pk_bf16_f32 v26, v40, v41
	v_cvt_pk_bf16_f32 v27, v42, v43
	global_store_dwordx4 v[38:39], v[20:23], off
	global_store_dwordx4 v[36:37], v[24:27], off
	s_nop 0
	v_ashrrev_i32_e32 v1, 31, v0
	v_lshlrev_b64 v[0:1], 13, v[0:1]
	v_lshl_add_u64 v[0:1], s[2:3], 0, v[0:1]
	v_lshl_add_u64 v[0:1], v[0:1], 0, v[134:135]
	s_mov_b64 s[2:3], s[6:7]
	s_waitcnt lgkmcnt(0)
	s_waitcnt vmcnt(14)
	v_ffbh_u32_e32 v2, v179
	v_min_u32_e32 v22, 32, v2
	v_lshlrev_b64 v[2:3], v22, v[178:179]
	v_min_u32_e32 v2, 1, v2
	v_or_b32_e32 v2, v3, v2
	v_cvt_f32_u32_e32 v2, v2
	v_sub_u32_e32 v3, 32, v22
	v_lshl_add_u64 v[20:21], v[0:1], 0, s[38:39]
	v_lshl_add_u64 v[22:23], v[0:1], 0, s[42:43]
	v_ldexp_f32 v2, v2, v3
	v_mul_f32_e32 v2, 0x33800000, v2
	v_fmamk_f32 v2, v2, 0x3a000000, v234
	v_mul_f32_e32 v3, 0x4b800000, v2
	v_cmp_gt_f32_e32 vcc, s50, v2
	s_nop 1
	v_cndmask_b32_e32 v2, v2, v3, vcc
	v_rsq_f32_e32 v2, v2
	s_nop 0
	v_mul_f32_e32 v0, 0x45800000, v2
	v_cndmask_b32_e32 v0, v2, v0, vcc
	v_pk_mul_f32 v[2:3], v[18:19], v[0:1] op_sel_hi:[1,0]
	v_pk_mul_f32 v[16:17], v[16:17], v[0:1] op_sel_hi:[1,0]
	v_pk_mul_f32 v[14:15], v[14:15], v[0:1] op_sel_hi:[1,0]
	v_pk_mul_f32 v[12:13], v[12:13], v[0:1] op_sel_hi:[1,0]
	v_pk_mul_f32 v[10:11], v[10:11], v[0:1] op_sel_hi:[1,0]
	v_pk_mul_f32 v[8:9], v[8:9], v[0:1] op_sel_hi:[1,0]
	v_pk_mul_f32 v[18:19], v[6:7], v[0:1] op_sel_hi:[1,0]
	v_pk_mul_f32 v[6:7], v[4:5], v[0:1] op_sel_hi:[1,0]
	v_cvt_pk_bf16_f32 v0, v16, v17
	v_cvt_pk_bf16_f32 v1, v2, v3
	v_cvt_pk_bf16_f32 v2, v12, v13
	v_cvt_pk_bf16_f32 v3, v14, v15
	v_cvt_pk_bf16_f32 v4, v8, v9
	v_cvt_pk_bf16_f32 v5, v10, v11
	s_nop 0
	v_cvt_pk_bf16_f32 v6, v6, v7
	v_cvt_pk_bf16_f32 v7, v18, v19
	global_store_dwordx4 v[20:21], v[0:3], off
	global_store_dwordx4 v[22:23], v[4:7], off
	s_cbranch_scc0 .LBB0_256
	s_waitcnt vmcnt(0)
	s_cmpk_gt_u32 s1, 0xff
	s_cbranch_scc1 .LBB0_261
	s_barrier

; #define G_STAGE(bufoff, gbase, voff) do { _Pragma("unroll") for (int _i = 0; _i < 2; ++_i) { unsigned _vo = (voff)[_i]; asm volatile("" : "+v"(_vo));   \
;     __builtin_amdgcn_global_load_lds((const unsigned*)((const char*)(gbase) + _vo), (LAS unsigned*)(lds + (bufoff) + ldsw + _i * 8192), 16, 0, 0); } } while (0)
; #define G_LDA(dst, b, h) do { _Pragma("unroll") for (int m = 0; m < 4; ++m) _Pragma("unroll") for (int k = 0; k < 2; ++k) dst[m][k] = *(const LAS bf16x8*)(lds + G_SA(b, h) + aoff + m * 2048 + k * 1024); } while (0)
; #define G_LDB(dst, b, h) do { _Pragma("unroll") for (int n = 0; n < 2; ++n) _Pragma("unroll") for (int k = 0; k < 2; ++k) dst[n][k] = *(const LAS bf16x8*)(lds + G_SB(b, h) + boff + n * 2048 + k * 1024); } while (0)
; #define G_MMA(ai, bj, At, Bt) do { __builtin_amdgcn_s_setprio(1); _Pragma("unroll") for (int m = 0; m < 4; ++m) _Pragma("unroll") for (int n = 0; n < 2; ++n) _Pragma("unroll") for (int k = 0; k < 2; ++k) \
;     acc[ai][bj][m][n] = __builtin_amdgcn_mfma_f32_16x16x32_bf16(Bt[n][k], At[m][k], acc[ai][bj][m][n], 0, 0, 0); __builtin_amdgcn_s_setprio(0); } while (0)
; #define G_WAIT_V(n) asm volatile("s_waitcnt vmcnt(" #n ")" ::: "memory")
; #define G_WAIT_L(n) asm volatile("s_waitcnt lgkmcnt(" #n ")" ::: "memory")
; #define G_BAR __builtin_amdgcn_s_barrier()
; template <class Epi>
; __device__ __forceinline__ void gemm_phase(LAS unsigned char* lds, const int K, const unsigned lda_b, const unsigned ldb_b, const Map& M, const Epi& E) {
;     ...
;     for (int t = 0; t < nt; t += 2) {
;       const bool last = (t == nt - 2);
;       const char* a1h1 = cur.a0 + a_h + (size_t)(t + 1) * kstep;
;       const char* a2h0 = last ? nxt.a0 : cur.a0 + (size_t)(t + 2) * kstep; const char* a2h1 = a2h0 + a_h;
;       const char* b2h0 = last ? nxt.b0 : cur.b0 + (size_t)(t + 2) * kstep; const char* b2h1 = last ? nxt.b1 : cur.b1 + (size_t)(t + 2) * kstep;
;       G_LDB(B0, 0, 0); G_SCHED; G_LDA(At, 0, 0); G_STAGE(G_SA(1, 1), a1h1, voffA);
;       G_WAIT_L(8); G_BAR; G_WAIT_L(0); G_MMA(0, 0, At, B0); G_BAR; G_SCHED;
;       G_LDB(B1, 0, 1); G_STAGE(G_SB(0, 0), b2h0, voffB);
;       G_BAR; G_WAIT_L(0); G_MMA(0, 1, At, B1); G_BAR;
;       G_LDA(At, 0, 1); G_STAGE(G_SA(0, 0), a2h0, voffA);
;       G_BAR; G_WAIT_L(0); G_MMA(1, 0, At, B0); G_BAR; G_SCHED;
;       G_STAGE(G_SB(0, 1), b2h1, voffB);
;       G_WAIT_V(6); G_BAR; G_MMA(1, 1, At, B1); G_BAR;
.LBB0_408:
	s_add_i32 s30, s29, 2
	s_add_u32 s42, s38, 0x100
	s_addc_u32 s43, s39, 0
	s_add_i32 s22, 0, 0x10000
	v_add_u32_e32 v80, s22, v133
	ds_read_b128 v[146:149], v80
	ds_read_b128 v[150:153], v80 offset:1024
	ds_read_b128 v[154:157], v80 offset:2048
	ds_read_b128 v[164:167], v80 offset:3072
	s_cmp_eq_u32 s76, s29
	s_cselect_b32 s69, s5, s43
	s_cselect_b32 s68, s4, s42
	s_cselect_b32 s95, s7, s28
	s_cselect_b32 s94, s6, vcc_hi
	s_cselect_b32 s44, s8, s87
	s_cselect_b32 s45, s9, vcc_lo
	s_add_u32 s96, s68, s18
	s_addc_u32 s97, s69, 0
	v_mov_b32_e32 v80, v130
	s_add_u32 s34, s38, s82
	ds_read_b128 v[168:171], v144
	ds_read_b128 v[172:175], v144 offset:1024
	ds_read_b128 v[176:179], v144 offset:2048
	ds_read_b128 v[184:187], v144 offset:3072
	ds_read_b128 v[190:193], v144 offset:4096
	ds_read_b128 v[194:197], v144 offset:5120
	ds_read_b128 v[198:201], v144 offset:6144
	ds_read_b128 v[202:205], v144 offset:7168
	s_addc_u32 s35, s39, s83
	s_add_i32 m0, s46, 0xc000
	s_nop 0
	global_load_lds_dwordx4 v80, s[34:35]
	v_mov_b32_e32 v80, v134
	s_add_i32 m0, s46, 0xe000
	s_nop 0
	global_load_lds_dwordx4 v80, s[34:35]
	s_waitcnt lgkmcnt(8)
	s_barrier
	s_waitcnt lgkmcnt(0)
	s_setprio 1
	s_waitcnt lgkmcnt(0)
	v_mfma_f32_16x16x32_bf16 v[126:129], v[146:149], v[168:171], v[126:129]
	v_mfma_f32_16x16x32_bf16 v[122:125], v[154:157], v[168:171], v[122:125]
	v_mfma_f32_16x16x32_bf16 v[118:121], v[146:149], v[176:179], v[118:121]
	v_mfma_f32_16x16x32_bf16 v[114:117], v[154:157], v[176:179], v[114:117]
	v_mfma_f32_16x16x32_bf16 v[102:105], v[146:149], v[190:193], v[102:105]
	v_mfma_f32_16x16x32_bf16 v[98:101], v[154:157], v[190:193], v[98:101]
	v_mfma_f32_16x16x32_bf16 v[86:89], v[146:149], v[198:201], v[86:89]
	v_mfma_f32_16x16x32_bf16 v[82:85], v[154:157], v[198:201], v[82:85]
	v_mfma_f32_16x16x32_bf16 v[126:129], v[150:153], v[172:175], v[126:129]
	v_mfma_f32_16x16x32_bf16 v[122:125], v[164:167], v[172:175], v[122:125]
	v_mfma_f32_16x16x32_bf16 v[118:121], v[150:153], v[184:187], v[118:121]
	v_mfma_f32_16x16x32_bf16 v[114:117], v[164:167], v[184:187], v[114:117]
	v_mfma_f32_16x16x32_bf16 v[102:105], v[150:153], v[194:197], v[102:105]
	v_mfma_f32_16x16x32_bf16 v[98:101], v[164:167], v[194:197], v[98:101]
	v_mfma_f32_16x16x32_bf16 v[86:89], v[150:153], v[202:205], v[86:89]
	v_mfma_f32_16x16x32_bf16 v[82:85], v[164:167], v[202:205], v[82:85]
	s_setprio 0
	s_barrier
	s_add_i32 s31, 0, 0x14000
	v_add_u32_e32 v80, s31, v133
	ds_read_b128 v[206:209], v80
	ds_read_b128 v[210:213], v80 offset:1024
	ds_read_b128 v[214:217], v80 offset:2048
	ds_read_b128 v[218:221], v80 offset:3072
	v_mov_b32_e32 v80, v132
	s_add_i32 s22, s22, s41
	s_mov_b32 m0, s22
	s_nop 0
	global_load_lds_dwordx4 v80, s[94:95]
	v_mov_b32_e32 v80, v136
	s_add_i32 m0, s22, 0x2000
	s_nop 0
	global_load_lds_dwordx4 v80, s[94:95]
	s_barrier
	s_waitcnt lgkmcnt(0)
	s_setprio 1
	s_waitcnt lgkmcnt(0)
	v_mfma_f32_16x16x32_bf16 v[110:113], v[206:209], v[168:171], v[110:113]
	v_mfma_f32_16x16x32_bf16 v[106:109], v[214:217], v[168:171], v[106:109]
	v_mfma_f32_16x16x32_bf16 v[94:97], v[206:209], v[176:179], v[94:97]
	v_mfma_f32_16x16x32_bf16 v[90:93], v[214:217], v[176:179], v[90:93]
	v_mfma_f32_16x16x32_bf16 v[76:79], v[206:209], v[190:193], v[76:79]
	v_mfma_f32_16x16x32_bf16 v[72:75], v[214:217], v[190:193], v[72:75]
	v_mfma_f32_16x16x32_bf16 v[68:71], v[206:209], v[198:201], v[68:71]
	v_mfma_f32_16x16x32_bf16 v[64:67], v[214:217], v[198:201], v[64:67]
	v_mfma_f32_16x16x32_bf16 v[110:113], v[210:213], v[172:175], v[110:113]
	v_mfma_f32_16x16x32_bf16 v[106:109], v[218:221], v[172:175], v[106:109]
	v_mfma_f32_16x16x32_bf16 v[94:97], v[210:213], v[184:187], v[94:97]
	v_mfma_f32_16x16x32_bf16 v[90:93], v[218:221], v[184:187], v[90:93]
	v_mfma_f32_16x16x32_bf16 v[76:79], v[210:213], v[194:197], v[76:79]
	v_mfma_f32_16x16x32_bf16 v[72:75], v[218:221], v[194:197], v[72:75]
	v_mfma_f32_16x16x32_bf16 v[68:71], v[210:213], v[202:205], v[68:71]
	v_mfma_f32_16x16x32_bf16 v[64:67], v[218:221], v[202:205], v[64:67]
	s_setprio 0
	v_mov_b32_e32 v80, v130
	s_mov_b32 m0, s46
	s_barrier
	ds_read_b128 v[168:171], v144 offset:16384
	ds_read_b128 v[172:175], v144 offset:17408
	ds_read_b128 v[176:179], v144 offset:18432
	ds_read_b128 v[184:187], v144 offset:19456
	ds_read_b128 v[190:193], v144 offset:20480
	ds_read_b128 v[194:197], v144 offset:21504
	ds_read_b128 v[198:201], v144 offset:22528
	ds_read_b128 v[202:205], v144 offset:23552
	s_nop 0
	global_load_lds_dwordx4 v80, s[68:69]
	v_mov_b32_e32 v80, v134
	s_mov_b32 m0, s47
	s_nop 0
	global_load_lds_dwordx4 v80, s[68:69]
	s_barrier
	s_waitcnt lgkmcnt(0)
	s_setprio 1
	s_waitcnt lgkmcnt(0)
	v_mfma_f32_16x16x32_bf16 v[60:63], v[146:149], v[168:171], v[60:63]
	v_mfma_f32_16x16x32_bf16 v[56:59], v[154:157], v[168:171], v[56:59]
	v_mfma_f32_16x16x32_bf16 v[52:55], v[146:149], v[176:179], v[52:55]
	v_mfma_f32_16x16x32_bf16 v[48:51], v[154:157], v[176:179], v[48:51]
	v_mfma_f32_16x16x32_bf16 v[36:39], v[146:149], v[190:193], v[36:39]
	v_mfma_f32_16x16x32_bf16 v[32:35], v[154:157], v[190:193], v[32:35]
	v_mfma_f32_16x16x32_bf16 v[20:23], v[146:149], v[198:201], v[20:23]
	v_mfma_f32_16x16x32_bf16 v[16:19], v[154:157], v[198:201], v[16:19]
	v_mfma_f32_16x16x32_bf16 v[60:63], v[150:153], v[172:175], v[60:63]
	v_mfma_f32_16x16x32_bf16 v[56:59], v[164:167], v[172:175], v[56:59]
	v_mfma_f32_16x16x32_bf16 v[52:55], v[150:153], v[184:187], v[52:55]
	v_mfma_f32_16x16x32_bf16 v[48:51], v[164:167], v[184:187], v[48:51]
	v_mfma_f32_16x16x32_bf16 v[36:39], v[150:153], v[194:197], v[36:39]
	v_mfma_f32_16x16x32_bf16 v[32:35], v[164:167], v[194:197], v[32:35]
	v_mfma_f32_16x16x32_bf16 v[20:23], v[150:153], v[202:205], v[20:23]
	v_mfma_f32_16x16x32_bf16 v[16:19], v[164:167], v[202:205], v[16:19]
	s_setprio 0
	s_barrier
; #define G_STAGE(bufoff, gbase, voff) do { _Pragma("unroll") for (int _i = 0; _i < 2; ++_i) { unsigned _vo = (voff)[_i]; asm volatile("" : "+v"(_vo));   \
;     __builtin_amdgcn_global_load_lds((const unsigned*)((const char*)(gbase) + _vo), (LAS unsigned*)(lds + (bufoff) + ldsw + _i * 8192), 16, 0, 0); } } while (0)
; #define G_LDA(dst, b, h) do { _Pragma("unroll") for (int m = 0; m < 4; ++m) _Pragma("unroll") for (int k = 0; k < 2; ++k) dst[m][k] = *(const LAS bf16x8*)(lds + G_SA(b, h) + aoff + m * 2048 + k * 1024); } while (0)
; #define G_LDB(dst, b, h) do { _Pragma("unroll") for (int n = 0; n < 2; ++n) _Pragma("unroll") for (int k = 0; k < 2; ++k) dst[n][k] = *(const LAS bf16x8*)(lds + G_SB(b, h) + boff + n * 2048 + k * 1024); } while (0)
; #define G_MMA(ai, bj, At, Bt) do { __builtin_amdgcn_s_setprio(1); _Pragma("unroll") for (int m = 0; m < 4; ++m) _Pragma("unroll") for (int n = 0; n < 2; ++n) _Pragma("unroll") for (int k = 0; k < 2; ++k) \
;     acc[ai][bj][m][n] = __builtin_amdgcn_mfma_f32_16x16x32_bf16(Bt[n][k], At[m][k], acc[ai][bj][m][n], 0, 0, 0); __builtin_amdgcn_s_setprio(0); } while (0)
; #define G_WAIT_V(n) asm volatile("s_waitcnt vmcnt(" #n ")" ::: "memory")
; #define G_WAIT_L(n) asm volatile("s_waitcnt lgkmcnt(" #n ")" ::: "memory")
; #define G_BAR __builtin_amdgcn_s_barrier()
; #define G_SCHED __builtin_amdgcn_sched_barrier(0)
; template <class Epi>
; __device__ __forceinline__ void gemm_phase(LAS unsigned char* lds, const int K, const unsigned lda_b, const unsigned ldb_b, const Map& M, const Epi& E) {
;     ...
;       G_WAIT_V(6); G_BAR; G_MMA(1, 1, At, B1); G_BAR;
;       G_LDB(B0, 1, 0); G_SCHED; G_LDA(At, 1, 0); G_STAGE(G_SA(0, 1), a2h1, voffA);
;       G_WAIT_L(8); G_BAR; G_WAIT_L(0); G_MMA(0, 0, At, B0); G_BAR; G_SCHED;
;       G_LDB(B1, 1, 1); G_STAGE(G_SB(1, 0), b2h0 + kstep, voffB);
;       G_BAR; G_WAIT_L(0); G_MMA(0, 1, At, B1); G_BAR;
;       G_LDA(At, 1, 1); G_STAGE(G_SA(1, 0), a2h0 + kstep, voffA);
;       G_BAR; G_WAIT_L(0); G_MMA(1, 0, At, B0); G_BAR; G_SCHED;
	v_mov_b32_e32 v80, v132
	s_add_i32 s22, s31, s41
	s_mov_b32 m0, s22
	s_nop 0
	global_load_lds_dwordx4 v80, s[44:45]
	v_mov_b32_e32 v80, v136
	s_add_i32 m0, s22, 0x2000
	s_nop 0
	global_load_lds_dwordx4 v80, s[44:45]
	s_waitcnt vmcnt(6)
	s_barrier
	s_setprio 1
	v_mfma_f32_16x16x32_bf16 v[44:47], v[206:209], v[168:171], v[44:47]
	v_mfma_f32_16x16x32_bf16 v[40:43], v[214:217], v[168:171], v[40:43]
	v_mfma_f32_16x16x32_bf16 v[28:31], v[206:209], v[176:179], v[28:31]
	v_mfma_f32_16x16x32_bf16 v[24:27], v[214:217], v[176:179], v[24:27]
	v_mfma_f32_16x16x32_bf16 v[12:15], v[206:209], v[190:193], v[12:15]
	v_mfma_f32_16x16x32_bf16 v[8:11], v[214:217], v[190:193], v[8:11]
	v_mfma_f32_16x16x32_bf16 v[4:7], v[206:209], v[198:201], v[4:7]
	v_mfma_f32_16x16x32_bf16 v[0:3], v[214:217], v[198:201], v[0:3]
	v_mfma_f32_16x16x32_bf16 v[44:47], v[210:213], v[172:175], v[44:47]
	v_mfma_f32_16x16x32_bf16 v[40:43], v[218:221], v[172:175], v[40:43]
	v_mfma_f32_16x16x32_bf16 v[28:31], v[210:213], v[184:187], v[28:31]
	v_mfma_f32_16x16x32_bf16 v[24:27], v[218:221], v[184:187], v[24:27]
	v_mfma_f32_16x16x32_bf16 v[12:15], v[210:213], v[194:197], v[12:15]
	v_mfma_f32_16x16x32_bf16 v[8:11], v[218:221], v[194:197], v[8:11]
	v_mfma_f32_16x16x32_bf16 v[4:7], v[210:213], v[202:205], v[4:7]
	v_mfma_f32_16x16x32_bf16 v[0:3], v[218:221], v[202:205], v[0:3]
	s_setprio 0
	s_add_i32 s22, 0, 0x18000
	v_add_u32_e32 v80, s22, v133
	s_barrier
	ds_read_b128 v[146:149], v80
	ds_read_b128 v[150:153], v80 offset:1024
	ds_read_b128 v[154:157], v80 offset:2048
	ds_read_b128 v[164:167], v80 offset:3072
	v_mov_b32_e32 v80, v130
	s_mov_b32 m0, s48
	ds_read_b128 v[168:171], v144 offset:32768
	ds_read_b128 v[172:175], v144 offset:33792
	ds_read_b128 v[176:179], v144 offset:34816
	ds_read_b128 v[184:187], v144 offset:35840
	ds_read_b128 v[190:193], v144 offset:36864
	ds_read_b128 v[194:197], v144 offset:37888
	ds_read_b128 v[198:201], v144 offset:38912
	ds_read_b128 v[202:205], v144 offset:39936
	s_nop 0
	global_load_lds_dwordx4 v80, s[96:97]
	v_mov_b32_e32 v80, v134
	s_mov_b32 m0, s49
	s_nop 0
	global_load_lds_dwordx4 v80, s[96:97]
	s_waitcnt lgkmcnt(8)
	s_barrier
	s_waitcnt lgkmcnt(0)
	s_setprio 1
	s_waitcnt lgkmcnt(0)
	v_mfma_f32_16x16x32_bf16 v[126:129], v[146:149], v[168:171], v[126:129]
	v_mfma_f32_16x16x32_bf16 v[122:125], v[154:157], v[168:171], v[122:125]
	v_mfma_f32_16x16x32_bf16 v[118:121], v[146:149], v[176:179], v[118:121]
	v_mfma_f32_16x16x32_bf16 v[114:117], v[154:157], v[176:179], v[114:117]
	v_mfma_f32_16x16x32_bf16 v[102:105], v[146:149], v[190:193], v[102:105]
	v_mfma_f32_16x16x32_bf16 v[98:101], v[154:157], v[190:193], v[98:101]
	v_mfma_f32_16x16x32_bf16 v[86:89], v[146:149], v[198:201], v[86:89]
	v_mfma_f32_16x16x32_bf16 v[82:85], v[154:157], v[198:201], v[82:85]
	v_mfma_f32_16x16x32_bf16 v[126:129], v[150:153], v[172:175], v[126:129]
	v_mfma_f32_16x16x32_bf16 v[122:125], v[164:167], v[172:175], v[122:125]
	v_mfma_f32_16x16x32_bf16 v[118:121], v[150:153], v[184:187], v[118:121]
	v_mfma_f32_16x16x32_bf16 v[114:117], v[164:167], v[184:187], v[114:117]
	v_mfma_f32_16x16x32_bf16 v[102:105], v[150:153], v[194:197], v[102:105]
	v_mfma_f32_16x16x32_bf16 v[98:101], v[164:167], v[194:197], v[98:101]
	v_mfma_f32_16x16x32_bf16 v[86:89], v[150:153], v[202:205], v[86:89]
	v_mfma_f32_16x16x32_bf16 v[82:85], v[164:167], v[202:205], v[82:85]
	s_setprio 0
	s_barrier
	s_add_i32 s31, 0, 0x1c000
	v_add_u32_e32 v80, s31, v133
	ds_read_b128 v[206:209], v80
	ds_read_b128 v[210:213], v80 offset:1024
	ds_read_b128 v[214:217], v80 offset:2048
	ds_read_b128 v[218:221], v80 offset:3072
	v_mov_b32_e32 v80, v132
	s_add_i32 s22, s22, s41
	s_add_i32 m0, s22, 0xffffff80
	v_mov_b32_e32 v80, v136
	global_load_lds_dwordx4 v132, s[94:95] offset:128
	s_add_i32 m0, s22, 0x1f80
	s_nop 0
	global_load_lds_dwordx4 v136, s[94:95] offset:128
	s_barrier
	s_waitcnt lgkmcnt(0)
	s_setprio 1
	s_waitcnt lgkmcnt(0)
	v_mfma_f32_16x16x32_bf16 v[110:113], v[206:209], v[168:171], v[110:113]
	v_mfma_f32_16x16x32_bf16 v[106:109], v[214:217], v[168:171], v[106:109]
	v_mfma_f32_16x16x32_bf16 v[94:97], v[206:209], v[176:179], v[94:97]
	v_mfma_f32_16x16x32_bf16 v[90:93], v[214:217], v[176:179], v[90:93]
	v_mfma_f32_16x16x32_bf16 v[76:79], v[206:209], v[190:193], v[76:79]
	v_mfma_f32_16x16x32_bf16 v[72:75], v[214:217], v[190:193], v[72:75]
	v_mfma_f32_16x16x32_bf16 v[68:71], v[206:209], v[198:201], v[68:71]
	v_mfma_f32_16x16x32_bf16 v[64:67], v[214:217], v[198:201], v[64:67]
	v_mfma_f32_16x16x32_bf16 v[110:113], v[210:213], v[172:175], v[110:113]
	v_mfma_f32_16x16x32_bf16 v[106:109], v[218:221], v[172:175], v[106:109]
	v_mfma_f32_16x16x32_bf16 v[94:97], v[210:213], v[184:187], v[94:97]
	v_mfma_f32_16x16x32_bf16 v[90:93], v[218:221], v[184:187], v[90:93]
	v_mfma_f32_16x16x32_bf16 v[76:79], v[210:213], v[194:197], v[76:79]
	v_mfma_f32_16x16x32_bf16 v[72:75], v[218:221], v[194:197], v[72:75]
	v_mfma_f32_16x16x32_bf16 v[68:71], v[210:213], v[202:205], v[68:71]
	v_mfma_f32_16x16x32_bf16 v[64:67], v[218:221], v[202:205], v[64:67]
	s_setprio 0
	v_mov_b32_e32 v80, v130
	s_barrier
	ds_read_b128 v[168:171], v144 offset:49152
	ds_read_b128 v[172:175], v144 offset:50176
	ds_read_b128 v[176:179], v144 offset:51200
	ds_read_b128 v[184:187], v144 offset:52224
	ds_read_b128 v[190:193], v144 offset:53248
	ds_read_b128 v[194:197], v144 offset:54272
	ds_read_b128 v[198:201], v144 offset:55296
	ds_read_b128 v[202:205], v144 offset:56320
	s_add_i32 m0, s66, 0xffffff80
	v_mov_b32_e32 v80, v134
	global_load_lds_dwordx4 v130, s[68:69] offset:128
	s_add_i32 m0, s75, 0xffffff80
	s_nop 0
	global_load_lds_dwordx4 v134, s[68:69] offset:128
	s_barrier
; #define G_STAGE(bufoff, gbase, voff) do { _Pragma("unroll") for (int _i = 0; _i < 2; ++_i) { unsigned _vo = (voff)[_i]; asm volatile("" : "+v"(_vo));   \
;     __builtin_amdgcn_global_load_lds((const unsigned*)((const char*)(gbase) + _vo), (LAS unsigned*)(lds + (bufoff) + ldsw + _i * 8192), 16, 0, 0); } } while (0)
; #define G_LDA(dst, b, h) do { _Pragma("unroll") for (int m = 0; m < 4; ++m) _Pragma("unroll") for (int k = 0; k < 2; ++k) dst[m][k] = *(const LAS bf16x8*)(lds + G_SA(b, h) + aoff + m * 2048 + k * 1024); } while (0)
; #define G_LDB(dst, b, h) do { _Pragma("unroll") for (int n = 0; n < 2; ++n) _Pragma("unroll") for (int k = 0; k < 2; ++k) dst[n][k] = *(const LAS bf16x8*)(lds + G_SB(b, h) + boff + n * 2048 + k * 1024); } while (0)
; #define G_MMA(ai, bj, At, Bt) do { __builtin_amdgcn_s_setprio(1); _Pragma("unroll") for (int m = 0; m < 4; ++m) _Pragma("unroll") for (int n = 0; n < 2; ++n) _Pragma("unroll") for (int k = 0; k < 2; ++k) \
;     acc[ai][bj][m][n] = __builtin_amdgcn_mfma_f32_16x16x32_bf16(Bt[n][k], At[m][k], acc[ai][bj][m][n], 0, 0, 0); __builtin_amdgcn_s_setprio(0); } while (0)
; #define G_WAIT_V(n) asm volatile("s_waitcnt vmcnt(" #n ")" ::: "memory")
; #define G_WAIT_L(n) asm volatile("s_waitcnt lgkmcnt(" #n ")" ::: "memory")
; #define G_BAR __builtin_amdgcn_s_barrier()
; #define G_SCHED __builtin_amdgcn_sched_barrier(0)
; template <class Epi>
; __device__ __forceinline__ void gemm_phase(LAS unsigned char* lds, const int K, const unsigned lda_b, const unsigned ldb_b, const Map& M, const Epi& E) {
;     ...
;       G_WAIT_V(6); G_BAR; G_MMA(1, 1, At, B1); G_BAR;
;       G_LDB(B0, 1, 0); G_SCHED; G_LDA(At, 1, 0); G_STAGE(G_SA(0, 1), a2h1, voffA);
;       G_WAIT_L(8); G_BAR; G_WAIT_L(0); G_MMA(0, 0, At, B0); G_BAR; G_SCHED;
;       G_LDB(B1, 1, 1); G_STAGE(G_SB(1, 0), b2h0 + kstep, voffB);
;       G_BAR; G_WAIT_L(0); G_MMA(0, 1, At, B1); G_BAR;
;       G_LDA(At, 1, 1); G_STAGE(G_SA(1, 0), a2h0 + kstep, voffA);
;       G_BAR; G_WAIT_L(0); G_MMA(1, 0, At, B0); G_BAR; G_SCHED;
;       G_STAGE(G_SB(1, 1), b2h1 + kstep, voffB);
;       G_WAIT_V(6); G_BAR; G_MMA(1, 1, At, B1); G_BAR;
;     }
	s_waitcnt lgkmcnt(0)
	s_setprio 1
	s_waitcnt lgkmcnt(0)
	v_mfma_f32_16x16x32_bf16 v[60:63], v[146:149], v[168:171], v[60:63]
	v_mfma_f32_16x16x32_bf16 v[56:59], v[154:157], v[168:171], v[56:59]
	v_mfma_f32_16x16x32_bf16 v[52:55], v[146:149], v[176:179], v[52:55]
	v_mfma_f32_16x16x32_bf16 v[48:51], v[154:157], v[176:179], v[48:51]
	v_mfma_f32_16x16x32_bf16 v[36:39], v[146:149], v[190:193], v[36:39]
	v_mfma_f32_16x16x32_bf16 v[32:35], v[154:157], v[190:193], v[32:35]
	v_mfma_f32_16x16x32_bf16 v[20:23], v[146:149], v[198:201], v[20:23]
	v_mfma_f32_16x16x32_bf16 v[16:19], v[154:157], v[198:201], v[16:19]
	v_mfma_f32_16x16x32_bf16 v[60:63], v[150:153], v[172:175], v[60:63]
	v_mfma_f32_16x16x32_bf16 v[56:59], v[164:167], v[172:175], v[56:59]
	v_mfma_f32_16x16x32_bf16 v[52:55], v[150:153], v[184:187], v[52:55]
	v_mfma_f32_16x16x32_bf16 v[48:51], v[164:167], v[184:187], v[48:51]
	v_mfma_f32_16x16x32_bf16 v[36:39], v[150:153], v[194:197], v[36:39]
	v_mfma_f32_16x16x32_bf16 v[32:35], v[164:167], v[194:197], v[32:35]
	v_mfma_f32_16x16x32_bf16 v[20:23], v[150:153], v[202:205], v[20:23]
	v_mfma_f32_16x16x32_bf16 v[16:19], v[164:167], v[202:205], v[16:19]
	s_setprio 0
	s_barrier
	v_mov_b32_e32 v80, v132
	s_add_i32 s22, s31, s41
	s_add_i32 m0, s22, 0xffffff80
	v_mov_b32_e32 v80, v136
	global_load_lds_dwordx4 v132, s[44:45] offset:128
	s_add_i32 m0, s22, 0x1f80
	s_nop 0
	global_load_lds_dwordx4 v136, s[44:45] offset:128
	s_waitcnt vmcnt(6)
	s_barrier
	s_setprio 1
	v_mfma_f32_16x16x32_bf16 v[44:47], v[206:209], v[168:171], v[44:47]
	v_mfma_f32_16x16x32_bf16 v[40:43], v[214:217], v[168:171], v[40:43]
	v_mfma_f32_16x16x32_bf16 v[28:31], v[206:209], v[176:179], v[28:31]
	v_mfma_f32_16x16x32_bf16 v[24:27], v[214:217], v[176:179], v[24:27]
	v_mfma_f32_16x16x32_bf16 v[12:15], v[206:209], v[190:193], v[12:15]
	v_mfma_f32_16x16x32_bf16 v[8:11], v[214:217], v[190:193], v[8:11]
	v_mfma_f32_16x16x32_bf16 v[4:7], v[206:209], v[198:201], v[4:7]
	v_mfma_f32_16x16x32_bf16 v[0:3], v[214:217], v[198:201], v[0:3]
	v_mfma_f32_16x16x32_bf16 v[44:47], v[210:213], v[172:175], v[44:47]
	v_mfma_f32_16x16x32_bf16 v[40:43], v[218:221], v[172:175], v[40:43]
	v_mfma_f32_16x16x32_bf16 v[28:31], v[210:213], v[184:187], v[28:31]
	v_mfma_f32_16x16x32_bf16 v[24:27], v[218:221], v[184:187], v[24:27]
	v_mfma_f32_16x16x32_bf16 v[12:15], v[210:213], v[194:197], v[12:15]
	v_mfma_f32_16x16x32_bf16 v[8:11], v[218:221], v[194:197], v[8:11]
	v_mfma_f32_16x16x32_bf16 v[4:7], v[210:213], v[202:205], v[4:7]
	v_mfma_f32_16x16x32_bf16 v[0:3], v[218:221], v[202:205], v[0:3]
	s_setprio 0
	s_add_u32 s87, s87, 0x100
	s_addc_u32 vcc_lo, vcc_lo, 0
	s_add_u32 vcc_hi, vcc_hi, 0x100
	s_addc_u32 s28, s28, 0
	s_cmp_ge_u32 s29, s76
	s_mov_b64 s[38:39], s[42:43]
	s_mov_b32 s29, s30
	s_barrier
	s_cbranch_scc0 .LBB0_408
; #define G_WAIT_V(n) asm volatile("s_waitcnt vmcnt(" #n ")" ::: "memory")
; #define G_BAR __builtin_amdgcn_s_barrier()
;   __device__ __forceinline__ void operator()(const f32x4 (&acc)[2][2][4][2], const Unit& u, const EpiCtx& x_, int wr, int wc, int fr, int fq) const {
; #pragma unroll
;     for (int ai = 0; ai < 2; ++ai)
; #pragma unroll
;       for (int m = 0; m < 4; ++m) {
;         const int row = (u.r0 + (ai ? x_.rdelta : 0)) + wr * 64 + m * 16 + fr;
;         float* rowp = (float*)u.C + (size_t)row * x_.ldc;
; #pragma unroll
;         for (int bj = 0; bj < 2; ++bj) {
;           const int cb = (u.c0 + bj * 128) + wc * 32 + 4 * fq;
;           *(f32x4*)(rowp + cb) = acc[ai][bj][m][0]; *(f32x4*)(rowp + cb + 16) = acc[ai][bj][m][1];
;         }
;       }
; template <class Epi>
; __device__ __forceinline__ void gemm_phase(LAS unsigned char* lds, const int K, const unsigned lda_b, const unsigned ldb_b, const Map& M, const Epi& E) {
;     ...
;     E(acc, cur, X, wr, wc, fr, fq);
;     if (!has_next) break;
; #pragma unroll
;     for (int a = 0; a < 2; ++a)
; #pragma unroll
;       for (int b = 0; b < 2; ++b)
; #pragma unroll
;         for (int m = 0; m < 4; ++m)
; #pragma unroll
;           for (int n = 0; n < 2; ++n) acc[a][b][m][n] = (f32x4){0.f, 0.f, 0.f, 0.f};
;     cur = nxt; ++ui;
;   }
;   G_WAIT_V(0);
;   if (wr == 0) G_BAR;
;   G_BAR;
	v_readfirstlane_b32 s22, v138
	v_add_u32_e32 v138, s67, v131
	v_readfirstlane_b32 s28, v139
	v_ashrrev_i32_e32 v139, 31, v138
	v_add_u32_e32 v148, s79, v135
	v_lshlrev_b64 v[146:147], 14, v[138:139]
	v_ashrrev_i32_e32 v149, 31, v148
	v_lshl_add_u64 v[146:147], s[2:3], 0, v[146:147]
	v_lshlrev_b64 v[148:149], 2, v[148:149]
	v_lshl_add_u64 v[150:151], v[146:147], 0, v[148:149]
	global_store_dwordx4 v[150:151], v[126:129], off
	global_store_dwordx4 v[150:151], v[122:125], off offset:64
	s_cmp_eq_u32 s86, s81
	s_mov_b64 s[38:39], s[4:5]
	v_add_u32_e32 v122, s79, v137
	v_ashrrev_i32_e32 v123, 31, v122
	v_lshlrev_b64 v[122:123], 2, v[122:123]
	v_lshl_add_u64 v[124:125], v[146:147], 0, v[122:123]
	global_store_dwordx4 v[124:125], v[110:113], off
	global_store_dwordx4 v[124:125], v[106:109], off offset:64
	s_mov_b64 s[42:43], s[6:7]
	s_mov_b64 s[44:45], s[8:9]
	v_add_u32_e32 v106, s67, v141
	v_ashrrev_i32_e32 v107, 31, v106
	v_lshlrev_b64 v[106:107], 14, v[106:107]
	v_lshl_add_u64 v[106:107], s[2:3], 0, v[106:107]
	v_lshl_add_u64 v[108:109], v[106:107], 0, v[148:149]
	v_lshl_add_u64 v[106:107], v[106:107], 0, v[122:123]
	global_store_dwordx4 v[108:109], v[118:121], off
	global_store_dwordx4 v[108:109], v[114:117], off offset:64
	global_store_dwordx4 v[106:107], v[94:97], off
	global_store_dwordx4 v[106:107], v[90:93], off offset:64
	s_mov_b32 s79, s28
	s_nop 0
	v_add_u32_e32 v90, s67, v142
	v_ashrrev_i32_e32 v91, 31, v90
	v_lshlrev_b64 v[90:91], 14, v[90:91]
	v_lshl_add_u64 v[90:91], s[2:3], 0, v[90:91]
	v_lshl_add_u64 v[92:93], v[90:91], 0, v[148:149]
	v_lshl_add_u64 v[90:91], v[90:91], 0, v[122:123]
	global_store_dwordx4 v[92:93], v[102:105], off
	global_store_dwordx4 v[92:93], v[98:101], off offset:64
	global_store_dwordx4 v[90:91], v[76:79], off
	global_store_dwordx4 v[90:91], v[72:75], off offset:64
	s_nop 1
	v_add_u32_e32 v72, s67, v143
	v_ashrrev_i32_e32 v73, 31, v72
	v_lshlrev_b64 v[72:73], 14, v[72:73]
	v_lshl_add_u64 v[72:73], s[2:3], 0, v[72:73]
	v_lshl_add_u64 v[74:75], v[72:73], 0, v[148:149]
	v_lshl_add_u64 v[72:73], v[72:73], 0, v[122:123]
	global_store_dwordx4 v[74:75], v[86:89], off
	global_store_dwordx4 v[74:75], v[82:85], off offset:64
	global_store_dwordx4 v[72:73], v[68:71], off
	global_store_dwordx4 v[72:73], v[64:67], off offset:64
	s_mov_b32 s67, s22
	s_nop 0
	v_add_u32_e32 v64, 0x80, v138
	v_ashrrev_i32_e32 v65, 31, v64
	v_lshlrev_b64 v[64:65], 14, v[64:65]
	v_lshl_add_u64 v[64:65], s[2:3], 0, v[64:65]
	v_lshl_add_u64 v[66:67], v[64:65], 0, v[148:149]
	global_store_dwordx4 v[66:67], v[60:63], off
	global_store_dwordx4 v[66:67], v[56:59], off offset:64
	s_nop 1
	v_lshl_add_u64 v[56:57], v[64:65], 0, v[122:123]
	global_store_dwordx4 v[56:57], v[44:47], off
	global_store_dwordx4 v[56:57], v[40:43], off offset:64
	s_nop 1
	v_add_u32_e32 v40, 0x90, v138
	v_ashrrev_i32_e32 v41, 31, v40
	v_lshlrev_b64 v[40:41], 14, v[40:41]
	v_lshl_add_u64 v[40:41], s[2:3], 0, v[40:41]
	v_lshl_add_u64 v[42:43], v[40:41], 0, v[148:149]
	v_lshl_add_u64 v[40:41], v[40:41], 0, v[122:123]
	global_store_dwordx4 v[42:43], v[52:55], off
	global_store_dwordx4 v[42:43], v[48:51], off offset:64
	global_store_dwordx4 v[40:41], v[28:31], off
	global_store_dwordx4 v[40:41], v[24:27], off offset:64
	s_nop 1
	v_add_u32_e32 v24, 0xa0, v138
	v_ashrrev_i32_e32 v25, 31, v24
	v_lshlrev_b64 v[24:25], 14, v[24:25]
	v_lshl_add_u64 v[24:25], s[2:3], 0, v[24:25]
	v_lshl_add_u64 v[26:27], v[24:25], 0, v[148:149]
	v_lshl_add_u64 v[24:25], v[24:25], 0, v[122:123]
	global_store_dwordx4 v[26:27], v[36:39], off
	global_store_dwordx4 v[26:27], v[32:35], off offset:64
	global_store_dwordx4 v[24:25], v[12:15], off
	global_store_dwordx4 v[24:25], v[8:11], off offset:64
	s_nop 1
	v_add_u32_e32 v8, 0xb0, v138
	v_ashrrev_i32_e32 v9, 31, v8
	v_lshlrev_b64 v[8:9], 14, v[8:9]
	v_lshl_add_u64 v[8:9], s[2:3], 0, v[8:9]
	v_lshl_add_u64 v[10:11], v[8:9], 0, v[148:149]
	v_lshl_add_u64 v[8:9], v[8:9], 0, v[122:123]
	s_mov_b64 s[2:3], s[36:37]
	global_store_dwordx4 v[10:11], v[20:23], off
	global_store_dwordx4 v[10:11], v[16:19], off offset:64
	global_store_dwordx4 v[8:9], v[4:7], off
	global_store_dwordx4 v[8:9], v[0:3], off offset:64
	s_cbranch_scc0 .LBB0_407
	s_waitcnt vmcnt(0)
	s_cmpk_gt_u32 s19, 0xff
	s_mov_b32 s86, 0x7f800000
	s_brev_b32 s82, 1
	s_cbranch_scc1 .LBB0_412
	s_barrier

; #define G_STAGE(bufoff, gbase, voff) do { _Pragma("unroll") for (int _i = 0; _i < 2; ++_i) { unsigned _vo = (voff)[_i]; asm volatile("" : "+v"(_vo));   \
;     __builtin_amdgcn_global_load_lds((const unsigned*)((const char*)(gbase) + _vo), (LAS unsigned*)(lds + (bufoff) + ldsw + _i * 8192), 16, 0, 0); } } while (0)
; #define G_LDA(dst, b, h) do { _Pragma("unroll") for (int m = 0; m < 4; ++m) _Pragma("unroll") for (int k = 0; k < 2; ++k) dst[m][k] = *(const LAS bf16x8*)(lds + G_SA(b, h) + aoff + m * 2048 + k * 1024); } while (0)
; #define G_LDB(dst, b, h) do { _Pragma("unroll") for (int n = 0; n < 2; ++n) _Pragma("unroll") for (int k = 0; k < 2; ++k) dst[n][k] = *(const LAS bf16x8*)(lds + G_SB(b, h) + boff + n * 2048 + k * 1024); } while (0)
; #define G_MMA(ai, bj, At, Bt) do { __builtin_amdgcn_s_setprio(1); _Pragma("unroll") for (int m = 0; m < 4; ++m) _Pragma("unroll") for (int n = 0; n < 2; ++n) _Pragma("unroll") for (int k = 0; k < 2; ++k) \
;     acc[ai][bj][m][n] = __builtin_amdgcn_mfma_f32_16x16x32_bf16(Bt[n][k], At[m][k], acc[ai][bj][m][n], 0, 0, 0); __builtin_amdgcn_s_setprio(0); } while (0)
; #define G_WAIT_L(n) asm volatile("s_waitcnt lgkmcnt(" #n ")" ::: "memory")
; #define G_BAR __builtin_amdgcn_s_barrier()
; #define G_SCHED __builtin_amdgcn_sched_barrier(0)
; template <class Epi>
; __device__ __forceinline__ void gemm_phase(LAS unsigned char* lds, const int K, const unsigned lda_b, const unsigned ldb_b, const Map& M, const Epi& E) {
;     ...
;     for (int t = 0; t < nt; t += 2) {
;       const bool last = (t == nt - 2);
;       const char* a1h1 = cur.a0 + a_h + (size_t)(t + 1) * kstep;
;       const char* a2h0 = last ? nxt.a0 : cur.a0 + (size_t)(t + 2) * kstep; const char* a2h1 = a2h0 + a_h;
;       const char* b2h0 = last ? nxt.b0 : cur.b0 + (size_t)(t + 2) * kstep; const char* b2h1 = last ? nxt.b1 : cur.b1 + (size_t)(t + 2) * kstep;
;       G_LDB(B0, 0, 0); G_SCHED; G_LDA(At, 0, 0); G_STAGE(G_SA(1, 1), a1h1, voffA);
;       G_WAIT_L(8); G_BAR; G_WAIT_L(0); G_MMA(0, 0, At, B0); G_BAR; G_SCHED;
;       G_LDB(B1, 0, 1); G_STAGE(G_SB(0, 0), b2h0, voffB);
;       G_BAR; G_WAIT_L(0); G_MMA(0, 1, At, B1); G_BAR;
;       G_LDA(At, 0, 1); G_STAGE(G_SA(0, 0), a2h0, voffA);
;       G_BAR; G_WAIT_L(0); G_MMA(1, 0, At, B0); G_BAR; G_SCHED;
.LBB0_554:
	s_add_u32 s22, s2, 0xfff00080
	s_addc_u32 s35, s3, -1
	s_add_u32 s38, s30, 0xfffc0000
	s_addc_u32 s39, s31, -1
	s_add_i32 s76, 0, 0x10000
	v_add_u32_e32 v80, s76, v139
	ds_read_b128 v[142:145], v80
	ds_read_b128 v[146:149], v80 offset:1024
	ds_read_b128 v[150:153], v80 offset:2048
	ds_read_b128 v[154:157], v80 offset:3072
	s_cmp_eq_u32 s34, 60
	s_cselect_b32 s43, s5, s35
	s_cselect_b32 s42, s4, s22
	s_cselect_b32 s45, s7, s39
	s_cselect_b32 s44, s6, s38
	v_mov_b32_e32 v80, v134
	s_cselect_b32 s39, s29, s31
	s_cselect_b32 s38, s28, s30
	s_add_u32 s68, s42, 0x100000
	ds_read_b128 v[164:167], v141
	ds_read_b128 v[168:171], v141 offset:1024
	ds_read_b128 v[172:175], v141 offset:2048
	ds_read_b128 v[176:179], v141 offset:3072
	ds_read_b128 v[184:187], v141 offset:4096
	ds_read_b128 v[190:193], v141 offset:5120
	ds_read_b128 v[194:197], v141 offset:6144
	ds_read_b128 v[198:201], v141 offset:7168
	s_addc_u32 s69, s43, 0
	s_add_i32 m0, s19, 0xc000
	s_nop 0
	global_load_lds_dwordx4 v80, s[2:3]
	v_mov_b32_e32 v80, v136
	s_add_i32 m0, s19, 0xe000
	s_nop 0
	global_load_lds_dwordx4 v80, s[2:3]
	s_waitcnt lgkmcnt(8)
	s_barrier
	s_waitcnt lgkmcnt(0)
	s_setprio 1
	s_waitcnt lgkmcnt(0)
	v_mfma_f32_16x16x32_bf16 v[126:129], v[142:145], v[164:167], v[126:129]
	v_mfma_f32_16x16x32_bf16 v[122:125], v[150:153], v[164:167], v[122:125]
	v_mfma_f32_16x16x32_bf16 v[110:113], v[142:145], v[172:175], v[110:113]
	v_mfma_f32_16x16x32_bf16 v[106:109], v[150:153], v[172:175], v[106:109]
	v_mfma_f32_16x16x32_bf16 v[94:97], v[142:145], v[184:187], v[94:97]
	v_mfma_f32_16x16x32_bf16 v[90:93], v[150:153], v[184:187], v[90:93]
	v_mfma_f32_16x16x32_bf16 v[76:79], v[142:145], v[194:197], v[76:79]
	v_mfma_f32_16x16x32_bf16 v[72:75], v[150:153], v[194:197], v[72:75]
	v_mfma_f32_16x16x32_bf16 v[126:129], v[146:149], v[168:171], v[126:129]
	v_mfma_f32_16x16x32_bf16 v[122:125], v[154:157], v[168:171], v[122:125]
	v_mfma_f32_16x16x32_bf16 v[110:113], v[146:149], v[176:179], v[110:113]
	v_mfma_f32_16x16x32_bf16 v[106:109], v[154:157], v[176:179], v[106:109]
	v_mfma_f32_16x16x32_bf16 v[94:97], v[146:149], v[190:193], v[94:97]
	v_mfma_f32_16x16x32_bf16 v[90:93], v[154:157], v[190:193], v[90:93]
	v_mfma_f32_16x16x32_bf16 v[76:79], v[146:149], v[198:201], v[76:79]
	v_mfma_f32_16x16x32_bf16 v[72:75], v[154:157], v[198:201], v[72:75]
	s_setprio 0
	s_barrier
	s_add_i32 s22, 0, 0x14000
	v_add_u32_e32 v80, s22, v139
	ds_read_b128 v[202:205], v80
	ds_read_b128 v[206:209], v80 offset:1024
	ds_read_b128 v[210:213], v80 offset:2048
	ds_read_b128 v[214:217], v80 offset:3072
	v_mov_b32_e32 v80, v135
	s_add_i32 s35, s76, s18
	s_mov_b32 m0, s35
	s_nop 0
	global_load_lds_dwordx4 v80, s[44:45]
	v_mov_b32_e32 v80, v137
	s_add_i32 m0, s35, 0x2000
	s_nop 0
	global_load_lds_dwordx4 v80, s[44:45]
	s_barrier
	s_waitcnt lgkmcnt(0)
	s_setprio 1
	s_waitcnt lgkmcnt(0)
	v_mfma_f32_16x16x32_bf16 v[118:121], v[202:205], v[164:167], v[118:121]
	v_mfma_f32_16x16x32_bf16 v[114:117], v[210:213], v[164:167], v[114:117]
	v_mfma_f32_16x16x32_bf16 v[102:105], v[202:205], v[172:175], v[102:105]
	v_mfma_f32_16x16x32_bf16 v[98:101], v[210:213], v[172:175], v[98:101]
	v_mfma_f32_16x16x32_bf16 v[86:89], v[202:205], v[184:187], v[86:89]
	v_mfma_f32_16x16x32_bf16 v[82:85], v[210:213], v[184:187], v[82:85]
	v_mfma_f32_16x16x32_bf16 v[68:71], v[202:205], v[194:197], v[68:71]
	v_mfma_f32_16x16x32_bf16 v[64:67], v[210:213], v[194:197], v[64:67]
	v_mfma_f32_16x16x32_bf16 v[118:121], v[206:209], v[168:171], v[118:121]
	v_mfma_f32_16x16x32_bf16 v[114:117], v[214:217], v[168:171], v[114:117]
	v_mfma_f32_16x16x32_bf16 v[102:105], v[206:209], v[176:179], v[102:105]
	v_mfma_f32_16x16x32_bf16 v[98:101], v[214:217], v[176:179], v[98:101]
	v_mfma_f32_16x16x32_bf16 v[86:89], v[206:209], v[190:193], v[86:89]
	v_mfma_f32_16x16x32_bf16 v[82:85], v[214:217], v[190:193], v[82:85]
	v_mfma_f32_16x16x32_bf16 v[68:71], v[206:209], v[198:201], v[68:71]
	v_mfma_f32_16x16x32_bf16 v[64:67], v[214:217], v[198:201], v[64:67]
	s_setprio 0
	v_mov_b32_e32 v80, v134
	s_mov_b32 m0, s19
	s_barrier
	ds_read_b128 v[164:167], v141 offset:16384
	ds_read_b128 v[168:171], v141 offset:17408
	ds_read_b128 v[172:175], v141 offset:18432
	ds_read_b128 v[176:179], v141 offset:19456
	ds_read_b128 v[184:187], v141 offset:20480
	ds_read_b128 v[190:193], v141 offset:21504
	ds_read_b128 v[194:197], v141 offset:22528
	ds_read_b128 v[198:201], v141 offset:23552
	s_nop 0
	global_load_lds_dwordx4 v80, s[42:43]
	v_mov_b32_e32 v80, v136
	s_mov_b32 m0, s46
	s_nop 0
	global_load_lds_dwordx4 v80, s[42:43]
	s_barrier
	s_waitcnt lgkmcnt(0)
	s_setprio 1
	s_waitcnt lgkmcnt(0)
	v_mfma_f32_16x16x32_bf16 v[60:63], v[142:145], v[164:167], v[60:63]
	v_mfma_f32_16x16x32_bf16 v[56:59], v[150:153], v[164:167], v[56:59]
	v_mfma_f32_16x16x32_bf16 v[44:47], v[142:145], v[172:175], v[44:47]
	v_mfma_f32_16x16x32_bf16 v[40:43], v[150:153], v[172:175], v[40:43]
	v_mfma_f32_16x16x32_bf16 v[28:31], v[142:145], v[184:187], v[28:31]
	v_mfma_f32_16x16x32_bf16 v[24:27], v[150:153], v[184:187], v[24:27]
	v_mfma_f32_16x16x32_bf16 v[12:15], v[142:145], v[194:197], v[12:15]
	v_mfma_f32_16x16x32_bf16 v[8:11], v[150:153], v[194:197], v[8:11]
	v_mfma_f32_16x16x32_bf16 v[60:63], v[146:149], v[168:171], v[60:63]
	v_mfma_f32_16x16x32_bf16 v[56:59], v[154:157], v[168:171], v[56:59]
	v_mfma_f32_16x16x32_bf16 v[44:47], v[146:149], v[176:179], v[44:47]
	v_mfma_f32_16x16x32_bf16 v[40:43], v[154:157], v[176:179], v[40:43]
	v_mfma_f32_16x16x32_bf16 v[28:31], v[146:149], v[190:193], v[28:31]
	v_mfma_f32_16x16x32_bf16 v[24:27], v[154:157], v[190:193], v[24:27]
	v_mfma_f32_16x16x32_bf16 v[12:15], v[146:149], v[198:201], v[12:15]
	v_mfma_f32_16x16x32_bf16 v[8:11], v[154:157], v[198:201], v[8:11]
	s_setprio 0
	s_barrier
; #define G_STAGE(bufoff, gbase, voff) do { _Pragma("unroll") for (int _i = 0; _i < 2; ++_i) { unsigned _vo = (voff)[_i]; asm volatile("" : "+v"(_vo));   \
;     __builtin_amdgcn_global_load_lds((const unsigned*)((const char*)(gbase) + _vo), (LAS unsigned*)(lds + (bufoff) + ldsw + _i * 8192), 16, 0, 0); } } while (0)
; #define G_LDA(dst, b, h) do { _Pragma("unroll") for (int m = 0; m < 4; ++m) _Pragma("unroll") for (int k = 0; k < 2; ++k) dst[m][k] = *(const LAS bf16x8*)(lds + G_SA(b, h) + aoff + m * 2048 + k * 1024); } while (0)
; #define G_LDB(dst, b, h) do { _Pragma("unroll") for (int n = 0; n < 2; ++n) _Pragma("unroll") for (int k = 0; k < 2; ++k) dst[n][k] = *(const LAS bf16x8*)(lds + G_SB(b, h) + boff + n * 2048 + k * 1024); } while (0)
; #define G_MMA(ai, bj, At, Bt) do { __builtin_amdgcn_s_setprio(1); _Pragma("unroll") for (int m = 0; m < 4; ++m) _Pragma("unroll") for (int n = 0; n < 2; ++n) _Pragma("unroll") for (int k = 0; k < 2; ++k) \
;     acc[ai][bj][m][n] = __builtin_amdgcn_mfma_f32_16x16x32_bf16(Bt[n][k], At[m][k], acc[ai][bj][m][n], 0, 0, 0); __builtin_amdgcn_s_setprio(0); } while (0)
; #define G_WAIT_V(n) asm volatile("s_waitcnt vmcnt(" #n ")" ::: "memory")
; #define G_WAIT_L(n) asm volatile("s_waitcnt lgkmcnt(" #n ")" ::: "memory")
; #define G_BAR __builtin_amdgcn_s_barrier()
; #define G_SCHED __builtin_amdgcn_sched_barrier(0)
; template <class Epi>
; __device__ __forceinline__ void gemm_phase(LAS unsigned char* lds, const int K, const unsigned lda_b, const unsigned ldb_b, const Map& M, const Epi& E) {
;     ...
;       G_STAGE(G_SB(0, 1), b2h1, voffB);
;       G_WAIT_V(6); G_BAR; G_MMA(1, 1, At, B1); G_BAR;
;       G_LDB(B0, 1, 0); G_SCHED; G_LDA(At, 1, 0); G_STAGE(G_SA(0, 1), a2h1, voffA);
;       G_WAIT_L(8); G_BAR; G_WAIT_L(0); G_MMA(0, 0, At, B0); G_BAR; G_SCHED;
;       G_LDB(B1, 1, 1); G_STAGE(G_SB(1, 0), b2h0 + kstep, voffB);
;       G_BAR; G_WAIT_L(0); G_MMA(0, 1, At, B1); G_BAR;
;       G_LDA(At, 1, 1); G_STAGE(G_SA(1, 0), a2h0 + kstep, voffA);
	v_mov_b32_e32 v80, v135
	s_add_i32 s22, s22, s18
	s_mov_b32 m0, s22
	s_nop 0
	global_load_lds_dwordx4 v80, s[38:39]
	v_mov_b32_e32 v80, v137
	s_add_i32 m0, s22, 0x2000
	s_nop 0
	global_load_lds_dwordx4 v80, s[38:39]
	s_waitcnt vmcnt(6)
	s_barrier
	s_setprio 1
	v_mfma_f32_16x16x32_bf16 v[52:55], v[202:205], v[164:167], v[52:55]
	v_mfma_f32_16x16x32_bf16 v[48:51], v[210:213], v[164:167], v[48:51]
	v_mfma_f32_16x16x32_bf16 v[36:39], v[202:205], v[172:175], v[36:39]
	v_mfma_f32_16x16x32_bf16 v[32:35], v[210:213], v[172:175], v[32:35]
	v_mfma_f32_16x16x32_bf16 v[20:23], v[202:205], v[184:187], v[20:23]
	v_mfma_f32_16x16x32_bf16 v[16:19], v[210:213], v[184:187], v[16:19]
	v_mfma_f32_16x16x32_bf16 v[4:7], v[202:205], v[194:197], v[4:7]
	v_mfma_f32_16x16x32_bf16 v[0:3], v[210:213], v[194:197], v[0:3]
	v_mfma_f32_16x16x32_bf16 v[52:55], v[206:209], v[168:171], v[52:55]
	v_mfma_f32_16x16x32_bf16 v[48:51], v[214:217], v[168:171], v[48:51]
	v_mfma_f32_16x16x32_bf16 v[36:39], v[206:209], v[176:179], v[36:39]
	v_mfma_f32_16x16x32_bf16 v[32:35], v[214:217], v[176:179], v[32:35]
	v_mfma_f32_16x16x32_bf16 v[20:23], v[206:209], v[190:193], v[20:23]
	v_mfma_f32_16x16x32_bf16 v[16:19], v[214:217], v[190:193], v[16:19]
	v_mfma_f32_16x16x32_bf16 v[4:7], v[206:209], v[198:201], v[4:7]
	v_mfma_f32_16x16x32_bf16 v[0:3], v[214:217], v[198:201], v[0:3]
	s_setprio 0
	s_add_i32 s22, 0, 0x18000
	v_add_u32_e32 v80, s22, v139
	s_barrier
	ds_read_b128 v[142:145], v80
	ds_read_b128 v[146:149], v80 offset:1024
	ds_read_b128 v[150:153], v80 offset:2048
	ds_read_b128 v[154:157], v80 offset:3072
	v_mov_b32_e32 v80, v134
	s_mov_b32 m0, s47
	ds_read_b128 v[164:167], v141 offset:32768
	ds_read_b128 v[168:171], v141 offset:33792
	ds_read_b128 v[172:175], v141 offset:34816
	ds_read_b128 v[176:179], v141 offset:35840
	ds_read_b128 v[184:187], v141 offset:36864
	ds_read_b128 v[190:193], v141 offset:37888
	ds_read_b128 v[194:197], v141 offset:38912
	ds_read_b128 v[198:201], v141 offset:39936
	s_nop 0
	global_load_lds_dwordx4 v80, s[68:69]
	v_mov_b32_e32 v80, v136
	s_mov_b32 m0, s48
	s_nop 0
	global_load_lds_dwordx4 v80, s[68:69]
	s_waitcnt lgkmcnt(8)
	s_barrier
	s_waitcnt lgkmcnt(0)
	s_setprio 1
	s_waitcnt lgkmcnt(0)
	v_mfma_f32_16x16x32_bf16 v[126:129], v[142:145], v[164:167], v[126:129]
	v_mfma_f32_16x16x32_bf16 v[122:125], v[150:153], v[164:167], v[122:125]
	v_mfma_f32_16x16x32_bf16 v[110:113], v[142:145], v[172:175], v[110:113]
	v_mfma_f32_16x16x32_bf16 v[106:109], v[150:153], v[172:175], v[106:109]
	v_mfma_f32_16x16x32_bf16 v[94:97], v[142:145], v[184:187], v[94:97]
	v_mfma_f32_16x16x32_bf16 v[90:93], v[150:153], v[184:187], v[90:93]
	v_mfma_f32_16x16x32_bf16 v[76:79], v[142:145], v[194:197], v[76:79]
	v_mfma_f32_16x16x32_bf16 v[72:75], v[150:153], v[194:197], v[72:75]
	v_mfma_f32_16x16x32_bf16 v[126:129], v[146:149], v[168:171], v[126:129]
	v_mfma_f32_16x16x32_bf16 v[122:125], v[154:157], v[168:171], v[122:125]
	v_mfma_f32_16x16x32_bf16 v[110:113], v[146:149], v[176:179], v[110:113]
	v_mfma_f32_16x16x32_bf16 v[106:109], v[154:157], v[176:179], v[106:109]
	v_mfma_f32_16x16x32_bf16 v[94:97], v[146:149], v[190:193], v[94:97]
	v_mfma_f32_16x16x32_bf16 v[90:93], v[154:157], v[190:193], v[90:93]
	v_mfma_f32_16x16x32_bf16 v[76:79], v[146:149], v[198:201], v[76:79]
	v_mfma_f32_16x16x32_bf16 v[72:75], v[154:157], v[198:201], v[72:75]
	s_setprio 0
	s_barrier
	s_add_i32 s35, 0, 0x1c000
	v_add_u32_e32 v80, s35, v139
	ds_read_b128 v[202:205], v80
	ds_read_b128 v[206:209], v80 offset:1024
	ds_read_b128 v[210:213], v80 offset:2048
	ds_read_b128 v[214:217], v80 offset:3072
	v_mov_b32_e32 v80, v135
	s_add_i32 s22, s22, s18
	s_add_i32 m0, s22, 0xffffff80
	v_mov_b32_e32 v80, v137
	global_load_lds_dwordx4 v135, s[44:45] offset:128
	s_add_i32 m0, s22, 0x1f80
	s_nop 0
	global_load_lds_dwordx4 v137, s[44:45] offset:128
	s_barrier
	s_waitcnt lgkmcnt(0)
	s_setprio 1
	s_waitcnt lgkmcnt(0)
	v_mfma_f32_16x16x32_bf16 v[118:121], v[202:205], v[164:167], v[118:121]
	v_mfma_f32_16x16x32_bf16 v[114:117], v[210:213], v[164:167], v[114:117]
	v_mfma_f32_16x16x32_bf16 v[102:105], v[202:205], v[172:175], v[102:105]
	v_mfma_f32_16x16x32_bf16 v[98:101], v[210:213], v[172:175], v[98:101]
	v_mfma_f32_16x16x32_bf16 v[86:89], v[202:205], v[184:187], v[86:89]
	v_mfma_f32_16x16x32_bf16 v[82:85], v[210:213], v[184:187], v[82:85]
	v_mfma_f32_16x16x32_bf16 v[68:71], v[202:205], v[194:197], v[68:71]
	v_mfma_f32_16x16x32_bf16 v[64:67], v[210:213], v[194:197], v[64:67]
	v_mfma_f32_16x16x32_bf16 v[118:121], v[206:209], v[168:171], v[118:121]
	v_mfma_f32_16x16x32_bf16 v[114:117], v[214:217], v[168:171], v[114:117]
	v_mfma_f32_16x16x32_bf16 v[102:105], v[206:209], v[176:179], v[102:105]
	v_mfma_f32_16x16x32_bf16 v[98:101], v[214:217], v[176:179], v[98:101]
	v_mfma_f32_16x16x32_bf16 v[86:89], v[206:209], v[190:193], v[86:89]
	v_mfma_f32_16x16x32_bf16 v[82:85], v[214:217], v[190:193], v[82:85]
	v_mfma_f32_16x16x32_bf16 v[68:71], v[206:209], v[198:201], v[68:71]
	v_mfma_f32_16x16x32_bf16 v[64:67], v[214:217], v[198:201], v[64:67]
	s_setprio 0
	v_mov_b32_e32 v80, v134
	s_barrier
	ds_read_b128 v[164:167], v141 offset:49152
	ds_read_b128 v[168:171], v141 offset:50176
	ds_read_b128 v[172:175], v141 offset:51200
	ds_read_b128 v[176:179], v141 offset:52224
	ds_read_b128 v[184:187], v141 offset:53248
	ds_read_b128 v[190:193], v141 offset:54272
	ds_read_b128 v[194:197], v141 offset:55296
	ds_read_b128 v[198:201], v141 offset:56320
	s_add_i32 m0, s49, 0xffffff80
	v_mov_b32_e32 v80, v136
	global_load_lds_dwordx4 v134, s[42:43] offset:128
	s_add_i32 m0, s61, 0xffffff80
	s_nop 0
	global_load_lds_dwordx4 v136, s[42:43] offset:128
	s_barrier
; #define G_STAGE(bufoff, gbase, voff) do { _Pragma("unroll") for (int _i = 0; _i < 2; ++_i) { unsigned _vo = (voff)[_i]; asm volatile("" : "+v"(_vo));   \
;     __builtin_amdgcn_global_load_lds((const unsigned*)((const char*)(gbase) + _vo), (LAS unsigned*)(lds + (bufoff) + ldsw + _i * 8192), 16, 0, 0); } } while (0)
; #define G_MMA(ai, bj, At, Bt) do { __builtin_amdgcn_s_setprio(1); _Pragma("unroll") for (int m = 0; m < 4; ++m) _Pragma("unroll") for (int n = 0; n < 2; ++n) _Pragma("unroll") for (int k = 0; k < 2; ++k) \
;     acc[ai][bj][m][n] = __builtin_amdgcn_mfma_f32_16x16x32_bf16(Bt[n][k], At[m][k], acc[ai][bj][m][n], 0, 0, 0); __builtin_amdgcn_s_setprio(0); } while (0)
; #define G_WAIT_V(n) asm volatile("s_waitcnt vmcnt(" #n ")" ::: "memory")
; #define G_WAIT_L(n) asm volatile("s_waitcnt lgkmcnt(" #n ")" ::: "memory")
; #define G_BAR __builtin_amdgcn_s_barrier()
; #define G_SCHED __builtin_amdgcn_sched_barrier(0)
; template <class Epi>
; __device__ __forceinline__ void gemm_phase(LAS unsigned char* lds, const int K, const unsigned lda_b, const unsigned ldb_b, const Map& M, const Epi& E) {
;     ...
;       G_BAR; G_WAIT_L(0); G_MMA(1, 0, At, B0); G_BAR; G_SCHED;
;       G_STAGE(G_SB(1, 1), b2h1 + kstep, voffB);
;       G_WAIT_V(6); G_BAR; G_MMA(1, 1, At, B1); G_BAR;
;     }
	s_waitcnt lgkmcnt(0)
	s_setprio 1
	s_waitcnt lgkmcnt(0)
	v_mfma_f32_16x16x32_bf16 v[60:63], v[142:145], v[164:167], v[60:63]
	v_mfma_f32_16x16x32_bf16 v[56:59], v[150:153], v[164:167], v[56:59]
	v_mfma_f32_16x16x32_bf16 v[44:47], v[142:145], v[172:175], v[44:47]
	v_mfma_f32_16x16x32_bf16 v[40:43], v[150:153], v[172:175], v[40:43]
	v_mfma_f32_16x16x32_bf16 v[28:31], v[142:145], v[184:187], v[28:31]
	v_mfma_f32_16x16x32_bf16 v[24:27], v[150:153], v[184:187], v[24:27]
	v_mfma_f32_16x16x32_bf16 v[12:15], v[142:145], v[194:197], v[12:15]
	v_mfma_f32_16x16x32_bf16 v[8:11], v[150:153], v[194:197], v[8:11]
	v_mfma_f32_16x16x32_bf16 v[60:63], v[146:149], v[168:171], v[60:63]
	v_mfma_f32_16x16x32_bf16 v[56:59], v[154:157], v[168:171], v[56:59]
	v_mfma_f32_16x16x32_bf16 v[44:47], v[146:149], v[176:179], v[44:47]
	v_mfma_f32_16x16x32_bf16 v[40:43], v[154:157], v[176:179], v[40:43]
	v_mfma_f32_16x16x32_bf16 v[28:31], v[146:149], v[190:193], v[28:31]
	v_mfma_f32_16x16x32_bf16 v[24:27], v[154:157], v[190:193], v[24:27]
	v_mfma_f32_16x16x32_bf16 v[12:15], v[146:149], v[198:201], v[12:15]
	v_mfma_f32_16x16x32_bf16 v[8:11], v[154:157], v[198:201], v[8:11]
	s_setprio 0
	s_barrier
	v_mov_b32_e32 v80, v135
	s_add_i32 s22, s35, s18
	s_add_i32 m0, s22, 0xffffff80
	v_mov_b32_e32 v80, v137
	global_load_lds_dwordx4 v135, s[38:39] offset:128
	s_add_i32 m0, s22, 0x1f80
	s_nop 0
	global_load_lds_dwordx4 v137, s[38:39] offset:128
	s_waitcnt vmcnt(6)
	s_barrier
	s_setprio 1
	v_mfma_f32_16x16x32_bf16 v[52:55], v[202:205], v[164:167], v[52:55]
	v_mfma_f32_16x16x32_bf16 v[48:51], v[210:213], v[164:167], v[48:51]
	v_mfma_f32_16x16x32_bf16 v[36:39], v[202:205], v[172:175], v[36:39]
	v_mfma_f32_16x16x32_bf16 v[32:35], v[210:213], v[172:175], v[32:35]
	v_mfma_f32_16x16x32_bf16 v[20:23], v[202:205], v[184:187], v[20:23]
	v_mfma_f32_16x16x32_bf16 v[16:19], v[210:213], v[184:187], v[16:19]
	v_mfma_f32_16x16x32_bf16 v[4:7], v[202:205], v[194:197], v[4:7]
	v_mfma_f32_16x16x32_bf16 v[0:3], v[210:213], v[194:197], v[0:3]
	v_mfma_f32_16x16x32_bf16 v[52:55], v[206:209], v[168:171], v[52:55]
	v_mfma_f32_16x16x32_bf16 v[48:51], v[214:217], v[168:171], v[48:51]
	v_mfma_f32_16x16x32_bf16 v[36:39], v[206:209], v[176:179], v[36:39]
	v_mfma_f32_16x16x32_bf16 v[32:35], v[214:217], v[176:179], v[32:35]
	v_mfma_f32_16x16x32_bf16 v[20:23], v[206:209], v[190:193], v[20:23]
	v_mfma_f32_16x16x32_bf16 v[16:19], v[214:217], v[190:193], v[16:19]
	v_mfma_f32_16x16x32_bf16 v[4:7], v[206:209], v[198:201], v[4:7]
	v_mfma_f32_16x16x32_bf16 v[0:3], v[214:217], v[198:201], v[0:3]
	s_setprio 0
	s_add_i32 s34, s34, 2
	s_add_u32 s30, s30, 0x100
	s_addc_u32 s31, s31, 0
	s_add_u32 s2, s2, 0x100
	s_addc_u32 s3, s3, 0
	s_cmp_gt_u32 s34, 61
	s_barrier
	s_cbranch_scc0 .LBB0_554
; __device__ __forceinline__ unsigned cvt_pk_bf16(float lo, float hi) { unsigned r; asm("v_cvt_pk_bf16_f32 %0, %1, %2" : "=v"(r) : "v"(lo), "v"(hi)); return r; }
; __device__ __forceinline__ float bf_lo(unsigned u) { return __uint_as_float(u << 16); }
; __device__ __forceinline__ float bf_hi(unsigned u) { return __uint_as_float(u & 0xffff0000u); }
; __device__ __forceinline__ unsigned long long ss_fix(float s) { return (unsigned long long)(s * 16777216.f); }
;   __device__ __forceinline__ void operator()(const f32x4 (&acc)[2][2][4][2], const Unit& u, const EpiCtx& x_, int wr, int wc, int fr, int fq) const {
; #pragma unroll
;     for (int ai = 0; ai < 2; ++ai)
; #pragma unroll
;       for (int m = 0; m < 4; ++m) {
;         const int row = (u.r0 + (ai ? x_.rdelta : 0)) + wr * 64 + m * 16 + fr;
;         const bf16_t* xin = (const bf16_t*)x_.aux + (size_t)row * DM;
;         bf16_t* xbp = x_.xb + (size_t)row * DM;
;         float sq = 0.f;
; #pragma unroll
;         for (int bj = 0; bj < 2; ++bj) {
;           const int cb = u.c0 + wc * 64 + bj * 32 + 8 * fq;
;           const uint4 xi = *(const uint4*)(xin + cb); const f32x4 a = acc[ai][bj][m][0], b = acc[ai][bj][m][1];
;           const float x0 = bf_lo(xi.x) + a[0], x1 = bf_hi(xi.x) + a[1], x2 = bf_lo(xi.y) + a[2], x3 = bf_hi(xi.y) + a[3];
;           const float x4 = bf_lo(xi.z) + b[0], x5 = bf_hi(xi.z) + b[1], x6 = bf_lo(xi.w) + b[2], x7 = bf_hi(xi.w) + b[3];
;           sq += x0 * x0 + x1 * x1 + x2 * x2 + x3 * x3 + x4 * x4 + x5 * x5 + x6 * x6 + x7 * x7;
;           uint4 o; o.x = cvt_pk_bf16(x0, x1); o.y = cvt_pk_bf16(x2, x3); o.z = cvt_pk_bf16(x4, x5); o.w = cvt_pk_bf16(x6, x7);
;           *(uint4*)(xbp + cb) = o;
;         }
;         sq += __shfl_xor(sq, 16); sq += __shfl_xor(sq, 32);
;         if (fq == 0) atomicAdd(x_.sso + row, ss_fix(sq));
;       }
;   }
	s_nop 1
	v_add_u32_e32 v194, s75, v138
	v_add_u32_e32 v196, s0, v140
	v_ashrrev_i32_e32 v195, 31, v194
	v_lshlrev_b64 v[198:199], 12, v[194:195]
	v_ashrrev_i32_e32 v197, 31, v196
	v_lshl_add_u64 v[200:201], s[8:9], 0, v[198:199]
	v_lshlrev_b64 v[202:203], 1, v[196:197]
	v_lshl_add_u64 v[204:205], v[200:201], 0, v[202:203]
	global_load_dwordx4 v[150:153], v[204:205], off
	global_load_dwordx4 v[154:157], v[204:205], off offset:64
	v_add_u32_e32 v198, 16, v194
	v_ashrrev_i32_e32 v195, 31, v198
	v_mov_b32_e32 v200, v198
	v_mov_b32_e32 v201, v195
	v_lshlrev_b64 v[204:205], 12, v[200:201]
	v_lshl_add_u64 v[200:201], s[8:9], 0, v[204:205]
	v_lshl_add_u64 v[206:207], v[200:201], 0, v[202:203]
	global_load_dwordx4 v[164:167], v[206:207], off
	global_load_dwordx4 v[168:171], v[206:207], off offset:64
	v_add_u32_e32 v198, 32, v194
	v_ashrrev_i32_e32 v195, 31, v198
	v_mov_b32_e32 v200, v198
	v_mov_b32_e32 v201, v195
	v_lshlrev_b64 v[204:205], 12, v[200:201]
	v_lshl_add_u64 v[200:201], s[8:9], 0, v[204:205]
	v_lshl_add_u64 v[206:207], v[200:201], 0, v[202:203]
	global_load_dwordx4 v[172:175], v[206:207], off
	global_load_dwordx4 v[176:179], v[206:207], off offset:64
	v_add_u32_e32 v198, 48, v194
	v_ashrrev_i32_e32 v195, 31, v198
	v_mov_b32_e32 v200, v198
	v_mov_b32_e32 v201, v195
	v_lshlrev_b64 v[204:205], 12, v[200:201]
	v_lshl_add_u64 v[200:201], s[8:9], 0, v[204:205]
	v_lshl_add_u64 v[206:207], v[200:201], 0, v[202:203]
	global_load_dwordx4 v[184:187], v[206:207], off
	global_load_dwordx4 v[190:193], v[206:207], off offset:64
	v_add_u32_e32 v132, s75, v138
	v_readfirstlane_b32 s38, v130
	v_add_u32_e32 v130, s0, v140
	v_ashrrev_i32_e32 v133, 31, v132
	v_readfirstlane_b32 s39, v131
	v_lshlrev_b64 v[142:143], 12, v[132:133]
	v_ashrrev_i32_e32 v131, 31, v130
	v_lshl_add_u64 v[144:145], s[8:9], 0, v[142:143]
	v_lshlrev_b64 v[130:131], 1, v[130:131]
	v_lshl_add_u64 v[148:149], v[144:145], 0, v[130:131]
	v_lshl_add_u64 v[146:147], s[36:37], 0, v[142:143]
	s_nop 0
	s_nop 0
	s_waitcnt lgkmcnt(0)
	s_nop 0
	s_waitcnt vmcnt(7)
	v_lshlrev_b32_e32 v80, 16, v150
	v_add_f32_e32 v80, v126, v80
	v_and_b32_e32 v126, 0xffff0000, v150
	v_add_f32_e32 v126, v127, v126
	v_lshlrev_b32_e32 v127, 16, v151
	v_add_f32_e32 v127, v128, v127
	v_and_b32_e32 v128, 0xffff0000, v151
	v_add_f32_e32 v128, v129, v128
	v_lshlrev_b32_e32 v129, 16, v152
	v_add_f32_e32 v129, v122, v129
	v_and_b32_e32 v122, 0xffff0000, v152
	v_mul_f32_e32 v144, v126, v126
	v_fmac_f32_e32 v144, v80, v80
	v_fmac_f32_e32 v144, v127, v127
	v_fmac_f32_e32 v144, v128, v128
	v_add_f32_e32 v142, v123, v122
	v_lshlrev_b32_e32 v122, 16, v153
	v_fmac_f32_e32 v144, v129, v129
	v_add_f32_e32 v143, v124, v122
	v_and_b32_e32 v122, 0xffff0000, v153
	v_fmac_f32_e32 v144, v142, v142
	v_add_f32_e32 v125, v125, v122
	v_fmac_f32_e32 v144, v143, v143
	v_cvt_pk_bf16_f32 v122, v80, v126
	v_cvt_pk_bf16_f32 v123, v127, v128
	v_lshl_add_u64 v[126:127], v[146:147], 0, v[130:131]
	v_fmac_f32_e32 v144, v125, v125
	v_cvt_pk_bf16_f32 v124, v129, v142
	v_cvt_pk_bf16_f32 v125, v143, v125
	global_store_dwordx4 v[126:127], v[122:125], off
	s_nop 0
	s_waitcnt lgkmcnt(0)
	s_nop 0
	s_waitcnt vmcnt(7)
	v_lshlrev_b32_e32 v80, 16, v154
	v_add_f32_e32 v80, v118, v80
	v_and_b32_e32 v118, 0xffff0000, v154
	v_add_f32_e32 v118, v119, v118
	v_lshlrev_b32_e32 v119, 16, v155
	v_add_f32_e32 v119, v120, v119
	v_and_b32_e32 v120, 0xffff0000, v155
	v_add_f32_e32 v120, v121, v120
	v_lshlrev_b32_e32 v121, 16, v156
	v_add_f32_e32 v121, v114, v121
	v_and_b32_e32 v114, 0xffff0000, v156
	v_add_f32_e32 v122, v115, v114
	v_lshlrev_b32_e32 v114, 16, v157
	v_add_f32_e32 v123, v116, v114
	v_and_b32_e32 v114, 0xffff0000, v157
	v_add_f32_e32 v117, v117, v114
	v_mul_f32_e32 v114, v118, v118
	v_fmac_f32_e32 v114, v80, v80
	v_fmac_f32_e32 v114, v119, v119
	v_fmac_f32_e32 v114, v120, v120
	v_fmac_f32_e32 v114, v121, v121
	v_fmac_f32_e32 v114, v122, v122
	v_fmac_f32_e32 v114, v123, v123
	v_fmac_f32_e32 v114, v117, v117
	v_add_f32_e32 v124, v144, v114
	v_cvt_pk_bf16_f32 v114, v80, v118
	v_cvt_pk_bf16_f32 v115, v119, v120
	v_cvt_pk_bf16_f32 v116, v121, v122
	v_cvt_pk_bf16_f32 v117, v123, v117
	global_store_dwordx4 v[126:127], v[114:117], off offset:64
	v_xor_b32_e32 v80, 16, v189
	s_nop 0
	v_and_b32_e32 v114, 64, v189
	v_add_u32_e32 v115, 64, v114
	v_cmp_lt_i32_e64 s[2:3], v80, v115
	v_xor_b32_e32 v116, 32, v189
	s_nop 0
	v_cndmask_b32_e64 v80, v189, v80, s[2:3]
	v_lshlrev_b32_e32 v80, 2, v80
	ds_bpermute_b32 v114, v80, v124
	v_cmp_lt_i32_e64 s[2:3], v116, v115
	s_waitcnt lgkmcnt(0)
	v_add_f32_e32 v114, v124, v114
	v_cndmask_b32_e64 v115, v189, v116, s[2:3]
	v_lshlrev_b32_e32 v116, 2, v115
	ds_bpermute_b32 v115, v116, v114
	s_and_saveexec_b64 s[2:3], vcc
	s_cbranch_execz .LBB0_557
	s_waitcnt lgkmcnt(0)
	v_add_f32_e32 v114, v114, v115
	v_mul_f32_e32 v114, 0x4b800000, v114
	v_trunc_f32_e32 v114, v114
	v_mul_f32_e32 v115, 0x2f800000, v114
	v_floor_f32_e32 v115, v115
	v_fmac_f32_e32 v114, 0xcf800000, v115
	v_cvt_u32_f32_e32 v114, v114
	v_cvt_u32_f32_e32 v115, v115
	v_lshl_add_u64 v[118:119], v[132:133], 3, s[40:41]
	global_atomic_add_x2 v[118:119], v[114:115], off

; #define G_STAGE(bufoff, gbase, voff) do { _Pragma("unroll") for (int _i = 0; _i < 2; ++_i) { unsigned _vo = (voff)[_i]; asm volatile("" : "+v"(_vo));   \
;     __builtin_amdgcn_global_load_lds((const unsigned*)((const char*)(gbase) + _vo), (LAS unsigned*)(lds + (bufoff) + ldsw + _i * 8192), 16, 0, 0); } } while (0)
; #define G_LDA(dst, b, h) do { _Pragma("unroll") for (int m = 0; m < 4; ++m) _Pragma("unroll") for (int k = 0; k < 2; ++k) dst[m][k] = *(const LAS bf16x8*)(lds + G_SA(b, h) + aoff + m * 2048 + k * 1024); } while (0)
; #define G_LDB(dst, b, h) do { _Pragma("unroll") for (int n = 0; n < 2; ++n) _Pragma("unroll") for (int k = 0; k < 2; ++k) dst[n][k] = *(const LAS bf16x8*)(lds + G_SB(b, h) + boff + n * 2048 + k * 1024); } while (0)
; #define G_MMA(ai, bj, At, Bt) do { __builtin_amdgcn_s_setprio(1); _Pragma("unroll") for (int m = 0; m < 4; ++m) _Pragma("unroll") for (int n = 0; n < 2; ++n) _Pragma("unroll") for (int k = 0; k < 2; ++k) \
;     acc[ai][bj][m][n] = __builtin_amdgcn_mfma_f32_16x16x32_bf16(Bt[n][k], At[m][k], acc[ai][bj][m][n], 0, 0, 0); __builtin_amdgcn_s_setprio(0); } while (0)
; #define G_WAIT_L(n) asm volatile("s_waitcnt lgkmcnt(" #n ")" ::: "memory")
; #define G_BAR __builtin_amdgcn_s_barrier()
; #define G_SCHED __builtin_amdgcn_sched_barrier(0)
; template <class Epi>
; __device__ __forceinline__ void gemm_phase(LAS unsigned char* lds, const int K, const unsigned lda_b, const unsigned ldb_b, const Map& M, const Epi& E) {
;     ...
;     for (int t = 0; t < nt; t += 2) {
;       const bool last = (t == nt - 2);
;       const char* a1h1 = cur.a0 + a_h + (size_t)(t + 1) * kstep;
;       const char* a2h0 = last ? nxt.a0 : cur.a0 + (size_t)(t + 2) * kstep; const char* a2h1 = a2h0 + a_h;
;       const char* b2h0 = last ? nxt.b0 : cur.b0 + (size_t)(t + 2) * kstep; const char* b2h1 = last ? nxt.b1 : cur.b1 + (size_t)(t + 2) * kstep;
;       G_LDB(B0, 0, 0); G_SCHED; G_LDA(At, 0, 0); G_STAGE(G_SA(1, 1), a1h1, voffA);
;       G_WAIT_L(8); G_BAR; G_WAIT_L(0); G_MMA(0, 0, At, B0); G_BAR; G_SCHED;
;       G_LDB(B1, 0, 1); G_STAGE(G_SB(0, 0), b2h0, voffB);
;       G_BAR; G_WAIT_L(0); G_MMA(0, 1, At, B1); G_BAR;
;       G_LDA(At, 0, 1); G_STAGE(G_SA(0, 0), a2h0, voffA);
;       G_BAR; G_WAIT_L(0); G_MMA(1, 0, At, B0); G_BAR; G_SCHED;
.LBB0_589:
	s_add_u32 s35, s2, 0xfff80080
	s_addc_u32 s38, s3, -1
	s_add_u32 s39, s30, 0xfffe0000
	s_addc_u32 s44, s31, -1
	s_add_i32 s22, 0, 0x10000
	v_add_u32_e32 v80, s22, v167
	ds_read_b128 v[132:135], v80
	ds_read_b128 v[140:143], v80 offset:1024
	ds_read_b128 v[144:147], v80 offset:2048
	ds_read_b128 v[148:151], v80 offset:3072
	s_cmp_eq_u32 s34, 28
	s_cselect_b32 s43, s9, s38
	s_cselect_b32 s42, s8, s35
	s_cselect_b32 s45, s37, s44
	s_cselect_b32 s44, s36, s39
	v_mov_b32_e32 v80, v139
	s_cselect_b32 s39, s29, s31
	s_cselect_b32 s38, s28, s30
	s_add_u32 s68, s42, 0x80000
	ds_read_b128 v[152:155], v173
	ds_read_b128 v[156:159], v173 offset:1024
	ds_read_b128 v[174:177], v173 offset:2048
	ds_read_b128 v[190:193], v173 offset:3072
	ds_read_b128 v[194:197], v173 offset:4096
	ds_read_b128 v[198:201], v173 offset:5120
	ds_read_b128 v[202:205], v173 offset:6144
	ds_read_b128 v[206:209], v173 offset:7168
	s_addc_u32 s69, s43, 0
	s_add_i32 m0, s66, 0xc000
	s_nop 0
	global_load_lds_dwordx4 v80, s[2:3]
	v_mov_b32_e32 v80, v164
	s_add_i32 m0, s66, 0xe000
	s_nop 0
	global_load_lds_dwordx4 v80, s[2:3]
	s_waitcnt lgkmcnt(8)
	s_barrier
	s_waitcnt lgkmcnt(0)
	s_setprio 1
	s_waitcnt lgkmcnt(0)
	v_mfma_f32_16x16x32_bf16 v[126:129], v[132:135], v[152:155], v[126:129]
	v_mfma_f32_16x16x32_bf16 v[122:125], v[144:147], v[152:155], v[122:125]
	v_mfma_f32_16x16x32_bf16 v[110:113], v[132:135], v[174:177], v[110:113]
	v_mfma_f32_16x16x32_bf16 v[106:109], v[144:147], v[174:177], v[106:109]
	v_mfma_f32_16x16x32_bf16 v[94:97], v[132:135], v[194:197], v[94:97]
	v_mfma_f32_16x16x32_bf16 v[90:93], v[144:147], v[194:197], v[90:93]
	v_mfma_f32_16x16x32_bf16 v[76:79], v[132:135], v[202:205], v[76:79]
	v_mfma_f32_16x16x32_bf16 v[72:75], v[144:147], v[202:205], v[72:75]
	v_mfma_f32_16x16x32_bf16 v[126:129], v[140:143], v[156:159], v[126:129]
	v_mfma_f32_16x16x32_bf16 v[122:125], v[148:151], v[156:159], v[122:125]
	v_mfma_f32_16x16x32_bf16 v[110:113], v[140:143], v[190:193], v[110:113]
	v_mfma_f32_16x16x32_bf16 v[106:109], v[148:151], v[190:193], v[106:109]
	v_mfma_f32_16x16x32_bf16 v[94:97], v[140:143], v[198:201], v[94:97]
	v_mfma_f32_16x16x32_bf16 v[90:93], v[148:151], v[198:201], v[90:93]
	v_mfma_f32_16x16x32_bf16 v[76:79], v[140:143], v[206:209], v[76:79]
	v_mfma_f32_16x16x32_bf16 v[72:75], v[148:151], v[206:209], v[72:75]
	s_setprio 0
	s_barrier
	s_add_i32 s35, 0, 0x14000
	v_add_u32_e32 v80, s35, v167
	ds_read_b128 v[210:213], v80
	ds_read_b128 v[214:217], v80 offset:1024
	ds_read_b128 v[238:241], v80 offset:2048
	ds_read_b128 v[242:245], v80 offset:3072
	v_mov_b32_e32 v80, v163
	s_add_i32 s22, s22, s49
	s_mov_b32 m0, s22
	s_nop 0
	global_load_lds_dwordx4 v80, s[44:45]
	v_mov_b32_e32 v80, v165
	s_add_i32 m0, s22, 0x2000
	s_nop 0
	global_load_lds_dwordx4 v80, s[44:45]
	s_barrier
	s_waitcnt lgkmcnt(0)
	s_setprio 1
	s_waitcnt lgkmcnt(0)
	v_mfma_f32_16x16x32_bf16 v[118:121], v[210:213], v[152:155], v[118:121]
	v_mfma_f32_16x16x32_bf16 v[114:117], v[238:241], v[152:155], v[114:117]
	v_mfma_f32_16x16x32_bf16 v[102:105], v[210:213], v[174:177], v[102:105]
	v_mfma_f32_16x16x32_bf16 v[98:101], v[238:241], v[174:177], v[98:101]
	v_mfma_f32_16x16x32_bf16 v[86:89], v[210:213], v[194:197], v[86:89]
	v_mfma_f32_16x16x32_bf16 v[82:85], v[238:241], v[194:197], v[82:85]
	v_mfma_f32_16x16x32_bf16 v[68:71], v[210:213], v[202:205], v[68:71]
	v_mfma_f32_16x16x32_bf16 v[64:67], v[238:241], v[202:205], v[64:67]
	v_mfma_f32_16x16x32_bf16 v[118:121], v[214:217], v[156:159], v[118:121]
	v_mfma_f32_16x16x32_bf16 v[114:117], v[242:245], v[156:159], v[114:117]
	v_mfma_f32_16x16x32_bf16 v[102:105], v[214:217], v[190:193], v[102:105]
	v_mfma_f32_16x16x32_bf16 v[98:101], v[242:245], v[190:193], v[98:101]
	v_mfma_f32_16x16x32_bf16 v[86:89], v[214:217], v[198:201], v[86:89]
	v_mfma_f32_16x16x32_bf16 v[82:85], v[242:245], v[198:201], v[82:85]
	v_mfma_f32_16x16x32_bf16 v[68:71], v[214:217], v[206:209], v[68:71]
	v_mfma_f32_16x16x32_bf16 v[64:67], v[242:245], v[206:209], v[64:67]
	s_setprio 0
	v_mov_b32_e32 v80, v139
	s_mov_b32 m0, s66
	s_barrier
	ds_read_b128 v[152:155], v173 offset:16384
	ds_read_b128 v[156:159], v173 offset:17408
	ds_read_b128 v[174:177], v173 offset:18432
	ds_read_b128 v[190:193], v173 offset:19456
	ds_read_b128 v[194:197], v173 offset:20480
	ds_read_b128 v[198:201], v173 offset:21504
	ds_read_b128 v[202:205], v173 offset:22528
	ds_read_b128 v[206:209], v173 offset:23552
	s_nop 0
	global_load_lds_dwordx4 v80, s[42:43]
	v_mov_b32_e32 v80, v164
	s_mov_b32 m0, s67
	s_nop 0
	global_load_lds_dwordx4 v80, s[42:43]
	s_barrier
	s_waitcnt lgkmcnt(0)
	s_setprio 1
	s_waitcnt lgkmcnt(0)
	v_mfma_f32_16x16x32_bf16 v[60:63], v[132:135], v[152:155], v[60:63]
	v_mfma_f32_16x16x32_bf16 v[56:59], v[144:147], v[152:155], v[56:59]
	v_mfma_f32_16x16x32_bf16 v[44:47], v[132:135], v[174:177], v[44:47]
	v_mfma_f32_16x16x32_bf16 v[40:43], v[144:147], v[174:177], v[40:43]
	v_mfma_f32_16x16x32_bf16 v[28:31], v[132:135], v[194:197], v[28:31]
	v_mfma_f32_16x16x32_bf16 v[24:27], v[144:147], v[194:197], v[24:27]
	v_mfma_f32_16x16x32_bf16 v[12:15], v[132:135], v[202:205], v[12:15]
	v_mfma_f32_16x16x32_bf16 v[8:11], v[144:147], v[202:205], v[8:11]
	v_mfma_f32_16x16x32_bf16 v[60:63], v[140:143], v[156:159], v[60:63]
	v_mfma_f32_16x16x32_bf16 v[56:59], v[148:151], v[156:159], v[56:59]
	v_mfma_f32_16x16x32_bf16 v[44:47], v[140:143], v[190:193], v[44:47]
	v_mfma_f32_16x16x32_bf16 v[40:43], v[148:151], v[190:193], v[40:43]
	v_mfma_f32_16x16x32_bf16 v[28:31], v[140:143], v[198:201], v[28:31]
	v_mfma_f32_16x16x32_bf16 v[24:27], v[148:151], v[198:201], v[24:27]
	v_mfma_f32_16x16x32_bf16 v[12:15], v[140:143], v[206:209], v[12:15]
	v_mfma_f32_16x16x32_bf16 v[8:11], v[148:151], v[206:209], v[8:11]
	s_setprio 0
	s_barrier
; #define G_STAGE(bufoff, gbase, voff) do { _Pragma("unroll") for (int _i = 0; _i < 2; ++_i) { unsigned _vo = (voff)[_i]; asm volatile("" : "+v"(_vo));   \
;     __builtin_amdgcn_global_load_lds((const unsigned*)((const char*)(gbase) + _vo), (LAS unsigned*)(lds + (bufoff) + ldsw + _i * 8192), 16, 0, 0); } } while (0)
; #define G_LDA(dst, b, h) do { _Pragma("unroll") for (int m = 0; m < 4; ++m) _Pragma("unroll") for (int k = 0; k < 2; ++k) dst[m][k] = *(const LAS bf16x8*)(lds + G_SA(b, h) + aoff + m * 2048 + k * 1024); } while (0)
; #define G_LDB(dst, b, h) do { _Pragma("unroll") for (int n = 0; n < 2; ++n) _Pragma("unroll") for (int k = 0; k < 2; ++k) dst[n][k] = *(const LAS bf16x8*)(lds + G_SB(b, h) + boff + n * 2048 + k * 1024); } while (0)
; #define G_MMA(ai, bj, At, Bt) do { __builtin_amdgcn_s_setprio(1); _Pragma("unroll") for (int m = 0; m < 4; ++m) _Pragma("unroll") for (int n = 0; n < 2; ++n) _Pragma("unroll") for (int k = 0; k < 2; ++k) \
;     acc[ai][bj][m][n] = __builtin_amdgcn_mfma_f32_16x16x32_bf16(Bt[n][k], At[m][k], acc[ai][bj][m][n], 0, 0, 0); __builtin_amdgcn_s_setprio(0); } while (0)
; #define G_WAIT_V(n) asm volatile("s_waitcnt vmcnt(" #n ")" ::: "memory")
; #define G_WAIT_L(n) asm volatile("s_waitcnt lgkmcnt(" #n ")" ::: "memory")
; #define G_BAR __builtin_amdgcn_s_barrier()
; #define G_SCHED __builtin_amdgcn_sched_barrier(0)
; template <class Epi>
; __device__ __forceinline__ void gemm_phase(LAS unsigned char* lds, const int K, const unsigned lda_b, const unsigned ldb_b, const Map& M, const Epi& E) {
;     ...
;       G_STAGE(G_SB(0, 1), b2h1, voffB);
;       G_WAIT_V(6); G_BAR; G_MMA(1, 1, At, B1); G_BAR;
;       G_LDB(B0, 1, 0); G_SCHED; G_LDA(At, 1, 0); G_STAGE(G_SA(0, 1), a2h1, voffA);
;       G_WAIT_L(8); G_BAR; G_WAIT_L(0); G_MMA(0, 0, At, B0); G_BAR; G_SCHED;
;       G_LDB(B1, 1, 1); G_STAGE(G_SB(1, 0), b2h0 + kstep, voffB);
;       G_BAR; G_WAIT_L(0); G_MMA(0, 1, At, B1); G_BAR;
	v_mov_b32_e32 v80, v163
	s_add_i32 s22, s35, s49
	s_mov_b32 m0, s22
	s_nop 0
	global_load_lds_dwordx4 v80, s[38:39]
	v_mov_b32_e32 v80, v165
	s_add_i32 m0, s22, 0x2000
	s_nop 0
	global_load_lds_dwordx4 v80, s[38:39]
	s_waitcnt vmcnt(6)
	s_barrier
	s_setprio 1
	v_mfma_f32_16x16x32_bf16 v[52:55], v[210:213], v[152:155], v[52:55]
	v_mfma_f32_16x16x32_bf16 v[48:51], v[238:241], v[152:155], v[48:51]
	v_mfma_f32_16x16x32_bf16 v[36:39], v[210:213], v[174:177], v[36:39]
	v_mfma_f32_16x16x32_bf16 v[32:35], v[238:241], v[174:177], v[32:35]
	v_mfma_f32_16x16x32_bf16 v[20:23], v[210:213], v[194:197], v[20:23]
	v_mfma_f32_16x16x32_bf16 v[16:19], v[238:241], v[194:197], v[16:19]
	v_mfma_f32_16x16x32_bf16 v[4:7], v[210:213], v[202:205], v[4:7]
	v_mfma_f32_16x16x32_bf16 v[0:3], v[238:241], v[202:205], v[0:3]
	v_mfma_f32_16x16x32_bf16 v[52:55], v[214:217], v[156:159], v[52:55]
	v_mfma_f32_16x16x32_bf16 v[48:51], v[242:245], v[156:159], v[48:51]
	v_mfma_f32_16x16x32_bf16 v[36:39], v[214:217], v[190:193], v[36:39]
	v_mfma_f32_16x16x32_bf16 v[32:35], v[242:245], v[190:193], v[32:35]
	v_mfma_f32_16x16x32_bf16 v[20:23], v[214:217], v[198:201], v[20:23]
	v_mfma_f32_16x16x32_bf16 v[16:19], v[242:245], v[198:201], v[16:19]
	v_mfma_f32_16x16x32_bf16 v[4:7], v[214:217], v[206:209], v[4:7]
	v_mfma_f32_16x16x32_bf16 v[0:3], v[242:245], v[206:209], v[0:3]
	s_setprio 0
	s_add_i32 s22, 0, 0x18000
	v_add_u32_e32 v80, s22, v167
	s_barrier
	ds_read_b128 v[132:135], v80
	ds_read_b128 v[140:143], v80 offset:1024
	ds_read_b128 v[144:147], v80 offset:2048
	ds_read_b128 v[148:151], v80 offset:3072
	v_mov_b32_e32 v80, v139
	s_mov_b32 m0, s81
	ds_read_b128 v[152:155], v173 offset:32768
	ds_read_b128 v[156:159], v173 offset:33792
	ds_read_b128 v[174:177], v173 offset:34816
	ds_read_b128 v[190:193], v173 offset:35840
	ds_read_b128 v[194:197], v173 offset:36864
	ds_read_b128 v[198:201], v173 offset:37888
	ds_read_b128 v[202:205], v173 offset:38912
	ds_read_b128 v[206:209], v173 offset:39936
	s_nop 0
	global_load_lds_dwordx4 v80, s[68:69]
	v_mov_b32_e32 v80, v164
	s_mov_b32 m0, s82
	s_nop 0
	global_load_lds_dwordx4 v80, s[68:69]
	s_waitcnt lgkmcnt(8)
	s_barrier
	s_waitcnt lgkmcnt(0)
	s_setprio 1
	s_waitcnt lgkmcnt(0)
	v_mfma_f32_16x16x32_bf16 v[126:129], v[132:135], v[152:155], v[126:129]
	v_mfma_f32_16x16x32_bf16 v[122:125], v[144:147], v[152:155], v[122:125]
	v_mfma_f32_16x16x32_bf16 v[110:113], v[132:135], v[174:177], v[110:113]
	v_mfma_f32_16x16x32_bf16 v[106:109], v[144:147], v[174:177], v[106:109]
	v_mfma_f32_16x16x32_bf16 v[94:97], v[132:135], v[194:197], v[94:97]
	v_mfma_f32_16x16x32_bf16 v[90:93], v[144:147], v[194:197], v[90:93]
	v_mfma_f32_16x16x32_bf16 v[76:79], v[132:135], v[202:205], v[76:79]
	v_mfma_f32_16x16x32_bf16 v[72:75], v[144:147], v[202:205], v[72:75]
	v_mfma_f32_16x16x32_bf16 v[126:129], v[140:143], v[156:159], v[126:129]
	v_mfma_f32_16x16x32_bf16 v[122:125], v[148:151], v[156:159], v[122:125]
	v_mfma_f32_16x16x32_bf16 v[110:113], v[140:143], v[190:193], v[110:113]
	v_mfma_f32_16x16x32_bf16 v[106:109], v[148:151], v[190:193], v[106:109]
	v_mfma_f32_16x16x32_bf16 v[94:97], v[140:143], v[198:201], v[94:97]
	v_mfma_f32_16x16x32_bf16 v[90:93], v[148:151], v[198:201], v[90:93]
	v_mfma_f32_16x16x32_bf16 v[76:79], v[140:143], v[206:209], v[76:79]
	v_mfma_f32_16x16x32_bf16 v[72:75], v[148:151], v[206:209], v[72:75]
	s_setprio 0
	s_barrier
	s_add_i32 s35, 0, 0x1c000
	v_add_u32_e32 v80, s35, v167
	ds_read_b128 v[210:213], v80
	ds_read_b128 v[214:217], v80 offset:1024
	ds_read_b128 v[238:241], v80 offset:2048
	ds_read_b128 v[242:245], v80 offset:3072
	v_mov_b32_e32 v80, v163
	s_add_i32 s22, s22, s49
	s_add_i32 m0, s22, 0xffffff80
	v_mov_b32_e32 v80, v165
	global_load_lds_dwordx4 v163, s[44:45] offset:128
	s_add_i32 m0, s22, 0x1f80
	s_nop 0
	global_load_lds_dwordx4 v165, s[44:45] offset:128
	s_barrier
	s_waitcnt lgkmcnt(0)
	s_setprio 1
	s_waitcnt lgkmcnt(0)
	v_mfma_f32_16x16x32_bf16 v[118:121], v[210:213], v[152:155], v[118:121]
	v_mfma_f32_16x16x32_bf16 v[114:117], v[238:241], v[152:155], v[114:117]
	v_mfma_f32_16x16x32_bf16 v[102:105], v[210:213], v[174:177], v[102:105]
	v_mfma_f32_16x16x32_bf16 v[98:101], v[238:241], v[174:177], v[98:101]
	v_mfma_f32_16x16x32_bf16 v[86:89], v[210:213], v[194:197], v[86:89]
	v_mfma_f32_16x16x32_bf16 v[82:85], v[238:241], v[194:197], v[82:85]
	v_mfma_f32_16x16x32_bf16 v[68:71], v[210:213], v[202:205], v[68:71]
	v_mfma_f32_16x16x32_bf16 v[64:67], v[238:241], v[202:205], v[64:67]
	v_mfma_f32_16x16x32_bf16 v[118:121], v[214:217], v[156:159], v[118:121]
	v_mfma_f32_16x16x32_bf16 v[114:117], v[242:245], v[156:159], v[114:117]
	v_mfma_f32_16x16x32_bf16 v[102:105], v[214:217], v[190:193], v[102:105]
	v_mfma_f32_16x16x32_bf16 v[98:101], v[242:245], v[190:193], v[98:101]
	v_mfma_f32_16x16x32_bf16 v[86:89], v[214:217], v[198:201], v[86:89]
	v_mfma_f32_16x16x32_bf16 v[82:85], v[242:245], v[198:201], v[82:85]
	v_mfma_f32_16x16x32_bf16 v[68:71], v[214:217], v[206:209], v[68:71]
	v_mfma_f32_16x16x32_bf16 v[64:67], v[242:245], v[206:209], v[64:67]
	s_setprio 0
	v_mov_b32_e32 v80, v139
	s_barrier
; #define LAS __attribute__((address_space(3)))
; #define G_STAGE(bufoff, gbase, voff) do { _Pragma("unroll") for (int _i = 0; _i < 2; ++_i) { unsigned _vo = (voff)[_i]; asm volatile("" : "+v"(_vo));   \
;     __builtin_amdgcn_global_load_lds((const unsigned*)((const char*)(gbase) + _vo), (LAS unsigned*)(lds + (bufoff) + ldsw + _i * 8192), 16, 0, 0); } } while (0)
; #define G_LDA(dst, b, h) do { _Pragma("unroll") for (int m = 0; m < 4; ++m) _Pragma("unroll") for (int k = 0; k < 2; ++k) dst[m][k] = *(const LAS bf16x8*)(lds + G_SA(b, h) + aoff + m * 2048 + k * 1024); } while (0)
; #define G_MMA(ai, bj, At, Bt) do { __builtin_amdgcn_s_setprio(1); _Pragma("unroll") for (int m = 0; m < 4; ++m) _Pragma("unroll") for (int n = 0; n < 2; ++n) _Pragma("unroll") for (int k = 0; k < 2; ++k) \
;     acc[ai][bj][m][n] = __builtin_amdgcn_mfma_f32_16x16x32_bf16(Bt[n][k], At[m][k], acc[ai][bj][m][n], 0, 0, 0); __builtin_amdgcn_s_setprio(0); } while (0)
;   __device__ __forceinline__ void operator()(const f32x4 (&acc)[2][2][4][2], const Unit& u, const EpiCtx& x_, int wr, int wc, int fr, int fq) const {
;     LAS float* red = x_.red;
;     const int S = x_.p1, hd = wc >> 1, wh = wc & 1, hq = (u.c0 >> 7) + hd;
;     unsigned long long ssv[2][4];
; #pragma unroll
;     for (int ai = 0; ai < 2; ++ai)
; #pragma unroll
;       for (int m = 0; m < 4; ++m) ssv[ai][m] = x_.ss[u.r0 + ai * 128 + wr * 64 + m * 16 + fr];
; #pragma unroll
;     for (int ai = 0; ai < 2; ++ai)
; #pragma unroll
;       for (int m = 0; m < 4; ++m) {
;         float s = 0.f;
; #pragma unroll
;         for (int bj = 0; bj < 2; ++bj) {
;           const f32x4 a = acc[ai][bj][m][0], b = acc[ai][bj][m][1];
;           s += a[0] * a[0] + a[1] * a[1] + a[2] * a[2] + a[3] * a[3] + b[0] * b[0] + b[1] * b[1] + b[2] * b[2] + b[3] * b[3];
;         }
;         s += __shfl_xor(s, 16); s += __shfl_xor(s, 32);
;         if (fq == 0) red[((wr * 2 + hd) * 128 + ai * 64 + m * 16 + fr) * 2 + wh] = s;
; template <class Epi>
; __device__ __forceinline__ void gemm_phase(LAS unsigned char* lds, const int K, const unsigned lda_b, const unsigned ldb_b, const Map& M, const Epi& E) {
;     ...
;       G_LDA(At, 1, 1); G_STAGE(G_SA(1, 0), a2h0 + kstep, voffA);
;       G_BAR; G_WAIT_L(0); G_MMA(1, 0, At, B0); G_BAR; G_SCHED;
;       G_STAGE(G_SB(1, 1), b2h1 + kstep, voffB);
;       G_WAIT_V(6); G_BAR; G_MMA(1, 1, At, B1); G_BAR;
;     }
	ds_read_b128 v[152:155], v173 offset:49152
	ds_read_b128 v[156:159], v173 offset:50176
	ds_read_b128 v[174:177], v173 offset:51200
	ds_read_b128 v[190:193], v173 offset:52224
	ds_read_b128 v[194:197], v173 offset:53248
	ds_read_b128 v[198:201], v173 offset:54272
	ds_read_b128 v[202:205], v173 offset:55296
	ds_read_b128 v[206:209], v173 offset:56320
	s_add_i32 m0, s96, 0xffffff80
	v_mov_b32_e32 v80, v164
	global_load_lds_dwordx4 v139, s[42:43] offset:128
	s_add_i32 m0, s97, 0xffffff80
	s_nop 0
	global_load_lds_dwordx4 v164, s[42:43] offset:128
	s_barrier
	s_waitcnt lgkmcnt(0)
	s_setprio 1
	s_waitcnt lgkmcnt(0)
	v_mfma_f32_16x16x32_bf16 v[60:63], v[132:135], v[152:155], v[60:63]
	v_mfma_f32_16x16x32_bf16 v[56:59], v[144:147], v[152:155], v[56:59]
	v_mfma_f32_16x16x32_bf16 v[44:47], v[132:135], v[174:177], v[44:47]
	v_mfma_f32_16x16x32_bf16 v[40:43], v[144:147], v[174:177], v[40:43]
	v_mfma_f32_16x16x32_bf16 v[28:31], v[132:135], v[194:197], v[28:31]
	v_mfma_f32_16x16x32_bf16 v[24:27], v[144:147], v[194:197], v[24:27]
	v_mfma_f32_16x16x32_bf16 v[12:15], v[132:135], v[202:205], v[12:15]
	v_mfma_f32_16x16x32_bf16 v[8:11], v[144:147], v[202:205], v[8:11]
	v_mfma_f32_16x16x32_bf16 v[60:63], v[140:143], v[156:159], v[60:63]
	v_mfma_f32_16x16x32_bf16 v[56:59], v[148:151], v[156:159], v[56:59]
	v_mfma_f32_16x16x32_bf16 v[44:47], v[140:143], v[190:193], v[44:47]
	v_mfma_f32_16x16x32_bf16 v[40:43], v[148:151], v[190:193], v[40:43]
	v_mfma_f32_16x16x32_bf16 v[28:31], v[140:143], v[198:201], v[28:31]
	v_mfma_f32_16x16x32_bf16 v[24:27], v[148:151], v[198:201], v[24:27]
	v_mfma_f32_16x16x32_bf16 v[12:15], v[140:143], v[206:209], v[12:15]
	v_mfma_f32_16x16x32_bf16 v[8:11], v[148:151], v[206:209], v[8:11]
	s_setprio 0
	s_barrier
	v_mov_b32_e32 v80, v163
	s_add_i32 s22, s35, s49
	s_add_i32 m0, s22, 0xffffff80
	v_mov_b32_e32 v80, v165
	global_load_lds_dwordx4 v163, s[38:39] offset:128
	s_add_i32 m0, s22, 0x1f80
	s_nop 0
	global_load_lds_dwordx4 v165, s[38:39] offset:128
	s_waitcnt vmcnt(6)
	s_barrier
	s_setprio 1
	v_mfma_f32_16x16x32_bf16 v[52:55], v[210:213], v[152:155], v[52:55]
	v_mfma_f32_16x16x32_bf16 v[48:51], v[238:241], v[152:155], v[48:51]
	v_mfma_f32_16x16x32_bf16 v[36:39], v[210:213], v[174:177], v[36:39]
	v_mfma_f32_16x16x32_bf16 v[32:35], v[238:241], v[174:177], v[32:35]
	v_mfma_f32_16x16x32_bf16 v[20:23], v[210:213], v[194:197], v[20:23]
	v_mfma_f32_16x16x32_bf16 v[16:19], v[238:241], v[194:197], v[16:19]
	v_mfma_f32_16x16x32_bf16 v[4:7], v[210:213], v[202:205], v[4:7]
	v_mfma_f32_16x16x32_bf16 v[0:3], v[238:241], v[202:205], v[0:3]
	v_mfma_f32_16x16x32_bf16 v[52:55], v[214:217], v[156:159], v[52:55]
	v_mfma_f32_16x16x32_bf16 v[48:51], v[242:245], v[156:159], v[48:51]
	v_mfma_f32_16x16x32_bf16 v[36:39], v[214:217], v[190:193], v[36:39]
	v_mfma_f32_16x16x32_bf16 v[32:35], v[242:245], v[190:193], v[32:35]
	v_mfma_f32_16x16x32_bf16 v[20:23], v[214:217], v[198:201], v[20:23]
	v_mfma_f32_16x16x32_bf16 v[16:19], v[242:245], v[198:201], v[16:19]
	v_mfma_f32_16x16x32_bf16 v[4:7], v[214:217], v[206:209], v[4:7]
	v_mfma_f32_16x16x32_bf16 v[0:3], v[242:245], v[206:209], v[0:3]
	s_setprio 0
	s_add_i32 s34, s34, 2
	s_add_u32 s30, s30, 0x100
	s_addc_u32 s31, s31, 0
	s_add_u32 s2, s2, 0x100
	s_addc_u32 s3, s3, 0
	s_cmp_gt_u32 s34, 29
	s_barrier
	s_cbranch_scc0 .LBB0_589
	s_nop 1
	v_add_u32_e32 v140, s0, v166
	v_ashrrev_i32_e32 v141, 31, v140
	v_lshl_add_u64 v[134:135], v[140:141], 3, s[40:41]
	global_load_dwordx2 v[132:133], v[134:135], off
	global_load_dwordx2 v[150:151], v[134:135], off offset:128
	global_load_dwordx2 v[158:159], v[134:135], off offset:256
	global_load_dwordx2 v[156:157], v[134:135], off offset:384
	global_load_dwordx2 v[154:155], v[134:135], off offset:1024
	global_load_dwordx2 v[152:153], v[134:135], off offset:1152
	global_load_dwordx2 v[148:149], v[134:135], off offset:1280
	global_load_dwordx2 v[144:145], v[134:135], off offset:1408
	v_mul_f32_e32 v135, v127, v127
	v_mul_f32_e32 v136, v119, v119
	v_fmac_f32_e32 v135, v126, v126
	v_fmac_f32_e32 v136, v118, v118
	v_fmac_f32_e32 v135, v128, v128
	v_fmac_f32_e32 v136, v120, v120
	v_fmac_f32_e32 v135, v129, v129
	v_fmac_f32_e32 v136, v121, v121
	v_and_b32_e32 v134, 64, v189
	v_fmac_f32_e32 v135, v122, v122
	v_fmac_f32_e32 v136, v114, v114
	v_xor_b32_e32 v80, 16, v189
	v_add_u32_e32 v134, 64, v134
	v_fmac_f32_e32 v135, v123, v123
	v_fmac_f32_e32 v136, v115, v115
	v_cmp_lt_i32_e64 s[2:3], v80, v134
	v_fmac_f32_e32 v135, v124, v124
	v_fmac_f32_e32 v136, v116, v116
	v_cndmask_b32_e64 v80, v189, v80, s[2:3]
	v_fmac_f32_e32 v135, v125, v125
	v_fmac_f32_e32 v136, v117, v117
	v_lshlrev_b32_e32 v80, 2, v80
	v_add_f32_e32 v135, v135, v136
	ds_bpermute_b32 v136, v80, v135
	v_xor_b32_e32 v137, 32, v189
	v_cmp_lt_i32_e64 s[2:3], v137, v134
	v_readfirstlane_b32 s38, v130
	v_readfirstlane_b32 s44, v131
	v_cndmask_b32_e64 v134, v189, v137, s[2:3]
	v_lshlrev_b32_e32 v134, 2, v134
	s_waitcnt lgkmcnt(0)
	v_add_f32_e32 v135, v135, v136
	ds_bpermute_b32 v136, v134, v135
	v_add_u32_e32 v130, s76, v168
	s_and_saveexec_b64 s[2:3], vcc
	s_cbranch_execz .LBB0_592
	s_waitcnt lgkmcnt(0)
	v_add_f32_e32 v131, v135, v136
	ds_write_b32 v130, v131

; #define G_STAGE(bufoff, gbase, voff) do { _Pragma("unroll") for (int _i = 0; _i < 2; ++_i) { unsigned _vo = (voff)[_i]; asm volatile("" : "+v"(_vo));   \
;     __builtin_amdgcn_global_load_lds((const unsigned*)((const char*)(gbase) + _vo), (LAS unsigned*)(lds + (bufoff) + ldsw + _i * 8192), 16, 0, 0); } } while (0)
; #define G_LDA(dst, b, h) do { _Pragma("unroll") for (int m = 0; m < 4; ++m) _Pragma("unroll") for (int k = 0; k < 2; ++k) dst[m][k] = *(const LAS bf16x8*)(lds + G_SA(b, h) + aoff + m * 2048 + k * 1024); } while (0)
; #define G_LDB(dst, b, h) do { _Pragma("unroll") for (int n = 0; n < 2; ++n) _Pragma("unroll") for (int k = 0; k < 2; ++k) dst[n][k] = *(const LAS bf16x8*)(lds + G_SB(b, h) + boff + n * 2048 + k * 1024); } while (0)
; #define G_MMA(ai, bj, At, Bt) do { __builtin_amdgcn_s_setprio(1); _Pragma("unroll") for (int m = 0; m < 4; ++m) _Pragma("unroll") for (int n = 0; n < 2; ++n) _Pragma("unroll") for (int k = 0; k < 2; ++k) \
;     acc[ai][bj][m][n] = __builtin_amdgcn_mfma_f32_16x16x32_bf16(Bt[n][k], At[m][k], acc[ai][bj][m][n], 0, 0, 0); __builtin_amdgcn_s_setprio(0); } while (0)
; #define G_WAIT_L(n) asm volatile("s_waitcnt lgkmcnt(" #n ")" ::: "memory")
; #define G_BAR __builtin_amdgcn_s_barrier()
; #define G_SCHED __builtin_amdgcn_sched_barrier(0)
; template <class Epi>
; __device__ __forceinline__ void gemm_phase(LAS unsigned char* lds, const int K, const unsigned lda_b, const unsigned ldb_b, const Map& M, const Epi& E) {
;     ...
;     for (int t = 0; t < nt; t += 2) {
;       const bool last = (t == nt - 2);
;       const char* a1h1 = cur.a0 + a_h + (size_t)(t + 1) * kstep;
;       const char* a2h0 = last ? nxt.a0 : cur.a0 + (size_t)(t + 2) * kstep; const char* a2h1 = a2h0 + a_h;
;       const char* b2h0 = last ? nxt.b0 : cur.b0 + (size_t)(t + 2) * kstep; const char* b2h1 = last ? nxt.b1 : cur.b1 + (size_t)(t + 2) * kstep;
;       G_LDB(B0, 0, 0); G_SCHED; G_LDA(At, 0, 0); G_STAGE(G_SA(1, 1), a1h1, voffA);
;       G_WAIT_L(8); G_BAR; G_WAIT_L(0); G_MMA(0, 0, At, B0); G_BAR; G_SCHED;
;       G_LDB(B1, 0, 1); G_STAGE(G_SB(0, 0), b2h0, voffB);
;       G_BAR; G_WAIT_L(0); G_MMA(0, 1, At, B1); G_BAR;
;       G_LDA(At, 0, 1); G_STAGE(G_SA(0, 0), a2h0, voffA);
;       G_BAR; G_WAIT_L(0); G_MMA(1, 0, At, B0); G_BAR; G_SCHED;
.LBB0_626:
	s_add_u32 s22, s38, 0xfff80080
	s_addc_u32 s35, s39, -1
	s_add_u32 s42, s30, 0xfffe0000
	s_addc_u32 s43, s31, -1
	s_add_i32 s81, 0, 0x10000
	v_add_u32_e32 v0, s81, v149
	ds_read_b128 v[136:139], v0
	ds_read_b128 v[140:143], v0 offset:1024
	ds_read_b128 v[154:157], v0 offset:2048
	ds_read_b128 v[158:161], v0 offset:3072
	s_cmp_eq_u32 s34, 28
	s_cselect_b32 s45, s37, s35
	s_cselect_b32 s44, s36, s22
	s_cselect_b32 s69, s41, s43
	s_cselect_b32 s68, s40, s42
	v_mov_b32_e32 v0, v144
	s_cselect_b32 s43, s29, s31
	s_cselect_b32 s42, s28, s30
	s_add_u32 s94, s44, 0x80000
	ds_read_b128 v[164:167], v153
	ds_read_b128 v[168:171], v153 offset:1024
	ds_read_b128 v[172:175], v153 offset:2048
	ds_read_b128 v[190:193], v153 offset:3072
	ds_read_b128 v[194:197], v153 offset:4096
	ds_read_b128 v[198:201], v153 offset:5120
	ds_read_b128 v[202:205], v153 offset:6144
	ds_read_b128 v[206:209], v153 offset:7168
	s_addc_u32 s95, s45, 0
	s_add_i32 m0, s18, 0xc000
	s_nop 0
	global_load_lds_dwordx4 v0, s[38:39]
	v_mov_b32_e32 v0, v146
	s_add_i32 m0, s18, 0xe000
	s_nop 0
	global_load_lds_dwordx4 v0, s[38:39]
	s_waitcnt lgkmcnt(8)
	s_barrier
	s_waitcnt lgkmcnt(0)
	s_setprio 1
	s_waitcnt lgkmcnt(0)
	v_mfma_f32_16x16x32_bf16 v[130:133], v[136:139], v[164:167], v[130:133]
	v_mfma_f32_16x16x32_bf16 v[126:129], v[154:157], v[164:167], v[126:129]
	v_mfma_f32_16x16x32_bf16 v[114:117], v[136:139], v[172:175], v[114:117]
	v_mfma_f32_16x16x32_bf16 v[110:113], v[154:157], v[172:175], v[110:113]
	v_mfma_f32_16x16x32_bf16 v[98:101], v[136:139], v[194:197], v[98:101]
	v_mfma_f32_16x16x32_bf16 v[94:97], v[154:157], v[194:197], v[94:97]
	v_mfma_f32_16x16x32_bf16 v[82:85], v[136:139], v[202:205], v[82:85]
	v_mfma_f32_16x16x32_bf16 v[76:79], v[154:157], v[202:205], v[76:79]
	v_mfma_f32_16x16x32_bf16 v[130:133], v[140:143], v[168:171], v[130:133]
	v_mfma_f32_16x16x32_bf16 v[126:129], v[158:161], v[168:171], v[126:129]
	v_mfma_f32_16x16x32_bf16 v[114:117], v[140:143], v[190:193], v[114:117]
	v_mfma_f32_16x16x32_bf16 v[110:113], v[158:161], v[190:193], v[110:113]
	v_mfma_f32_16x16x32_bf16 v[98:101], v[140:143], v[198:201], v[98:101]
	v_mfma_f32_16x16x32_bf16 v[94:97], v[158:161], v[198:201], v[94:97]
	v_mfma_f32_16x16x32_bf16 v[82:85], v[140:143], v[206:209], v[82:85]
	v_mfma_f32_16x16x32_bf16 v[76:79], v[158:161], v[206:209], v[76:79]
	s_setprio 0
	s_barrier
	s_add_i32 s22, 0, 0x14000
	v_add_u32_e32 v0, s22, v149
	ds_read_b128 v[210:213], v0
	ds_read_b128 v[214:217], v0 offset:1024
	ds_read_b128 v[238:241], v0 offset:2048
	ds_read_b128 v[242:245], v0 offset:3072
	v_mov_b32_e32 v0, v145
	s_add_i32 s35, s81, s13
	s_mov_b32 m0, s35
	s_nop 0
	global_load_lds_dwordx4 v0, s[68:69]
	v_mov_b32_e32 v0, v147
	s_add_i32 m0, s35, 0x2000
	s_nop 0
	global_load_lds_dwordx4 v0, s[68:69]
	s_barrier
	s_waitcnt lgkmcnt(0)
	s_setprio 1
	s_waitcnt lgkmcnt(0)
	v_mfma_f32_16x16x32_bf16 v[122:125], v[210:213], v[164:167], v[122:125]
	v_mfma_f32_16x16x32_bf16 v[118:121], v[238:241], v[164:167], v[118:121]
	v_mfma_f32_16x16x32_bf16 v[106:109], v[210:213], v[172:175], v[106:109]
	v_mfma_f32_16x16x32_bf16 v[102:105], v[238:241], v[172:175], v[102:105]
	v_mfma_f32_16x16x32_bf16 v[90:93], v[210:213], v[194:197], v[90:93]
	v_mfma_f32_16x16x32_bf16 v[86:89], v[238:241], v[194:197], v[86:89]
	v_mfma_f32_16x16x32_bf16 v[72:75], v[210:213], v[202:205], v[72:75]
	v_mfma_f32_16x16x32_bf16 v[68:71], v[238:241], v[202:205], v[68:71]
	v_mfma_f32_16x16x32_bf16 v[122:125], v[214:217], v[168:171], v[122:125]
	v_mfma_f32_16x16x32_bf16 v[118:121], v[242:245], v[168:171], v[118:121]
	v_mfma_f32_16x16x32_bf16 v[106:109], v[214:217], v[190:193], v[106:109]
	v_mfma_f32_16x16x32_bf16 v[102:105], v[242:245], v[190:193], v[102:105]
	v_mfma_f32_16x16x32_bf16 v[90:93], v[214:217], v[198:201], v[90:93]
	v_mfma_f32_16x16x32_bf16 v[86:89], v[242:245], v[198:201], v[86:89]
	v_mfma_f32_16x16x32_bf16 v[72:75], v[214:217], v[206:209], v[72:75]
	v_mfma_f32_16x16x32_bf16 v[68:71], v[242:245], v[206:209], v[68:71]
	s_setprio 0
	v_mov_b32_e32 v0, v144
	s_mov_b32 m0, s18
	s_barrier
	ds_read_b128 v[164:167], v153 offset:16384
	ds_read_b128 v[168:171], v153 offset:17408
	ds_read_b128 v[172:175], v153 offset:18432
	ds_read_b128 v[190:193], v153 offset:19456
	ds_read_b128 v[194:197], v153 offset:20480
	ds_read_b128 v[198:201], v153 offset:21504
	ds_read_b128 v[202:205], v153 offset:22528
	ds_read_b128 v[206:209], v153 offset:23552
	s_nop 0
	global_load_lds_dwordx4 v0, s[44:45]
	v_mov_b32_e32 v0, v146
	s_mov_b32 m0, s19
	s_nop 0
	global_load_lds_dwordx4 v0, s[44:45]
	s_barrier
	s_waitcnt lgkmcnt(0)
	s_setprio 1
	s_waitcnt lgkmcnt(0)
	v_mfma_f32_16x16x32_bf16 v[64:67], v[136:139], v[164:167], v[64:67]
	v_mfma_f32_16x16x32_bf16 v[60:63], v[154:157], v[164:167], v[60:63]
	v_mfma_f32_16x16x32_bf16 v[48:51], v[136:139], v[172:175], v[48:51]
	v_mfma_f32_16x16x32_bf16 v[44:47], v[154:157], v[172:175], v[44:47]
	v_mfma_f32_16x16x32_bf16 v[32:35], v[136:139], v[194:197], v[32:35]
	v_mfma_f32_16x16x32_bf16 v[28:31], v[154:157], v[194:197], v[28:31]
	v_mfma_f32_16x16x32_bf16 v[16:19], v[136:139], v[202:205], v[16:19]
	v_mfma_f32_16x16x32_bf16 v[12:15], v[154:157], v[202:205], v[12:15]
	v_mfma_f32_16x16x32_bf16 v[64:67], v[140:143], v[168:171], v[64:67]
	v_mfma_f32_16x16x32_bf16 v[60:63], v[158:161], v[168:171], v[60:63]
	v_mfma_f32_16x16x32_bf16 v[48:51], v[140:143], v[190:193], v[48:51]
	v_mfma_f32_16x16x32_bf16 v[44:47], v[158:161], v[190:193], v[44:47]
	v_mfma_f32_16x16x32_bf16 v[32:35], v[140:143], v[198:201], v[32:35]
	v_mfma_f32_16x16x32_bf16 v[28:31], v[158:161], v[198:201], v[28:31]
	v_mfma_f32_16x16x32_bf16 v[16:19], v[140:143], v[206:209], v[16:19]
	v_mfma_f32_16x16x32_bf16 v[12:15], v[158:161], v[206:209], v[12:15]
	s_setprio 0
	s_barrier
; #define G_STAGE(bufoff, gbase, voff) do { _Pragma("unroll") for (int _i = 0; _i < 2; ++_i) { unsigned _vo = (voff)[_i]; asm volatile("" : "+v"(_vo));   \
;     __builtin_amdgcn_global_load_lds((const unsigned*)((const char*)(gbase) + _vo), (LAS unsigned*)(lds + (bufoff) + ldsw + _i * 8192), 16, 0, 0); } } while (0)
; #define G_LDA(dst, b, h) do { _Pragma("unroll") for (int m = 0; m < 4; ++m) _Pragma("unroll") for (int k = 0; k < 2; ++k) dst[m][k] = *(const LAS bf16x8*)(lds + G_SA(b, h) + aoff + m * 2048 + k * 1024); } while (0)
; #define G_LDB(dst, b, h) do { _Pragma("unroll") for (int n = 0; n < 2; ++n) _Pragma("unroll") for (int k = 0; k < 2; ++k) dst[n][k] = *(const LAS bf16x8*)(lds + G_SB(b, h) + boff + n * 2048 + k * 1024); } while (0)
; #define G_MMA(ai, bj, At, Bt) do { __builtin_amdgcn_s_setprio(1); _Pragma("unroll") for (int m = 0; m < 4; ++m) _Pragma("unroll") for (int n = 0; n < 2; ++n) _Pragma("unroll") for (int k = 0; k < 2; ++k) \
;     acc[ai][bj][m][n] = __builtin_amdgcn_mfma_f32_16x16x32_bf16(Bt[n][k], At[m][k], acc[ai][bj][m][n], 0, 0, 0); __builtin_amdgcn_s_setprio(0); } while (0)
; #define G_WAIT_V(n) asm volatile("s_waitcnt vmcnt(" #n ")" ::: "memory")
; #define G_WAIT_L(n) asm volatile("s_waitcnt lgkmcnt(" #n ")" ::: "memory")
; #define G_BAR __builtin_amdgcn_s_barrier()
; #define G_SCHED __builtin_amdgcn_sched_barrier(0)
; template <class Epi>
; __device__ __forceinline__ void gemm_phase(LAS unsigned char* lds, const int K, const unsigned lda_b, const unsigned ldb_b, const Map& M, const Epi& E) {
;     ...
;       G_STAGE(G_SB(0, 1), b2h1, voffB);
;       G_WAIT_V(6); G_BAR; G_MMA(1, 1, At, B1); G_BAR;
;       G_LDB(B0, 1, 0); G_SCHED; G_LDA(At, 1, 0); G_STAGE(G_SA(0, 1), a2h1, voffA);
;       G_WAIT_L(8); G_BAR; G_WAIT_L(0); G_MMA(0, 0, At, B0); G_BAR; G_SCHED;
;       G_LDB(B1, 1, 1); G_STAGE(G_SB(1, 0), b2h0 + kstep, voffB);
;       G_BAR; G_WAIT_L(0); G_MMA(0, 1, At, B1); G_BAR;
;       G_LDA(At, 1, 1); G_STAGE(G_SA(1, 0), a2h0 + kstep, voffA);
	v_mov_b32_e32 v0, v145
	s_add_i32 s22, s22, s13
	s_mov_b32 m0, s22
	s_nop 0
	global_load_lds_dwordx4 v0, s[42:43]
	v_mov_b32_e32 v0, v147
	s_add_i32 m0, s22, 0x2000
	s_nop 0
	global_load_lds_dwordx4 v0, s[42:43]
	s_waitcnt vmcnt(6)
	s_barrier
	s_setprio 1
	v_mfma_f32_16x16x32_bf16 v[56:59], v[210:213], v[164:167], v[56:59]
	v_mfma_f32_16x16x32_bf16 v[52:55], v[238:241], v[164:167], v[52:55]
	v_mfma_f32_16x16x32_bf16 v[40:43], v[210:213], v[172:175], v[40:43]
	v_mfma_f32_16x16x32_bf16 v[36:39], v[238:241], v[172:175], v[36:39]
	v_mfma_f32_16x16x32_bf16 v[24:27], v[210:213], v[194:197], v[24:27]
	v_mfma_f32_16x16x32_bf16 v[20:23], v[238:241], v[194:197], v[20:23]
	v_mfma_f32_16x16x32_bf16 v[8:11], v[210:213], v[202:205], v[8:11]
	v_mfma_f32_16x16x32_bf16 v[4:7], v[238:241], v[202:205], v[4:7]
	v_mfma_f32_16x16x32_bf16 v[56:59], v[214:217], v[168:171], v[56:59]
	v_mfma_f32_16x16x32_bf16 v[52:55], v[242:245], v[168:171], v[52:55]
	v_mfma_f32_16x16x32_bf16 v[40:43], v[214:217], v[190:193], v[40:43]
	v_mfma_f32_16x16x32_bf16 v[36:39], v[242:245], v[190:193], v[36:39]
	v_mfma_f32_16x16x32_bf16 v[24:27], v[214:217], v[198:201], v[24:27]
	v_mfma_f32_16x16x32_bf16 v[20:23], v[242:245], v[198:201], v[20:23]
	v_mfma_f32_16x16x32_bf16 v[8:11], v[214:217], v[206:209], v[8:11]
	v_mfma_f32_16x16x32_bf16 v[4:7], v[242:245], v[206:209], v[4:7]
	s_setprio 0
	s_add_i32 s22, 0, 0x18000
	v_add_u32_e32 v0, s22, v149
	s_barrier
	ds_read_b128 v[136:139], v0
	ds_read_b128 v[140:143], v0 offset:1024
	ds_read_b128 v[154:157], v0 offset:2048
	ds_read_b128 v[158:161], v0 offset:3072
	v_mov_b32_e32 v0, v144
	s_mov_b32 m0, s46
	ds_read_b128 v[164:167], v153 offset:32768
	ds_read_b128 v[168:171], v153 offset:33792
	ds_read_b128 v[172:175], v153 offset:34816
	ds_read_b128 v[190:193], v153 offset:35840
	ds_read_b128 v[194:197], v153 offset:36864
	ds_read_b128 v[198:201], v153 offset:37888
	ds_read_b128 v[202:205], v153 offset:38912
	ds_read_b128 v[206:209], v153 offset:39936
	s_nop 0
	global_load_lds_dwordx4 v0, s[94:95]
	v_mov_b32_e32 v0, v146
	s_mov_b32 m0, s47
	s_nop 0
	global_load_lds_dwordx4 v0, s[94:95]
	s_waitcnt lgkmcnt(8)
	s_barrier
	s_waitcnt lgkmcnt(0)
	s_setprio 1
	s_waitcnt lgkmcnt(0)
	v_mfma_f32_16x16x32_bf16 v[130:133], v[136:139], v[164:167], v[130:133]
	v_mfma_f32_16x16x32_bf16 v[126:129], v[154:157], v[164:167], v[126:129]
	v_mfma_f32_16x16x32_bf16 v[114:117], v[136:139], v[172:175], v[114:117]
	v_mfma_f32_16x16x32_bf16 v[110:113], v[154:157], v[172:175], v[110:113]
	v_mfma_f32_16x16x32_bf16 v[98:101], v[136:139], v[194:197], v[98:101]
	v_mfma_f32_16x16x32_bf16 v[94:97], v[154:157], v[194:197], v[94:97]
	v_mfma_f32_16x16x32_bf16 v[82:85], v[136:139], v[202:205], v[82:85]
	v_mfma_f32_16x16x32_bf16 v[76:79], v[154:157], v[202:205], v[76:79]
	v_mfma_f32_16x16x32_bf16 v[130:133], v[140:143], v[168:171], v[130:133]
	v_mfma_f32_16x16x32_bf16 v[126:129], v[158:161], v[168:171], v[126:129]
	v_mfma_f32_16x16x32_bf16 v[114:117], v[140:143], v[190:193], v[114:117]
	v_mfma_f32_16x16x32_bf16 v[110:113], v[158:161], v[190:193], v[110:113]
	v_mfma_f32_16x16x32_bf16 v[98:101], v[140:143], v[198:201], v[98:101]
	v_mfma_f32_16x16x32_bf16 v[94:97], v[158:161], v[198:201], v[94:97]
	v_mfma_f32_16x16x32_bf16 v[82:85], v[140:143], v[206:209], v[82:85]
	v_mfma_f32_16x16x32_bf16 v[76:79], v[158:161], v[206:209], v[76:79]
	s_setprio 0
	s_barrier
	s_add_i32 s35, 0, 0x1c000
	v_add_u32_e32 v0, s35, v149
	v_mov_b32_e32 v80, v145
	ds_read_b128 v[210:213], v0
	ds_read_b128 v[214:217], v0 offset:1024
	ds_read_b128 v[238:241], v0 offset:2048
	ds_read_b128 v[242:245], v0 offset:3072
	s_add_i32 s22, s22, s13
	s_add_i32 m0, s22, 0xffffff80
	v_mov_b32_e32 v80, v147
	global_load_lds_dwordx4 v145, s[68:69] offset:128
	s_add_i32 m0, s22, 0x1f80
	s_nop 0
	global_load_lds_dwordx4 v147, s[68:69] offset:128
	s_barrier
	s_waitcnt lgkmcnt(0)
	s_setprio 1
	s_waitcnt lgkmcnt(0)
	v_mfma_f32_16x16x32_bf16 v[122:125], v[210:213], v[164:167], v[122:125]
	v_mfma_f32_16x16x32_bf16 v[118:121], v[238:241], v[164:167], v[118:121]
	v_mfma_f32_16x16x32_bf16 v[106:109], v[210:213], v[172:175], v[106:109]
	v_mfma_f32_16x16x32_bf16 v[102:105], v[238:241], v[172:175], v[102:105]
	v_mfma_f32_16x16x32_bf16 v[90:93], v[210:213], v[194:197], v[90:93]
	v_mfma_f32_16x16x32_bf16 v[86:89], v[238:241], v[194:197], v[86:89]
	v_mfma_f32_16x16x32_bf16 v[72:75], v[210:213], v[202:205], v[72:75]
	v_mfma_f32_16x16x32_bf16 v[68:71], v[238:241], v[202:205], v[68:71]
	v_mfma_f32_16x16x32_bf16 v[122:125], v[214:217], v[168:171], v[122:125]
	v_mfma_f32_16x16x32_bf16 v[118:121], v[242:245], v[168:171], v[118:121]
	v_mfma_f32_16x16x32_bf16 v[106:109], v[214:217], v[190:193], v[106:109]
	v_mfma_f32_16x16x32_bf16 v[102:105], v[242:245], v[190:193], v[102:105]
	v_mfma_f32_16x16x32_bf16 v[90:93], v[214:217], v[198:201], v[90:93]
	v_mfma_f32_16x16x32_bf16 v[86:89], v[242:245], v[198:201], v[86:89]
	v_mfma_f32_16x16x32_bf16 v[72:75], v[214:217], v[206:209], v[72:75]
	v_mfma_f32_16x16x32_bf16 v[68:71], v[242:245], v[206:209], v[68:71]
	s_setprio 0
	v_mov_b32_e32 v80, v144
	s_barrier
	ds_read_b128 v[164:167], v153 offset:49152
	ds_read_b128 v[168:171], v153 offset:50176
	ds_read_b128 v[172:175], v153 offset:51200
	ds_read_b128 v[190:193], v153 offset:52224
	ds_read_b128 v[194:197], v153 offset:53248
	ds_read_b128 v[198:201], v153 offset:54272
	ds_read_b128 v[202:205], v153 offset:55296
	ds_read_b128 v[206:209], v153 offset:56320
	s_add_i32 m0, s48, 0xffffff80
	v_mov_b32_e32 v80, v146
	global_load_lds_dwordx4 v144, s[44:45] offset:128
	s_add_i32 m0, s49, 0xffffff80
	s_nop 0
	global_load_lds_dwordx4 v146, s[44:45] offset:128
	s_barrier
; __device__ __forceinline__ unsigned cvt_pk_bf16(float lo, float hi) { unsigned r; asm("v_cvt_pk_bf16_f32 %0, %1, %2" : "=v"(r) : "v"(lo), "v"(hi)); return r; }
; __device__ __forceinline__ float rinv_of(unsigned long long ss) { return rsqrtf((float)ss * (1.f / 16777216.f) * (1.f / DM) + 1e-6f); }
; #define G_STAGE(bufoff, gbase, voff) do { _Pragma("unroll") for (int _i = 0; _i < 2; ++_i) { unsigned _vo = (voff)[_i]; asm volatile("" : "+v"(_vo));   \
;     __builtin_amdgcn_global_load_lds((const unsigned*)((const char*)(gbase) + _vo), (LAS unsigned*)(lds + (bufoff) + ldsw + _i * 8192), 16, 0, 0); } } while (0)
; #define G_WAIT_V(n) asm volatile("s_waitcnt vmcnt(" #n ")" ::: "memory")
;   __device__ __forceinline__ void operator()(const f32x4 (&acc)[2][2][4][2], const Unit& u, const EpiCtx& x_, int wr, int wc, int fr, int fq) const {
;     ...
;     for (int ai = 0; ai < 2; ++ai)
; #pragma unroll
;       for (int m = 0; m < 4; ++m) {
;         const int row = (u.r0 + (ai ? x_.rdelta : 0)) + wr * 64 + m * 16 + fr;
;         bf16_t* rowp = (bf16_t*)u.C + (size_t)row * x_.ldc;
;         const float rs = (SCALE == 1) ? rinv_of(x_.ss[row]) : 1.f;
; #pragma unroll
;         for (int bj = 0; bj < 2; ++bj) {
;           const int cb = PERM ? (u.c0 + wc * 64 + bj * 32) : (u.c0 + bj * 128) + wc * 32;
;           f32x4 v0 = acc[ai][bj][m][0], v1 = acc[ai][bj][m][1];
;           if (SCALE == 1) { v0 *= rs; v1 *= rs; }
;           if (SCALE == 2) { v0 *= cs[bj][0]; v1 *= cs[bj][1]; }
;           if (PERM) {
;             uint4 o; o.x = cvt_pk_bf16(v0[0], v0[1]); o.y = cvt_pk_bf16(v0[2], v0[3]); o.z = cvt_pk_bf16(v1[0], v1[1]); o.w = cvt_pk_bf16(v1[2], v1[3]);
;             *(uint4*)(rowp + cb + 8 * fq) = o;
;           } else {
;             uint2 o0, o1; o0.x = cvt_pk_bf16(v0[0], v0[1]); o0.y = cvt_pk_bf16(v0[2], v0[3]); o1.x = cvt_pk_bf16(v1[0], v1[1]); o1.y = cvt_pk_bf16(v1[2], v1[3]);
;             *(uint2*)(rowp + cb + 4 * fq) = o0; *(uint2*)(rowp + cb + 16 + 4 * fq) = o1;
;           }
; template <class Epi>
; __device__ __forceinline__ void gemm_phase(LAS unsigned char* lds, const int K, const unsigned lda_b, const unsigned ldb_b, const Map& M, const Epi& E) {
;     ...
;       G_BAR; G_WAIT_L(0); G_MMA(1, 0, At, B0); G_BAR; G_SCHED;
;       G_STAGE(G_SB(1, 1), b2h1 + kstep, voffB);
;       G_WAIT_V(6); G_BAR; G_MMA(1, 1, At, B1); G_BAR;
;     }
	s_waitcnt lgkmcnt(0)
	s_setprio 1
	s_waitcnt lgkmcnt(0)
	v_mfma_f32_16x16x32_bf16 v[64:67], v[136:139], v[164:167], v[64:67]
	v_mfma_f32_16x16x32_bf16 v[60:63], v[154:157], v[164:167], v[60:63]
	v_mfma_f32_16x16x32_bf16 v[48:51], v[136:139], v[172:175], v[48:51]
	v_mfma_f32_16x16x32_bf16 v[44:47], v[154:157], v[172:175], v[44:47]
	v_mfma_f32_16x16x32_bf16 v[32:35], v[136:139], v[194:197], v[32:35]
	v_mfma_f32_16x16x32_bf16 v[28:31], v[154:157], v[194:197], v[28:31]
	v_mfma_f32_16x16x32_bf16 v[16:19], v[136:139], v[202:205], v[16:19]
	v_mfma_f32_16x16x32_bf16 v[12:15], v[154:157], v[202:205], v[12:15]
	v_mfma_f32_16x16x32_bf16 v[64:67], v[140:143], v[168:171], v[64:67]
	v_mfma_f32_16x16x32_bf16 v[60:63], v[158:161], v[168:171], v[60:63]
	v_mfma_f32_16x16x32_bf16 v[48:51], v[140:143], v[190:193], v[48:51]
	v_mfma_f32_16x16x32_bf16 v[44:47], v[158:161], v[190:193], v[44:47]
	v_mfma_f32_16x16x32_bf16 v[32:35], v[140:143], v[198:201], v[32:35]
	v_mfma_f32_16x16x32_bf16 v[28:31], v[158:161], v[198:201], v[28:31]
	v_mfma_f32_16x16x32_bf16 v[16:19], v[140:143], v[206:209], v[16:19]
	v_mfma_f32_16x16x32_bf16 v[12:15], v[158:161], v[206:209], v[12:15]
	s_setprio 0
	s_barrier
	v_mov_b32_e32 v80, v145
	s_add_i32 s22, s35, s13
	s_add_i32 m0, s22, 0xffffff80
	v_mov_b32_e32 v80, v147
	global_load_lds_dwordx4 v145, s[42:43] offset:128
	s_add_i32 m0, s22, 0x1f80
	s_nop 0
	global_load_lds_dwordx4 v147, s[42:43] offset:128
	s_waitcnt vmcnt(6)
	s_barrier
	s_setprio 1
	v_mfma_f32_16x16x32_bf16 v[56:59], v[210:213], v[164:167], v[56:59]
	v_mfma_f32_16x16x32_bf16 v[52:55], v[238:241], v[164:167], v[52:55]
	v_mfma_f32_16x16x32_bf16 v[40:43], v[210:213], v[172:175], v[40:43]
	v_mfma_f32_16x16x32_bf16 v[36:39], v[238:241], v[172:175], v[36:39]
	v_mfma_f32_16x16x32_bf16 v[24:27], v[210:213], v[194:197], v[24:27]
	v_mfma_f32_16x16x32_bf16 v[20:23], v[238:241], v[194:197], v[20:23]
	v_mfma_f32_16x16x32_bf16 v[8:11], v[210:213], v[202:205], v[8:11]
	v_mfma_f32_16x16x32_bf16 v[4:7], v[238:241], v[202:205], v[4:7]
	v_mfma_f32_16x16x32_bf16 v[56:59], v[214:217], v[168:171], v[56:59]
	v_mfma_f32_16x16x32_bf16 v[52:55], v[242:245], v[168:171], v[52:55]
	v_mfma_f32_16x16x32_bf16 v[40:43], v[214:217], v[190:193], v[40:43]
	v_mfma_f32_16x16x32_bf16 v[36:39], v[242:245], v[190:193], v[36:39]
	v_mfma_f32_16x16x32_bf16 v[24:27], v[214:217], v[198:201], v[24:27]
	v_mfma_f32_16x16x32_bf16 v[20:23], v[242:245], v[198:201], v[20:23]
	v_mfma_f32_16x16x32_bf16 v[8:11], v[214:217], v[206:209], v[8:11]
	v_mfma_f32_16x16x32_bf16 v[4:7], v[242:245], v[206:209], v[4:7]
	s_setprio 0
	s_add_i32 s34, s34, 2
	s_add_u32 s30, s30, 0x100
	s_addc_u32 s31, s31, 0
	s_add_u32 s38, s38, 0x100
	s_addc_u32 s39, s39, 0
	s_cmp_gt_u32 s34, 29
	s_barrier
	s_cbranch_scc0 .LBB0_626
	s_nop 1
	v_add_u32_e32 v192, s76, v148
	v_ashrrev_i32_e32 v193, 31, v192
	v_lshl_add_u64 v[194:195], v[192:193], 3, s[4:5]
	global_load_dwordx2 v[160:161], v[194:195], off
	v_add_u32_e32 v196, s76, v150
	v_ashrrev_i32_e32 v197, 31, v196
	v_lshl_add_u64 v[198:199], v[196:197], 3, s[4:5]
	global_load_dwordx2 v[164:165], v[198:199], off
	v_add_u32_e32 v200, s76, v151
	v_ashrrev_i32_e32 v201, 31, v200
	v_lshl_add_u64 v[202:203], v[200:201], 3, s[4:5]
	global_load_dwordx2 v[166:167], v[202:203], off
	v_add_u32_e32 v204, s76, v152
	v_ashrrev_i32_e32 v205, 31, v204
	v_lshl_add_u64 v[206:207], v[204:205], 3, s[4:5]
	global_load_dwordx2 v[168:169], v[206:207], off
	global_load_dwordx2 v[170:171], v[194:195], off offset:1024
	global_load_dwordx2 v[172:173], v[198:199], off offset:1024
	global_load_dwordx2 v[174:175], v[202:203], off offset:1024
	global_load_dwordx2 v[190:191], v[206:207], off offset:1024
	v_add_u32_e32 v138, s76, v148
	v_ashrrev_i32_e32 v139, 31, v138
	v_lshl_add_u64 v[140:141], v[138:139], 3, s[4:5]
	s_nop 0
	v_lshlrev_b64 v[154:155], 12, v[138:139]
	s_add_i32 s28, s79, s61
	v_mov_b32_e32 v135, v81
	s_add_i32 s30, s66, s79
	s_ashr_i32 s29, s28, 31
	v_add_u32_e32 v136, s76, v150
	s_ashr_i32 s31, s30, 31
	s_lshl_b64 s[38:39], s[28:29], 1
	v_ashrrev_i32_e32 v137, 31, v136
	s_lshl_b64 s[42:43], s[30:31], 1
	v_lshl_add_u64 v[142:143], v[136:137], 3, s[4:5]
	v_readfirstlane_b32 s79, v3
	s_mov_b64 s[44:45], s[36:37]
	s_mov_b64 s[68:69], s[40:41]
	s_cmp_eq_u32 s75, s67
	s_waitcnt lgkmcnt(0)
	s_waitcnt vmcnt(7)
	v_ffbh_u32_e32 v80, v161
	v_min_u32_e32 v80, 32, v80
	v_lshlrev_b64 v[0:1], v80, v[160:161]
	v_min_u32_e32 v0, 1, v0
	v_or_b32_e32 v0, v1, v0
	v_cvt_f32_u32_e32 v139, v0
	v_sub_u32_e32 v80, 32, v80
	v_lshl_add_u64 v[0:1], s[2:3], 0, v[154:155]
	v_lshl_add_u64 v[0:1], v[0:1], 0, v[134:135]
	v_ldexp_f32 v80, v139, v80
	v_mul_f32_e32 v80, 0x33800000, v80
	v_fmamk_f32 v80, v80, 0x3a000000, v234
	v_mul_f32_e32 v139, 0x4b800000, v80
	v_cmp_gt_f32_e32 vcc, s50, v80
	v_lshl_add_u64 v[154:155], v[0:1], 0, s[38:39]
	v_lshl_add_u64 v[0:1], v[0:1], 0, s[42:43]
	v_cndmask_b32_e32 v80, v80, v139, vcc
	v_rsq_f32_e32 v80, v80
	s_nop 0
	v_mul_f32_e32 v139, 0x45800000, v80
	v_cndmask_b32_e32 v80, v80, v139, vcc
	v_pk_mul_f32 v[132:133], v[132:133], v[80:81] op_sel_hi:[1,0]
	v_pk_mul_f32 v[130:131], v[130:131], v[80:81] op_sel_hi:[1,0]
	v_pk_mul_f32 v[128:129], v[128:129], v[80:81] op_sel_hi:[1,0]
	v_pk_mul_f32 v[126:127], v[126:127], v[80:81] op_sel_hi:[1,0]
	v_pk_mul_f32 v[124:125], v[124:125], v[80:81] op_sel_hi:[1,0]
	v_pk_mul_f32 v[122:123], v[122:123], v[80:81] op_sel_hi:[1,0]
	v_pk_mul_f32 v[156:157], v[120:121], v[80:81] op_sel_hi:[1,0]
	v_pk_mul_f32 v[158:159], v[118:119], v[80:81] op_sel_hi:[1,0]
	v_cvt_pk_bf16_f32 v118, v130, v131
	v_cvt_pk_bf16_f32 v119, v132, v133
	v_cvt_pk_bf16_f32 v120, v126, v127
	v_cvt_pk_bf16_f32 v121, v128, v129
	v_cvt_pk_bf16_f32 v122, v122, v123
	v_cvt_pk_bf16_f32 v123, v124, v125
	s_nop 0
	v_cvt_pk_bf16_f32 v124, v158, v159
	v_cvt_pk_bf16_f32 v125, v156, v157
	global_store_dwordx4 v[154:155], v[118:121], off
	global_store_dwordx4 v[0:1], v[122:125], off
	s_nop 0
	v_add_u32_e32 v118, s76, v151
	v_lshlrev_b64 v[122:123], 12, v[136:137]
	v_ashrrev_i32_e32 v119, 31, v118
	v_lshl_add_u64 v[120:121], v[118:119], 3, s[4:5]
	s_waitcnt lgkmcnt(0)
; __device__ __forceinline__ unsigned cvt_pk_bf16(float lo, float hi) { unsigned r; asm("v_cvt_pk_bf16_f32 %0, %1, %2" : "=v"(r) : "v"(lo), "v"(hi)); return r; }
; __device__ __forceinline__ float rinv_of(unsigned long long ss) { return rsqrtf((float)ss * (1.f / 16777216.f) * (1.f / DM) + 1e-6f); }
;   __device__ __forceinline__ void operator()(const f32x4 (&acc)[2][2][4][2], const Unit& u, const EpiCtx& x_, int wr, int wc, int fr, int fq) const {
;     ...
;     for (int ai = 0; ai < 2; ++ai)
; #pragma unroll
;       for (int m = 0; m < 4; ++m) {
;         const int row = (u.r0 + (ai ? x_.rdelta : 0)) + wr * 64 + m * 16 + fr;
;         bf16_t* rowp = (bf16_t*)u.C + (size_t)row * x_.ldc;
;         const float rs = (SCALE == 1) ? rinv_of(x_.ss[row]) : 1.f;
; #pragma unroll
;         for (int bj = 0; bj < 2; ++bj) {
;           const int cb = PERM ? (u.c0 + wc * 64 + bj * 32) : (u.c0 + bj * 128) + wc * 32;
;           f32x4 v0 = acc[ai][bj][m][0], v1 = acc[ai][bj][m][1];
;           if (SCALE == 1) { v0 *= rs; v1 *= rs; }
;           if (SCALE == 2) { v0 *= cs[bj][0]; v1 *= cs[bj][1]; }
;           if (PERM) {
;             uint4 o; o.x = cvt_pk_bf16(v0[0], v0[1]); o.y = cvt_pk_bf16(v0[2], v0[3]); o.z = cvt_pk_bf16(v1[0], v1[1]); o.w = cvt_pk_bf16(v1[2], v1[3]);
;             *(uint4*)(rowp + cb + 8 * fq) = o;
;           } else {
;             uint2 o0, o1; o0.x = cvt_pk_bf16(v0[0], v0[1]); o0.y = cvt_pk_bf16(v0[2], v0[3]); o1.x = cvt_pk_bf16(v1[0], v1[1]); o1.y = cvt_pk_bf16(v1[2], v1[3]);
;             *(uint2*)(rowp + cb + 4 * fq) = o0; *(uint2*)(rowp + cb + 16 + 4 * fq) = o1;
;           }
	s_waitcnt vmcnt(8)
	v_ffbh_u32_e32 v80, v165
	v_min_u32_e32 v80, 32, v80
	v_lshlrev_b64 v[0:1], v80, v[164:165]
	v_min_u32_e32 v0, 1, v0
	v_or_b32_e32 v0, v1, v0
	v_cvt_f32_u32_e32 v124, v0
	v_sub_u32_e32 v80, 32, v80
	v_lshl_add_u64 v[0:1], s[2:3], 0, v[122:123]
	v_lshl_add_u64 v[0:1], v[0:1], 0, v[134:135]
	v_ldexp_f32 v80, v124, v80
	v_mul_f32_e32 v80, 0x33800000, v80
	v_fmamk_f32 v80, v80, 0x3a000000, v234
	v_mul_f32_e32 v122, 0x4b800000, v80
	v_cmp_gt_f32_e32 vcc, s50, v80
	s_nop 1
	v_cndmask_b32_e32 v80, v80, v122, vcc
	v_rsq_f32_e32 v80, v80
	v_lshl_add_u64 v[122:123], v[0:1], 0, s[38:39]
	v_lshl_add_u64 v[0:1], v[0:1], 0, s[42:43]
	v_mul_f32_e32 v124, 0x45800000, v80
	v_cndmask_b32_e32 v80, v80, v124, vcc
	v_pk_mul_f32 v[116:117], v[116:117], v[80:81] op_sel_hi:[1,0]
	v_pk_mul_f32 v[114:115], v[114:115], v[80:81] op_sel_hi:[1,0]
	v_pk_mul_f32 v[112:113], v[112:113], v[80:81] op_sel_hi:[1,0]
	v_pk_mul_f32 v[110:111], v[110:111], v[80:81] op_sel_hi:[1,0]
	v_pk_mul_f32 v[108:109], v[108:109], v[80:81] op_sel_hi:[1,0]
	v_pk_mul_f32 v[106:107], v[106:107], v[80:81] op_sel_hi:[1,0]
	v_pk_mul_f32 v[124:125], v[104:105], v[80:81] op_sel_hi:[1,0]
	v_pk_mul_f32 v[126:127], v[102:103], v[80:81] op_sel_hi:[1,0]
	v_cvt_pk_bf16_f32 v102, v114, v115
	v_cvt_pk_bf16_f32 v103, v116, v117
	v_cvt_pk_bf16_f32 v104, v110, v111
	v_cvt_pk_bf16_f32 v105, v112, v113
	v_cvt_pk_bf16_f32 v106, v106, v107
	v_cvt_pk_bf16_f32 v107, v108, v109
	s_nop 0
	v_cvt_pk_bf16_f32 v108, v126, v127
	v_cvt_pk_bf16_f32 v109, v124, v125
	global_store_dwordx4 v[122:123], v[102:105], off
	global_store_dwordx4 v[0:1], v[106:109], off
	s_nop 0
	v_lshlrev_b64 v[104:105], 12, v[118:119]
	v_lshl_add_u64 v[104:105], s[2:3], 0, v[104:105]
	v_add_u32_e32 v0, s76, v152
	v_lshl_add_u64 v[104:105], v[104:105], 0, v[134:135]
	v_ashrrev_i32_e32 v1, 31, v0
	v_readfirstlane_b32 s76, v2
	s_waitcnt lgkmcnt(0)
	s_waitcnt vmcnt(9)
	v_ffbh_u32_e32 v80, v167
	v_min_u32_e32 v80, 32, v80
	v_lshlrev_b64 v[102:103], v80, v[166:167]
	v_min_u32_e32 v102, 1, v102
	v_or_b32_e32 v102, v103, v102
	v_cvt_f32_u32_e32 v106, v102
	v_sub_u32_e32 v80, 32, v80
	v_lshl_add_u64 v[102:103], v[0:1], 3, s[4:5]
	v_ldexp_f32 v80, v106, v80
	v_mul_f32_e32 v80, 0x33800000, v80
	v_fmamk_f32 v80, v80, 0x3a000000, v234
	v_mul_f32_e32 v106, 0x4b800000, v80
	v_cmp_gt_f32_e32 vcc, s50, v80
	s_nop 1
	v_cndmask_b32_e32 v80, v80, v106, vcc
	v_rsq_f32_e32 v80, v80
	v_lshl_add_u64 v[106:107], v[104:105], 0, s[38:39]
	v_lshl_add_u64 v[104:105], v[104:105], 0, s[42:43]
	v_mul_f32_e32 v108, 0x45800000, v80
	v_cndmask_b32_e32 v80, v80, v108, vcc
	v_pk_mul_f32 v[100:101], v[100:101], v[80:81] op_sel_hi:[1,0]
	v_pk_mul_f32 v[98:99], v[98:99], v[80:81] op_sel_hi:[1,0]
	v_pk_mul_f32 v[96:97], v[96:97], v[80:81] op_sel_hi:[1,0]
	v_pk_mul_f32 v[94:95], v[94:95], v[80:81] op_sel_hi:[1,0]
	v_pk_mul_f32 v[92:93], v[92:93], v[80:81] op_sel_hi:[1,0]
	v_pk_mul_f32 v[90:91], v[90:91], v[80:81] op_sel_hi:[1,0]
	v_pk_mul_f32 v[108:109], v[88:89], v[80:81] op_sel_hi:[1,0]
	v_pk_mul_f32 v[110:111], v[86:87], v[80:81] op_sel_hi:[1,0]
	v_cvt_pk_bf16_f32 v86, v98, v99
	v_cvt_pk_bf16_f32 v87, v100, v101
	v_cvt_pk_bf16_f32 v88, v94, v95
	v_cvt_pk_bf16_f32 v89, v96, v97
	v_cvt_pk_bf16_f32 v90, v90, v91
	v_cvt_pk_bf16_f32 v91, v92, v93
	s_nop 0
	v_cvt_pk_bf16_f32 v92, v110, v111
	v_cvt_pk_bf16_f32 v93, v108, v109
	global_store_dwordx4 v[106:107], v[86:89], off
	global_store_dwordx4 v[104:105], v[90:93], off
	s_nop 0
	s_waitcnt lgkmcnt(0)
	s_waitcnt vmcnt(10)
	v_ffbh_u32_e32 v80, v169
	v_min_u32_e32 v80, 32, v80
	v_lshlrev_b64 v[86:87], v80, v[168:169]
	v_min_u32_e32 v86, 1, v86
	v_or_b32_e32 v86, v87, v86
	v_cvt_f32_u32_e32 v88, v86
	v_lshlrev_b64 v[86:87], 12, v[0:1]
	v_sub_u32_e32 v1, 32, v80
	v_lshl_add_u64 v[86:87], s[2:3], 0, v[86:87]
	v_ldexp_f32 v1, v88, v1
	v_mul_f32_e32 v1, 0x33800000, v1
	v_fmamk_f32 v1, v1, 0x3a000000, v234
	v_mul_f32_e32 v80, 0x4b800000, v1
	v_cmp_gt_f32_e32 vcc, s50, v1
	v_lshl_add_u64 v[86:87], v[86:87], 0, v[134:135]
	v_lshl_add_u64 v[88:89], v[86:87], 0, s[38:39]
	v_cndmask_b32_e32 v1, v1, v80, vcc
	v_rsq_f32_e32 v1, v1
	v_lshl_add_u64 v[86:87], v[86:87], 0, s[42:43]
	v_add_u32_e32 v0, 0x80, v0
	v_mul_f32_e32 v80, 0x45800000, v1
	v_cndmask_b32_e32 v80, v1, v80, vcc
	v_pk_mul_f32 v[84:85], v[84:85], v[80:81] op_sel_hi:[1,0]
	v_pk_mul_f32 v[82:83], v[82:83], v[80:81] op_sel_hi:[1,0]
	v_pk_mul_f32 v[78:79], v[78:79], v[80:81] op_sel_hi:[1,0]
	v_pk_mul_f32 v[76:77], v[76:77], v[80:81] op_sel_hi:[1,0]
	v_pk_mul_f32 v[74:75], v[74:75], v[80:81] op_sel_hi:[1,0]
	v_pk_mul_f32 v[72:73], v[72:73], v[80:81] op_sel_hi:[1,0]
	v_pk_mul_f32 v[90:91], v[70:71], v[80:81] op_sel_hi:[1,0]
	v_pk_mul_f32 v[92:93], v[68:69], v[80:81] op_sel_hi:[1,0]
	v_cvt_pk_bf16_f32 v68, v82, v83
	v_cvt_pk_bf16_f32 v69, v84, v85
	v_cvt_pk_bf16_f32 v70, v76, v77
	v_cvt_pk_bf16_f32 v71, v78, v79
	v_cvt_pk_bf16_f32 v72, v72, v73
	v_cvt_pk_bf16_f32 v73, v74, v75
	s_nop 0
	v_cvt_pk_bf16_f32 v74, v92, v93
	v_cvt_pk_bf16_f32 v75, v90, v91
	global_store_dwordx4 v[88:89], v[68:71], off
	global_store_dwordx4 v[86:87], v[72:75], off
	s_nop 0
	v_add_u32_e32 v70, 0x80, v138
	v_ashrrev_i32_e32 v71, 31, v70
	s_waitcnt lgkmcnt(0)
	s_waitcnt vmcnt(11)
; __device__ __forceinline__ unsigned cvt_pk_bf16(float lo, float hi) { unsigned r; asm("v_cvt_pk_bf16_f32 %0, %1, %2" : "=v"(r) : "v"(lo), "v"(hi)); return r; }
; __device__ __forceinline__ float rinv_of(unsigned long long ss) { return rsqrtf((float)ss * (1.f / 16777216.f) * (1.f / DM) + 1e-6f); }
;   __device__ __forceinline__ void operator()(const f32x4 (&acc)[2][2][4][2], const Unit& u, const EpiCtx& x_, int wr, int wc, int fr, int fq) const {
;     ...
;     for (int ai = 0; ai < 2; ++ai)
; #pragma unroll
;       for (int m = 0; m < 4; ++m) {
;         const int row = (u.r0 + (ai ? x_.rdelta : 0)) + wr * 64 + m * 16 + fr;
;         bf16_t* rowp = (bf16_t*)u.C + (size_t)row * x_.ldc;
;         const float rs = (SCALE == 1) ? rinv_of(x_.ss[row]) : 1.f;
; #pragma unroll
;         for (int bj = 0; bj < 2; ++bj) {
;           const int cb = PERM ? (u.c0 + wc * 64 + bj * 32) : (u.c0 + bj * 128) + wc * 32;
;           f32x4 v0 = acc[ai][bj][m][0], v1 = acc[ai][bj][m][1];
;           if (SCALE == 1) { v0 *= rs; v1 *= rs; }
;           if (SCALE == 2) { v0 *= cs[bj][0]; v1 *= cs[bj][1]; }
;           if (PERM) {
;             uint4 o; o.x = cvt_pk_bf16(v0[0], v0[1]); o.y = cvt_pk_bf16(v0[2], v0[3]); o.z = cvt_pk_bf16(v1[0], v1[1]); o.w = cvt_pk_bf16(v1[2], v1[3]);
;             *(uint4*)(rowp + cb + 8 * fq) = o;
;           } else {
;             uint2 o0, o1; o0.x = cvt_pk_bf16(v0[0], v0[1]); o0.y = cvt_pk_bf16(v0[2], v0[3]); o1.x = cvt_pk_bf16(v1[0], v1[1]); o1.y = cvt_pk_bf16(v1[2], v1[3]);
;             *(uint2*)(rowp + cb + 4 * fq) = o0; *(uint2*)(rowp + cb + 16 + 4 * fq) = o1;
;           }
;         }
;       }
	v_ffbh_u32_e32 v1, v171
	v_min_u32_e32 v1, 32, v1
	v_lshlrev_b64 v[68:69], v1, v[170:171]
	v_min_u32_e32 v68, 1, v68
	v_or_b32_e32 v68, v69, v68
	v_cvt_f32_u32_e32 v72, v68
	v_sub_u32_e32 v1, 32, v1
	v_lshlrev_b64 v[68:69], 12, v[70:71]
	v_lshl_add_u64 v[68:69], s[2:3], 0, v[68:69]
	v_ldexp_f32 v1, v72, v1
	v_mul_f32_e32 v1, 0x33800000, v1
	v_fmamk_f32 v1, v1, 0x3a000000, v234
	v_mul_f32_e32 v70, 0x4b800000, v1
	v_cmp_gt_f32_e32 vcc, s50, v1
	v_lshl_add_u64 v[68:69], v[68:69], 0, v[134:135]
	s_nop 0
	v_cndmask_b32_e32 v1, v1, v70, vcc
	v_rsq_f32_e32 v1, v1
	v_lshl_add_u64 v[70:71], v[68:69], 0, s[38:39]
	v_lshl_add_u64 v[68:69], v[68:69], 0, s[42:43]
	v_mul_f32_e32 v72, 0x45800000, v1
	v_cndmask_b32_e32 v72, v1, v72, vcc
	v_pk_mul_f32 v[66:67], v[66:67], v[72:73] op_sel_hi:[1,0]
	v_pk_mul_f32 v[64:65], v[64:65], v[72:73] op_sel_hi:[1,0]
	v_pk_mul_f32 v[62:63], v[62:63], v[72:73] op_sel_hi:[1,0]
	v_pk_mul_f32 v[60:61], v[60:61], v[72:73] op_sel_hi:[1,0]
	v_pk_mul_f32 v[58:59], v[58:59], v[72:73] op_sel_hi:[1,0]
	v_pk_mul_f32 v[56:57], v[56:57], v[72:73] op_sel_hi:[1,0]
	v_pk_mul_f32 v[74:75], v[54:55], v[72:73] op_sel_hi:[1,0]
	v_pk_mul_f32 v[72:73], v[52:53], v[72:73] op_sel_hi:[1,0]
	v_cvt_pk_bf16_f32 v52, v64, v65
	v_cvt_pk_bf16_f32 v53, v66, v67
	v_cvt_pk_bf16_f32 v54, v60, v61
	v_cvt_pk_bf16_f32 v55, v62, v63
	v_cvt_pk_bf16_f32 v56, v56, v57
	v_cvt_pk_bf16_f32 v57, v58, v59
	s_nop 0
	v_cvt_pk_bf16_f32 v58, v72, v73
	v_cvt_pk_bf16_f32 v59, v74, v75
	global_store_dwordx4 v[70:71], v[52:55], off
	global_store_dwordx4 v[68:69], v[56:59], off
	s_nop 0
	v_add_u32_e32 v54, 0x80, v136
	v_ashrrev_i32_e32 v55, 31, v54
	s_waitcnt lgkmcnt(0)
	s_waitcnt vmcnt(12)
	v_ffbh_u32_e32 v1, v173
	v_min_u32_e32 v1, 32, v1
	v_lshlrev_b64 v[52:53], v1, v[172:173]
	v_min_u32_e32 v52, 1, v52
	v_or_b32_e32 v52, v53, v52
	v_cvt_f32_u32_e32 v56, v52
	v_sub_u32_e32 v1, 32, v1
	v_lshlrev_b64 v[52:53], 12, v[54:55]
	v_lshl_add_u64 v[52:53], s[2:3], 0, v[52:53]
	v_ldexp_f32 v1, v56, v1
	v_mul_f32_e32 v1, 0x33800000, v1
	v_fmamk_f32 v1, v1, 0x3a000000, v234
	v_mul_f32_e32 v54, 0x4b800000, v1
	v_cmp_gt_f32_e32 vcc, s50, v1
	v_lshl_add_u64 v[52:53], v[52:53], 0, v[134:135]
	s_nop 0
	v_cndmask_b32_e32 v1, v1, v54, vcc
	v_rsq_f32_e32 v1, v1
	v_lshl_add_u64 v[54:55], v[52:53], 0, s[38:39]
	v_lshl_add_u64 v[52:53], v[52:53], 0, s[42:43]
	v_mul_f32_e32 v56, 0x45800000, v1
	v_cndmask_b32_e32 v56, v1, v56, vcc
	v_pk_mul_f32 v[50:51], v[50:51], v[56:57] op_sel_hi:[1,0]
	v_pk_mul_f32 v[48:49], v[48:49], v[56:57] op_sel_hi:[1,0]
	v_pk_mul_f32 v[46:47], v[46:47], v[56:57] op_sel_hi:[1,0]
	v_pk_mul_f32 v[44:45], v[44:45], v[56:57] op_sel_hi:[1,0]
	v_pk_mul_f32 v[42:43], v[42:43], v[56:57] op_sel_hi:[1,0]
	v_pk_mul_f32 v[40:41], v[40:41], v[56:57] op_sel_hi:[1,0]
	v_pk_mul_f32 v[58:59], v[38:39], v[56:57] op_sel_hi:[1,0]
	v_pk_mul_f32 v[56:57], v[36:37], v[56:57] op_sel_hi:[1,0]
	v_cvt_pk_bf16_f32 v36, v48, v49
	v_cvt_pk_bf16_f32 v37, v50, v51
	v_cvt_pk_bf16_f32 v38, v44, v45
	v_cvt_pk_bf16_f32 v39, v46, v47
	v_cvt_pk_bf16_f32 v40, v40, v41
	v_cvt_pk_bf16_f32 v41, v42, v43
	s_nop 0
	v_cvt_pk_bf16_f32 v42, v56, v57
	v_cvt_pk_bf16_f32 v43, v58, v59
	global_store_dwordx4 v[54:55], v[36:39], off
	global_store_dwordx4 v[52:53], v[40:43], off
	s_nop 0
	v_add_u32_e32 v38, 0x80, v118
	v_ashrrev_i32_e32 v39, 31, v38
	s_waitcnt lgkmcnt(0)
	s_waitcnt vmcnt(13)
	v_ffbh_u32_e32 v1, v175
	v_min_u32_e32 v1, 32, v1
	v_lshlrev_b64 v[36:37], v1, v[174:175]
	v_min_u32_e32 v36, 1, v36
	v_or_b32_e32 v36, v37, v36
	v_cvt_f32_u32_e32 v40, v36
	v_sub_u32_e32 v1, 32, v1
	v_lshlrev_b64 v[36:37], 12, v[38:39]
	v_lshl_add_u64 v[36:37], s[2:3], 0, v[36:37]
	v_ldexp_f32 v1, v40, v1
	v_mul_f32_e32 v1, 0x33800000, v1
	v_fmamk_f32 v1, v1, 0x3a000000, v234
	v_mul_f32_e32 v38, 0x4b800000, v1
	v_cmp_gt_f32_e32 vcc, s50, v1
	v_lshl_add_u64 v[36:37], v[36:37], 0, v[134:135]
	s_nop 0
	v_cndmask_b32_e32 v1, v1, v38, vcc
	v_rsq_f32_e32 v1, v1
	v_lshl_add_u64 v[38:39], v[36:37], 0, s[38:39]
	v_lshl_add_u64 v[36:37], v[36:37], 0, s[42:43]
	v_mul_f32_e32 v40, 0x45800000, v1
	v_cndmask_b32_e32 v40, v1, v40, vcc
	v_pk_mul_f32 v[34:35], v[34:35], v[40:41] op_sel_hi:[1,0]
	v_pk_mul_f32 v[32:33], v[32:33], v[40:41] op_sel_hi:[1,0]
	v_pk_mul_f32 v[30:31], v[30:31], v[40:41] op_sel_hi:[1,0]
	v_pk_mul_f32 v[28:29], v[28:29], v[40:41] op_sel_hi:[1,0]
	v_pk_mul_f32 v[26:27], v[26:27], v[40:41] op_sel_hi:[1,0]
	v_pk_mul_f32 v[24:25], v[24:25], v[40:41] op_sel_hi:[1,0]
	v_pk_mul_f32 v[42:43], v[22:23], v[40:41] op_sel_hi:[1,0]
	v_pk_mul_f32 v[40:41], v[20:21], v[40:41] op_sel_hi:[1,0]
	v_cvt_pk_bf16_f32 v20, v32, v33
	v_cvt_pk_bf16_f32 v21, v34, v35
	v_cvt_pk_bf16_f32 v22, v28, v29
	v_cvt_pk_bf16_f32 v23, v30, v31
	v_cvt_pk_bf16_f32 v24, v24, v25
	v_cvt_pk_bf16_f32 v25, v26, v27
	s_nop 0
	v_cvt_pk_bf16_f32 v26, v40, v41
	v_cvt_pk_bf16_f32 v27, v42, v43
	global_store_dwordx4 v[38:39], v[20:23], off
	global_store_dwordx4 v[36:37], v[24:27], off
	s_nop 0
	v_ashrrev_i32_e32 v1, 31, v0
	v_lshlrev_b64 v[0:1], 12, v[0:1]
	v_lshl_add_u64 v[0:1], s[2:3], 0, v[0:1]
	v_lshl_add_u64 v[0:1], v[0:1], 0, v[134:135]
	s_mov_b64 s[2:3], s[8:9]
	s_waitcnt lgkmcnt(0)
	s_waitcnt vmcnt(14)
	v_ffbh_u32_e32 v2, v191
	v_min_u32_e32 v22, 32, v2
	v_lshlrev_b64 v[2:3], v22, v[190:191]
	v_min_u32_e32 v2, 1, v2
	v_or_b32_e32 v2, v3, v2
	v_cvt_f32_u32_e32 v2, v2
	v_sub_u32_e32 v3, 32, v22
	v_lshl_add_u64 v[20:21], v[0:1], 0, s[38:39]
	v_lshl_add_u64 v[22:23], v[0:1], 0, s[42:43]
	v_ldexp_f32 v2, v2, v3
	v_mul_f32_e32 v2, 0x33800000, v2
	v_fmamk_f32 v2, v2, 0x3a000000, v234
	v_mul_f32_e32 v3, 0x4b800000, v2
	v_cmp_gt_f32_e32 vcc, s50, v2
	s_nop 1
	v_cndmask_b32_e32 v2, v2, v3, vcc
	v_rsq_f32_e32 v2, v2
	s_nop 0
	v_mul_f32_e32 v0, 0x45800000, v2
	v_cndmask_b32_e32 v0, v2, v0, vcc
	v_pk_mul_f32 v[2:3], v[18:19], v[0:1] op_sel_hi:[1,0]
	v_pk_mul_f32 v[16:17], v[16:17], v[0:1] op_sel_hi:[1,0]
	v_pk_mul_f32 v[14:15], v[14:15], v[0:1] op_sel_hi:[1,0]
	v_pk_mul_f32 v[12:13], v[12:13], v[0:1] op_sel_hi:[1,0]
	v_pk_mul_f32 v[10:11], v[10:11], v[0:1] op_sel_hi:[1,0]
	v_pk_mul_f32 v[8:9], v[8:9], v[0:1] op_sel_hi:[1,0]
	v_pk_mul_f32 v[18:19], v[6:7], v[0:1] op_sel_hi:[1,0]
	v_pk_mul_f32 v[6:7], v[4:5], v[0:1] op_sel_hi:[1,0]
	v_cvt_pk_bf16_f32 v0, v16, v17
	v_cvt_pk_bf16_f32 v1, v2, v3
	v_cvt_pk_bf16_f32 v2, v12, v13
	v_cvt_pk_bf16_f32 v3, v14, v15
	v_cvt_pk_bf16_f32 v4, v8, v9
	v_cvt_pk_bf16_f32 v5, v10, v11
	s_nop 0
	v_cvt_pk_bf16_f32 v6, v6, v7
	v_cvt_pk_bf16_f32 v7, v18, v19
	global_store_dwordx4 v[20:21], v[0:3], off
	global_store_dwordx4 v[22:23], v[4:7], off
	s_cbranch_scc0 .LBB0_625
	s_waitcnt vmcnt(0)
	s_cmpk_gt_u32 s1, 0xff
	s_cbranch_scc1 .LBB0_630
	s_barrier

; #define G_STAGE(bufoff, gbase, voff) do { _Pragma("unroll") for (int _i = 0; _i < 2; ++_i) { unsigned _vo = (voff)[_i]; asm volatile("" : "+v"(_vo));   \
;     __builtin_amdgcn_global_load_lds((const unsigned*)((const char*)(gbase) + _vo), (LAS unsigned*)(lds + (bufoff) + ldsw + _i * 8192), 16, 0, 0); } } while (0)
; #define G_LDA(dst, b, h) do { _Pragma("unroll") for (int m = 0; m < 4; ++m) _Pragma("unroll") for (int k = 0; k < 2; ++k) dst[m][k] = *(const LAS bf16x8*)(lds + G_SA(b, h) + aoff + m * 2048 + k * 1024); } while (0)
; #define G_LDB(dst, b, h) do { _Pragma("unroll") for (int n = 0; n < 2; ++n) _Pragma("unroll") for (int k = 0; k < 2; ++k) dst[n][k] = *(const LAS bf16x8*)(lds + G_SB(b, h) + boff + n * 2048 + k * 1024); } while (0)
; #define G_MMA(ai, bj, At, Bt) do { __builtin_amdgcn_s_setprio(1); _Pragma("unroll") for (int m = 0; m < 4; ++m) _Pragma("unroll") for (int n = 0; n < 2; ++n) _Pragma("unroll") for (int k = 0; k < 2; ++k) \
;     acc[ai][bj][m][n] = __builtin_amdgcn_mfma_f32_16x16x32_bf16(Bt[n][k], At[m][k], acc[ai][bj][m][n], 0, 0, 0); __builtin_amdgcn_s_setprio(0); } while (0)
; #define G_WAIT_L(n) asm volatile("s_waitcnt lgkmcnt(" #n ")" ::: "memory")
; #define G_BAR __builtin_amdgcn_s_barrier()
; #define G_SCHED __builtin_amdgcn_sched_barrier(0)
; template <class Epi>
; __device__ __forceinline__ void gemm_phase(LAS unsigned char* lds, const int K, const unsigned lda_b, const unsigned ldb_b, const Map& M, const Epi& E) {
;     ...
;     for (int t = 0; t < nt; t += 2) {
;       const bool last = (t == nt - 2);
;       const char* a1h1 = cur.a0 + a_h + (size_t)(t + 1) * kstep;
;       const char* a2h0 = last ? nxt.a0 : cur.a0 + (size_t)(t + 2) * kstep; const char* a2h1 = a2h0 + a_h;
;       const char* b2h0 = last ? nxt.b0 : cur.b0 + (size_t)(t + 2) * kstep; const char* b2h1 = last ? nxt.b1 : cur.b1 + (size_t)(t + 2) * kstep;
;       G_LDB(B0, 0, 0); G_SCHED; G_LDA(At, 0, 0); G_STAGE(G_SA(1, 1), a1h1, voffA);
;       G_WAIT_L(8); G_BAR; G_WAIT_L(0); G_MMA(0, 0, At, B0); G_BAR; G_SCHED;
;       G_LDB(B1, 0, 1); G_STAGE(G_SB(0, 0), b2h0, voffB);
;       G_BAR; G_WAIT_L(0); G_MMA(0, 1, At, B1); G_BAR;
;       G_LDA(At, 0, 1); G_STAGE(G_SA(0, 0), a2h0, voffA);
;       G_BAR; G_WAIT_L(0); G_MMA(1, 0, At, B0); G_BAR; G_SCHED;
.LBB0_651:
	s_add_u32 s22, s2, 0xfff80080
	s_addc_u32 s34, s3, -1
	s_add_u32 s35, s29, s46
	s_addc_u32 s38, s30, 0
	s_add_i32 vcc_lo, 0, 0x10000
	v_add_u32_e32 v80, vcc_lo, v158
	ds_read_b128 v[132:135], v80
	ds_read_b128 v[136:139], v80 offset:1024
	ds_read_b128 v[140:143], v80 offset:2048
	ds_read_b128 v[144:147], v80 offset:3072
	s_cmp_eq_u32 s31, 28
	s_cselect_b32 s43, s9, s34
	s_cselect_b32 s42, s8, s22
	s_cselect_b32 s45, s37, s30
	s_cselect_b32 s44, s36, s29
	v_mov_b32_e32 v80, v153
	s_cselect_b32 s39, s28, s38
	s_cselect_b32 s38, s0, s35
	s_add_u32 s68, s42, 0x80000
	ds_read_b128 v[148:151], v170
	ds_read_b128 v[172:175], v170 offset:1024
	ds_read_b128 v[190:193], v170 offset:2048
	ds_read_b128 v[194:197], v170 offset:3072
	ds_read_b128 v[198:201], v170 offset:4096
	ds_read_b128 v[202:205], v170 offset:5120
	ds_read_b128 v[206:209], v170 offset:6144
	ds_read_b128 v[210:213], v170 offset:7168
	s_addc_u32 s69, s43, 0
	s_add_i32 m0, s48, 0xc000
	s_nop 0
	global_load_lds_dwordx4 v80, s[2:3]
	v_mov_b32_e32 v80, v155
	s_add_i32 m0, s48, 0xe000
	s_nop 0
	global_load_lds_dwordx4 v80, s[2:3]
	s_waitcnt lgkmcnt(8)
	s_barrier
	s_waitcnt lgkmcnt(0)
	s_setprio 1
	s_waitcnt lgkmcnt(0)
	v_mfma_f32_16x16x32_bf16 v[126:129], v[132:135], v[148:151], v[126:129]
	v_mfma_f32_16x16x32_bf16 v[122:125], v[140:143], v[148:151], v[122:125]
	v_mfma_f32_16x16x32_bf16 v[110:113], v[132:135], v[190:193], v[110:113]
	v_mfma_f32_16x16x32_bf16 v[106:109], v[140:143], v[190:193], v[106:109]
	v_mfma_f32_16x16x32_bf16 v[94:97], v[132:135], v[198:201], v[94:97]
	v_mfma_f32_16x16x32_bf16 v[90:93], v[140:143], v[198:201], v[90:93]
	v_mfma_f32_16x16x32_bf16 v[76:79], v[132:135], v[206:209], v[76:79]
	v_mfma_f32_16x16x32_bf16 v[72:75], v[140:143], v[206:209], v[72:75]
	v_mfma_f32_16x16x32_bf16 v[126:129], v[136:139], v[172:175], v[126:129]
	v_mfma_f32_16x16x32_bf16 v[122:125], v[144:147], v[172:175], v[122:125]
	v_mfma_f32_16x16x32_bf16 v[110:113], v[136:139], v[194:197], v[110:113]
	v_mfma_f32_16x16x32_bf16 v[106:109], v[144:147], v[194:197], v[106:109]
	v_mfma_f32_16x16x32_bf16 v[94:97], v[136:139], v[202:205], v[94:97]
	v_mfma_f32_16x16x32_bf16 v[90:93], v[144:147], v[202:205], v[90:93]
	v_mfma_f32_16x16x32_bf16 v[76:79], v[136:139], v[210:213], v[76:79]
	v_mfma_f32_16x16x32_bf16 v[72:75], v[144:147], v[210:213], v[72:75]
	s_setprio 0
	s_barrier
	s_add_i32 s22, 0, 0x14000
	v_add_u32_e32 v80, s22, v158
	ds_read_b128 v[214:217], v80
	ds_read_b128 v[226:229], v80 offset:1024
	ds_read_b128 v[238:241], v80 offset:2048
	ds_read_b128 v[242:245], v80 offset:3072
	v_mov_b32_e32 v80, v154
	s_add_i32 s34, vcc_lo, s47
	s_mov_b32 m0, s34
	s_nop 0
	global_load_lds_dwordx4 v80, s[44:45]
	v_mov_b32_e32 v80, v156
	s_add_i32 m0, s34, 0x2000
	s_nop 0
	global_load_lds_dwordx4 v80, s[44:45]
	s_barrier
	s_waitcnt lgkmcnt(0)
	s_setprio 1
	s_waitcnt lgkmcnt(0)
	v_mfma_f32_16x16x32_bf16 v[118:121], v[214:217], v[148:151], v[118:121]
	v_mfma_f32_16x16x32_bf16 v[114:117], v[238:241], v[148:151], v[114:117]
	v_mfma_f32_16x16x32_bf16 v[102:105], v[214:217], v[190:193], v[102:105]
	v_mfma_f32_16x16x32_bf16 v[98:101], v[238:241], v[190:193], v[98:101]
	v_mfma_f32_16x16x32_bf16 v[86:89], v[214:217], v[198:201], v[86:89]
	v_mfma_f32_16x16x32_bf16 v[82:85], v[238:241], v[198:201], v[82:85]
	v_mfma_f32_16x16x32_bf16 v[68:71], v[214:217], v[206:209], v[68:71]
	v_mfma_f32_16x16x32_bf16 v[64:67], v[238:241], v[206:209], v[64:67]
	v_mfma_f32_16x16x32_bf16 v[118:121], v[226:229], v[172:175], v[118:121]
	v_mfma_f32_16x16x32_bf16 v[114:117], v[242:245], v[172:175], v[114:117]
	v_mfma_f32_16x16x32_bf16 v[102:105], v[226:229], v[194:197], v[102:105]
	v_mfma_f32_16x16x32_bf16 v[98:101], v[242:245], v[194:197], v[98:101]
	v_mfma_f32_16x16x32_bf16 v[86:89], v[226:229], v[202:205], v[86:89]
	v_mfma_f32_16x16x32_bf16 v[82:85], v[242:245], v[202:205], v[82:85]
	v_mfma_f32_16x16x32_bf16 v[68:71], v[226:229], v[210:213], v[68:71]
	v_mfma_f32_16x16x32_bf16 v[64:67], v[242:245], v[210:213], v[64:67]
	s_setprio 0
	v_mov_b32_e32 v80, v153
	s_mov_b32 m0, s48
	s_barrier
	ds_read_b128 v[148:151], v170 offset:16384
	ds_read_b128 v[172:175], v170 offset:17408
	ds_read_b128 v[190:193], v170 offset:18432
	ds_read_b128 v[194:197], v170 offset:19456
	ds_read_b128 v[198:201], v170 offset:20480
	ds_read_b128 v[202:205], v170 offset:21504
	ds_read_b128 v[206:209], v170 offset:22528
	ds_read_b128 v[210:213], v170 offset:23552
	s_nop 0
	global_load_lds_dwordx4 v80, s[42:43]
	v_mov_b32_e32 v80, v155
	s_mov_b32 m0, s49
	s_nop 0
	global_load_lds_dwordx4 v80, s[42:43]
	s_barrier
	s_waitcnt lgkmcnt(0)
	s_setprio 1
	s_waitcnt lgkmcnt(0)
	v_mfma_f32_16x16x32_bf16 v[60:63], v[132:135], v[148:151], v[60:63]
	v_mfma_f32_16x16x32_bf16 v[56:59], v[140:143], v[148:151], v[56:59]
	v_mfma_f32_16x16x32_bf16 v[44:47], v[132:135], v[190:193], v[44:47]
	v_mfma_f32_16x16x32_bf16 v[40:43], v[140:143], v[190:193], v[40:43]
	v_mfma_f32_16x16x32_bf16 v[28:31], v[132:135], v[198:201], v[28:31]
	v_mfma_f32_16x16x32_bf16 v[24:27], v[140:143], v[198:201], v[24:27]
	v_mfma_f32_16x16x32_bf16 v[12:15], v[132:135], v[206:209], v[12:15]
	v_mfma_f32_16x16x32_bf16 v[8:11], v[140:143], v[206:209], v[8:11]
	v_mfma_f32_16x16x32_bf16 v[60:63], v[136:139], v[172:175], v[60:63]
	v_mfma_f32_16x16x32_bf16 v[56:59], v[144:147], v[172:175], v[56:59]
	v_mfma_f32_16x16x32_bf16 v[44:47], v[136:139], v[194:197], v[44:47]
	v_mfma_f32_16x16x32_bf16 v[40:43], v[144:147], v[194:197], v[40:43]
	v_mfma_f32_16x16x32_bf16 v[28:31], v[136:139], v[202:205], v[28:31]
	v_mfma_f32_16x16x32_bf16 v[24:27], v[144:147], v[202:205], v[24:27]
	v_mfma_f32_16x16x32_bf16 v[12:15], v[136:139], v[210:213], v[12:15]
	v_mfma_f32_16x16x32_bf16 v[8:11], v[144:147], v[210:213], v[8:11]
	s_setprio 0
	s_barrier
; #define G_STAGE(bufoff, gbase, voff) do { _Pragma("unroll") for (int _i = 0; _i < 2; ++_i) { unsigned _vo = (voff)[_i]; asm volatile("" : "+v"(_vo));   \
;     __builtin_amdgcn_global_load_lds((const unsigned*)((const char*)(gbase) + _vo), (LAS unsigned*)(lds + (bufoff) + ldsw + _i * 8192), 16, 0, 0); } } while (0)
; #define G_LDA(dst, b, h) do { _Pragma("unroll") for (int m = 0; m < 4; ++m) _Pragma("unroll") for (int k = 0; k < 2; ++k) dst[m][k] = *(const LAS bf16x8*)(lds + G_SA(b, h) + aoff + m * 2048 + k * 1024); } while (0)
; #define G_LDB(dst, b, h) do { _Pragma("unroll") for (int n = 0; n < 2; ++n) _Pragma("unroll") for (int k = 0; k < 2; ++k) dst[n][k] = *(const LAS bf16x8*)(lds + G_SB(b, h) + boff + n * 2048 + k * 1024); } while (0)
; #define G_MMA(ai, bj, At, Bt) do { __builtin_amdgcn_s_setprio(1); _Pragma("unroll") for (int m = 0; m < 4; ++m) _Pragma("unroll") for (int n = 0; n < 2; ++n) _Pragma("unroll") for (int k = 0; k < 2; ++k) \
;     acc[ai][bj][m][n] = __builtin_amdgcn_mfma_f32_16x16x32_bf16(Bt[n][k], At[m][k], acc[ai][bj][m][n], 0, 0, 0); __builtin_amdgcn_s_setprio(0); } while (0)
; #define G_WAIT_V(n) asm volatile("s_waitcnt vmcnt(" #n ")" ::: "memory")
; #define G_WAIT_L(n) asm volatile("s_waitcnt lgkmcnt(" #n ")" ::: "memory")
; #define G_BAR __builtin_amdgcn_s_barrier()
; #define G_SCHED __builtin_amdgcn_sched_barrier(0)
; template <class Epi>
; __device__ __forceinline__ void gemm_phase(LAS unsigned char* lds, const int K, const unsigned lda_b, const unsigned ldb_b, const Map& M, const Epi& E) {
;     ...
;       G_STAGE(G_SB(0, 1), b2h1, voffB);
;       G_WAIT_V(6); G_BAR; G_MMA(1, 1, At, B1); G_BAR;
;       G_LDB(B0, 1, 0); G_SCHED; G_LDA(At, 1, 0); G_STAGE(G_SA(0, 1), a2h1, voffA);
;       G_WAIT_L(8); G_BAR; G_WAIT_L(0); G_MMA(0, 0, At, B0); G_BAR; G_SCHED;
;       G_LDB(B1, 1, 1); G_STAGE(G_SB(1, 0), b2h0 + kstep, voffB);
;       G_BAR; G_WAIT_L(0); G_MMA(0, 1, At, B1); G_BAR;
;       G_LDA(At, 1, 1); G_STAGE(G_SA(1, 0), a2h0 + kstep, voffA);
	v_mov_b32_e32 v80, v154
	s_add_i32 s22, s22, s47
	s_mov_b32 m0, s22
	s_nop 0
	global_load_lds_dwordx4 v80, s[38:39]
	v_mov_b32_e32 v80, v156
	s_add_i32 m0, s22, 0x2000
	s_nop 0
	global_load_lds_dwordx4 v80, s[38:39]
	s_waitcnt vmcnt(6)
	s_barrier
	s_setprio 1
	v_mfma_f32_16x16x32_bf16 v[52:55], v[214:217], v[148:151], v[52:55]
	v_mfma_f32_16x16x32_bf16 v[48:51], v[238:241], v[148:151], v[48:51]
	v_mfma_f32_16x16x32_bf16 v[36:39], v[214:217], v[190:193], v[36:39]
	v_mfma_f32_16x16x32_bf16 v[32:35], v[238:241], v[190:193], v[32:35]
	v_mfma_f32_16x16x32_bf16 v[20:23], v[214:217], v[198:201], v[20:23]
	v_mfma_f32_16x16x32_bf16 v[16:19], v[238:241], v[198:201], v[16:19]
	v_mfma_f32_16x16x32_bf16 v[4:7], v[214:217], v[206:209], v[4:7]
	v_mfma_f32_16x16x32_bf16 v[0:3], v[238:241], v[206:209], v[0:3]
	v_mfma_f32_16x16x32_bf16 v[52:55], v[226:229], v[172:175], v[52:55]
	v_mfma_f32_16x16x32_bf16 v[48:51], v[242:245], v[172:175], v[48:51]
	v_mfma_f32_16x16x32_bf16 v[36:39], v[226:229], v[194:197], v[36:39]
	v_mfma_f32_16x16x32_bf16 v[32:35], v[242:245], v[194:197], v[32:35]
	v_mfma_f32_16x16x32_bf16 v[20:23], v[226:229], v[202:205], v[20:23]
	v_mfma_f32_16x16x32_bf16 v[16:19], v[242:245], v[202:205], v[16:19]
	v_mfma_f32_16x16x32_bf16 v[4:7], v[226:229], v[210:213], v[4:7]
	v_mfma_f32_16x16x32_bf16 v[0:3], v[242:245], v[210:213], v[0:3]
	s_setprio 0
	s_add_i32 s22, 0, 0x18000
	v_add_u32_e32 v80, s22, v158
	s_barrier
	ds_read_b128 v[132:135], v80
	ds_read_b128 v[136:139], v80 offset:1024
	ds_read_b128 v[140:143], v80 offset:2048
	ds_read_b128 v[144:147], v80 offset:3072
	v_mov_b32_e32 v80, v153
	s_mov_b32 m0, s61
	ds_read_b128 v[148:151], v170 offset:32768
	ds_read_b128 v[172:175], v170 offset:33792
	ds_read_b128 v[190:193], v170 offset:34816
	ds_read_b128 v[194:197], v170 offset:35840
	ds_read_b128 v[198:201], v170 offset:36864
	ds_read_b128 v[202:205], v170 offset:37888
	ds_read_b128 v[206:209], v170 offset:38912
	ds_read_b128 v[210:213], v170 offset:39936
	s_nop 0
	global_load_lds_dwordx4 v80, s[68:69]
	v_mov_b32_e32 v80, v155
	s_mov_b32 m0, s66
	s_nop 0
	global_load_lds_dwordx4 v80, s[68:69]
	s_waitcnt lgkmcnt(8)
	s_barrier
	s_waitcnt lgkmcnt(0)
	s_setprio 1
	s_waitcnt lgkmcnt(0)
	v_mfma_f32_16x16x32_bf16 v[126:129], v[132:135], v[148:151], v[126:129]
	v_mfma_f32_16x16x32_bf16 v[122:125], v[140:143], v[148:151], v[122:125]
	v_mfma_f32_16x16x32_bf16 v[110:113], v[132:135], v[190:193], v[110:113]
	v_mfma_f32_16x16x32_bf16 v[106:109], v[140:143], v[190:193], v[106:109]
	v_mfma_f32_16x16x32_bf16 v[94:97], v[132:135], v[198:201], v[94:97]
	v_mfma_f32_16x16x32_bf16 v[90:93], v[140:143], v[198:201], v[90:93]
	v_mfma_f32_16x16x32_bf16 v[76:79], v[132:135], v[206:209], v[76:79]
	v_mfma_f32_16x16x32_bf16 v[72:75], v[140:143], v[206:209], v[72:75]
	v_mfma_f32_16x16x32_bf16 v[126:129], v[136:139], v[172:175], v[126:129]
	v_mfma_f32_16x16x32_bf16 v[122:125], v[144:147], v[172:175], v[122:125]
	v_mfma_f32_16x16x32_bf16 v[110:113], v[136:139], v[194:197], v[110:113]
	v_mfma_f32_16x16x32_bf16 v[106:109], v[144:147], v[194:197], v[106:109]
	v_mfma_f32_16x16x32_bf16 v[94:97], v[136:139], v[202:205], v[94:97]
	v_mfma_f32_16x16x32_bf16 v[90:93], v[144:147], v[202:205], v[90:93]
	v_mfma_f32_16x16x32_bf16 v[76:79], v[136:139], v[210:213], v[76:79]
	v_mfma_f32_16x16x32_bf16 v[72:75], v[144:147], v[210:213], v[72:75]
	s_setprio 0
	s_barrier
	s_add_i32 s34, 0, 0x1c000
	v_add_u32_e32 v80, s34, v158
	ds_read_b128 v[214:217], v80
	ds_read_b128 v[226:229], v80 offset:1024
	ds_read_b128 v[238:241], v80 offset:2048
	ds_read_b128 v[242:245], v80 offset:3072
	v_mov_b32_e32 v80, v154
	s_add_i32 s22, s22, s47
	s_add_i32 m0, s22, 0xffffff80
	v_mov_b32_e32 v80, v156
	global_load_lds_dwordx4 v154, s[44:45] offset:128
	s_add_i32 m0, s22, 0x1f80
	s_nop 0
	global_load_lds_dwordx4 v156, s[44:45] offset:128
	s_barrier
	s_waitcnt lgkmcnt(0)
	s_setprio 1
	s_waitcnt lgkmcnt(0)
	v_mfma_f32_16x16x32_bf16 v[118:121], v[214:217], v[148:151], v[118:121]
	v_mfma_f32_16x16x32_bf16 v[114:117], v[238:241], v[148:151], v[114:117]
	v_mfma_f32_16x16x32_bf16 v[102:105], v[214:217], v[190:193], v[102:105]
	v_mfma_f32_16x16x32_bf16 v[98:101], v[238:241], v[190:193], v[98:101]
	v_mfma_f32_16x16x32_bf16 v[86:89], v[214:217], v[198:201], v[86:89]
	v_mfma_f32_16x16x32_bf16 v[82:85], v[238:241], v[198:201], v[82:85]
	v_mfma_f32_16x16x32_bf16 v[68:71], v[214:217], v[206:209], v[68:71]
	v_mfma_f32_16x16x32_bf16 v[64:67], v[238:241], v[206:209], v[64:67]
	v_mfma_f32_16x16x32_bf16 v[118:121], v[226:229], v[172:175], v[118:121]
	v_mfma_f32_16x16x32_bf16 v[114:117], v[242:245], v[172:175], v[114:117]
	v_mfma_f32_16x16x32_bf16 v[102:105], v[226:229], v[194:197], v[102:105]
	v_mfma_f32_16x16x32_bf16 v[98:101], v[242:245], v[194:197], v[98:101]
	v_mfma_f32_16x16x32_bf16 v[86:89], v[226:229], v[202:205], v[86:89]
	v_mfma_f32_16x16x32_bf16 v[82:85], v[242:245], v[202:205], v[82:85]
	v_mfma_f32_16x16x32_bf16 v[68:71], v[226:229], v[210:213], v[68:71]
	v_mfma_f32_16x16x32_bf16 v[64:67], v[242:245], v[210:213], v[64:67]
	s_setprio 0
	v_mov_b32_e32 v80, v153
	s_barrier
	ds_read_b128 v[148:151], v170 offset:49152
	ds_read_b128 v[172:175], v170 offset:50176
	ds_read_b128 v[190:193], v170 offset:51200
	ds_read_b128 v[194:197], v170 offset:52224
	ds_read_b128 v[198:201], v170 offset:53248
	ds_read_b128 v[202:205], v170 offset:54272
	ds_read_b128 v[206:209], v170 offset:55296
	ds_read_b128 v[210:213], v170 offset:56320
	s_add_i32 m0, s67, 0xffffff80
	v_mov_b32_e32 v80, v155
	global_load_lds_dwordx4 v153, s[42:43] offset:128
	s_add_i32 m0, s76, 0xffffff80
	s_nop 0
	global_load_lds_dwordx4 v155, s[42:43] offset:128
	s_barrier
; __device__ __forceinline__ float rinv_of(unsigned long long ss) { return rsqrtf((float)ss * (1.f / 16777216.f) * (1.f / DM) + 1e-6f); }
; #define G_STAGE(bufoff, gbase, voff) do { _Pragma("unroll") for (int _i = 0; _i < 2; ++_i) { unsigned _vo = (voff)[_i]; asm volatile("" : "+v"(_vo));   \
;     __builtin_amdgcn_global_load_lds((const unsigned*)((const char*)(gbase) + _vo), (LAS unsigned*)(lds + (bufoff) + ldsw + _i * 8192), 16, 0, 0); } } while (0)
; #define G_MMA(ai, bj, At, Bt) do { __builtin_amdgcn_s_setprio(1); _Pragma("unroll") for (int m = 0; m < 4; ++m) _Pragma("unroll") for (int n = 0; n < 2; ++n) _Pragma("unroll") for (int k = 0; k < 2; ++k) \
;     acc[ai][bj][m][n] = __builtin_amdgcn_mfma_f32_16x16x32_bf16(Bt[n][k], At[m][k], acc[ai][bj][m][n], 0, 0, 0); __builtin_amdgcn_s_setprio(0); } while (0)
; #define G_WAIT_V(n) asm volatile("s_waitcnt vmcnt(" #n ")" ::: "memory")
; #define G_WAIT_L(n) asm volatile("s_waitcnt lgkmcnt(" #n ")" ::: "memory")
; #define G_BAR __builtin_amdgcn_s_barrier()
; #define G_SCHED __builtin_amdgcn_sched_barrier(0)
;   __device__ __forceinline__ void operator()(const f32x4 (&acc)[2][2][4][2], const Unit& u, const EpiCtx& x_, int wr, int wc, int fr, int fq) const {
;     ...
;     { const int lg = x_.p0, S = x_.p1, L = S >> lg;
; #pragma unroll
;       for (int bj = 0; bj < 2; ++bj) {
;         const int col = u.c0 + wc * 64 + bj * 32 + 8 * fq, seq = col / S, rem = col % S, r = rem / L, m0 = rem % L;
;         const unsigned long long* sp = x_.ss + (size_t)seq * S + r;
; #pragma unroll
;         for (int i = 0; i < 8; ++i) cs[bj][i >> 2][i & 3] = rinv_of(sp[(size_t)(m0 + i) << lg]);
; template <class Epi>
; __device__ __forceinline__ void gemm_phase(LAS unsigned char* lds, const int K, const unsigned lda_b, const unsigned ldb_b, const Map& M, const Epi& E) {
;     ...
;       G_BAR; G_WAIT_L(0); G_MMA(1, 0, At, B0); G_BAR; G_SCHED;
;       G_STAGE(G_SB(1, 1), b2h1 + kstep, voffB);
;       G_WAIT_V(6); G_BAR; G_MMA(1, 1, At, B1); G_BAR;
;     }
	s_waitcnt lgkmcnt(0)
	s_setprio 1
	s_waitcnt lgkmcnt(0)
	v_mfma_f32_16x16x32_bf16 v[60:63], v[132:135], v[148:151], v[60:63]
	v_mfma_f32_16x16x32_bf16 v[56:59], v[140:143], v[148:151], v[56:59]
	v_mfma_f32_16x16x32_bf16 v[44:47], v[132:135], v[190:193], v[44:47]
	v_mfma_f32_16x16x32_bf16 v[40:43], v[140:143], v[190:193], v[40:43]
	v_mfma_f32_16x16x32_bf16 v[28:31], v[132:135], v[198:201], v[28:31]
	v_mfma_f32_16x16x32_bf16 v[24:27], v[140:143], v[198:201], v[24:27]
	v_mfma_f32_16x16x32_bf16 v[12:15], v[132:135], v[206:209], v[12:15]
	v_mfma_f32_16x16x32_bf16 v[8:11], v[140:143], v[206:209], v[8:11]
	v_mfma_f32_16x16x32_bf16 v[60:63], v[136:139], v[172:175], v[60:63]
	v_mfma_f32_16x16x32_bf16 v[56:59], v[144:147], v[172:175], v[56:59]
	v_mfma_f32_16x16x32_bf16 v[44:47], v[136:139], v[194:197], v[44:47]
	v_mfma_f32_16x16x32_bf16 v[40:43], v[144:147], v[194:197], v[40:43]
	v_mfma_f32_16x16x32_bf16 v[28:31], v[136:139], v[202:205], v[28:31]
	v_mfma_f32_16x16x32_bf16 v[24:27], v[144:147], v[202:205], v[24:27]
	v_mfma_f32_16x16x32_bf16 v[12:15], v[136:139], v[210:213], v[12:15]
	v_mfma_f32_16x16x32_bf16 v[8:11], v[144:147], v[210:213], v[8:11]
	s_setprio 0
	s_barrier
	v_mov_b32_e32 v80, v154
	s_add_i32 s22, s34, s47
	s_add_i32 m0, s22, 0xffffff80
	v_mov_b32_e32 v80, v156
	global_load_lds_dwordx4 v154, s[38:39] offset:128
	s_add_i32 m0, s22, 0x1f80
	s_nop 0
	global_load_lds_dwordx4 v156, s[38:39] offset:128
	s_waitcnt vmcnt(6)
	s_barrier
	s_setprio 1
	v_mfma_f32_16x16x32_bf16 v[52:55], v[214:217], v[148:151], v[52:55]
	v_mfma_f32_16x16x32_bf16 v[48:51], v[238:241], v[148:151], v[48:51]
	v_mfma_f32_16x16x32_bf16 v[36:39], v[214:217], v[190:193], v[36:39]
	v_mfma_f32_16x16x32_bf16 v[32:35], v[238:241], v[190:193], v[32:35]
	v_mfma_f32_16x16x32_bf16 v[20:23], v[214:217], v[198:201], v[20:23]
	v_mfma_f32_16x16x32_bf16 v[16:19], v[238:241], v[198:201], v[16:19]
	v_mfma_f32_16x16x32_bf16 v[4:7], v[214:217], v[206:209], v[4:7]
	v_mfma_f32_16x16x32_bf16 v[0:3], v[238:241], v[206:209], v[0:3]
	v_mfma_f32_16x16x32_bf16 v[52:55], v[226:229], v[172:175], v[52:55]
	v_mfma_f32_16x16x32_bf16 v[48:51], v[242:245], v[172:175], v[48:51]
	v_mfma_f32_16x16x32_bf16 v[36:39], v[226:229], v[194:197], v[36:39]
	v_mfma_f32_16x16x32_bf16 v[32:35], v[242:245], v[194:197], v[32:35]
	v_mfma_f32_16x16x32_bf16 v[20:23], v[226:229], v[202:205], v[20:23]
	v_mfma_f32_16x16x32_bf16 v[16:19], v[242:245], v[202:205], v[16:19]
	v_mfma_f32_16x16x32_bf16 v[4:7], v[226:229], v[210:213], v[4:7]
	v_mfma_f32_16x16x32_bf16 v[0:3], v[242:245], v[210:213], v[0:3]
	s_setprio 0
	s_add_i32 s31, s31, 2
	s_add_u32 s29, s29, 0x100
	s_addc_u32 s30, s30, 0
	s_add_u32 s2, s2, 0x100
	s_addc_u32 s3, s3, 0
	s_cmp_gt_u32 s31, 29
	s_barrier
	s_cbranch_scc0 .LBB0_651
	v_add_u32_e32 v171, s97, v159
	v_readfirstlane_b32 s0, v130
	v_sub_u32_e32 v130, 0, v171
	v_max_i32_e32 v130, v171, v130
	v_readfirstlane_b32 s42, v131
	v_mul_hi_u32 v131, v130, v152
	v_mul_lo_u32 v132, v131, s17
	v_sub_u32_e32 v130, v130, v132
	v_cmp_le_u32_e32 vcc, s17, v130
	v_add_u32_e32 v132, 1, v131
	v_ashrrev_i32_e32 v80, 31, v171
	v_cndmask_b32_e32 v131, v131, v132, vcc
	v_subrev_u32_e32 v132, s17, v130
	v_cndmask_b32_e32 v130, v130, v132, vcc
	v_cmp_le_u32_e32 vcc, s17, v130
	v_add_u32_e32 v130, 1, v131
	v_mov_b64_e32 v[136:137], s[62:63]
	v_cndmask_b32_e32 v130, v131, v130, vcc
	v_xor_b32_e32 v130, v130, v80
	v_sub_u32_e32 v130, v130, v80
	v_mul_lo_u32 v80, v130, s17
	v_sub_u32_e32 v80, v171, v80
	v_sub_u32_e32 v132, 0, v80
	v_max_i32_e32 v132, v80, v132
	v_mul_hi_u32 v133, v132, v169
	v_mul_lo_u32 v134, v133, s83
	v_sub_u32_e32 v132, v132, v134
	v_cmp_le_u32_e32 vcc, s83, v132
	v_add_u32_e32 v134, 1, v133
	v_ashrrev_i32_e32 v131, 31, v80
	v_cndmask_b32_e32 v133, v133, v134, vcc
	v_subrev_u32_e32 v134, s83, v132
	v_cndmask_b32_e32 v132, v132, v134, vcc
	v_cmp_le_u32_e32 vcc, s83, v132
	v_add_u32_e32 v132, 1, v133
	v_xor_b32_e32 v131, s87, v131
	v_cndmask_b32_e32 v132, v133, v132, vcc
	v_xor_b32_e32 v132, v132, v131
	v_sub_u32_e32 v132, v132, v131
	v_mul_lo_u32 v131, v132, s79
	v_sub_u32_e32 v138, v80, v131
	v_ashrrev_i32_e32 v131, 31, v130
	v_lshlrev_b64 v[130:131], s81, v[130:131]
	v_lshl_add_u64 v[130:131], v[130:131], 3, s[4:5]
	v_ashrrev_i32_e32 v133, 31, v132
	v_ashrrev_i32_e32 v139, 31, v138
	v_lshl_add_u64 v[140:141], v[132:133], 3, v[130:131]
	v_lshlrev_b64 v[130:131], s18, v[138:139]
	v_lshl_add_u64 v[130:131], v[130:131], 3, v[140:141]
	global_load_dwordx2 v[130:131], v[130:131], off
	v_add_u32_e32 v132, 1, v138
	v_ashrrev_i32_e32 v133, 31, v132
	v_lshlrev_b64 v[132:133], s18, v[132:133]
	v_lshl_add_u64 v[132:133], v[132:133], 3, v[140:141]
	global_load_dwordx2 v[132:133], v[132:133], off
	v_add_u32_e32 v134, 3, v138
	v_ashrrev_i32_e32 v135, 31, v134
	v_lshlrev_b64 v[134:135], s18, v[134:135]
	v_lshl_add_u64 v[134:135], v[134:135], 3, v[140:141]
	global_load_dwordx2 v[134:135], v[134:135], off
	v_add_u32_e32 v142, 5, v138
	v_ashrrev_i32_e32 v143, 31, v142
	v_lshlrev_b64 v[142:143], s18, v[142:143]
	v_lshl_add_u64 v[142:143], v[142:143], 3, v[140:141]
	s_cmp_eq_u32 s96, s86
	s_mov_b64 s[38:39], s[36:37]
	global_load_dwordx2 v[142:143], v[142:143], off
	s_waitcnt vmcnt(0) lgkmcnt(0)
; __device__ __forceinline__ float rinv_of(unsigned long long ss) { return rsqrtf((float)ss * (1.f / 16777216.f) * (1.f / DM) + 1e-6f); }
;   __device__ __forceinline__ void operator()(const f32x4 (&acc)[2][2][4][2], const Unit& u, const EpiCtx& x_, int wr, int wc, int fr, int fq) const {
;     ...
;     { const int lg = x_.p0, S = x_.p1, L = S >> lg;
; #pragma unroll
;       for (int bj = 0; bj < 2; ++bj) {
;         const int col = u.c0 + wc * 64 + bj * 32 + 8 * fq, seq = col / S, rem = col % S, r = rem / L, m0 = rem % L;
;         const unsigned long long* sp = x_.ss + (size_t)seq * S + r;
; #pragma unroll
;         for (int i = 0; i < 8; ++i) cs[bj][i >> 2][i & 3] = rinv_of(sp[(size_t)(m0 + i) << lg]);
	v_ffbh_u32_e32 v80, v131
	v_min_u32_e32 v80, 32, v80
	v_lshlrev_b64 v[130:131], v80, v[130:131]
	v_min_u32_e32 v130, 1, v130
	v_or_b32_e32 v130, v131, v130
	v_cvt_f32_u32_e32 v130, v130
	v_sub_u32_e32 v80, 32, v80
	v_ldexp_f32 v130, v130, v80
	v_ffbh_u32_e32 v80, v133
	v_min_u32_e32 v80, 32, v80
	v_lshlrev_b64 v[132:133], v80, v[132:133]
	v_min_u32_e32 v131, 1, v132
	v_or_b32_e32 v131, v133, v131
	v_cvt_f32_u32_e32 v131, v131
	v_sub_u32_e32 v80, 32, v80
	v_ldexp_f32 v131, v131, v80
	v_pk_mul_f32 v[130:131], v[130:131], s[60:61] op_sel_hi:[1,0]
	s_nop 0
	v_pk_fma_f32 v[130:131], v[130:131], s[26:27], v[136:137] op_sel_hi:[1,0,0]
	s_nop 0
	v_mul_f32_e32 v80, 0x4b800000, v130
	v_cmp_gt_f32_e64 s[2:3], s50, v130
	v_cmp_gt_f32_e32 vcc, s50, v131
	s_nop 0
	v_cndmask_b32_e64 v80, v130, v80, s[2:3]
	v_rsq_f32_e32 v130, v80
	v_mul_f32_e32 v80, 0x4b800000, v131
	v_cndmask_b32_e32 v80, v131, v80, vcc
	v_rsq_f32_e32 v131, v80
	v_ffbh_u32_e32 v80, v135
	v_min_u32_e32 v80, 32, v80
	v_lshlrev_b64 v[134:135], v80, v[134:135]
	v_pk_mul_f32 v[132:133], v[130:131], s[64:65] op_sel_hi:[1,0]
	v_min_u32_e32 v134, 1, v134
	v_cndmask_b32_e64 v130, v130, v132, s[2:3]
	v_add_u32_e32 v132, 2, v138
	v_cndmask_b32_e32 v131, v131, v133, vcc
	v_ashrrev_i32_e32 v133, 31, v132
	v_lshlrev_b64 v[132:133], s18, v[132:133]
	v_lshl_add_u64 v[132:133], v[132:133], 3, v[140:141]
	global_load_dwordx2 v[132:133], v[132:133], off
	v_or_b32_e32 v134, v135, v134
	v_cvt_f32_u32_e32 v134, v134
	v_sub_u32_e32 v80, 32, v80
	v_pk_mul_f32 v[126:127], v[126:127], v[130:131]
	v_pk_mul_f32 v[110:111], v[110:111], v[130:131]
	v_ldexp_f32 v135, v134, v80
	v_cvt_pk_bf16_f32 v126, v126, v127
	v_pk_mul_f32 v[94:95], v[94:95], v[130:131]
	v_pk_mul_f32 v[76:77], v[76:77], v[130:131]
	v_pk_mul_f32 v[60:61], v[60:61], v[130:131]
	v_pk_mul_f32 v[44:45], v[44:45], v[130:131]
	v_pk_mul_f32 v[28:29], v[28:29], v[130:131]
	v_pk_mul_f32 v[12:13], v[12:13], v[130:131]
	s_waitcnt vmcnt(0) lgkmcnt(0)
	v_ffbh_u32_e32 v80, v133
	v_min_u32_e32 v80, 32, v80
	v_lshlrev_b64 v[132:133], v80, v[132:133]
	v_min_u32_e32 v132, 1, v132
	v_or_b32_e32 v132, v133, v132
	v_cvt_f32_u32_e32 v132, v132
	v_sub_u32_e32 v80, 32, v80
	v_ldexp_f32 v134, v132, v80
	v_pk_mul_f32 v[132:133], v[134:135], s[60:61] op_sel_hi:[1,0]
	s_nop 0
	v_pk_fma_f32 v[132:133], v[132:133], s[26:27], v[136:137] op_sel_hi:[1,0,0]
	s_nop 0
	v_mul_f32_e32 v80, 0x4b800000, v132
	v_cmp_gt_f32_e64 s[2:3], s50, v132
	v_cmp_gt_f32_e32 vcc, s50, v133
	s_nop 0
	v_cndmask_b32_e64 v80, v132, v80, s[2:3]
	v_rsq_f32_e32 v132, v80
	v_mul_f32_e32 v80, 0x4b800000, v133
	v_cndmask_b32_e32 v80, v133, v80, vcc
	v_rsq_f32_e32 v133, v80
	v_ffbh_u32_e32 v80, v143
	v_min_u32_e32 v80, 32, v80
	v_lshlrev_b64 v[142:143], v80, v[142:143]
	v_pk_mul_f32 v[134:135], v[132:133], s[64:65] op_sel_hi:[1,0]
	v_min_u32_e32 v139, 1, v142
	v_cndmask_b32_e64 v132, v132, v134, s[2:3]
	v_add_u32_e32 v134, 4, v138
	v_cndmask_b32_e32 v133, v133, v135, vcc
	v_ashrrev_i32_e32 v135, 31, v134
	v_lshlrev_b64 v[134:135], s18, v[134:135]
	v_lshl_add_u64 v[134:135], v[134:135], 3, v[140:141]
	global_load_dwordx2 v[134:135], v[134:135], off
	v_or_b32_e32 v139, v143, v139
	v_cvt_f32_u32_e32 v139, v139
	v_sub_u32_e32 v80, 32, v80
	v_pk_mul_f32 v[128:129], v[128:129], v[132:133]
	v_pk_mul_f32 v[112:113], v[112:113], v[132:133]
	v_ldexp_f32 v143, v139, v80
	v_cvt_pk_bf16_f32 v127, v128, v129
	v_pk_mul_f32 v[96:97], v[96:97], v[132:133]
	v_pk_mul_f32 v[78:79], v[78:79], v[132:133]
	v_pk_mul_f32 v[62:63], v[62:63], v[132:133]
	v_pk_mul_f32 v[46:47], v[46:47], v[132:133]
	v_pk_mul_f32 v[30:31], v[30:31], v[132:133]
	v_pk_mul_f32 v[14:15], v[14:15], v[132:133]
	s_waitcnt vmcnt(0) lgkmcnt(0)
	v_ffbh_u32_e32 v80, v135
	v_min_u32_e32 v80, 32, v80
	v_lshlrev_b64 v[134:135], v80, v[134:135]
	v_min_u32_e32 v134, 1, v134
	v_or_b32_e32 v134, v135, v134
	v_cvt_f32_u32_e32 v134, v134
	v_sub_u32_e32 v80, 32, v80
	v_ldexp_f32 v142, v134, v80
	v_pk_mul_f32 v[134:135], v[142:143], s[60:61] op_sel_hi:[1,0]
	s_nop 0
	v_pk_fma_f32 v[134:135], v[134:135], s[26:27], v[136:137] op_sel_hi:[1,0,0]
	s_nop 0
	v_mul_f32_e32 v80, 0x4b800000, v134
	v_cmp_gt_f32_e64 s[2:3], s50, v134
	v_cmp_gt_f32_e32 vcc, s50, v135
	s_nop 0
	v_cndmask_b32_e64 v80, v134, v80, s[2:3]
	v_rsq_f32_e32 v134, v80
	v_mul_f32_e32 v80, 0x4b800000, v135
	v_cndmask_b32_e32 v80, v135, v80, vcc
	v_rsq_f32_e32 v135, v80
	s_nop 0
	v_pk_mul_f32 v[142:143], v[134:135], s[64:65] op_sel_hi:[1,0]
	s_nop 0
	v_cndmask_b32_e64 v134, v134, v142, s[2:3]
	v_add_u32_e32 v142, 6, v138
	v_add_u32_e32 v138, 7, v138
	v_cndmask_b32_e32 v135, v135, v143, vcc
	v_ashrrev_i32_e32 v143, 31, v142
	v_ashrrev_i32_e32 v139, 31, v138
	v_lshlrev_b64 v[142:143], s18, v[142:143]
	v_lshlrev_b64 v[138:139], s18, v[138:139]
	v_lshl_add_u64 v[142:143], v[142:143], 3, v[140:141]
	v_lshl_add_u64 v[138:139], v[138:139], 3, v[140:141]
	global_load_dwordx2 v[142:143], v[142:143], off
	v_pk_mul_f32 v[122:123], v[122:123], v[134:135]
	global_load_dwordx2 v[138:139], v[138:139], off
	v_cvt_pk_bf16_f32 v128, v122, v123
	v_ashrrev_i32_e32 v122, 5, v171
	v_ashrrev_i32_e32 v123, 31, v122
	v_lshlrev_b64 v[122:123], 13, v[122:123]
	v_lshl_add_u64 v[122:123], s[94:95], 0, v[122:123]
	s_waitcnt vmcnt(0) lgkmcnt(0)
; __device__ __forceinline__ float rinv_of(unsigned long long ss) { return rsqrtf((float)ss * (1.f / 16777216.f) * (1.f / DM) + 1e-6f); }
;   __device__ __forceinline__ void operator()(const f32x4 (&acc)[2][2][4][2], const Unit& u, const EpiCtx& x_, int wr, int wc, int fr, int fq) const {
;     ...
;     { const int lg = x_.p0, S = x_.p1, L = S >> lg;
; #pragma unroll
;       for (int bj = 0; bj < 2; ++bj) {
;         const int col = u.c0 + wc * 64 + bj * 32 + 8 * fq, seq = col / S, rem = col % S, r = rem / L, m0 = rem % L;
;         const unsigned long long* sp = x_.ss + (size_t)seq * S + r;
; #pragma unroll
;         for (int i = 0; i < 8; ++i) cs[bj][i >> 2][i & 3] = rinv_of(sp[(size_t)(m0 + i) << lg]);
;       } }
; #pragma unroll
;     for (int ai = 0; ai < 2; ++ai)
; #pragma unroll
;       for (int m = 0; m < 4; ++m) {
;         const int row = u.r0 + ai * 128 + wr * 64 + m * 16 + fr, hh = (x_.p0 >> 1) * 16 + (row >> 7), d = row & 127;
; #pragma unroll
;         for (int bj = 0; bj < 2; ++bj) {
;           const int col = u.c0 + wc * 64 + bj * 32 + 8 * fq;
;           const f32x4 v0 = acc[ai][bj][m][0] * cs[bj][0], v1 = acc[ai][bj][m][1] * cs[bj][1];
	v_ffbh_u32_e32 v80, v139
	v_min_u32_e32 v80, 32, v80
	v_lshlrev_b64 v[138:139], v80, v[138:139]
	v_min_u32_e32 v138, 1, v138
	v_or_b32_e32 v138, v139, v138
	v_cvt_f32_u32_e32 v138, v138
	v_sub_u32_e32 v80, 32, v80
	v_ldexp_f32 v139, v138, v80
	v_ffbh_u32_e32 v80, v143
	v_min_u32_e32 v80, 32, v80
	v_lshlrev_b64 v[140:141], v80, v[142:143]
	v_min_u32_e32 v138, 1, v140
	v_or_b32_e32 v138, v141, v138
	v_cvt_f32_u32_e32 v138, v138
	v_sub_u32_e32 v80, 32, v80
	v_ldexp_f32 v138, v138, v80
	v_pk_mul_f32 v[138:139], v[138:139], s[60:61] op_sel_hi:[1,0]
	s_nop 0
	v_pk_fma_f32 v[138:139], v[138:139], s[26:27], v[136:137] op_sel_hi:[1,0,0]
	s_nop 0
	v_mul_f32_e32 v80, 0x4b800000, v138
	v_cmp_gt_f32_e64 s[2:3], s50, v138
	v_cmp_gt_f32_e32 vcc, s50, v139
	s_nop 0
	v_cndmask_b32_e64 v80, v138, v80, s[2:3]
	v_rsq_f32_e32 v138, v80
	v_mul_f32_e32 v80, 0x4b800000, v139
	v_cndmask_b32_e32 v80, v139, v80, vcc
	v_rsq_f32_e32 v139, v80
	v_add_u32_e32 v80, 32, v171
	v_pk_mul_f32 v[140:141], v[138:139], s[64:65] op_sel_hi:[1,0]
	s_nop 0
	v_cndmask_b32_e32 v139, v139, v141, vcc
	v_sub_u32_e32 v141, 0xffffffe0, v171
	v_max_i32_e32 v141, v80, v141
	v_mul_hi_u32 v142, v141, v152
	v_mul_lo_u32 v143, v142, s17
	v_sub_u32_e32 v141, v141, v143
	v_cmp_le_u32_e32 vcc, s17, v141
	v_add_u32_e32 v143, 1, v142
	v_cndmask_b32_e64 v138, v138, v140, s[2:3]
	v_cndmask_b32_e32 v142, v142, v143, vcc
	v_subrev_u32_e32 v143, s17, v141
	v_cndmask_b32_e32 v141, v141, v143, vcc
	v_cmp_le_u32_e32 vcc, s17, v141
	v_add_u32_e32 v141, 1, v142
	v_ashrrev_i32_e32 v140, 31, v80
	v_cndmask_b32_e32 v141, v142, v141, vcc
	v_xor_b32_e32 v141, v141, v140
	v_sub_u32_e32 v140, v141, v140
	v_mul_lo_u32 v141, v140, s17
	v_sub_u32_e32 v80, v80, v141
	v_sub_u32_e32 v142, 0, v80
	v_max_i32_e32 v142, v80, v142
	v_mul_hi_u32 v143, v142, v169
	v_mul_lo_u32 v144, v143, s83
	v_sub_u32_e32 v142, v142, v144
	v_cmp_le_u32_e32 vcc, s83, v142
	v_add_u32_e32 v144, 1, v143
	v_ashrrev_i32_e32 v141, 31, v80
	v_cndmask_b32_e32 v143, v143, v144, vcc
	v_subrev_u32_e32 v144, s83, v142
	v_cndmask_b32_e32 v142, v142, v144, vcc
	v_cmp_le_u32_e32 vcc, s83, v142
	v_add_u32_e32 v142, 1, v143
	v_xor_b32_e32 v141, s87, v141
	v_cndmask_b32_e32 v142, v143, v142, vcc
	v_xor_b32_e32 v142, v142, v141
	v_sub_u32_e32 v142, v142, v141
	v_mul_lo_u32 v141, v142, s79
	v_sub_u32_e32 v146, v80, v141
	v_ashrrev_i32_e32 v141, 31, v140
	v_lshlrev_b64 v[140:141], s81, v[140:141]
	v_lshl_add_u64 v[140:141], v[140:141], 3, s[4:5]
	v_ashrrev_i32_e32 v143, 31, v142
	v_ashrrev_i32_e32 v147, 31, v146
	v_lshl_add_u64 v[148:149], v[142:143], 3, v[140:141]
	v_lshlrev_b64 v[140:141], s18, v[146:147]
	v_lshl_add_u64 v[140:141], v[140:141], 3, v[148:149]
	global_load_dwordx2 v[140:141], v[140:141], off
	v_add_u32_e32 v142, 1, v146
	v_ashrrev_i32_e32 v143, 31, v142
	v_lshlrev_b64 v[142:143], s18, v[142:143]
	v_lshl_add_u64 v[142:143], v[142:143], 3, v[148:149]
	global_load_dwordx2 v[142:143], v[142:143], off
	v_add_u32_e32 v144, 3, v146
	v_ashrrev_i32_e32 v145, 31, v144
	v_lshlrev_b64 v[144:145], s18, v[144:145]
	v_lshl_add_u64 v[144:145], v[144:145], 3, v[148:149]
	global_load_dwordx2 v[144:145], v[144:145], off
	v_add_u32_e32 v150, 5, v146
	v_ashrrev_i32_e32 v151, 31, v150
	v_lshlrev_b64 v[150:151], s18, v[150:151]
	v_lshl_add_u64 v[150:151], v[150:151], 3, v[148:149]
	v_pk_mul_f32 v[124:125], v[124:125], v[138:139]
	global_load_dwordx2 v[150:151], v[150:151], off
	v_cvt_pk_bf16_f32 v129, v124, v125
	s_waitcnt vmcnt(0) lgkmcnt(0)
	v_ffbh_u32_e32 v80, v141
	v_min_u32_e32 v80, 32, v80
	v_lshlrev_b64 v[140:141], v80, v[140:141]
	v_min_u32_e32 v140, 1, v140
	v_or_b32_e32 v140, v141, v140
	v_cvt_f32_u32_e32 v140, v140
	v_sub_u32_e32 v80, 32, v80
	v_ldexp_f32 v140, v140, v80
	v_ffbh_u32_e32 v80, v143
	v_min_u32_e32 v80, 32, v80
	v_lshlrev_b64 v[142:143], v80, v[142:143]
	v_min_u32_e32 v141, 1, v142
	v_or_b32_e32 v141, v143, v141
	v_cvt_f32_u32_e32 v141, v141
	v_sub_u32_e32 v80, 32, v80
	v_ldexp_f32 v141, v141, v80
	v_pk_mul_f32 v[140:141], v[140:141], s[60:61] op_sel_hi:[1,0]
	s_nop 0
	v_pk_fma_f32 v[140:141], v[140:141], s[26:27], v[136:137] op_sel_hi:[1,0,0]
	s_nop 0
	v_mul_f32_e32 v80, 0x4b800000, v140
	v_cmp_gt_f32_e64 s[2:3], s50, v140
	v_cmp_gt_f32_e32 vcc, s50, v141
	s_nop 0
	v_cndmask_b32_e64 v80, v140, v80, s[2:3]
	v_rsq_f32_e32 v140, v80
	v_mul_f32_e32 v80, 0x4b800000, v141
	v_cndmask_b32_e32 v80, v141, v80, vcc
	v_rsq_f32_e32 v141, v80
	v_ffbh_u32_e32 v80, v145
	v_min_u32_e32 v80, 32, v80
	v_lshlrev_b64 v[144:145], v80, v[144:145]
	v_pk_mul_f32 v[142:143], v[140:141], s[64:65] op_sel_hi:[1,0]
	v_min_u32_e32 v144, 1, v144
	v_cndmask_b32_e64 v140, v140, v142, s[2:3]
	v_add_u32_e32 v142, 2, v146
	v_cndmask_b32_e32 v141, v141, v143, vcc
	v_ashrrev_i32_e32 v143, 31, v142
	v_lshlrev_b64 v[142:143], s18, v[142:143]
	v_lshl_add_u64 v[142:143], v[142:143], 3, v[148:149]
	global_load_dwordx2 v[142:143], v[142:143], off
	v_or_b32_e32 v144, v145, v144
	v_cvt_f32_u32_e32 v144, v144
	v_sub_u32_e32 v80, 32, v80
	v_pk_mul_f32 v[118:119], v[118:119], v[140:141]
	v_pk_mul_f32 v[102:103], v[102:103], v[140:141]
	v_ldexp_f32 v145, v144, v80
	v_pk_mul_f32 v[86:87], v[86:87], v[140:141]
	v_pk_mul_f32 v[68:69], v[68:69], v[140:141]
	v_pk_mul_f32 v[52:53], v[52:53], v[140:141]
	v_pk_mul_f32 v[36:37], v[36:37], v[140:141]
	v_pk_mul_f32 v[20:21], v[20:21], v[140:141]
	v_pk_mul_f32 v[4:5], v[4:5], v[140:141]
	s_waitcnt vmcnt(0) lgkmcnt(0)
; __device__ __forceinline__ unsigned cvt_pk_bf16(float lo, float hi) { unsigned r; asm("v_cvt_pk_bf16_f32 %0, %1, %2" : "=v"(r) : "v"(lo), "v"(hi)); return r; }
; __device__ __forceinline__ float rinv_of(unsigned long long ss) { return rsqrtf((float)ss * (1.f / 16777216.f) * (1.f / DM) + 1e-6f); }
;   __device__ __forceinline__ void operator()(const f32x4 (&acc)[2][2][4][2], const Unit& u, const EpiCtx& x_, int wr, int wc, int fr, int fq) const {
;     ...
;         for (int i = 0; i < 8; ++i) cs[bj][i >> 2][i & 3] = rinv_of(sp[(size_t)(m0 + i) << lg]);
;       } }
; #pragma unroll
;     for (int ai = 0; ai < 2; ++ai)
; #pragma unroll
;       for (int m = 0; m < 4; ++m) {
;         const int row = u.r0 + ai * 128 + wr * 64 + m * 16 + fr, hh = (x_.p0 >> 1) * 16 + (row >> 7), d = row & 127;
; #pragma unroll
;         for (int bj = 0; bj < 2; ++bj) {
;           const int col = u.c0 + wc * 64 + bj * 32 + 8 * fq;
;           const f32x4 v0 = acc[ai][bj][m][0] * cs[bj][0], v1 = acc[ai][bj][m][1] * cs[bj][1];
;           uint4 o; o.x = cvt_pk_bf16(v0[0], v0[1]); o.y = cvt_pk_bf16(v0[2], v0[3]); o.z = cvt_pk_bf16(v1[0], v1[1]); o.w = cvt_pk_bf16(v1[2], v1[3]);
;           *(uint4*)((bf16_t*)u.C + (((size_t)hh * (TS / 32) + (col >> 5)) * 128 + d) * 32 + (col & 31)) = o;
	v_ffbh_u32_e32 v80, v143
	v_min_u32_e32 v80, 32, v80
	v_lshlrev_b64 v[142:143], v80, v[142:143]
	v_min_u32_e32 v142, 1, v142
	v_or_b32_e32 v142, v143, v142
	v_cvt_f32_u32_e32 v142, v142
	v_sub_u32_e32 v80, 32, v80
	v_ldexp_f32 v144, v142, v80
	v_pk_mul_f32 v[142:143], v[144:145], s[60:61] op_sel_hi:[1,0]
	s_nop 0
	v_pk_fma_f32 v[142:143], v[142:143], s[26:27], v[136:137] op_sel_hi:[1,0,0]
	s_nop 0
	v_mul_f32_e32 v80, 0x4b800000, v142
	v_cmp_gt_f32_e64 s[2:3], s50, v142
	v_cmp_gt_f32_e32 vcc, s50, v143
	s_nop 0
	v_cndmask_b32_e64 v80, v142, v80, s[2:3]
	v_rsq_f32_e32 v142, v80
	v_mul_f32_e32 v80, 0x4b800000, v143
	v_cndmask_b32_e32 v80, v143, v80, vcc
	v_rsq_f32_e32 v143, v80
	v_ffbh_u32_e32 v80, v151
	v_min_u32_e32 v80, 32, v80
	v_lshlrev_b64 v[150:151], v80, v[150:151]
	v_pk_mul_f32 v[144:145], v[142:143], s[64:65] op_sel_hi:[1,0]
	v_min_u32_e32 v147, 1, v150
	v_cndmask_b32_e64 v142, v142, v144, s[2:3]
	v_add_u32_e32 v144, 4, v146
	v_cndmask_b32_e32 v143, v143, v145, vcc
	v_ashrrev_i32_e32 v145, 31, v144
	v_lshlrev_b64 v[144:145], s18, v[144:145]
	v_lshl_add_u64 v[144:145], v[144:145], 3, v[148:149]
	global_load_dwordx2 v[144:145], v[144:145], off
	v_or_b32_e32 v147, v151, v147
	v_cvt_f32_u32_e32 v147, v147
	v_sub_u32_e32 v80, 32, v80
	v_pk_mul_f32 v[120:121], v[120:121], v[142:143]
	v_pk_mul_f32 v[104:105], v[104:105], v[142:143]
	v_ldexp_f32 v151, v147, v80
	v_pk_mul_f32 v[88:89], v[88:89], v[142:143]
	v_pk_mul_f32 v[70:71], v[70:71], v[142:143]
	v_pk_mul_f32 v[54:55], v[54:55], v[142:143]
	v_pk_mul_f32 v[38:39], v[38:39], v[142:143]
	v_pk_mul_f32 v[22:23], v[22:23], v[142:143]
	v_pk_mul_f32 v[6:7], v[6:7], v[142:143]
	s_waitcnt vmcnt(0) lgkmcnt(0)
	v_ffbh_u32_e32 v80, v145
	v_min_u32_e32 v80, 32, v80
	v_lshlrev_b64 v[144:145], v80, v[144:145]
	v_min_u32_e32 v144, 1, v144
	v_or_b32_e32 v144, v145, v144
	v_cvt_f32_u32_e32 v144, v144
	v_sub_u32_e32 v80, 32, v80
	v_ldexp_f32 v150, v144, v80
	v_pk_mul_f32 v[144:145], v[150:151], s[60:61] op_sel_hi:[1,0]
	s_nop 0
	v_pk_fma_f32 v[144:145], v[144:145], s[26:27], v[136:137] op_sel_hi:[1,0,0]
	s_nop 0
	v_mul_f32_e32 v80, 0x4b800000, v144
	v_cmp_gt_f32_e64 s[2:3], s50, v144
	v_cmp_gt_f32_e32 vcc, s50, v145
	s_nop 0
	v_cndmask_b32_e64 v80, v144, v80, s[2:3]
	v_rsq_f32_e32 v144, v80
	v_mul_f32_e32 v80, 0x4b800000, v145
	v_cndmask_b32_e32 v80, v145, v80, vcc
	v_rsq_f32_e32 v145, v80
	s_nop 0
	v_pk_mul_f32 v[150:151], v[144:145], s[64:65] op_sel_hi:[1,0]
	s_nop 0
	v_cndmask_b32_e64 v144, v144, v150, s[2:3]
	v_add_u32_e32 v150, 6, v146
	v_add_u32_e32 v146, 7, v146
	v_cndmask_b32_e32 v145, v145, v151, vcc
	v_ashrrev_i32_e32 v151, 31, v150
	v_ashrrev_i32_e32 v147, 31, v146
	v_lshlrev_b64 v[150:151], s18, v[150:151]
	v_lshlrev_b64 v[146:147], s18, v[146:147]
	v_lshl_add_u64 v[150:151], v[150:151], 3, v[148:149]
	v_lshl_add_u64 v[146:147], v[146:147], 3, v[148:149]
	global_load_dwordx2 v[150:151], v[150:151], off
	v_pk_mul_f32 v[114:115], v[114:115], v[144:145]
	global_load_dwordx2 v[146:147], v[146:147], off
	s_waitcnt vmcnt(0) lgkmcnt(0)
	v_ffbh_u32_e32 v80, v147
	v_min_u32_e32 v80, 32, v80
	v_lshlrev_b64 v[146:147], v80, v[146:147]
	v_min_u32_e32 v146, 1, v146
	v_or_b32_e32 v146, v147, v146
	v_cvt_f32_u32_e32 v146, v146
	v_sub_u32_e32 v80, 32, v80
	v_ldexp_f32 v147, v146, v80
	v_ffbh_u32_e32 v80, v151
	v_min_u32_e32 v80, 32, v80
	v_lshlrev_b64 v[148:149], v80, v[150:151]
	v_min_u32_e32 v146, 1, v148
	v_or_b32_e32 v146, v149, v146
	v_cvt_f32_u32_e32 v146, v146
	v_sub_u32_e32 v80, 32, v80
	v_ldexp_f32 v146, v146, v80
	v_pk_mul_f32 v[146:147], v[146:147], s[60:61] op_sel_hi:[1,0]
	s_nop 0
	v_pk_fma_f32 v[136:137], v[146:147], s[26:27], v[136:137] op_sel_hi:[1,0,0]
	s_nop 0
	v_mul_f32_e32 v80, 0x4b800000, v136
	v_cmp_gt_f32_e64 s[2:3], s50, v136
	v_cmp_gt_f32_e32 vcc, s50, v137
	s_nop 0
	v_cndmask_b32_e64 v80, v136, v80, s[2:3]
	v_rsq_f32_e32 v136, v80
	v_mul_f32_e32 v80, 0x4b800000, v137
	v_cndmask_b32_e32 v80, v137, v80, vcc
	v_rsq_f32_e32 v137, v80
	v_add_u32_e32 v80, s75, v157
	v_pk_mul_f32 v[146:147], v[136:137], s[64:65] op_sel_hi:[1,0]
	s_nop 0
	v_cndmask_b32_e64 v136, v136, v146, s[2:3]
	v_ashrrev_i32_e32 v146, 7, v80
	v_add_u32_e32 v146, s82, v146
	v_cndmask_b32_e32 v137, v137, v147, vcc
	v_ashrrev_i32_e32 v147, 31, v146
	v_lshlrev_b64 v[146:147], 22, v[146:147]
	v_lshlrev_b32_e32 v80, 6, v80
	v_and_b32_e32 v80, 0x1fc0, v80
	v_lshl_add_u64 v[124:125], v[122:123], 0, v[146:147]
	v_lshl_add_u64 v[148:149], v[124:125], 0, v[80:81]
	v_and_b32_e32 v124, 31, v171
	v_lshlrev_b32_e32 v124, 1, v124
	v_mov_b32_e32 v125, v81
	v_lshl_add_u64 v[148:149], v[148:149], 0, v[124:125]
	global_store_dwordx4 v[148:149], v[126:129], off
	s_mov_b64 s[2:3], s[8:9]
	s_nop 0
	v_add_u32_e32 v128, s97, v160
	v_pk_mul_f32 v[126:127], v[116:117], v[136:137]
	v_cvt_pk_bf16_f32 v116, v118, v119
	v_cvt_pk_bf16_f32 v118, v114, v115
	v_ashrrev_i32_e32 v114, 5, v128
	v_ashrrev_i32_e32 v115, 31, v114
	v_lshlrev_b64 v[114:115], 13, v[114:115]
	v_lshl_add_u64 v[114:115], s[94:95], 0, v[114:115]
	v_cvt_pk_bf16_f32 v117, v120, v121
	v_lshl_add_u64 v[120:121], v[114:115], 0, v[146:147]
	v_lshl_add_u64 v[120:121], v[120:121], 0, v[80:81]
	v_and_b32_e32 v80, 31, v128
	v_lshlrev_b32_e32 v80, 1, v80
	v_lshl_add_u64 v[120:121], v[120:121], 0, v[80:81]
	v_cvt_pk_bf16_f32 v119, v126, v127
	global_store_dwordx4 v[120:121], v[116:119], off
	v_add_u32_e32 v120, s75, v161
	s_mov_b64 s[94:95], s[40:41]
	v_ashrrev_i32_e32 v116, 7, v120
	v_add_u32_e32 v116, s82, v116
	v_ashrrev_i32_e32 v117, 31, v116
	v_pk_mul_f32 v[118:119], v[108:109], v[138:139]
	v_pk_mul_f32 v[108:109], v[106:107], v[134:135]
	v_cvt_pk_bf16_f32 v106, v110, v111
; __device__ __forceinline__ unsigned cvt_pk_bf16(float lo, float hi) { unsigned r; asm("v_cvt_pk_bf16_f32 %0, %1, %2" : "=v"(r) : "v"(lo), "v"(hi)); return r; }
;   __device__ __forceinline__ void operator()(const f32x4 (&acc)[2][2][4][2], const Unit& u, const EpiCtx& x_, int wr, int wc, int fr, int fq) const {
;     ...
; #pragma unroll
;     for (int ai = 0; ai < 2; ++ai)
; #pragma unroll
;       for (int m = 0; m < 4; ++m) {
;         const int row = u.r0 + ai * 128 + wr * 64 + m * 16 + fr, hh = (x_.p0 >> 1) * 16 + (row >> 7), d = row & 127;
; #pragma unroll
;         for (int bj = 0; bj < 2; ++bj) {
;           const int col = u.c0 + wc * 64 + bj * 32 + 8 * fq;
;           const f32x4 v0 = acc[ai][bj][m][0] * cs[bj][0], v1 = acc[ai][bj][m][1] * cs[bj][1];
;           uint4 o; o.x = cvt_pk_bf16(v0[0], v0[1]); o.y = cvt_pk_bf16(v0[2], v0[3]); o.z = cvt_pk_bf16(v1[0], v1[1]); o.w = cvt_pk_bf16(v1[2], v1[3]);
;           *(uint4*)((bf16_t*)u.C + (((size_t)hh * (TS / 32) + (col >> 5)) * 128 + d) * 32 + (col & 31)) = o;
;         }
;       }
	v_cvt_pk_bf16_f32 v107, v112, v113
	v_lshlrev_b64 v[110:111], 22, v[116:117]
	v_lshlrev_b32_e32 v112, 6, v120
	v_and_b32_e32 v112, 0x1fc0, v112
	v_mov_b32_e32 v113, v81
	v_lshl_add_u64 v[116:117], v[122:123], 0, v[110:111]
	v_lshl_add_u64 v[116:117], v[116:117], 0, v[112:113]
	v_lshl_add_u64 v[116:117], v[116:117], 0, v[124:125]
	v_cvt_pk_bf16_f32 v108, v108, v109
	v_cvt_pk_bf16_f32 v109, v118, v119
	global_store_dwordx4 v[116:117], v[106:109], off
	s_mov_b32 s97, s42
	s_nop 0
	v_pk_mul_f32 v[106:107], v[100:101], v[136:137]
	v_pk_mul_f32 v[100:101], v[98:99], v[144:145]
	v_cvt_pk_bf16_f32 v98, v102, v103
	v_lshl_add_u64 v[102:103], v[114:115], 0, v[110:111]
	v_lshl_add_u64 v[102:103], v[102:103], 0, v[112:113]
	v_lshl_add_u64 v[102:103], v[102:103], 0, v[80:81]
	v_cvt_pk_bf16_f32 v99, v104, v105
	v_cvt_pk_bf16_f32 v100, v100, v101
	v_cvt_pk_bf16_f32 v101, v106, v107
	global_store_dwordx4 v[102:103], v[98:101], off
	v_add_u32_e32 v102, s75, v163
	s_nop 0
	v_ashrrev_i32_e32 v98, 7, v102
	v_add_u32_e32 v98, s82, v98
	v_ashrrev_i32_e32 v99, 31, v98
	v_pk_mul_f32 v[100:101], v[92:93], v[138:139]
	v_pk_mul_f32 v[92:93], v[90:91], v[134:135]
	v_cvt_pk_bf16_f32 v90, v94, v95
	v_cvt_pk_bf16_f32 v91, v96, v97
	v_lshlrev_b64 v[94:95], 22, v[98:99]
	v_lshlrev_b32_e32 v96, 6, v102
	v_and_b32_e32 v96, 0x1fc0, v96
	v_mov_b32_e32 v97, v81
	v_lshl_add_u64 v[98:99], v[122:123], 0, v[94:95]
	v_lshl_add_u64 v[98:99], v[98:99], 0, v[96:97]
	v_lshl_add_u64 v[98:99], v[98:99], 0, v[124:125]
	v_cvt_pk_bf16_f32 v92, v92, v93
	v_cvt_pk_bf16_f32 v93, v100, v101
	global_store_dwordx4 v[98:99], v[90:93], off
	s_nop 1
	v_pk_mul_f32 v[90:91], v[84:85], v[136:137]
	v_pk_mul_f32 v[84:85], v[82:83], v[144:145]
	v_cvt_pk_bf16_f32 v82, v86, v87
	v_lshl_add_u64 v[86:87], v[114:115], 0, v[94:95]
	v_lshl_add_u64 v[86:87], v[86:87], 0, v[96:97]
	v_lshl_add_u64 v[86:87], v[86:87], 0, v[80:81]
	v_cvt_pk_bf16_f32 v83, v88, v89
	v_cvt_pk_bf16_f32 v84, v84, v85
	v_cvt_pk_bf16_f32 v85, v90, v91
	global_store_dwordx4 v[86:87], v[82:85], off
	v_add_u32_e32 v86, s75, v164
	s_nop 0
	v_ashrrev_i32_e32 v82, 7, v86
	v_add_u32_e32 v82, s82, v82
	v_ashrrev_i32_e32 v83, 31, v82
	v_pk_mul_f32 v[84:85], v[74:75], v[138:139]
	v_pk_mul_f32 v[74:75], v[72:73], v[134:135]
	v_cvt_pk_bf16_f32 v72, v76, v77
	v_cvt_pk_bf16_f32 v73, v78, v79
	v_lshlrev_b64 v[76:77], 22, v[82:83]
	v_lshlrev_b32_e32 v78, 6, v86
	v_and_b32_e32 v78, 0x1fc0, v78
	v_mov_b32_e32 v79, v81
	v_lshl_add_u64 v[82:83], v[122:123], 0, v[76:77]
	v_lshl_add_u64 v[82:83], v[82:83], 0, v[78:79]
	v_lshl_add_u64 v[82:83], v[82:83], 0, v[124:125]
	v_cvt_pk_bf16_f32 v74, v74, v75
	v_cvt_pk_bf16_f32 v75, v84, v85
	global_store_dwordx4 v[82:83], v[72:75], off
	s_nop 1
	v_pk_mul_f32 v[72:73], v[66:67], v[136:137]
	v_pk_mul_f32 v[66:67], v[64:65], v[144:145]
	v_cvt_pk_bf16_f32 v64, v68, v69
	v_lshl_add_u64 v[68:69], v[114:115], 0, v[76:77]
	v_lshl_add_u64 v[68:69], v[68:69], 0, v[78:79]
	v_lshl_add_u64 v[68:69], v[68:69], 0, v[80:81]
	v_cvt_pk_bf16_f32 v65, v70, v71
	v_cvt_pk_bf16_f32 v66, v66, v67
	v_cvt_pk_bf16_f32 v67, v72, v73
	global_store_dwordx4 v[68:69], v[64:67], off
	v_add_u32_e32 v68, s75, v165
	s_nop 0
	v_ashrrev_i32_e32 v64, 7, v68
	v_add_u32_e32 v64, s82, v64
	v_ashrrev_i32_e32 v65, 31, v64
	v_pk_mul_f32 v[66:67], v[58:59], v[138:139]
	v_pk_mul_f32 v[58:59], v[56:57], v[134:135]
	v_cvt_pk_bf16_f32 v56, v60, v61
	v_cvt_pk_bf16_f32 v57, v62, v63
	v_lshlrev_b64 v[60:61], 22, v[64:65]
	v_lshlrev_b32_e32 v62, 6, v68
	v_and_b32_e32 v62, 0x1fc0, v62
	v_mov_b32_e32 v63, v81
	v_lshl_add_u64 v[64:65], v[122:123], 0, v[60:61]
	v_lshl_add_u64 v[64:65], v[64:65], 0, v[62:63]
	v_lshl_add_u64 v[64:65], v[64:65], 0, v[124:125]
	v_cvt_pk_bf16_f32 v58, v58, v59
	v_cvt_pk_bf16_f32 v59, v66, v67
	global_store_dwordx4 v[64:65], v[56:59], off
	s_nop 1
; __device__ __forceinline__ unsigned cvt_pk_bf16(float lo, float hi) { unsigned r; asm("v_cvt_pk_bf16_f32 %0, %1, %2" : "=v"(r) : "v"(lo), "v"(hi)); return r; }
;   __device__ __forceinline__ void operator()(const f32x4 (&acc)[2][2][4][2], const Unit& u, const EpiCtx& x_, int wr, int wc, int fr, int fq) const {
;     ...
; #pragma unroll
;     for (int ai = 0; ai < 2; ++ai)
; #pragma unroll
;       for (int m = 0; m < 4; ++m) {
;         const int row = u.r0 + ai * 128 + wr * 64 + m * 16 + fr, hh = (x_.p0 >> 1) * 16 + (row >> 7), d = row & 127;
; #pragma unroll
;         for (int bj = 0; bj < 2; ++bj) {
;           const int col = u.c0 + wc * 64 + bj * 32 + 8 * fq;
;           const f32x4 v0 = acc[ai][bj][m][0] * cs[bj][0], v1 = acc[ai][bj][m][1] * cs[bj][1];
;           uint4 o; o.x = cvt_pk_bf16(v0[0], v0[1]); o.y = cvt_pk_bf16(v0[2], v0[3]); o.z = cvt_pk_bf16(v1[0], v1[1]); o.w = cvt_pk_bf16(v1[2], v1[3]);
;           *(uint4*)((bf16_t*)u.C + (((size_t)hh * (TS / 32) + (col >> 5)) * 128 + d) * 32 + (col & 31)) = o;
;         }
;       }
	v_pk_mul_f32 v[56:57], v[50:51], v[136:137]
	v_pk_mul_f32 v[50:51], v[48:49], v[144:145]
	v_cvt_pk_bf16_f32 v48, v52, v53
	v_lshl_add_u64 v[52:53], v[114:115], 0, v[60:61]
	v_lshl_add_u64 v[52:53], v[52:53], 0, v[62:63]
	v_lshl_add_u64 v[52:53], v[52:53], 0, v[80:81]
	v_cvt_pk_bf16_f32 v49, v54, v55
	v_cvt_pk_bf16_f32 v50, v50, v51
	v_cvt_pk_bf16_f32 v51, v56, v57
	global_store_dwordx4 v[52:53], v[48:51], off
	v_add_u32_e32 v52, s75, v166
	s_nop 0
	v_ashrrev_i32_e32 v48, 7, v52
	v_add_u32_e32 v48, s82, v48
	v_ashrrev_i32_e32 v49, 31, v48
	v_pk_mul_f32 v[50:51], v[42:43], v[138:139]
	v_pk_mul_f32 v[42:43], v[40:41], v[134:135]
	v_cvt_pk_bf16_f32 v40, v44, v45
	v_cvt_pk_bf16_f32 v41, v46, v47
	v_lshlrev_b64 v[44:45], 22, v[48:49]
	v_lshlrev_b32_e32 v46, 6, v52
	v_and_b32_e32 v46, 0x1fc0, v46
	v_mov_b32_e32 v47, v81
	v_lshl_add_u64 v[48:49], v[122:123], 0, v[44:45]
	v_lshl_add_u64 v[48:49], v[48:49], 0, v[46:47]
	v_lshl_add_u64 v[48:49], v[48:49], 0, v[124:125]
	v_cvt_pk_bf16_f32 v42, v42, v43
	v_cvt_pk_bf16_f32 v43, v50, v51
	global_store_dwordx4 v[48:49], v[40:43], off
	s_nop 1
	v_pk_mul_f32 v[40:41], v[34:35], v[136:137]
	v_pk_mul_f32 v[34:35], v[32:33], v[144:145]
	v_cvt_pk_bf16_f32 v32, v36, v37
	v_lshl_add_u64 v[36:37], v[114:115], 0, v[44:45]
	v_lshl_add_u64 v[36:37], v[36:37], 0, v[46:47]
	v_lshl_add_u64 v[36:37], v[36:37], 0, v[80:81]
	v_cvt_pk_bf16_f32 v33, v38, v39
	v_cvt_pk_bf16_f32 v34, v34, v35
	v_cvt_pk_bf16_f32 v35, v40, v41
	global_store_dwordx4 v[36:37], v[32:35], off
	v_add_u32_e32 v36, s75, v167
	s_nop 0
	v_ashrrev_i32_e32 v32, 7, v36
	v_add_u32_e32 v32, s82, v32
	v_ashrrev_i32_e32 v33, 31, v32
	v_pk_mul_f32 v[34:35], v[26:27], v[138:139]
	v_pk_mul_f32 v[26:27], v[24:25], v[134:135]
	v_cvt_pk_bf16_f32 v24, v28, v29
	v_cvt_pk_bf16_f32 v25, v30, v31
	v_lshlrev_b64 v[28:29], 22, v[32:33]
	v_lshlrev_b32_e32 v30, 6, v36
	v_and_b32_e32 v30, 0x1fc0, v30
	v_mov_b32_e32 v31, v81
	v_lshl_add_u64 v[32:33], v[122:123], 0, v[28:29]
	v_lshl_add_u64 v[32:33], v[32:33], 0, v[30:31]
	v_lshl_add_u64 v[32:33], v[32:33], 0, v[124:125]
	v_cvt_pk_bf16_f32 v26, v26, v27
	v_cvt_pk_bf16_f32 v27, v34, v35
	global_store_dwordx4 v[32:33], v[24:27], off
	s_nop 1
	v_pk_mul_f32 v[24:25], v[18:19], v[136:137]
	v_pk_mul_f32 v[18:19], v[16:17], v[144:145]
	v_cvt_pk_bf16_f32 v16, v20, v21
	v_lshl_add_u64 v[20:21], v[114:115], 0, v[28:29]
	v_lshl_add_u64 v[20:21], v[20:21], 0, v[30:31]
	v_lshl_add_u64 v[20:21], v[20:21], 0, v[80:81]
	v_cvt_pk_bf16_f32 v17, v22, v23
	v_cvt_pk_bf16_f32 v18, v18, v19
	v_cvt_pk_bf16_f32 v19, v24, v25
	global_store_dwordx4 v[20:21], v[16:19], off
	v_add_u32_e32 v20, s75, v168
	s_mov_b32 s75, s0
	v_ashrrev_i32_e32 v16, 7, v20
	v_add_u32_e32 v16, s82, v16
	v_ashrrev_i32_e32 v17, 31, v16
	v_pk_mul_f32 v[18:19], v[10:11], v[138:139]
	v_pk_mul_f32 v[10:11], v[8:9], v[134:135]
	v_cvt_pk_bf16_f32 v8, v12, v13
	v_cvt_pk_bf16_f32 v9, v14, v15
	v_lshlrev_b64 v[12:13], 22, v[16:17]
	v_lshlrev_b32_e32 v14, 6, v20
	v_and_b32_e32 v14, 0x1fc0, v14
	v_mov_b32_e32 v15, v81
	v_lshl_add_u64 v[16:17], v[122:123], 0, v[12:13]
	v_lshl_add_u64 v[16:17], v[16:17], 0, v[14:15]
	v_lshl_add_u64 v[16:17], v[16:17], 0, v[124:125]
	v_cvt_pk_bf16_f32 v10, v10, v11
	v_cvt_pk_bf16_f32 v11, v18, v19
	global_store_dwordx4 v[16:17], v[8:11], off
	s_nop 1
	v_pk_mul_f32 v[8:9], v[2:3], v[136:137]
	v_pk_mul_f32 v[2:3], v[0:1], v[144:145]
	v_cvt_pk_bf16_f32 v0, v4, v5
	v_lshl_add_u64 v[4:5], v[114:115], 0, v[12:13]
	v_lshl_add_u64 v[4:5], v[4:5], 0, v[14:15]
	v_lshl_add_u64 v[4:5], v[4:5], 0, v[80:81]
	v_cvt_pk_bf16_f32 v1, v6, v7
	v_cvt_pk_bf16_f32 v2, v2, v3
	v_cvt_pk_bf16_f32 v3, v8, v9
	global_store_dwordx4 v[4:5], v[0:3], off
	s_cbranch_scc0 .LBB0_650
	s_waitcnt vmcnt(0)
	s_cmpk_gt_u32 s19, 0xff
	s_mov_b32 s86, 0x7f800000
	s_brev_b32 s82, 1
	s_cbranch_scc1 .LBB0_632
	s_barrier
	s_branch .LBB0_632

; #define G_STAGE(bufoff, gbase, voff) do { _Pragma("unroll") for (int _i = 0; _i < 2; ++_i) { unsigned _vo = (voff)[_i]; asm volatile("" : "+v"(_vo));   \
;     __builtin_amdgcn_global_load_lds((const unsigned*)((const char*)(gbase) + _vo), (LAS unsigned*)(lds + (bufoff) + ldsw + _i * 8192), 16, 0, 0); } } while (0)
; #define G_LDA(dst, b, h) do { _Pragma("unroll") for (int m = 0; m < 4; ++m) _Pragma("unroll") for (int k = 0; k < 2; ++k) dst[m][k] = *(const LAS bf16x8*)(lds + G_SA(b, h) + aoff + m * 2048 + k * 1024); } while (0)
; #define G_LDB(dst, b, h) do { _Pragma("unroll") for (int n = 0; n < 2; ++n) _Pragma("unroll") for (int k = 0; k < 2; ++k) dst[n][k] = *(const LAS bf16x8*)(lds + G_SB(b, h) + boff + n * 2048 + k * 1024); } while (0)
; #define G_MMA(ai, bj, At, Bt) do { __builtin_amdgcn_s_setprio(1); _Pragma("unroll") for (int m = 0; m < 4; ++m) _Pragma("unroll") for (int n = 0; n < 2; ++n) _Pragma("unroll") for (int k = 0; k < 2; ++k) \
;     acc[ai][bj][m][n] = __builtin_amdgcn_mfma_f32_16x16x32_bf16(Bt[n][k], At[m][k], acc[ai][bj][m][n], 0, 0, 0); __builtin_amdgcn_s_setprio(0); } while (0)
; #define G_WAIT_L(n) asm volatile("s_waitcnt lgkmcnt(" #n ")" ::: "memory")
; #define G_BAR __builtin_amdgcn_s_barrier()
; #define G_SCHED __builtin_amdgcn_sched_barrier(0)
; template <class Epi>
; __device__ __forceinline__ void gemm_phase(LAS unsigned char* lds, const int K, const unsigned lda_b, const unsigned ldb_b, const Map& M, const Epi& E) {
;     ...
;     for (int t = 0; t < nt; t += 2) {
;       const bool last = (t == nt - 2);
;       const char* a1h1 = cur.a0 + a_h + (size_t)(t + 1) * kstep;
;       const char* a2h0 = last ? nxt.a0 : cur.a0 + (size_t)(t + 2) * kstep; const char* a2h1 = a2h0 + a_h;
;       const char* b2h0 = last ? nxt.b0 : cur.b0 + (size_t)(t + 2) * kstep; const char* b2h1 = last ? nxt.b1 : cur.b1 + (size_t)(t + 2) * kstep;
;       G_LDB(B0, 0, 0); G_SCHED; G_LDA(At, 0, 0); G_STAGE(G_SA(1, 1), a1h1, voffA);
;       G_WAIT_L(8); G_BAR; G_WAIT_L(0); G_MMA(0, 0, At, B0); G_BAR; G_SCHED;
;       G_LDB(B1, 0, 1); G_STAGE(G_SB(0, 0), b2h0, voffB);
;       G_BAR; G_WAIT_L(0); G_MMA(0, 1, At, B1); G_BAR;
;       G_LDA(At, 0, 1); G_STAGE(G_SA(0, 0), a2h0, voffA);
;       G_BAR; G_WAIT_L(0); G_MMA(1, 0, At, B0); G_BAR; G_SCHED;
.LBB0_844:
	s_add_u32 s22, s2, 0xfff80080
	s_addc_u32 s35, s3, -1
	s_add_u32 s38, s30, 0xfffe0000
	s_addc_u32 s39, s31, -1
	s_add_i32 s75, 0, 0x10000
	v_add_u32_e32 v80, s75, v139
	ds_read_b128 v[142:145], v80
	ds_read_b128 v[146:149], v80 offset:1024
	ds_read_b128 v[150:153], v80 offset:2048
	ds_read_b128 v[154:157], v80 offset:3072
	s_cmp_eq_u32 s34, 28
	s_cselect_b32 s43, s5, s35
	s_cselect_b32 s42, s4, s22
	s_cselect_b32 s45, s7, s39
	s_cselect_b32 s44, s6, s38
	v_mov_b32_e32 v80, v134
	s_cselect_b32 s39, s29, s31
	s_cselect_b32 s38, s28, s30
	s_add_u32 s68, s42, 0x80000
	ds_read_b128 v[158:161], v141
	ds_read_b128 v[162:165], v141 offset:1024
	ds_read_b128 v[166:169], v141 offset:2048
	ds_read_b128 v[170:173], v141 offset:3072
	ds_read_b128 v[174:177], v141 offset:4096
	ds_read_b128 v[190:193], v141 offset:5120
	ds_read_b128 v[194:197], v141 offset:6144
	ds_read_b128 v[198:201], v141 offset:7168
	s_addc_u32 s69, s43, 0
	s_add_i32 m0, s18, 0xc000
	s_nop 0
	global_load_lds_dwordx4 v80, s[2:3]
	v_mov_b32_e32 v80, v136
	s_add_i32 m0, s18, 0xe000
	s_nop 0
	global_load_lds_dwordx4 v80, s[2:3]
	s_waitcnt lgkmcnt(8)
	s_barrier
	s_waitcnt lgkmcnt(0)
	s_setprio 1
	s_waitcnt lgkmcnt(0)
	v_mfma_f32_16x16x32_bf16 v[126:129], v[142:145], v[158:161], v[126:129]
	v_mfma_f32_16x16x32_bf16 v[122:125], v[150:153], v[158:161], v[122:125]
	v_mfma_f32_16x16x32_bf16 v[110:113], v[142:145], v[166:169], v[110:113]
	v_mfma_f32_16x16x32_bf16 v[106:109], v[150:153], v[166:169], v[106:109]
	v_mfma_f32_16x16x32_bf16 v[94:97], v[142:145], v[174:177], v[94:97]
	v_mfma_f32_16x16x32_bf16 v[90:93], v[150:153], v[174:177], v[90:93]
	v_mfma_f32_16x16x32_bf16 v[76:79], v[142:145], v[194:197], v[76:79]
	v_mfma_f32_16x16x32_bf16 v[72:75], v[150:153], v[194:197], v[72:75]
	v_mfma_f32_16x16x32_bf16 v[126:129], v[146:149], v[162:165], v[126:129]
	v_mfma_f32_16x16x32_bf16 v[122:125], v[154:157], v[162:165], v[122:125]
	v_mfma_f32_16x16x32_bf16 v[110:113], v[146:149], v[170:173], v[110:113]
	v_mfma_f32_16x16x32_bf16 v[106:109], v[154:157], v[170:173], v[106:109]
	v_mfma_f32_16x16x32_bf16 v[94:97], v[146:149], v[190:193], v[94:97]
	v_mfma_f32_16x16x32_bf16 v[90:93], v[154:157], v[190:193], v[90:93]
	v_mfma_f32_16x16x32_bf16 v[76:79], v[146:149], v[198:201], v[76:79]
	v_mfma_f32_16x16x32_bf16 v[72:75], v[154:157], v[198:201], v[72:75]
	s_setprio 0
	s_barrier
	s_add_i32 s22, 0, 0x14000
	v_add_u32_e32 v80, s22, v139
	ds_read_b128 v[202:205], v80
	ds_read_b128 v[206:209], v80 offset:1024
	ds_read_b128 v[210:213], v80 offset:2048
	ds_read_b128 v[214:217], v80 offset:3072
	v_mov_b32_e32 v80, v135
	s_add_i32 s35, s75, s17
	s_mov_b32 m0, s35
	s_nop 0
	global_load_lds_dwordx4 v80, s[44:45]
	v_mov_b32_e32 v80, v137
	s_add_i32 m0, s35, 0x2000
	s_nop 0
	global_load_lds_dwordx4 v80, s[44:45]
	s_barrier
	s_waitcnt lgkmcnt(0)
	s_setprio 1
	s_waitcnt lgkmcnt(0)
	v_mfma_f32_16x16x32_bf16 v[118:121], v[202:205], v[158:161], v[118:121]
	v_mfma_f32_16x16x32_bf16 v[114:117], v[210:213], v[158:161], v[114:117]
	v_mfma_f32_16x16x32_bf16 v[102:105], v[202:205], v[166:169], v[102:105]
	v_mfma_f32_16x16x32_bf16 v[98:101], v[210:213], v[166:169], v[98:101]
	v_mfma_f32_16x16x32_bf16 v[86:89], v[202:205], v[174:177], v[86:89]
	v_mfma_f32_16x16x32_bf16 v[82:85], v[210:213], v[174:177], v[82:85]
	v_mfma_f32_16x16x32_bf16 v[68:71], v[202:205], v[194:197], v[68:71]
	v_mfma_f32_16x16x32_bf16 v[64:67], v[210:213], v[194:197], v[64:67]
	v_mfma_f32_16x16x32_bf16 v[118:121], v[206:209], v[162:165], v[118:121]
	v_mfma_f32_16x16x32_bf16 v[114:117], v[214:217], v[162:165], v[114:117]
	v_mfma_f32_16x16x32_bf16 v[102:105], v[206:209], v[170:173], v[102:105]
	v_mfma_f32_16x16x32_bf16 v[98:101], v[214:217], v[170:173], v[98:101]
	v_mfma_f32_16x16x32_bf16 v[86:89], v[206:209], v[190:193], v[86:89]
	v_mfma_f32_16x16x32_bf16 v[82:85], v[214:217], v[190:193], v[82:85]
	v_mfma_f32_16x16x32_bf16 v[68:71], v[206:209], v[198:201], v[68:71]
	v_mfma_f32_16x16x32_bf16 v[64:67], v[214:217], v[198:201], v[64:67]
	s_setprio 0
	v_mov_b32_e32 v80, v134
	s_mov_b32 m0, s18
	s_barrier
	ds_read_b128 v[158:161], v141 offset:16384
	ds_read_b128 v[162:165], v141 offset:17408
	ds_read_b128 v[166:169], v141 offset:18432
	ds_read_b128 v[170:173], v141 offset:19456
	ds_read_b128 v[174:177], v141 offset:20480
	ds_read_b128 v[190:193], v141 offset:21504
	ds_read_b128 v[194:197], v141 offset:22528
	ds_read_b128 v[198:201], v141 offset:23552
	s_nop 0
	global_load_lds_dwordx4 v80, s[42:43]
	v_mov_b32_e32 v80, v136
	s_mov_b32 m0, s19
	s_nop 0
	global_load_lds_dwordx4 v80, s[42:43]
	s_barrier
	s_waitcnt lgkmcnt(0)
	s_setprio 1
	s_waitcnt lgkmcnt(0)
	v_mfma_f32_16x16x32_bf16 v[60:63], v[142:145], v[158:161], v[60:63]
	v_mfma_f32_16x16x32_bf16 v[56:59], v[150:153], v[158:161], v[56:59]
	v_mfma_f32_16x16x32_bf16 v[44:47], v[142:145], v[166:169], v[44:47]
	v_mfma_f32_16x16x32_bf16 v[40:43], v[150:153], v[166:169], v[40:43]
	v_mfma_f32_16x16x32_bf16 v[28:31], v[142:145], v[174:177], v[28:31]
	v_mfma_f32_16x16x32_bf16 v[24:27], v[150:153], v[174:177], v[24:27]
	v_mfma_f32_16x16x32_bf16 v[12:15], v[142:145], v[194:197], v[12:15]
	v_mfma_f32_16x16x32_bf16 v[8:11], v[150:153], v[194:197], v[8:11]
	v_mfma_f32_16x16x32_bf16 v[60:63], v[146:149], v[162:165], v[60:63]
	v_mfma_f32_16x16x32_bf16 v[56:59], v[154:157], v[162:165], v[56:59]
	v_mfma_f32_16x16x32_bf16 v[44:47], v[146:149], v[170:173], v[44:47]
	v_mfma_f32_16x16x32_bf16 v[40:43], v[154:157], v[170:173], v[40:43]
	v_mfma_f32_16x16x32_bf16 v[28:31], v[146:149], v[190:193], v[28:31]
	v_mfma_f32_16x16x32_bf16 v[24:27], v[154:157], v[190:193], v[24:27]
	v_mfma_f32_16x16x32_bf16 v[12:15], v[146:149], v[198:201], v[12:15]
	v_mfma_f32_16x16x32_bf16 v[8:11], v[154:157], v[198:201], v[8:11]
	s_setprio 0
	s_barrier
; #define G_STAGE(bufoff, gbase, voff) do { _Pragma("unroll") for (int _i = 0; _i < 2; ++_i) { unsigned _vo = (voff)[_i]; asm volatile("" : "+v"(_vo));   \
;     __builtin_amdgcn_global_load_lds((const unsigned*)((const char*)(gbase) + _vo), (LAS unsigned*)(lds + (bufoff) + ldsw + _i * 8192), 16, 0, 0); } } while (0)
; #define G_LDA(dst, b, h) do { _Pragma("unroll") for (int m = 0; m < 4; ++m) _Pragma("unroll") for (int k = 0; k < 2; ++k) dst[m][k] = *(const LAS bf16x8*)(lds + G_SA(b, h) + aoff + m * 2048 + k * 1024); } while (0)
; #define G_LDB(dst, b, h) do { _Pragma("unroll") for (int n = 0; n < 2; ++n) _Pragma("unroll") for (int k = 0; k < 2; ++k) dst[n][k] = *(const LAS bf16x8*)(lds + G_SB(b, h) + boff + n * 2048 + k * 1024); } while (0)
; #define G_MMA(ai, bj, At, Bt) do { __builtin_amdgcn_s_setprio(1); _Pragma("unroll") for (int m = 0; m < 4; ++m) _Pragma("unroll") for (int n = 0; n < 2; ++n) _Pragma("unroll") for (int k = 0; k < 2; ++k) \
;     acc[ai][bj][m][n] = __builtin_amdgcn_mfma_f32_16x16x32_bf16(Bt[n][k], At[m][k], acc[ai][bj][m][n], 0, 0, 0); __builtin_amdgcn_s_setprio(0); } while (0)
; #define G_WAIT_V(n) asm volatile("s_waitcnt vmcnt(" #n ")" ::: "memory")
; template <class Epi>
; __device__ __forceinline__ void gemm_phase(LAS unsigned char* lds, const int K, const unsigned lda_b, const unsigned ldb_b, const Map& M, const Epi& E) {
;     ...
;       G_LDB(B0, 0, 0); G_SCHED; G_LDA(At, 0, 0); G_STAGE(G_SA(1, 1), a1h1, voffA);
;       G_WAIT_L(8); G_BAR; G_WAIT_L(0); G_MMA(0, 0, At, B0); G_BAR; G_SCHED;
;       G_LDB(B1, 0, 1); G_STAGE(G_SB(0, 0), b2h0, voffB);
;       G_BAR; G_WAIT_L(0); G_MMA(0, 1, At, B1); G_BAR;
;       G_LDA(At, 0, 1); G_STAGE(G_SA(0, 0), a2h0, voffA);
;       G_BAR; G_WAIT_L(0); G_MMA(1, 0, At, B0); G_BAR; G_SCHED;
;       G_STAGE(G_SB(0, 1), b2h1, voffB);
;       G_WAIT_V(6); G_BAR; G_MMA(1, 1, At, B1); G_BAR;
;       G_LDB(B0, 1, 0); G_SCHED; G_LDA(At, 1, 0); G_STAGE(G_SA(0, 1), a2h1, voffA);
;       G_WAIT_L(8); G_BAR; G_WAIT_L(0); G_MMA(0, 0, At, B0); G_BAR; G_SCHED;
;       G_LDB(B1, 1, 1); G_STAGE(G_SB(1, 0), b2h0 + kstep, voffB);
;       G_BAR; G_WAIT_L(0); G_MMA(0, 1, At, B1); G_BAR;
;       G_LDA(At, 1, 1); G_STAGE(G_SA(1, 0), a2h0 + kstep, voffA);
;       G_BAR; G_WAIT_L(0); G_MMA(1, 0, At, B0); G_BAR; G_SCHED;
;       G_STAGE(G_SB(1, 1), b2h1 + kstep, voffB);
;       G_WAIT_V(6); G_BAR; G_MMA(1, 1, At, B1); G_BAR;
	v_mov_b32_e32 v80, v135
	s_add_i32 s22, s22, s17
	s_mov_b32 m0, s22
	s_nop 0
	global_load_lds_dwordx4 v80, s[38:39]
	v_mov_b32_e32 v80, v137
	s_add_i32 m0, s22, 0x2000
	s_nop 0
	global_load_lds_dwordx4 v80, s[38:39]
	s_waitcnt vmcnt(6)
	s_barrier
	s_setprio 1
	v_mfma_f32_16x16x32_bf16 v[52:55], v[202:205], v[158:161], v[52:55]
	v_mfma_f32_16x16x32_bf16 v[48:51], v[210:213], v[158:161], v[48:51]
	v_mfma_f32_16x16x32_bf16 v[36:39], v[202:205], v[166:169], v[36:39]
	v_mfma_f32_16x16x32_bf16 v[32:35], v[210:213], v[166:169], v[32:35]
	v_mfma_f32_16x16x32_bf16 v[20:23], v[202:205], v[174:177], v[20:23]
	v_mfma_f32_16x16x32_bf16 v[16:19], v[210:213], v[174:177], v[16:19]
	v_mfma_f32_16x16x32_bf16 v[4:7], v[202:205], v[194:197], v[4:7]
	v_mfma_f32_16x16x32_bf16 v[0:3], v[210:213], v[194:197], v[0:3]
	v_mfma_f32_16x16x32_bf16 v[52:55], v[206:209], v[162:165], v[52:55]
	v_mfma_f32_16x16x32_bf16 v[48:51], v[214:217], v[162:165], v[48:51]
	v_mfma_f32_16x16x32_bf16 v[36:39], v[206:209], v[170:173], v[36:39]
	v_mfma_f32_16x16x32_bf16 v[32:35], v[214:217], v[170:173], v[32:35]
	v_mfma_f32_16x16x32_bf16 v[20:23], v[206:209], v[190:193], v[20:23]
	v_mfma_f32_16x16x32_bf16 v[16:19], v[214:217], v[190:193], v[16:19]
	v_mfma_f32_16x16x32_bf16 v[4:7], v[206:209], v[198:201], v[4:7]
	v_mfma_f32_16x16x32_bf16 v[0:3], v[214:217], v[198:201], v[0:3]
	s_setprio 0
	s_add_i32 s22, 0, 0x18000
	v_add_u32_e32 v80, s22, v139
	s_barrier
	ds_read_b128 v[142:145], v80
	ds_read_b128 v[146:149], v80 offset:1024
	ds_read_b128 v[150:153], v80 offset:2048
	ds_read_b128 v[154:157], v80 offset:3072
	v_mov_b32_e32 v80, v134
	s_mov_b32 m0, s46
	ds_read_b128 v[158:161], v141 offset:32768
	ds_read_b128 v[162:165], v141 offset:33792
	ds_read_b128 v[166:169], v141 offset:34816
	ds_read_b128 v[170:173], v141 offset:35840
	ds_read_b128 v[174:177], v141 offset:36864
	ds_read_b128 v[190:193], v141 offset:37888
	ds_read_b128 v[194:197], v141 offset:38912
	ds_read_b128 v[198:201], v141 offset:39936
	s_nop 0
	global_load_lds_dwordx4 v80, s[68:69]
	v_mov_b32_e32 v80, v136
	s_mov_b32 m0, s47
	s_nop 0
	global_load_lds_dwordx4 v80, s[68:69]
	s_waitcnt lgkmcnt(8)
	s_barrier
	s_waitcnt lgkmcnt(0)
	s_setprio 1
	s_waitcnt lgkmcnt(0)
	v_mfma_f32_16x16x32_bf16 v[126:129], v[142:145], v[158:161], v[126:129]
	v_mfma_f32_16x16x32_bf16 v[122:125], v[150:153], v[158:161], v[122:125]
	v_mfma_f32_16x16x32_bf16 v[110:113], v[142:145], v[166:169], v[110:113]
	v_mfma_f32_16x16x32_bf16 v[106:109], v[150:153], v[166:169], v[106:109]
	v_mfma_f32_16x16x32_bf16 v[94:97], v[142:145], v[174:177], v[94:97]
	v_mfma_f32_16x16x32_bf16 v[90:93], v[150:153], v[174:177], v[90:93]
	v_mfma_f32_16x16x32_bf16 v[76:79], v[142:145], v[194:197], v[76:79]
	v_mfma_f32_16x16x32_bf16 v[72:75], v[150:153], v[194:197], v[72:75]
	v_mfma_f32_16x16x32_bf16 v[126:129], v[146:149], v[162:165], v[126:129]
	v_mfma_f32_16x16x32_bf16 v[122:125], v[154:157], v[162:165], v[122:125]
	v_mfma_f32_16x16x32_bf16 v[110:113], v[146:149], v[170:173], v[110:113]
	v_mfma_f32_16x16x32_bf16 v[106:109], v[154:157], v[170:173], v[106:109]
	v_mfma_f32_16x16x32_bf16 v[94:97], v[146:149], v[190:193], v[94:97]
	v_mfma_f32_16x16x32_bf16 v[90:93], v[154:157], v[190:193], v[90:93]
	v_mfma_f32_16x16x32_bf16 v[76:79], v[146:149], v[198:201], v[76:79]
	v_mfma_f32_16x16x32_bf16 v[72:75], v[154:157], v[198:201], v[72:75]
	s_setprio 0
	s_barrier
	s_add_i32 s35, 0, 0x1c000
	v_add_u32_e32 v80, s35, v139
	ds_read_b128 v[202:205], v80
	ds_read_b128 v[206:209], v80 offset:1024
	ds_read_b128 v[210:213], v80 offset:2048
	ds_read_b128 v[214:217], v80 offset:3072
	v_mov_b32_e32 v80, v135
	s_add_i32 s22, s22, s17
	s_add_i32 m0, s22, 0xffffff80
	v_mov_b32_e32 v80, v137
	global_load_lds_dwordx4 v135, s[44:45] offset:128
	s_add_i32 m0, s22, 0x1f80
	s_nop 0
	global_load_lds_dwordx4 v137, s[44:45] offset:128
	s_barrier
	s_waitcnt lgkmcnt(0)
	s_setprio 1
	s_waitcnt lgkmcnt(0)
	v_mfma_f32_16x16x32_bf16 v[118:121], v[202:205], v[158:161], v[118:121]
	v_mfma_f32_16x16x32_bf16 v[114:117], v[210:213], v[158:161], v[114:117]
	v_mfma_f32_16x16x32_bf16 v[102:105], v[202:205], v[166:169], v[102:105]
	v_mfma_f32_16x16x32_bf16 v[98:101], v[210:213], v[166:169], v[98:101]
	v_mfma_f32_16x16x32_bf16 v[86:89], v[202:205], v[174:177], v[86:89]
	v_mfma_f32_16x16x32_bf16 v[82:85], v[210:213], v[174:177], v[82:85]
	v_mfma_f32_16x16x32_bf16 v[68:71], v[202:205], v[194:197], v[68:71]
	v_mfma_f32_16x16x32_bf16 v[64:67], v[210:213], v[194:197], v[64:67]
	v_mfma_f32_16x16x32_bf16 v[118:121], v[206:209], v[162:165], v[118:121]
	v_mfma_f32_16x16x32_bf16 v[114:117], v[214:217], v[162:165], v[114:117]
	v_mfma_f32_16x16x32_bf16 v[102:105], v[206:209], v[170:173], v[102:105]
	v_mfma_f32_16x16x32_bf16 v[98:101], v[214:217], v[170:173], v[98:101]
	v_mfma_f32_16x16x32_bf16 v[86:89], v[206:209], v[190:193], v[86:89]
	v_mfma_f32_16x16x32_bf16 v[82:85], v[214:217], v[190:193], v[82:85]
	v_mfma_f32_16x16x32_bf16 v[68:71], v[206:209], v[198:201], v[68:71]
	v_mfma_f32_16x16x32_bf16 v[64:67], v[214:217], v[198:201], v[64:67]
	s_setprio 0
	v_mov_b32_e32 v80, v134
	s_barrier
	ds_read_b128 v[158:161], v141 offset:49152
	ds_read_b128 v[162:165], v141 offset:50176
	ds_read_b128 v[166:169], v141 offset:51200
	ds_read_b128 v[170:173], v141 offset:52224
	ds_read_b128 v[174:177], v141 offset:53248
	ds_read_b128 v[190:193], v141 offset:54272
	ds_read_b128 v[194:197], v141 offset:55296
	ds_read_b128 v[198:201], v141 offset:56320
	s_add_i32 m0, s48, 0xffffff80
	v_mov_b32_e32 v80, v136
	global_load_lds_dwordx4 v134, s[42:43] offset:128
	s_add_i32 m0, s49, 0xffffff80
	s_nop 0
	global_load_lds_dwordx4 v136, s[42:43] offset:128
	s_barrier
; #define G_STAGE(bufoff, gbase, voff) do { _Pragma("unroll") for (int _i = 0; _i < 2; ++_i) { unsigned _vo = (voff)[_i]; asm volatile("" : "+v"(_vo));   \
;     __builtin_amdgcn_global_load_lds((const unsigned*)((const char*)(gbase) + _vo), (LAS unsigned*)(lds + (bufoff) + ldsw + _i * 8192), 16, 0, 0); } } while (0)
; #define G_LDA(dst, b, h) do { _Pragma("unroll") for (int m = 0; m < 4; ++m) _Pragma("unroll") for (int k = 0; k < 2; ++k) dst[m][k] = *(const LAS bf16x8*)(lds + G_SA(b, h) + aoff + m * 2048 + k * 1024); } while (0)
; #define G_MMA(ai, bj, At, Bt) do { __builtin_amdgcn_s_setprio(1); _Pragma("unroll") for (int m = 0; m < 4; ++m) _Pragma("unroll") for (int n = 0; n < 2; ++n) _Pragma("unroll") for (int k = 0; k < 2; ++k) \
;     acc[ai][bj][m][n] = __builtin_amdgcn_mfma_f32_16x16x32_bf16(Bt[n][k], At[m][k], acc[ai][bj][m][n], 0, 0, 0); __builtin_amdgcn_s_setprio(0); } while (0)
; #define G_WAIT_V(n) asm volatile("s_waitcnt vmcnt(" #n ")" ::: "memory")
; #define G_WAIT_L(n) asm volatile("s_waitcnt lgkmcnt(" #n ")" ::: "memory")
; #define G_BAR __builtin_amdgcn_s_barrier()
; #define G_SCHED __builtin_amdgcn_sched_barrier(0)
; template <class Epi>
; __device__ __forceinline__ void gemm_phase(LAS unsigned char* lds, const int K, const unsigned lda_b, const unsigned ldb_b, const Map& M, const Epi& E) {
;     ...
;     for (int t = 0; t < nt; t += 2) {
;     ...
;       G_LDA(At, 1, 1); G_STAGE(G_SA(1, 0), a2h0 + kstep, voffA);
;       G_BAR; G_WAIT_L(0); G_MMA(1, 0, At, B0); G_BAR; G_SCHED;
;       G_STAGE(G_SB(1, 1), b2h1 + kstep, voffB);
;       G_WAIT_V(6); G_BAR; G_MMA(1, 1, At, B1); G_BAR;
	s_waitcnt lgkmcnt(0)
	s_setprio 1
	s_waitcnt lgkmcnt(0)
	v_mfma_f32_16x16x32_bf16 v[60:63], v[142:145], v[158:161], v[60:63]
	v_mfma_f32_16x16x32_bf16 v[56:59], v[150:153], v[158:161], v[56:59]
	v_mfma_f32_16x16x32_bf16 v[44:47], v[142:145], v[166:169], v[44:47]
	v_mfma_f32_16x16x32_bf16 v[40:43], v[150:153], v[166:169], v[40:43]
	v_mfma_f32_16x16x32_bf16 v[28:31], v[142:145], v[174:177], v[28:31]
	v_mfma_f32_16x16x32_bf16 v[24:27], v[150:153], v[174:177], v[24:27]
	v_mfma_f32_16x16x32_bf16 v[12:15], v[142:145], v[194:197], v[12:15]
	v_mfma_f32_16x16x32_bf16 v[8:11], v[150:153], v[194:197], v[8:11]
	v_mfma_f32_16x16x32_bf16 v[60:63], v[146:149], v[162:165], v[60:63]
	v_mfma_f32_16x16x32_bf16 v[56:59], v[154:157], v[162:165], v[56:59]
	v_mfma_f32_16x16x32_bf16 v[44:47], v[146:149], v[170:173], v[44:47]
	v_mfma_f32_16x16x32_bf16 v[40:43], v[154:157], v[170:173], v[40:43]
	v_mfma_f32_16x16x32_bf16 v[28:31], v[146:149], v[190:193], v[28:31]
	v_mfma_f32_16x16x32_bf16 v[24:27], v[154:157], v[190:193], v[24:27]
	v_mfma_f32_16x16x32_bf16 v[12:15], v[146:149], v[198:201], v[12:15]
	v_mfma_f32_16x16x32_bf16 v[8:11], v[154:157], v[198:201], v[8:11]
	s_setprio 0
	s_barrier
	v_mov_b32_e32 v80, v135
	s_add_i32 s22, s35, s17
	s_add_i32 m0, s22, 0xffffff80
	v_mov_b32_e32 v80, v137
	global_load_lds_dwordx4 v135, s[38:39] offset:128
	s_add_i32 m0, s22, 0x1f80
	s_nop 0
	global_load_lds_dwordx4 v137, s[38:39] offset:128
	s_waitcnt vmcnt(6)
	s_barrier
	s_setprio 1
	v_mfma_f32_16x16x32_bf16 v[52:55], v[202:205], v[158:161], v[52:55]
	v_mfma_f32_16x16x32_bf16 v[48:51], v[210:213], v[158:161], v[48:51]
	v_mfma_f32_16x16x32_bf16 v[36:39], v[202:205], v[166:169], v[36:39]
	v_mfma_f32_16x16x32_bf16 v[32:35], v[210:213], v[166:169], v[32:35]
	v_mfma_f32_16x16x32_bf16 v[20:23], v[202:205], v[174:177], v[20:23]
	v_mfma_f32_16x16x32_bf16 v[16:19], v[210:213], v[174:177], v[16:19]
	v_mfma_f32_16x16x32_bf16 v[4:7], v[202:205], v[194:197], v[4:7]
	v_mfma_f32_16x16x32_bf16 v[0:3], v[210:213], v[194:197], v[0:3]
	v_mfma_f32_16x16x32_bf16 v[52:55], v[206:209], v[162:165], v[52:55]
	v_mfma_f32_16x16x32_bf16 v[48:51], v[214:217], v[162:165], v[48:51]
	v_mfma_f32_16x16x32_bf16 v[36:39], v[206:209], v[170:173], v[36:39]
	v_mfma_f32_16x16x32_bf16 v[32:35], v[214:217], v[170:173], v[32:35]
	v_mfma_f32_16x16x32_bf16 v[20:23], v[206:209], v[190:193], v[20:23]
	v_mfma_f32_16x16x32_bf16 v[16:19], v[214:217], v[190:193], v[16:19]
	v_mfma_f32_16x16x32_bf16 v[4:7], v[206:209], v[198:201], v[4:7]
	v_mfma_f32_16x16x32_bf16 v[0:3], v[214:217], v[198:201], v[0:3]
	s_setprio 0
	s_add_i32 s34, s34, 2
	s_add_u32 s30, s30, 0x100
	s_addc_u32 s31, s31, 0
	s_add_u32 s2, s2, 0x100
	s_addc_u32 s3, s3, 0
	s_cmp_gt_u32 s34, 29
	s_barrier
	s_cbranch_scc0 .LBB0_844
; __device__ __forceinline__ unsigned cvt_pk_bf16(float lo, float hi) { unsigned r; asm("v_cvt_pk_bf16_f32 %0, %1, %2" : "=v"(r) : "v"(lo), "v"(hi)); return r; }
; __device__ __forceinline__ float bf_lo(unsigned u) { return __uint_as_float(u << 16); }
; __device__ __forceinline__ float bf_hi(unsigned u) { return __uint_as_float(u & 0xffff0000u); }
; __device__ __forceinline__ unsigned long long ss_fix(float s) { return (unsigned long long)(s * 16777216.f); }
;   __device__ __forceinline__ void operator()(const f32x4 (&acc)[2][2][4][2], const Unit& u, const EpiCtx& x_, int wr, int wc, int fr, int fq) const {
; #pragma unroll
;     for (int ai = 0; ai < 2; ++ai)
; #pragma unroll
;       for (int m = 0; m < 4; ++m) {
;         const int row = (u.r0 + (ai ? x_.rdelta : 0)) + wr * 64 + m * 16 + fr;
;         const bf16_t* xin = (const bf16_t*)x_.aux + (size_t)row * DM;
;         bf16_t* xbp = x_.xb + (size_t)row * DM;
;         float sq = 0.f;
; #pragma unroll
;         for (int bj = 0; bj < 2; ++bj) {
;           const int cb = u.c0 + wc * 64 + bj * 32 + 8 * fq;
;           const uint4 xi = *(const uint4*)(xin + cb); const f32x4 a = acc[ai][bj][m][0], b = acc[ai][bj][m][1];
;           const float x0 = bf_lo(xi.x) + a[0], x1 = bf_hi(xi.x) + a[1], x2 = bf_lo(xi.y) + a[2], x3 = bf_hi(xi.y) + a[3];
;           const float x4 = bf_lo(xi.z) + b[0], x5 = bf_hi(xi.z) + b[1], x6 = bf_lo(xi.w) + b[2], x7 = bf_hi(xi.w) + b[3];
;           sq += x0 * x0 + x1 * x1 + x2 * x2 + x3 * x3 + x4 * x4 + x5 * x5 + x6 * x6 + x7 * x7;
;           uint4 o; o.x = cvt_pk_bf16(x0, x1); o.y = cvt_pk_bf16(x2, x3); o.z = cvt_pk_bf16(x4, x5); o.w = cvt_pk_bf16(x6, x7);
;           *(uint4*)(xbp + cb) = o;
;         }
;         sq += __shfl_xor(sq, 16); sq += __shfl_xor(sq, 32);
;         if (fq == 0) atomicAdd(x_.sso + row, ss_fix(sq));
;       }
;   }
	s_nop 1
	v_add_u32_e32 v194, s67, v138
	v_add_u32_e32 v196, s0, v140
	v_ashrrev_i32_e32 v195, 31, v194
	v_lshlrev_b64 v[198:199], 12, v[194:195]
	v_ashrrev_i32_e32 v197, 31, v196
	v_lshl_add_u64 v[200:201], s[8:9], 0, v[198:199]
	v_lshlrev_b64 v[202:203], 1, v[196:197]
	v_lshl_add_u64 v[204:205], v[200:201], 0, v[202:203]
	global_load_dwordx4 v[150:153], v[204:205], off
	global_load_dwordx4 v[154:157], v[204:205], off offset:64
	v_add_u32_e32 v198, 16, v194
	v_ashrrev_i32_e32 v195, 31, v198
	v_mov_b32_e32 v200, v198
	v_mov_b32_e32 v201, v195
	v_lshlrev_b64 v[204:205], 12, v[200:201]
	v_lshl_add_u64 v[200:201], s[8:9], 0, v[204:205]
	v_lshl_add_u64 v[206:207], v[200:201], 0, v[202:203]
	global_load_dwordx4 v[158:161], v[206:207], off
	global_load_dwordx4 v[162:165], v[206:207], off offset:64
	v_add_u32_e32 v198, 32, v194
	v_ashrrev_i32_e32 v195, 31, v198
	v_mov_b32_e32 v200, v198
	v_mov_b32_e32 v201, v195
	v_lshlrev_b64 v[204:205], 12, v[200:201]
	v_lshl_add_u64 v[200:201], s[8:9], 0, v[204:205]
	v_lshl_add_u64 v[206:207], v[200:201], 0, v[202:203]
	global_load_dwordx4 v[166:169], v[206:207], off
	global_load_dwordx4 v[170:173], v[206:207], off offset:64
	v_add_u32_e32 v198, 48, v194
	v_ashrrev_i32_e32 v195, 31, v198
	v_mov_b32_e32 v200, v198
	v_mov_b32_e32 v201, v195
	v_lshlrev_b64 v[204:205], 12, v[200:201]
	v_lshl_add_u64 v[200:201], s[8:9], 0, v[204:205]
	v_lshl_add_u64 v[206:207], v[200:201], 0, v[202:203]
	global_load_dwordx4 v[174:177], v[206:207], off
	global_load_dwordx4 v[190:193], v[206:207], off offset:64
	v_add_u32_e32 v132, s67, v138
	v_readfirstlane_b32 s38, v130
	v_add_u32_e32 v130, s0, v140
	v_ashrrev_i32_e32 v133, 31, v132
	v_readfirstlane_b32 s39, v131
	v_lshlrev_b64 v[142:143], 12, v[132:133]
	v_ashrrev_i32_e32 v131, 31, v130
	v_lshl_add_u64 v[144:145], s[8:9], 0, v[142:143]
	v_lshlrev_b64 v[130:131], 1, v[130:131]
	v_lshl_add_u64 v[148:149], v[144:145], 0, v[130:131]
	v_lshl_add_u64 v[146:147], s[36:37], 0, v[142:143]
	s_nop 0
	s_nop 0
	s_waitcnt lgkmcnt(0)
	s_nop 0
	s_waitcnt vmcnt(7)
	v_lshlrev_b32_e32 v80, 16, v150
	v_add_f32_e32 v80, v126, v80
	v_and_b32_e32 v126, 0xffff0000, v150
	v_add_f32_e32 v126, v127, v126
	v_lshlrev_b32_e32 v127, 16, v151
	v_add_f32_e32 v127, v128, v127
	v_and_b32_e32 v128, 0xffff0000, v151
	v_add_f32_e32 v128, v129, v128
	v_lshlrev_b32_e32 v129, 16, v152
	v_add_f32_e32 v129, v122, v129
	v_and_b32_e32 v122, 0xffff0000, v152
	v_mul_f32_e32 v144, v126, v126
	v_fmac_f32_e32 v144, v80, v80
	v_fmac_f32_e32 v144, v127, v127
	v_fmac_f32_e32 v144, v128, v128
	v_add_f32_e32 v142, v123, v122
	v_lshlrev_b32_e32 v122, 16, v153
	v_fmac_f32_e32 v144, v129, v129
	v_add_f32_e32 v143, v124, v122
	v_and_b32_e32 v122, 0xffff0000, v153
	v_fmac_f32_e32 v144, v142, v142
	v_add_f32_e32 v125, v125, v122
	v_fmac_f32_e32 v144, v143, v143
	v_cvt_pk_bf16_f32 v122, v80, v126
	v_cvt_pk_bf16_f32 v123, v127, v128
	v_lshl_add_u64 v[126:127], v[146:147], 0, v[130:131]
	v_fmac_f32_e32 v144, v125, v125
	v_cvt_pk_bf16_f32 v124, v129, v142
	v_cvt_pk_bf16_f32 v125, v143, v125
	global_store_dwordx4 v[126:127], v[122:125], off
	s_nop 0
	s_waitcnt lgkmcnt(0)
	s_nop 0
	s_waitcnt vmcnt(7)
	v_lshlrev_b32_e32 v80, 16, v154
	v_add_f32_e32 v80, v118, v80
	v_and_b32_e32 v118, 0xffff0000, v154
	v_add_f32_e32 v118, v119, v118
	v_lshlrev_b32_e32 v119, 16, v155
	v_add_f32_e32 v119, v120, v119
	v_and_b32_e32 v120, 0xffff0000, v155
	v_add_f32_e32 v120, v121, v120
	v_lshlrev_b32_e32 v121, 16, v156
	v_add_f32_e32 v121, v114, v121
	v_and_b32_e32 v114, 0xffff0000, v156
	v_add_f32_e32 v122, v115, v114
	v_lshlrev_b32_e32 v114, 16, v157
	v_add_f32_e32 v123, v116, v114
	v_and_b32_e32 v114, 0xffff0000, v157
	v_add_f32_e32 v117, v117, v114
	v_mul_f32_e32 v114, v118, v118
	v_fmac_f32_e32 v114, v80, v80
	v_fmac_f32_e32 v114, v119, v119
	v_fmac_f32_e32 v114, v120, v120
	v_fmac_f32_e32 v114, v121, v121
	v_fmac_f32_e32 v114, v122, v122
	v_fmac_f32_e32 v114, v123, v123
	v_fmac_f32_e32 v114, v117, v117
	v_add_f32_e32 v124, v144, v114
	v_cvt_pk_bf16_f32 v114, v80, v118
	v_cvt_pk_bf16_f32 v115, v119, v120
	v_cvt_pk_bf16_f32 v116, v121, v122
	v_cvt_pk_bf16_f32 v117, v123, v117
	global_store_dwordx4 v[126:127], v[114:117], off offset:64
	v_xor_b32_e32 v80, 16, v189
	s_nop 0
	v_and_b32_e32 v114, 64, v189
	v_add_u32_e32 v115, 64, v114
	v_cmp_lt_i32_e64 s[2:3], v80, v115
	v_xor_b32_e32 v116, 32, v189
	s_nop 0
	v_cndmask_b32_e64 v80, v189, v80, s[2:3]
	v_lshlrev_b32_e32 v80, 2, v80
	ds_bpermute_b32 v114, v80, v124
	v_cmp_lt_i32_e64 s[2:3], v116, v115
	s_waitcnt lgkmcnt(0)
	v_add_f32_e32 v114, v124, v114
	v_cndmask_b32_e64 v115, v189, v116, s[2:3]
	v_lshlrev_b32_e32 v116, 2, v115
	ds_bpermute_b32 v115, v116, v114
	s_and_saveexec_b64 s[2:3], vcc
	s_cbranch_execz .LBB0_847
	s_waitcnt lgkmcnt(0)
	v_add_f32_e32 v114, v114, v115
	v_mul_f32_e32 v114, 0x4b800000, v114
	v_trunc_f32_e32 v114, v114
	v_mul_f32_e32 v115, 0x2f800000, v114
	v_floor_f32_e32 v115, v115
	v_fmac_f32_e32 v114, 0xcf800000, v115
	v_cvt_u32_f32_e32 v114, v114
	v_cvt_u32_f32_e32 v115, v115
	v_lshl_add_u64 v[118:119], v[132:133], 3, s[40:41]
	global_atomic_add_x2 v[118:119], v[114:115], off

; #define G_STAGE(bufoff, gbase, voff) do { _Pragma("unroll") for (int _i = 0; _i < 2; ++_i) { unsigned _vo = (voff)[_i]; asm volatile("" : "+v"(_vo));   \
;     __builtin_amdgcn_global_load_lds((const unsigned*)((const char*)(gbase) + _vo), (LAS unsigned*)(lds + (bufoff) + ldsw + _i * 8192), 16, 0, 0); } } while (0)
; #define G_LDA(dst, b, h) do { _Pragma("unroll") for (int m = 0; m < 4; ++m) _Pragma("unroll") for (int k = 0; k < 2; ++k) dst[m][k] = *(const LAS bf16x8*)(lds + G_SA(b, h) + aoff + m * 2048 + k * 1024); } while (0)
; #define G_LDB(dst, b, h) do { _Pragma("unroll") for (int n = 0; n < 2; ++n) _Pragma("unroll") for (int k = 0; k < 2; ++k) dst[n][k] = *(const LAS bf16x8*)(lds + G_SB(b, h) + boff + n * 2048 + k * 1024); } while (0)
; #define G_MMA(ai, bj, At, Bt) do { __builtin_amdgcn_s_setprio(1); _Pragma("unroll") for (int m = 0; m < 4; ++m) _Pragma("unroll") for (int n = 0; n < 2; ++n) _Pragma("unroll") for (int k = 0; k < 2; ++k) \
;     acc[ai][bj][m][n] = __builtin_amdgcn_mfma_f32_16x16x32_bf16(Bt[n][k], At[m][k], acc[ai][bj][m][n], 0, 0, 0); __builtin_amdgcn_s_setprio(0); } while (0)
; #define G_WAIT_V(n) asm volatile("s_waitcnt vmcnt(" #n ")" ::: "memory")
; #define G_WAIT_L(n) asm volatile("s_waitcnt lgkmcnt(" #n ")" ::: "memory")
; #define G_BAR __builtin_amdgcn_s_barrier()
; template <class Epi>
; __device__ __forceinline__ void gemm_phase(LAS unsigned char* lds, const int K, const unsigned lda_b, const unsigned ldb_b, const Map& M, const Epi& E) {
;     ...
;       const bool last = (t == nt - 2);
;       const char* a1h1 = cur.a0 + a_h + (size_t)(t + 1) * kstep;
;       const char* a2h0 = last ? nxt.a0 : cur.a0 + (size_t)(t + 2) * kstep; const char* a2h1 = a2h0 + a_h;
;       const char* b2h0 = last ? nxt.b0 : cur.b0 + (size_t)(t + 2) * kstep; const char* b2h1 = last ? nxt.b1 : cur.b1 + (size_t)(t + 2) * kstep;
;       G_LDB(B0, 0, 0); G_SCHED; G_LDA(At, 0, 0); G_STAGE(G_SA(1, 1), a1h1, voffA);
;       G_WAIT_L(8); G_BAR; G_WAIT_L(0); G_MMA(0, 0, At, B0); G_BAR; G_SCHED;
;       G_LDB(B1, 0, 1); G_STAGE(G_SB(0, 0), b2h0, voffB);
;       G_BAR; G_WAIT_L(0); G_MMA(0, 1, At, B1); G_BAR;
;       G_LDA(At, 0, 1); G_STAGE(G_SA(0, 0), a2h0, voffA);
;       G_BAR; G_WAIT_L(0); G_MMA(1, 0, At, B0); G_BAR; G_SCHED;
;       G_STAGE(G_SB(0, 1), b2h1, voffB);
;       G_WAIT_V(6); G_BAR; G_MMA(1, 1, At, B1); G_BAR;
.LBB0_958:
	s_add_u32 s22, s4, 0xfff80080
	s_addc_u32 s30, s5, -1
	s_add_u32 s31, s19, 0xfffe0000
	s_addc_u32 s34, s28, -1
	s_add_i32 s35, 0, 0x10000
	v_add_u32_e32 v80, s35, v165
	ds_read_b128 v[132:135], v80
	ds_read_b128 v[136:139], v80 offset:1024
	ds_read_b128 v[140:143], v80 offset:2048
	ds_read_b128 v[144:147], v80 offset:3072
	s_cmp_eq_u32 s29, 28
	s_cselect_b32 s43, s7, s30
	s_cselect_b32 s42, s6, s22
	s_cselect_b32 s45, s9, s34
	s_cselect_b32 s44, s8, s31
	v_mov_b32_e32 v80, v160
	s_cselect_b32 s39, s18, s28
	s_cselect_b32 s38, s1, s19
	s_add_u32 s68, s42, 0x80000
	ds_read_b128 v[148:151], v171
	ds_read_b128 v[152:155], v171 offset:1024
	ds_read_b128 v[172:175], v171 offset:2048
	ds_read_b128 v[176:179], v171 offset:3072
	ds_read_b128 v[184:187], v171 offset:4096
	ds_read_b128 v[190:193], v171 offset:5120
	ds_read_b128 v[194:197], v171 offset:6144
	ds_read_b128 v[198:201], v171 offset:7168
	s_addc_u32 s69, s43, 0
	s_add_i32 m0, s47, 0xc000
	s_nop 0
	global_load_lds_dwordx4 v80, s[4:5]
	v_mov_b32_e32 v80, v162
	s_add_i32 m0, s47, 0xe000
	s_nop 0
	global_load_lds_dwordx4 v80, s[4:5]
	s_waitcnt lgkmcnt(8)
	s_barrier
	s_waitcnt lgkmcnt(0)
	s_setprio 1
	s_waitcnt lgkmcnt(0)
	v_mfma_f32_16x16x32_bf16 v[128:131], v[132:135], v[148:151], v[128:131]
	v_mfma_f32_16x16x32_bf16 v[124:127], v[140:143], v[148:151], v[124:127]
	v_mfma_f32_16x16x32_bf16 v[110:113], v[132:135], v[172:175], v[110:113]
	v_mfma_f32_16x16x32_bf16 v[106:109], v[140:143], v[172:175], v[106:109]
	v_mfma_f32_16x16x32_bf16 v[94:97], v[132:135], v[184:187], v[94:97]
	v_mfma_f32_16x16x32_bf16 v[90:93], v[140:143], v[184:187], v[90:93]
	v_mfma_f32_16x16x32_bf16 v[76:79], v[132:135], v[194:197], v[76:79]
	v_mfma_f32_16x16x32_bf16 v[72:75], v[140:143], v[194:197], v[72:75]
	v_mfma_f32_16x16x32_bf16 v[128:131], v[136:139], v[152:155], v[128:131]
	v_mfma_f32_16x16x32_bf16 v[124:127], v[144:147], v[152:155], v[124:127]
	v_mfma_f32_16x16x32_bf16 v[110:113], v[136:139], v[176:179], v[110:113]
	v_mfma_f32_16x16x32_bf16 v[106:109], v[144:147], v[176:179], v[106:109]
	v_mfma_f32_16x16x32_bf16 v[94:97], v[136:139], v[190:193], v[94:97]
	v_mfma_f32_16x16x32_bf16 v[90:93], v[144:147], v[190:193], v[90:93]
	v_mfma_f32_16x16x32_bf16 v[76:79], v[136:139], v[198:201], v[76:79]
	v_mfma_f32_16x16x32_bf16 v[72:75], v[144:147], v[198:201], v[72:75]
	s_setprio 0
	s_barrier
	s_add_i32 s22, 0, 0x14000
	v_add_u32_e32 v80, s22, v165
	ds_read_b128 v[202:205], v80
	ds_read_b128 v[206:209], v80 offset:1024
	ds_read_b128 v[210:213], v80 offset:2048
	ds_read_b128 v[214:217], v80 offset:3072
	v_mov_b32_e32 v80, v161
	s_add_i32 s30, s35, s46
	s_mov_b32 m0, s30
	s_nop 0
	global_load_lds_dwordx4 v80, s[44:45]
	v_mov_b32_e32 v80, v163
	s_add_i32 m0, s30, 0x2000
	s_nop 0
	global_load_lds_dwordx4 v80, s[44:45]
	s_barrier
	s_waitcnt lgkmcnt(0)
	s_setprio 1
	s_waitcnt lgkmcnt(0)
	v_mfma_f32_16x16x32_bf16 v[118:121], v[202:205], v[148:151], v[118:121]
	v_mfma_f32_16x16x32_bf16 v[114:117], v[210:213], v[148:151], v[114:117]
	v_mfma_f32_16x16x32_bf16 v[102:105], v[202:205], v[172:175], v[102:105]
	v_mfma_f32_16x16x32_bf16 v[98:101], v[210:213], v[172:175], v[98:101]
	v_mfma_f32_16x16x32_bf16 v[86:89], v[202:205], v[184:187], v[86:89]
	v_mfma_f32_16x16x32_bf16 v[82:85], v[210:213], v[184:187], v[82:85]
	v_mfma_f32_16x16x32_bf16 v[68:71], v[202:205], v[194:197], v[68:71]
	v_mfma_f32_16x16x32_bf16 v[64:67], v[210:213], v[194:197], v[64:67]
	v_mfma_f32_16x16x32_bf16 v[118:121], v[206:209], v[152:155], v[118:121]
	v_mfma_f32_16x16x32_bf16 v[114:117], v[214:217], v[152:155], v[114:117]
	v_mfma_f32_16x16x32_bf16 v[102:105], v[206:209], v[176:179], v[102:105]
	v_mfma_f32_16x16x32_bf16 v[98:101], v[214:217], v[176:179], v[98:101]
	v_mfma_f32_16x16x32_bf16 v[86:89], v[206:209], v[190:193], v[86:89]
	v_mfma_f32_16x16x32_bf16 v[82:85], v[214:217], v[190:193], v[82:85]
	v_mfma_f32_16x16x32_bf16 v[68:71], v[206:209], v[198:201], v[68:71]
	v_mfma_f32_16x16x32_bf16 v[64:67], v[214:217], v[198:201], v[64:67]
	s_setprio 0
	v_mov_b32_e32 v80, v160
	s_mov_b32 m0, s47
	s_barrier
	ds_read_b128 v[148:151], v171 offset:16384
	ds_read_b128 v[152:155], v171 offset:17408
	ds_read_b128 v[172:175], v171 offset:18432
	ds_read_b128 v[176:179], v171 offset:19456
	ds_read_b128 v[184:187], v171 offset:20480
	ds_read_b128 v[190:193], v171 offset:21504
	ds_read_b128 v[194:197], v171 offset:22528
	ds_read_b128 v[198:201], v171 offset:23552
	s_nop 0
	global_load_lds_dwordx4 v80, s[42:43]
	v_mov_b32_e32 v80, v162
	s_mov_b32 m0, s48
	s_nop 0
	global_load_lds_dwordx4 v80, s[42:43]
	s_barrier
	s_waitcnt lgkmcnt(0)
	s_setprio 1
	s_waitcnt lgkmcnt(0)
	v_mfma_f32_16x16x32_bf16 v[60:63], v[132:135], v[148:151], v[60:63]
	v_mfma_f32_16x16x32_bf16 v[56:59], v[140:143], v[148:151], v[56:59]
	v_mfma_f32_16x16x32_bf16 v[44:47], v[132:135], v[172:175], v[44:47]
	v_mfma_f32_16x16x32_bf16 v[40:43], v[140:143], v[172:175], v[40:43]
	v_mfma_f32_16x16x32_bf16 v[28:31], v[132:135], v[184:187], v[28:31]
	v_mfma_f32_16x16x32_bf16 v[24:27], v[140:143], v[184:187], v[24:27]
	v_mfma_f32_16x16x32_bf16 v[12:15], v[132:135], v[194:197], v[12:15]
	v_mfma_f32_16x16x32_bf16 v[8:11], v[140:143], v[194:197], v[8:11]
	v_mfma_f32_16x16x32_bf16 v[60:63], v[136:139], v[152:155], v[60:63]
	v_mfma_f32_16x16x32_bf16 v[56:59], v[144:147], v[152:155], v[56:59]
	v_mfma_f32_16x16x32_bf16 v[44:47], v[136:139], v[176:179], v[44:47]
	v_mfma_f32_16x16x32_bf16 v[40:43], v[144:147], v[176:179], v[40:43]
	v_mfma_f32_16x16x32_bf16 v[28:31], v[136:139], v[190:193], v[28:31]
	v_mfma_f32_16x16x32_bf16 v[24:27], v[144:147], v[190:193], v[24:27]
	v_mfma_f32_16x16x32_bf16 v[12:15], v[136:139], v[198:201], v[12:15]
	v_mfma_f32_16x16x32_bf16 v[8:11], v[144:147], v[198:201], v[8:11]
	s_setprio 0
	s_barrier
; #define G_STAGE(bufoff, gbase, voff) do { _Pragma("unroll") for (int _i = 0; _i < 2; ++_i) { unsigned _vo = (voff)[_i]; asm volatile("" : "+v"(_vo));   \
;     __builtin_amdgcn_global_load_lds((const unsigned*)((const char*)(gbase) + _vo), (LAS unsigned*)(lds + (bufoff) + ldsw + _i * 8192), 16, 0, 0); } } while (0)
; #define G_LDA(dst, b, h) do { _Pragma("unroll") for (int m = 0; m < 4; ++m) _Pragma("unroll") for (int k = 0; k < 2; ++k) dst[m][k] = *(const LAS bf16x8*)(lds + G_SA(b, h) + aoff + m * 2048 + k * 1024); } while (0)
; #define G_LDB(dst, b, h) do { _Pragma("unroll") for (int n = 0; n < 2; ++n) _Pragma("unroll") for (int k = 0; k < 2; ++k) dst[n][k] = *(const LAS bf16x8*)(lds + G_SB(b, h) + boff + n * 2048 + k * 1024); } while (0)
; #define G_MMA(ai, bj, At, Bt) do { __builtin_amdgcn_s_setprio(1); _Pragma("unroll") for (int m = 0; m < 4; ++m) _Pragma("unroll") for (int n = 0; n < 2; ++n) _Pragma("unroll") for (int k = 0; k < 2; ++k) \
;     acc[ai][bj][m][n] = __builtin_amdgcn_mfma_f32_16x16x32_bf16(Bt[n][k], At[m][k], acc[ai][bj][m][n], 0, 0, 0); __builtin_amdgcn_s_setprio(0); } while (0)
; #define G_WAIT_L(n) asm volatile("s_waitcnt lgkmcnt(" #n ")" ::: "memory")
; #define G_BAR __builtin_amdgcn_s_barrier()
; #define G_SCHED __builtin_amdgcn_sched_barrier(0)
; template <class Epi>
; __device__ __forceinline__ void gemm_phase(LAS unsigned char* lds, const int K, const unsigned lda_b, const unsigned ldb_b, const Map& M, const Epi& E) {
;     ...
;       G_LDB(B0, 1, 0); G_SCHED; G_LDA(At, 1, 0); G_STAGE(G_SA(0, 1), a2h1, voffA);
;       G_WAIT_L(8); G_BAR; G_WAIT_L(0); G_MMA(0, 0, At, B0); G_BAR; G_SCHED;
;       G_LDB(B1, 1, 1); G_STAGE(G_SB(1, 0), b2h0 + kstep, voffB);
;       G_BAR; G_WAIT_L(0); G_MMA(0, 1, At, B1); G_BAR;
;       G_LDA(At, 1, 1); G_STAGE(G_SA(1, 0), a2h0 + kstep, voffA);
;       G_BAR; G_WAIT_L(0); G_MMA(1, 0, At, B0); G_BAR; G_SCHED;
	v_mov_b32_e32 v80, v161
	s_add_i32 s22, s22, s46
	s_mov_b32 m0, s22
	s_nop 0
	global_load_lds_dwordx4 v80, s[38:39]
	v_mov_b32_e32 v80, v163
	s_add_i32 m0, s22, 0x2000
	s_nop 0
	global_load_lds_dwordx4 v80, s[38:39]
	s_waitcnt vmcnt(6)
	s_barrier
	s_setprio 1
	v_mfma_f32_16x16x32_bf16 v[52:55], v[202:205], v[148:151], v[52:55]
	v_mfma_f32_16x16x32_bf16 v[48:51], v[210:213], v[148:151], v[48:51]
	v_mfma_f32_16x16x32_bf16 v[36:39], v[202:205], v[172:175], v[36:39]
	v_mfma_f32_16x16x32_bf16 v[32:35], v[210:213], v[172:175], v[32:35]
	v_mfma_f32_16x16x32_bf16 v[20:23], v[202:205], v[184:187], v[20:23]
	v_mfma_f32_16x16x32_bf16 v[16:19], v[210:213], v[184:187], v[16:19]
	v_mfma_f32_16x16x32_bf16 v[4:7], v[202:205], v[194:197], v[4:7]
	v_mfma_f32_16x16x32_bf16 v[0:3], v[210:213], v[194:197], v[0:3]
	v_mfma_f32_16x16x32_bf16 v[52:55], v[206:209], v[152:155], v[52:55]
	v_mfma_f32_16x16x32_bf16 v[48:51], v[214:217], v[152:155], v[48:51]
	v_mfma_f32_16x16x32_bf16 v[36:39], v[206:209], v[176:179], v[36:39]
	v_mfma_f32_16x16x32_bf16 v[32:35], v[214:217], v[176:179], v[32:35]
	v_mfma_f32_16x16x32_bf16 v[20:23], v[206:209], v[190:193], v[20:23]
	v_mfma_f32_16x16x32_bf16 v[16:19], v[214:217], v[190:193], v[16:19]
	v_mfma_f32_16x16x32_bf16 v[4:7], v[206:209], v[198:201], v[4:7]
	v_mfma_f32_16x16x32_bf16 v[0:3], v[214:217], v[198:201], v[0:3]
	s_setprio 0
	s_add_i32 s22, 0, 0x18000
	v_add_u32_e32 v80, s22, v165
	s_barrier
	ds_read_b128 v[132:135], v80
	ds_read_b128 v[136:139], v80 offset:1024
	ds_read_b128 v[140:143], v80 offset:2048
	ds_read_b128 v[144:147], v80 offset:3072
	v_mov_b32_e32 v80, v160
	s_mov_b32 m0, s49
	ds_read_b128 v[148:151], v171 offset:32768
	ds_read_b128 v[152:155], v171 offset:33792
	ds_read_b128 v[172:175], v171 offset:34816
	ds_read_b128 v[176:179], v171 offset:35840
	ds_read_b128 v[184:187], v171 offset:36864
	ds_read_b128 v[190:193], v171 offset:37888
	ds_read_b128 v[194:197], v171 offset:38912
	ds_read_b128 v[198:201], v171 offset:39936
	s_nop 0
	global_load_lds_dwordx4 v80, s[68:69]
	v_mov_b32_e32 v80, v162
	s_mov_b32 m0, s66
	s_nop 0
	global_load_lds_dwordx4 v80, s[68:69]
	s_waitcnt lgkmcnt(8)
	s_barrier
	s_waitcnt lgkmcnt(0)
	s_setprio 1
	s_waitcnt lgkmcnt(0)
	v_mfma_f32_16x16x32_bf16 v[128:131], v[132:135], v[148:151], v[128:131]
	v_mfma_f32_16x16x32_bf16 v[124:127], v[140:143], v[148:151], v[124:127]
	v_mfma_f32_16x16x32_bf16 v[110:113], v[132:135], v[172:175], v[110:113]
	v_mfma_f32_16x16x32_bf16 v[106:109], v[140:143], v[172:175], v[106:109]
	v_mfma_f32_16x16x32_bf16 v[94:97], v[132:135], v[184:187], v[94:97]
	v_mfma_f32_16x16x32_bf16 v[90:93], v[140:143], v[184:187], v[90:93]
	v_mfma_f32_16x16x32_bf16 v[76:79], v[132:135], v[194:197], v[76:79]
	v_mfma_f32_16x16x32_bf16 v[72:75], v[140:143], v[194:197], v[72:75]
	v_mfma_f32_16x16x32_bf16 v[128:131], v[136:139], v[152:155], v[128:131]
	v_mfma_f32_16x16x32_bf16 v[124:127], v[144:147], v[152:155], v[124:127]
	v_mfma_f32_16x16x32_bf16 v[110:113], v[136:139], v[176:179], v[110:113]
	v_mfma_f32_16x16x32_bf16 v[106:109], v[144:147], v[176:179], v[106:109]
	v_mfma_f32_16x16x32_bf16 v[94:97], v[136:139], v[190:193], v[94:97]
	v_mfma_f32_16x16x32_bf16 v[90:93], v[144:147], v[190:193], v[90:93]
	v_mfma_f32_16x16x32_bf16 v[76:79], v[136:139], v[198:201], v[76:79]
	v_mfma_f32_16x16x32_bf16 v[72:75], v[144:147], v[198:201], v[72:75]
	s_setprio 0
	s_barrier
	s_add_i32 s30, 0, 0x1c000
	v_add_u32_e32 v80, s30, v165
	ds_read_b128 v[202:205], v80
	ds_read_b128 v[206:209], v80 offset:1024
	ds_read_b128 v[210:213], v80 offset:2048
	ds_read_b128 v[214:217], v80 offset:3072
	v_mov_b32_e32 v80, v161
	s_add_i32 s22, s22, s46
	s_add_i32 m0, s22, 0xffffff80
	v_mov_b32_e32 v80, v163
	global_load_lds_dwordx4 v161, s[44:45] offset:128
	s_add_i32 m0, s22, 0x1f80
	s_nop 0
	global_load_lds_dwordx4 v163, s[44:45] offset:128
	s_barrier
	s_waitcnt lgkmcnt(0)
	s_setprio 1
	s_waitcnt lgkmcnt(0)
	v_mfma_f32_16x16x32_bf16 v[118:121], v[202:205], v[148:151], v[118:121]
	v_mfma_f32_16x16x32_bf16 v[114:117], v[210:213], v[148:151], v[114:117]
	v_mfma_f32_16x16x32_bf16 v[102:105], v[202:205], v[172:175], v[102:105]
	v_mfma_f32_16x16x32_bf16 v[98:101], v[210:213], v[172:175], v[98:101]
	v_mfma_f32_16x16x32_bf16 v[86:89], v[202:205], v[184:187], v[86:89]
	v_mfma_f32_16x16x32_bf16 v[82:85], v[210:213], v[184:187], v[82:85]
	v_mfma_f32_16x16x32_bf16 v[68:71], v[202:205], v[194:197], v[68:71]
	v_mfma_f32_16x16x32_bf16 v[64:67], v[210:213], v[194:197], v[64:67]
	v_mfma_f32_16x16x32_bf16 v[118:121], v[206:209], v[152:155], v[118:121]
	v_mfma_f32_16x16x32_bf16 v[114:117], v[214:217], v[152:155], v[114:117]
	v_mfma_f32_16x16x32_bf16 v[102:105], v[206:209], v[176:179], v[102:105]
	v_mfma_f32_16x16x32_bf16 v[98:101], v[214:217], v[176:179], v[98:101]
	v_mfma_f32_16x16x32_bf16 v[86:89], v[206:209], v[190:193], v[86:89]
	v_mfma_f32_16x16x32_bf16 v[82:85], v[214:217], v[190:193], v[82:85]
	v_mfma_f32_16x16x32_bf16 v[68:71], v[206:209], v[198:201], v[68:71]
	v_mfma_f32_16x16x32_bf16 v[64:67], v[214:217], v[198:201], v[64:67]
	s_setprio 0
	v_mov_b32_e32 v80, v160
	s_barrier
	ds_read_b128 v[148:151], v171 offset:49152
	ds_read_b128 v[152:155], v171 offset:50176
	ds_read_b128 v[172:175], v171 offset:51200
	ds_read_b128 v[176:179], v171 offset:52224
	ds_read_b128 v[184:187], v171 offset:53248
	ds_read_b128 v[190:193], v171 offset:54272
	ds_read_b128 v[194:197], v171 offset:55296
	ds_read_b128 v[198:201], v171 offset:56320
	s_add_i32 m0, s67, 0xffffff80
	v_mov_b32_e32 v80, v162
	global_load_lds_dwordx4 v160, s[42:43] offset:128
	s_add_i32 m0, s81, 0xffffff80
	s_nop 0
	global_load_lds_dwordx4 v162, s[42:43] offset:128
	s_barrier
; __device__ __forceinline__ float bf_lo(unsigned u) { return __uint_as_float(u << 16); }
; __device__ __forceinline__ float bf_hi(unsigned u) { return __uint_as_float(u & 0xffff0000u); }
; __device__ __forceinline__ float sigmoidf_(float x) { return 1.f / (1.f + __expf(-x)); }
; __device__ __forceinline__ float rinv_of(unsigned long long ss) { return rsqrtf((float)ss * (1.f / 16777216.f) * (1.f / DM) + 1e-6f); }
; #define G_LDA(dst, b, h) do { _Pragma("unroll") for (int m = 0; m < 4; ++m) _Pragma("unroll") for (int k = 0; k < 2; ++k) dst[m][k] = *(const LAS bf16x8*)(lds + G_SA(b, h) + aoff + m * 2048 + k * 1024); } while (0)
; #define G_BAR __builtin_amdgcn_s_barrier()
;   __device__ __forceinline__ void operator()(const f32x4 (&acc)[2][2][4][2], const Unit& u, const EpiCtx& x_, int wr, int wc, int fr, int fq) const {
;     ...
;         const int row = (u.r0 + (ai ? x_.rdelta : 0)) + wr * 64 + m * 16 + fr;
;         const bf16_t* pep = (const bf16_t*)x_.aux + (size_t)row * DM;
;         const bf16_t* xin = (const bf16_t*)x_.aux2 + (size_t)row * DM;
;         bf16_t* xbp = x_.xb + (size_t)row * DM;
;         const float rs = rinv_of(x_.ss[row]);
;         float sq = 0.f;
; #pragma unroll
;         for (int bj = 0; bj < 2; ++bj) {
;           const int cb = u.c0 + wc * 64 + bj * 32 + 8 * fq;
;           const uint4 pe = *(const uint4*)(pep + cb), xi = *(const uint4*)(xin + cb);
;           const f32x4 a = acc[ai][bj][m][0] * rs, b = acc[ai][bj][m][1] * rs;
;           f32x4 xa, xc;
;           xa[0] = bf_lo(xi.x) + bf_lo(pe.x) * sigmoidf_(a[0]); xa[1] = bf_hi(xi.x) + bf_hi(pe.x) * sigmoidf_(a[1]);
;           xa[2] = bf_lo(xi.y) + bf_lo(pe.y) * sigmoidf_(a[2]); xa[3] = bf_hi(xi.y) + bf_hi(pe.y) * sigmoidf_(a[3]);
;           xc[0] = bf_lo(xi.z) + bf_lo(pe.z) * sigmoidf_(b[0]); xc[1] = bf_hi(xi.z) + bf_hi(pe.z) * sigmoidf_(b[1]);
;           xc[2] = bf_lo(xi.w) + bf_lo(pe.w) * sigmoidf_(b[2]); xc[3] = bf_hi(xi.w) + bf_hi(pe.w) * sigmoidf_(b[3]);
; template <class Epi>
; __device__ __forceinline__ void gemm_phase(LAS unsigned char* lds, const int K, const unsigned lda_b, const unsigned ldb_b, const Map& M, const Epi& E) {
;     ...
;       G_LDA(At, 1, 1); G_STAGE(G_SA(1, 0), a2h0 + kstep, voffA);
;       G_BAR; G_WAIT_L(0); G_MMA(1, 0, At, B0); G_BAR; G_SCHED;
;       G_STAGE(G_SB(1, 1), b2h1 + kstep, voffB);
;       G_WAIT_V(6); G_BAR; G_MMA(1, 1, At, B1); G_BAR;
	s_waitcnt lgkmcnt(0)
	s_setprio 1
	s_waitcnt lgkmcnt(0)
	v_mfma_f32_16x16x32_bf16 v[60:63], v[132:135], v[148:151], v[60:63]
	v_mfma_f32_16x16x32_bf16 v[56:59], v[140:143], v[148:151], v[56:59]
	v_mfma_f32_16x16x32_bf16 v[44:47], v[132:135], v[172:175], v[44:47]
	v_mfma_f32_16x16x32_bf16 v[40:43], v[140:143], v[172:175], v[40:43]
	v_mfma_f32_16x16x32_bf16 v[28:31], v[132:135], v[184:187], v[28:31]
	v_mfma_f32_16x16x32_bf16 v[24:27], v[140:143], v[184:187], v[24:27]
	v_mfma_f32_16x16x32_bf16 v[12:15], v[132:135], v[194:197], v[12:15]
	v_mfma_f32_16x16x32_bf16 v[8:11], v[140:143], v[194:197], v[8:11]
	v_mfma_f32_16x16x32_bf16 v[60:63], v[136:139], v[152:155], v[60:63]
	v_mfma_f32_16x16x32_bf16 v[56:59], v[144:147], v[152:155], v[56:59]
	v_mfma_f32_16x16x32_bf16 v[44:47], v[136:139], v[176:179], v[44:47]
	v_mfma_f32_16x16x32_bf16 v[40:43], v[144:147], v[176:179], v[40:43]
	v_mfma_f32_16x16x32_bf16 v[28:31], v[136:139], v[190:193], v[28:31]
	v_mfma_f32_16x16x32_bf16 v[24:27], v[144:147], v[190:193], v[24:27]
	v_mfma_f32_16x16x32_bf16 v[12:15], v[136:139], v[198:201], v[12:15]
	v_mfma_f32_16x16x32_bf16 v[8:11], v[144:147], v[198:201], v[8:11]
	s_setprio 0
	s_barrier
	v_mov_b32_e32 v80, v161
	s_add_i32 s22, s30, s46
	s_add_i32 m0, s22, 0xffffff80
	v_mov_b32_e32 v80, v163
	global_load_lds_dwordx4 v161, s[38:39] offset:128
	s_add_i32 m0, s22, 0x1f80
	s_nop 0
	global_load_lds_dwordx4 v163, s[38:39] offset:128
	s_waitcnt vmcnt(6)
	s_barrier
	s_setprio 1
	v_mfma_f32_16x16x32_bf16 v[52:55], v[202:205], v[148:151], v[52:55]
	v_mfma_f32_16x16x32_bf16 v[48:51], v[210:213], v[148:151], v[48:51]
	v_mfma_f32_16x16x32_bf16 v[36:39], v[202:205], v[172:175], v[36:39]
	v_mfma_f32_16x16x32_bf16 v[32:35], v[210:213], v[172:175], v[32:35]
	v_mfma_f32_16x16x32_bf16 v[20:23], v[202:205], v[184:187], v[20:23]
	v_mfma_f32_16x16x32_bf16 v[16:19], v[210:213], v[184:187], v[16:19]
	v_mfma_f32_16x16x32_bf16 v[4:7], v[202:205], v[194:197], v[4:7]
	v_mfma_f32_16x16x32_bf16 v[0:3], v[210:213], v[194:197], v[0:3]
	v_mfma_f32_16x16x32_bf16 v[52:55], v[206:209], v[152:155], v[52:55]
	v_mfma_f32_16x16x32_bf16 v[48:51], v[214:217], v[152:155], v[48:51]
	v_mfma_f32_16x16x32_bf16 v[36:39], v[206:209], v[176:179], v[36:39]
	v_mfma_f32_16x16x32_bf16 v[32:35], v[214:217], v[176:179], v[32:35]
	v_mfma_f32_16x16x32_bf16 v[20:23], v[206:209], v[190:193], v[20:23]
	v_mfma_f32_16x16x32_bf16 v[16:19], v[214:217], v[190:193], v[16:19]
	v_mfma_f32_16x16x32_bf16 v[4:7], v[206:209], v[198:201], v[4:7]
	v_mfma_f32_16x16x32_bf16 v[0:3], v[214:217], v[198:201], v[0:3]
	s_setprio 0
	s_add_i32 s29, s29, 2
	s_add_u32 s19, s19, 0x100
	s_addc_u32 s28, s28, 0
	s_add_u32 s4, s4, 0x100
	s_addc_u32 s5, s5, 0
	s_cmp_gt_u32 s29, 29
	s_barrier
	s_cbranch_scc0 .LBB0_958
	s_nop 1
	v_add_u32_e32 v198, s87, v164
	v_ashrrev_i32_e32 v199, 31, v198
	v_lshl_add_u64 v[200:201], v[198:199], 3, s[96:97]
	global_load_dwordx2 v[174:175], v[200:201], off
	v_lshlrev_b64 v[200:201], 12, v[198:199]
	v_lshl_add_u64 v[202:203], s[92:93], 0, v[200:201]
	v_add_u32_e32 v204, s0, v166
	v_ashrrev_i32_e32 v205, 31, v204
	v_lshlrev_b64 v[206:207], 1, v[204:205]
	v_lshl_add_u64 v[208:209], v[202:203], 0, v[206:207]
	global_load_dwordx4 v[176:179], v[208:209], off
	v_lshl_add_u64 v[208:209], s[94:95], 0, v[200:201]
	v_lshl_add_u64 v[210:211], v[208:209], 0, v[206:207]
	global_load_dwordx4 v[184:187], v[210:211], off
	v_add_u32_e32 v204, s0, v167
	v_ashrrev_i32_e32 v205, 31, v204
	v_lshlrev_b64 v[206:207], 1, v[204:205]
	v_lshl_add_u64 v[210:211], v[202:203], 0, v[206:207]
	global_load_dwordx4 v[190:193], v[210:211], off
	v_lshl_add_u64 v[202:203], v[208:209], 0, v[206:207]
	global_load_dwordx4 v[194:197], v[202:203], off
	v_add_u32_e32 v146, s87, v164
	v_ashrrev_i32_e32 v147, 31, v146
	v_readfirstlane_b32 s42, v122
	v_readfirstlane_b32 s43, v123
	v_lshlrev_b64 v[122:123], 12, v[146:147]
	v_lshl_add_u64 v[152:153], s[92:93], 0, v[122:123]
	v_lshl_add_u64 v[150:151], s[94:95], 0, v[122:123]
	v_lshl_add_u64 v[148:149], s[90:91], 0, v[122:123]
	v_lshl_add_u64 v[122:123], v[146:147], 3, s[96:97]
	s_nop 0
	v_add_u32_e32 v140, s0, v166
	v_ashrrev_i32_e32 v141, 31, v140
	v_lshlrev_b64 v[142:143], 1, v[140:141]
	s_cmp_lg_u64 s[36:37], 0
	v_lshlrev_b64 v[144:145], 11, v[146:147]
	s_cselect_b64 s[38:39], -1, 0
	s_cmp_eq_u64 s[36:37], 0
	s_waitcnt lgkmcnt(0)
	s_nop 0
	s_nop 0
	s_nop 0
	s_nop 0
	s_nop 0
	s_nop 0
	s_nop 0
	s_nop 0
	s_nop 0
	s_nop 0
	s_nop 0
	s_nop 0
	s_nop 0
	s_nop 0
	s_waitcnt vmcnt(4)
	v_ffbh_u32_e32 v80, v175
	v_min_u32_e32 v80, 32, v80
	v_lshlrev_b64 v[122:123], v80, v[174:175]
	v_min_u32_e32 v122, 1, v122
	v_or_b32_e32 v122, v123, v122
	v_cvt_f32_u32_e32 v122, v122
	v_sub_u32_e32 v80, 32, v80
	v_ldexp_f32 v80, v122, v80
	v_mul_f32_e32 v80, 0x33800000, v80
	v_fmamk_f32 v80, v80, 0x3a000000, v234
	v_cmp_gt_f32_e32 vcc, s50, v80
	v_mul_f32_e32 v122, 0x4b800000, v80
	s_nop 0
	v_cndmask_b32_e32 v80, v80, v122, vcc
	v_rsq_f32_e32 v80, v80
	s_nop 0
	v_mul_f32_e32 v122, 0x45800000, v80
	v_cndmask_b32_e32 v154, v80, v122, vcc
	v_lshl_add_u64 v[122:123], v[152:153], 0, v[142:143]
	s_nop 0
	v_lshl_add_u64 v[122:123], v[150:151], 0, v[142:143]
	s_nop 0
	v_pk_mul_f32 v[122:123], v[128:129], v[154:155] op_sel_hi:[1,0]
	v_pk_mul_f32 v[128:129], v[126:127], v[154:155] op_sel_hi:[1,0]
	v_mul_f32_e32 v80, 0xbfb8aa3b, v122
	v_exp_f32_e32 v122, v80
	v_mul_f32_e32 v80, 0xbfb8aa3b, v123
	v_exp_f32_e32 v123, v80
	v_pk_mul_f32 v[126:127], v[124:125], v[154:155] op_sel_hi:[1,0]
	v_pk_mul_f32 v[130:131], v[130:131], v[154:155] op_sel_hi:[1,0]
	v_pk_add_f32 v[122:123], v[122:123], 1.0 op_sel_hi:[1,0]
	s_nop 0
	v_div_scale_f32 v80, s[4:5], v123, v123, 1.0
	s_waitcnt lgkmcnt(0)
; __device__ __forceinline__ unsigned cvt_pk_bf16(float lo, float hi) { unsigned r; asm("v_cvt_pk_bf16_f32 %0, %1, %2" : "=v"(r) : "v"(lo), "v"(hi)); return r; }
; __device__ __forceinline__ float bf_lo(unsigned u) { return __uint_as_float(u << 16); }
; __device__ __forceinline__ float bf_hi(unsigned u) { return __uint_as_float(u & 0xffff0000u); }
; __device__ __forceinline__ float sigmoidf_(float x) { return 1.f / (1.f + __expf(-x)); }
;   __device__ __forceinline__ void operator()(const f32x4 (&acc)[2][2][4][2], const Unit& u, const EpiCtx& x_, int wr, int wc, int fr, int fq) const {
;     ...
;           const uint4 pe = *(const uint4*)(pep + cb), xi = *(const uint4*)(xin + cb);
;           const f32x4 a = acc[ai][bj][m][0] * rs, b = acc[ai][bj][m][1] * rs;
;           f32x4 xa, xc;
;           xa[0] = bf_lo(xi.x) + bf_lo(pe.x) * sigmoidf_(a[0]); xa[1] = bf_hi(xi.x) + bf_hi(pe.x) * sigmoidf_(a[1]);
;           xa[2] = bf_lo(xi.y) + bf_lo(pe.y) * sigmoidf_(a[2]); xa[3] = bf_hi(xi.y) + bf_hi(pe.y) * sigmoidf_(a[3]);
;           xc[0] = bf_lo(xi.z) + bf_lo(pe.z) * sigmoidf_(b[0]); xc[1] = bf_hi(xi.z) + bf_hi(pe.z) * sigmoidf_(b[1]);
;           xc[2] = bf_lo(xi.w) + bf_lo(pe.w) * sigmoidf_(b[2]); xc[3] = bf_hi(xi.w) + bf_hi(pe.w) * sigmoidf_(b[3]);
;           sq += xa[0] * xa[0] + xa[1] * xa[1] + xa[2] * xa[2] + xa[3] * xa[3] + xc[0] * xc[0] + xc[1] * xc[1] + xc[2] * xc[2] + xc[3] * xc[3];
;           uint4 o; o.x = cvt_pk_bf16(xa[0], xa[1]); o.y = cvt_pk_bf16(xa[2], xa[3]); o.z = cvt_pk_bf16(xc[0], xc[1]); o.w = cvt_pk_bf16(xc[2], xc[3]);
;           *(uint4*)(xbp + cb) = o;
;           if (last) { float* op = (float*)u.C + (size_t)row * DM + cb; *(f32x4*)op = xa; *(f32x4*)(op + 4) = xc; }
	s_nop 0
	s_nop 0
	s_nop 0
	s_nop 0
	s_nop 0
	s_nop 0
	s_nop 0
	s_nop 0
	s_nop 0
	s_nop 0
	s_nop 0
	s_nop 0
	s_nop 0
	s_nop 0
	s_waitcnt vmcnt(3)
	v_lshlrev_b32_e32 v156, 16, v176
	v_and_b32_e32 v157, 0xffff0000, v176
	v_rcp_f32_e32 v132, v80
	s_nop 0
	s_nop 0
	s_nop 0
	s_nop 0
	s_nop 0
	s_nop 0
	s_nop 0
	s_nop 0
	s_nop 0
	s_nop 0
	s_nop 0
	s_nop 0
	s_nop 0
	s_nop 0
	s_waitcnt vmcnt(2)
	v_lshlrev_b32_e32 v124, 16, v184
	v_and_b32_e32 v125, 0xffff0000, v184
	v_fma_f32 v136, -v80, v132, 1.0
	v_fmac_f32_e32 v132, v136, v132
	v_div_scale_f32 v136, vcc, 1.0, v123, 1.0
	v_mul_f32_e32 v155, v136, v132
	v_fma_f32 v172, -v80, v155, v136
	v_fmac_f32_e32 v155, v172, v132
	v_fma_f32 v80, -v80, v155, v136
	v_div_fmas_f32 v80, v80, v132, v155
	v_div_fixup_f32 v123, v80, v123, 1.0
	v_div_scale_f32 v80, s[4:5], v122, v122, 1.0
	v_rcp_f32_e32 v132, v80
	s_nop 0
	v_fma_f32 v136, -v80, v132, 1.0
	v_fmac_f32_e32 v132, v136, v132
	v_div_scale_f32 v136, vcc, 1.0, v122, 1.0
	v_mul_f32_e32 v155, v136, v132
	v_fma_f32 v172, -v80, v155, v136
	v_fmac_f32_e32 v155, v172, v132
	v_fma_f32 v80, -v80, v155, v136
	v_div_fmas_f32 v80, v80, v132, v155
	v_div_fixup_f32 v122, v80, v122, 1.0
	v_mul_f32_e32 v80, 0xbfb8aa3b, v130
	v_exp_f32_e32 v130, v80
	v_mul_f32_e32 v80, 0xbfb8aa3b, v131
	v_exp_f32_e32 v131, v80
	v_pk_fma_f32 v[122:123], v[122:123], v[156:157], v[124:125]
	v_lshlrev_b32_e32 v124, 16, v185
	v_and_b32_e32 v125, 0xffff0000, v185
	v_pk_add_f32 v[130:131], v[130:131], 1.0 op_sel_hi:[1,0]
	v_lshlrev_b32_e32 v132, 16, v177
	v_div_scale_f32 v80, s[4:5], v131, v131, 1.0
	v_rcp_f32_e32 v136, v80
	v_and_b32_e32 v133, 0xffff0000, v177
	v_fma_f32 v137, -v80, v136, 1.0
	v_fmac_f32_e32 v136, v137, v136
	v_div_scale_f32 v137, vcc, 1.0, v131, 1.0
	v_mul_f32_e32 v155, v137, v136
	v_fma_f32 v156, -v80, v155, v137
	v_fmac_f32_e32 v155, v156, v136
	v_fma_f32 v80, -v80, v155, v137
	v_div_fmas_f32 v80, v80, v136, v155
	v_div_fixup_f32 v131, v80, v131, 1.0
	v_div_scale_f32 v80, s[4:5], v130, v130, 1.0
	v_rcp_f32_e32 v136, v80
	s_nop 0
	v_fma_f32 v137, -v80, v136, 1.0
	v_fmac_f32_e32 v136, v137, v136
	v_div_scale_f32 v137, vcc, 1.0, v130, 1.0
	v_mul_f32_e32 v155, v137, v136
	v_fma_f32 v156, -v80, v155, v137
	v_fmac_f32_e32 v155, v156, v136
	v_fma_f32 v80, -v80, v155, v137
	v_div_fmas_f32 v80, v80, v136, v155
	v_div_fixup_f32 v130, v80, v130, 1.0
	v_mul_f32_e32 v80, 0xbfb8aa3b, v126
	v_exp_f32_e32 v126, v80
	v_mul_f32_e32 v80, 0xbfb8aa3b, v127
	v_exp_f32_e32 v127, v80
	v_pk_fma_f32 v[124:125], v[130:131], v[132:133], v[124:125]
	v_lshlrev_b32_e32 v132, 16, v178
	v_and_b32_e32 v133, 0xffff0000, v178
	v_pk_add_f32 v[126:127], v[126:127], 1.0 op_sel_hi:[1,0]
	v_lshlrev_b32_e32 v130, 16, v186
	v_div_scale_f32 v80, s[4:5], v127, v127, 1.0
	v_rcp_f32_e32 v134, v80
	v_and_b32_e32 v131, 0xffff0000, v186
	v_lshl_add_u64 v[156:157], v[144:145], 2, s[36:37]
	v_fma_f32 v136, -v80, v134, 1.0
	v_fmac_f32_e32 v134, v136, v134
	v_div_scale_f32 v136, vcc, 1.0, v127, 1.0
	v_mul_f32_e32 v137, v136, v134
	v_fma_f32 v138, -v80, v137, v136
	v_fmac_f32_e32 v137, v138, v134
	v_fma_f32 v80, -v80, v137, v136
	v_div_fmas_f32 v80, v80, v134, v137
	v_div_fixup_f32 v127, v80, v127, 1.0
	v_div_scale_f32 v80, s[4:5], v126, v126, 1.0
	v_rcp_f32_e32 v134, v80
	s_nop 0
	v_fma_f32 v136, -v80, v134, 1.0
	v_fmac_f32_e32 v134, v136, v134
	v_div_scale_f32 v136, vcc, 1.0, v126, 1.0
	v_mul_f32_e32 v137, v136, v134
	v_fma_f32 v138, -v80, v137, v136
	v_fmac_f32_e32 v137, v138, v134
	v_fma_f32 v80, -v80, v137, v136
	v_div_fmas_f32 v80, v80, v134, v137
	v_div_fixup_f32 v126, v80, v126, 1.0
	v_mul_f32_e32 v80, 0xbfb8aa3b, v128
	v_exp_f32_e32 v128, v80
	v_mul_f32_e32 v80, 0xbfb8aa3b, v129
	v_exp_f32_e32 v129, v80
	v_pk_fma_f32 v[126:127], v[126:127], v[132:133], v[130:131]
	v_lshlrev_b32_e32 v132, 16, v179
	v_and_b32_e32 v133, 0xffff0000, v179
	v_pk_add_f32 v[128:129], v[128:129], 1.0 op_sel_hi:[1,0]
	v_lshlrev_b32_e32 v130, 16, v187
	v_div_scale_f32 v80, s[4:5], v129, v129, 1.0
	v_rcp_f32_e32 v134, v80
	v_and_b32_e32 v131, 0xffff0000, v187
	v_fma_f32 v135, -v80, v134, 1.0
	v_fmac_f32_e32 v134, v135, v134
	v_div_scale_f32 v135, vcc, 1.0, v129, 1.0
	v_mul_f32_e32 v136, v135, v134
	v_fma_f32 v137, -v80, v136, v135
	v_fmac_f32_e32 v136, v137, v134
	v_fma_f32 v80, -v80, v136, v135
	v_div_fmas_f32 v80, v80, v134, v136
	v_div_fixup_f32 v129, v80, v129, 1.0
	v_div_scale_f32 v80, s[4:5], v128, v128, 1.0
	v_rcp_f32_e32 v134, v80
	s_nop 0
	v_fma_f32 v135, -v80, v134, 1.0
	v_fmac_f32_e32 v134, v135, v134
	v_div_scale_f32 v135, vcc, 1.0, v128, 1.0
	v_mul_f32_e32 v136, v135, v134
	v_fma_f32 v137, -v80, v136, v135
	v_fmac_f32_e32 v136, v137, v134
	v_fma_f32 v80, -v80, v136, v135
	v_div_fmas_f32 v80, v80, v134, v136
	v_div_fixup_f32 v128, v80, v128, 1.0
	v_pk_fma_f32 v[128:129], v[128:129], v[132:133], v[130:131]
	v_lshl_add_u64 v[134:135], v[148:149], 0, v[142:143]
	v_cvt_pk_bf16_f32 v130, v122, v123
	v_cvt_pk_bf16_f32 v131, v124, v125
	v_cvt_pk_bf16_f32 v132, v126, v127
	v_cvt_pk_bf16_f32 v133, v128, v129
	global_store_dwordx4 v[134:135], v[130:133], off
	s_cbranch_scc1 .LBB0_961
	s_nop 0
	v_lshl_add_u64 v[130:131], v[140:141], 2, v[156:157]
	global_store_dwordx4 v[130:131], v[122:125], off
	global_store_dwordx4 v[130:131], v[126:129], off offset:16
